# GEMM K-loops all trims: no setprio, single pre-barrier lgkmcnt(0), ds_reads first, post-MFMA tails past the barrier
# speedup vs baseline: 1.0049x; 1.0049x over previous
; #define PG8_STAGE(bufoff, gbase, voff) do { _Pragma("unroll") for (int _i = 0; _i < 2; ++_i) \
;         __builtin_amdgcn_global_load_lds((const unsigned*)((const char*)(gbase) + (voff)[_i]), (PG8_LAS unsigned*)(lds + (bufoff) + ldsw + _i * 8192), 16, 0, 0); } while (0)
; #define PG8_LDA(dst, b, h) do { _Pragma("unroll") for (int m = 0; m < 4; ++m) _Pragma("unroll") for (int k = 0; k < 2; ++k) dst[m][k] = *(const PG8_LAS bf16x8*)(lds + PG8_SA(b, h) + aoff + m * 2048 + k * 1024); } while (0)
; #define PG8_LDB(dst, b, h) do { _Pragma("unroll") for (int n = 0; n < 2; ++n) _Pragma("unroll") for (int k = 0; k < 2; ++k) dst[n][k] = *(const PG8_LAS bf16x8*)(lds + PG8_SB(b, h) + boff + n * 2048 + k * 1024); } while (0)
; #define PG8_MMA(ai, bj, At, Bt) do { __builtin_amdgcn_s_setprio(1); _Pragma("unroll") for (int m = 0; m < 4; ++m) _Pragma("unroll") for (int n = 0; n < 2; ++n) _Pragma("unroll") for (int k = 0; k < 2; ++k) \
;         acc[ai][bj][m][n] = __builtin_amdgcn_mfma_f32_16x16x32_bf16(Bt[n][k], At[m][k], acc[ai][bj][m][n], 0, 0, 0); __builtin_amdgcn_s_setprio(0); } while (0)
; #define PG8_WAIT_L(n) asm volatile("s_waitcnt lgkmcnt(" #n ")" ::: "memory")
; #define PG8_BAR __builtin_amdgcn_s_barrier()
; #define PG8_SCHED __builtin_amdgcn_sched_barrier(0)
; template <class Epi, class Sched>
; __device__ __forceinline__ void gemm_phase(PG8_LAS unsigned char* lds, const Gemm g, const Sched& S, const Epi& E) {
;     ...
;             const bool last = (t == nt - 2);
;             const char* a1 = cA + (size_t)(t + 1) * kstep;
;             const char* a2 = last ? nA : cA + (size_t)(t + 2) * kstep; const char* b2 = last ? nB : cB + (size_t)(t + 2) * kstep;
;             const char* a3 = a2 + kstep; const char* b3 = b2 + kstep;
;             if (last && has_next) S.a_ready(nxt);
;             PG8_LDB(B0, 0, 0); PG8_SCHED; PG8_LDA(At, 0, 0); PG8_STAGE(PG8_SA(1, 1), a1 + hstep, voffA);
;             PG8_WAIT_L(8); PG8_BAR; PG8_WAIT_L(0); PG8_MMA(0, 0, At, B0); PG8_BAR; PG8_SCHED;
;             PG8_LDB(B1, 0, 1); PG8_STAGE(PG8_SB(0, 0), b2, voffB);
;             PG8_BAR; PG8_WAIT_L(0); PG8_MMA(0, 1, At, B1); PG8_BAR;
;             PG8_LDA(At, 0, 1); PG8_STAGE(PG8_SA(0, 0), a2, voffA);
;             PG8_BAR; PG8_WAIT_L(0); PG8_MMA(1, 0, At, B0); PG8_BAR; PG8_SCHED;
.LBB0_195:
	ds_read_b128 v[144:147], v151
	ds_read_b128 v[156:159], v151 offset:1024
	ds_read_b128 v[160:163], v151 offset:2048
	ds_read_b128 v[166:169], v151 offset:3072
	ds_read_b128 v[170:173], v153
	ds_read_b128 v[182:185], v153 offset:1024
	ds_read_b128 v[190:193], v153 offset:2048
	ds_read_b128 v[194:197], v153 offset:3072
	ds_read_b128 v[198:201], v153 offset:4096
	ds_read_b128 v[202:205], v153 offset:5120
	ds_read_b128 v[206:209], v153 offset:6144
	ds_read_b128 v[210:213], v153 offset:7168
	s_add_u32 s30, s28, 0xfffc0080
	s_addc_u32 s31, s29, -1
	s_cmp_eq_u32 s58, 12
	s_cselect_b32 s35, s17, s31
	s_cselect_b32 s34, s54, s30
	s_cselect_b32 s31, s15, s57
	s_cselect_b32 s30, s55, s56
	v_lshl_add_u64 v[174:175], s[28:29], 0, v[136:137]
	s_add_i32 m0, s27, 0xc000
	s_nop 0
	global_load_lds_dwordx4 v[174:175], off
	v_lshl_add_u64 v[174:175], s[28:29], 0, v[138:139]
	s_add_i32 m0, s27, 0xe000
	s_nop 0
	global_load_lds_dwordx4 v[174:175], off
	s_waitcnt lgkmcnt(0)
	s_barrier
	v_mfma_f32_16x16x32_bf16 v[124:127], v[144:147], v[170:173], v[124:127]
	v_mfma_f32_16x16x32_bf16 v[120:123], v[160:163], v[170:173], v[120:123]
	v_mfma_f32_16x16x32_bf16 v[108:111], v[144:147], v[190:193], v[108:111]
	v_mfma_f32_16x16x32_bf16 v[104:107], v[160:163], v[190:193], v[104:107]
	v_mfma_f32_16x16x32_bf16 v[92:95], v[144:147], v[198:201], v[92:95]
	v_mfma_f32_16x16x32_bf16 v[88:91], v[160:163], v[198:201], v[88:91]
	v_mfma_f32_16x16x32_bf16 v[76:79], v[144:147], v[206:209], v[76:79]
	v_mfma_f32_16x16x32_bf16 v[72:75], v[160:163], v[206:209], v[72:75]
	v_mfma_f32_16x16x32_bf16 v[124:127], v[156:159], v[182:185], v[124:127]
	v_mfma_f32_16x16x32_bf16 v[120:123], v[166:169], v[182:185], v[120:123]
	v_mfma_f32_16x16x32_bf16 v[108:111], v[156:159], v[194:197], v[108:111]
	v_mfma_f32_16x16x32_bf16 v[104:107], v[166:169], v[194:197], v[104:107]
	v_mfma_f32_16x16x32_bf16 v[92:95], v[156:159], v[202:205], v[92:95]
	v_mfma_f32_16x16x32_bf16 v[88:91], v[166:169], v[202:205], v[88:91]
	v_mfma_f32_16x16x32_bf16 v[76:79], v[156:159], v[210:213], v[76:79]
	v_mfma_f32_16x16x32_bf16 v[72:75], v[166:169], v[210:213], v[72:75]
	s_barrier
	ds_read_b128 v[214:217], v154
	ds_read_b128 v[218:221], v154 offset:1024
	ds_read_b128 v[222:225], v154 offset:2048
	ds_read_b128 v[226:229], v154 offset:3072
	s_add_i32 s59, s50, s40
	v_lshl_add_u64 v[174:175], s[30:31], 0, v[132:133]
	s_mov_b32 m0, s59
	s_nop 0
	global_load_lds_dwordx4 v[174:175], off
	v_lshl_add_u64 v[178:179], s[30:31], 0, v[128:129]
	s_add_i32 m0, s59, 0x2000
	s_nop 0
	global_load_lds_dwordx4 v[178:179], off
	s_waitcnt lgkmcnt(0)
	s_barrier
	v_mfma_f32_16x16x32_bf16 v[116:119], v[214:217], v[170:173], v[116:119]
	v_mfma_f32_16x16x32_bf16 v[112:115], v[222:225], v[170:173], v[112:115]
	v_mfma_f32_16x16x32_bf16 v[100:103], v[214:217], v[190:193], v[100:103]
	v_mfma_f32_16x16x32_bf16 v[96:99], v[222:225], v[190:193], v[96:99]
	v_mfma_f32_16x16x32_bf16 v[84:87], v[214:217], v[198:201], v[84:87]
	v_mfma_f32_16x16x32_bf16 v[80:83], v[222:225], v[198:201], v[80:83]
	v_mfma_f32_16x16x32_bf16 v[68:71], v[214:217], v[206:209], v[68:71]
	v_mfma_f32_16x16x32_bf16 v[64:67], v[222:225], v[206:209], v[64:67]
	v_mfma_f32_16x16x32_bf16 v[116:119], v[218:221], v[182:185], v[116:119]
	v_mfma_f32_16x16x32_bf16 v[112:115], v[226:229], v[182:185], v[112:115]
	v_mfma_f32_16x16x32_bf16 v[100:103], v[218:221], v[194:197], v[100:103]
	v_mfma_f32_16x16x32_bf16 v[96:99], v[226:229], v[194:197], v[96:99]
	v_mfma_f32_16x16x32_bf16 v[84:87], v[218:221], v[202:205], v[84:87]
	v_mfma_f32_16x16x32_bf16 v[80:83], v[226:229], v[202:205], v[80:83]
	v_mfma_f32_16x16x32_bf16 v[68:71], v[218:221], v[210:213], v[68:71]
	v_mfma_f32_16x16x32_bf16 v[64:67], v[226:229], v[210:213], v[64:67]
	s_barrier
	s_mov_b32 m0, s27
	v_lshl_add_u64 v[186:187], s[34:35], 0, v[134:135]
	ds_read_b128 v[170:173], v153 offset:16384
	ds_read_b128 v[182:185], v153 offset:17408
	ds_read_b128 v[190:193], v153 offset:18432
	ds_read_b128 v[194:197], v153 offset:19456
	ds_read_b128 v[198:201], v153 offset:20480
	ds_read_b128 v[202:205], v153 offset:21504
	ds_read_b128 v[206:209], v153 offset:22528
	ds_read_b128 v[210:213], v153 offset:23552
	global_load_lds_dwordx4 v[186:187], off
	v_lshl_add_u64 v[230:231], s[34:35], 0, v[130:131]
	s_mov_b32 m0, s43
	s_nop 0
	global_load_lds_dwordx4 v[230:231], off
	s_waitcnt lgkmcnt(0)
	s_barrier
	v_mfma_f32_16x16x32_bf16 v[60:63], v[144:147], v[170:173], v[60:63]
	v_mfma_f32_16x16x32_bf16 v[56:59], v[160:163], v[170:173], v[56:59]
	v_mfma_f32_16x16x32_bf16 v[44:47], v[144:147], v[190:193], v[44:47]
	v_mfma_f32_16x16x32_bf16 v[40:43], v[160:163], v[190:193], v[40:43]
	v_mfma_f32_16x16x32_bf16 v[28:31], v[144:147], v[198:201], v[28:31]
	v_mfma_f32_16x16x32_bf16 v[24:27], v[160:163], v[198:201], v[24:27]
	v_mfma_f32_16x16x32_bf16 v[12:15], v[144:147], v[206:209], v[12:15]
	v_mfma_f32_16x16x32_bf16 v[8:11], v[160:163], v[206:209], v[8:11]
	v_mfma_f32_16x16x32_bf16 v[60:63], v[156:159], v[182:185], v[60:63]
	v_mfma_f32_16x16x32_bf16 v[56:59], v[166:169], v[182:185], v[56:59]
	v_mfma_f32_16x16x32_bf16 v[44:47], v[156:159], v[194:197], v[44:47]
	v_mfma_f32_16x16x32_bf16 v[40:43], v[166:169], v[194:197], v[40:43]
	v_mfma_f32_16x16x32_bf16 v[28:31], v[156:159], v[202:205], v[28:31]
	v_mfma_f32_16x16x32_bf16 v[24:27], v[166:169], v[202:205], v[24:27]
	v_mfma_f32_16x16x32_bf16 v[12:15], v[156:159], v[210:213], v[12:15]
	v_mfma_f32_16x16x32_bf16 v[8:11], v[166:169], v[210:213], v[8:11]
	s_barrier
; #define PG8_STAGE(bufoff, gbase, voff) do { _Pragma("unroll") for (int _i = 0; _i < 2; ++_i) \
;         __builtin_amdgcn_global_load_lds((const unsigned*)((const char*)(gbase) + (voff)[_i]), (PG8_LAS unsigned*)(lds + (bufoff) + ldsw + _i * 8192), 16, 0, 0); } while (0)
; #define PG8_LDA(dst, b, h) do { _Pragma("unroll") for (int m = 0; m < 4; ++m) _Pragma("unroll") for (int k = 0; k < 2; ++k) dst[m][k] = *(const PG8_LAS bf16x8*)(lds + PG8_SA(b, h) + aoff + m * 2048 + k * 1024); } while (0)
; #define PG8_LDB(dst, b, h) do { _Pragma("unroll") for (int n = 0; n < 2; ++n) _Pragma("unroll") for (int k = 0; k < 2; ++k) dst[n][k] = *(const PG8_LAS bf16x8*)(lds + PG8_SB(b, h) + boff + n * 2048 + k * 1024); } while (0)
; #define PG8_MMA(ai, bj, At, Bt) do { __builtin_amdgcn_s_setprio(1); _Pragma("unroll") for (int m = 0; m < 4; ++m) _Pragma("unroll") for (int n = 0; n < 2; ++n) _Pragma("unroll") for (int k = 0; k < 2; ++k) \
;         acc[ai][bj][m][n] = __builtin_amdgcn_mfma_f32_16x16x32_bf16(Bt[n][k], At[m][k], acc[ai][bj][m][n], 0, 0, 0); __builtin_amdgcn_s_setprio(0); } while (0)
; #define PG8_WAIT_V(n) asm volatile("s_waitcnt vmcnt(" #n ")" ::: "memory")
; #define PG8_WAIT_L(n) asm volatile("s_waitcnt lgkmcnt(" #n ")" ::: "memory")
; #define PG8_BAR __builtin_amdgcn_s_barrier()
; #define PG8_SCHED __builtin_amdgcn_sched_barrier(0)
; template <class Epi, class Sched>
; __device__ __forceinline__ void gemm_phase(PG8_LAS unsigned char* lds, const Gemm g, const Sched& S, const Epi& E) {
;     ...
;             PG8_STAGE(PG8_SB(0, 1), b2 + hstep, voffB);
;             PG8_WAIT_V(6); PG8_BAR; PG8_MMA(1, 1, At, B1); PG8_BAR;
;             PG8_LDB(B0, 1, 0); PG8_SCHED; PG8_LDA(At, 1, 0); PG8_STAGE(PG8_SA(0, 1), a2 + hstep, voffA);
;             PG8_WAIT_L(8); PG8_BAR; PG8_WAIT_L(0); PG8_MMA(0, 0, At, B0); PG8_BAR; PG8_SCHED;
;             PG8_LDB(B1, 1, 1); PG8_STAGE(PG8_SB(1, 0), b3, voffB);
;             PG8_BAR; PG8_WAIT_L(0); PG8_MMA(0, 1, At, B1); PG8_BAR;
;             PG8_LDA(At, 1, 1); PG8_STAGE(PG8_SA(1, 0), a3, voffA);
	s_add_u32 s60, s30, 0x40000
	s_addc_u32 s61, s31, 0
	s_add_i32 s59, s51, s40
	v_lshl_add_u64 v[144:145], s[60:61], 0, v[132:133]
	s_mov_b32 m0, s59
	s_nop 0
	global_load_lds_dwordx4 v[144:145], off
	v_lshl_add_u64 v[144:145], s[60:61], 0, v[128:129]
	s_add_i32 m0, s59, 0x2000
	s_nop 0
	global_load_lds_dwordx4 v[144:145], off
	s_waitcnt vmcnt(6)
	s_barrier
	v_mfma_f32_16x16x32_bf16 v[52:55], v[214:217], v[170:173], v[52:55]
	v_mfma_f32_16x16x32_bf16 v[48:51], v[222:225], v[170:173], v[48:51]
	v_mfma_f32_16x16x32_bf16 v[36:39], v[214:217], v[190:193], v[36:39]
	v_mfma_f32_16x16x32_bf16 v[32:35], v[222:225], v[190:193], v[32:35]
	v_mfma_f32_16x16x32_bf16 v[20:23], v[214:217], v[198:201], v[20:23]
	v_mfma_f32_16x16x32_bf16 v[16:19], v[222:225], v[198:201], v[16:19]
	v_mfma_f32_16x16x32_bf16 v[4:7], v[214:217], v[206:209], v[4:7]
	v_mfma_f32_16x16x32_bf16 v[0:3], v[222:225], v[206:209], v[0:3]
	v_mfma_f32_16x16x32_bf16 v[52:55], v[218:221], v[182:185], v[52:55]
	v_mfma_f32_16x16x32_bf16 v[48:51], v[226:229], v[182:185], v[48:51]
	v_mfma_f32_16x16x32_bf16 v[36:39], v[218:221], v[194:197], v[36:39]
	v_mfma_f32_16x16x32_bf16 v[32:35], v[226:229], v[194:197], v[32:35]
	v_mfma_f32_16x16x32_bf16 v[20:23], v[218:221], v[202:205], v[20:23]
	v_mfma_f32_16x16x32_bf16 v[16:19], v[226:229], v[202:205], v[16:19]
	v_mfma_f32_16x16x32_bf16 v[4:7], v[218:221], v[210:213], v[4:7]
	v_mfma_f32_16x16x32_bf16 v[0:3], v[226:229], v[210:213], v[0:3]
	s_barrier
	s_add_i32 s59, 0, 0x18000
	v_add_u32_e32 v155, s59, v149
	ds_read_b128 v[144:147], v155
	ds_read_b128 v[156:159], v155 offset:1024
	ds_read_b128 v[160:163], v155 offset:2048
	ds_read_b128 v[166:169], v155 offset:3072
	ds_read_b128 v[170:173], v153 offset:32768
	ds_read_b128 v[182:185], v153 offset:33792
	ds_read_b128 v[190:193], v153 offset:34816
	ds_read_b128 v[194:197], v153 offset:35840
	ds_read_b128 v[198:201], v153 offset:36864
	ds_read_b128 v[202:205], v153 offset:37888
	ds_read_b128 v[206:209], v153 offset:38912
	ds_read_b128 v[210:213], v153 offset:39936
	s_add_u32 s34, s34, 0x40000
	s_addc_u32 s35, s35, 0
	s_mov_b32 m0, s44
	v_lshl_add_u64 v[214:215], s[34:35], 0, v[134:135]
	global_load_lds_dwordx4 v[214:215], off
	v_lshl_add_u64 v[214:215], s[34:35], 0, v[130:131]
	s_mov_b32 m0, s45
	s_nop 0
	global_load_lds_dwordx4 v[214:215], off
	s_waitcnt lgkmcnt(0)
	s_barrier
	v_mfma_f32_16x16x32_bf16 v[124:127], v[144:147], v[170:173], v[124:127]
	v_mfma_f32_16x16x32_bf16 v[120:123], v[160:163], v[170:173], v[120:123]
	v_mfma_f32_16x16x32_bf16 v[108:111], v[144:147], v[190:193], v[108:111]
	v_mfma_f32_16x16x32_bf16 v[104:107], v[160:163], v[190:193], v[104:107]
	v_mfma_f32_16x16x32_bf16 v[92:95], v[144:147], v[198:201], v[92:95]
	v_mfma_f32_16x16x32_bf16 v[88:91], v[160:163], v[198:201], v[88:91]
	v_mfma_f32_16x16x32_bf16 v[76:79], v[144:147], v[206:209], v[76:79]
	v_mfma_f32_16x16x32_bf16 v[72:75], v[160:163], v[206:209], v[72:75]
	v_mfma_f32_16x16x32_bf16 v[124:127], v[156:159], v[182:185], v[124:127]
	v_mfma_f32_16x16x32_bf16 v[120:123], v[166:169], v[182:185], v[120:123]
	v_mfma_f32_16x16x32_bf16 v[108:111], v[156:159], v[194:197], v[108:111]
	v_mfma_f32_16x16x32_bf16 v[104:107], v[166:169], v[194:197], v[104:107]
	v_mfma_f32_16x16x32_bf16 v[92:95], v[156:159], v[202:205], v[92:95]
	v_mfma_f32_16x16x32_bf16 v[88:91], v[166:169], v[202:205], v[88:91]
	v_mfma_f32_16x16x32_bf16 v[76:79], v[156:159], v[210:213], v[76:79]
	v_mfma_f32_16x16x32_bf16 v[72:75], v[166:169], v[210:213], v[72:75]
	s_barrier
	s_add_i32 s34, 0, 0x1c000
	v_add_u32_e32 v155, s34, v149
	ds_read_b128 v[214:217], v155
	ds_read_b128 v[218:221], v155 offset:1024
	ds_read_b128 v[222:225], v155 offset:2048
	ds_read_b128 v[226:229], v155 offset:3072
	s_add_i32 s35, s59, s40
	v_lshl_add_u64 v[174:175], v[174:175], 0, s[10:11]
	s_mov_b32 m0, s35
	s_nop 0
	global_load_lds_dwordx4 v[174:175], off
	v_lshl_add_u64 v[174:175], v[178:179], 0, s[10:11]
	s_add_i32 m0, s35, 0x2000
	s_nop 0
	global_load_lds_dwordx4 v[174:175], off
	s_waitcnt lgkmcnt(0)
	s_barrier
	v_mfma_f32_16x16x32_bf16 v[116:119], v[214:217], v[170:173], v[116:119]
	v_mfma_f32_16x16x32_bf16 v[112:115], v[222:225], v[170:173], v[112:115]
	v_mfma_f32_16x16x32_bf16 v[100:103], v[214:217], v[190:193], v[100:103]
	v_mfma_f32_16x16x32_bf16 v[96:99], v[222:225], v[190:193], v[96:99]
	v_mfma_f32_16x16x32_bf16 v[84:87], v[214:217], v[198:201], v[84:87]
	v_mfma_f32_16x16x32_bf16 v[80:83], v[222:225], v[198:201], v[80:83]
	v_mfma_f32_16x16x32_bf16 v[68:71], v[214:217], v[206:209], v[68:71]
	v_mfma_f32_16x16x32_bf16 v[64:67], v[222:225], v[206:209], v[64:67]
	v_mfma_f32_16x16x32_bf16 v[116:119], v[218:221], v[182:185], v[116:119]
	v_mfma_f32_16x16x32_bf16 v[112:115], v[226:229], v[182:185], v[112:115]
	v_mfma_f32_16x16x32_bf16 v[100:103], v[218:221], v[194:197], v[100:103]
	v_mfma_f32_16x16x32_bf16 v[96:99], v[226:229], v[194:197], v[96:99]
	v_mfma_f32_16x16x32_bf16 v[84:87], v[218:221], v[202:205], v[84:87]
	v_mfma_f32_16x16x32_bf16 v[80:83], v[226:229], v[202:205], v[80:83]
	v_mfma_f32_16x16x32_bf16 v[68:71], v[218:221], v[210:213], v[68:71]
	v_mfma_f32_16x16x32_bf16 v[64:67], v[226:229], v[210:213], v[64:67]
	s_barrier
	s_mov_b32 m0, s47
	v_lshl_add_u64 v[174:175], v[186:187], 0, s[10:11]
	ds_read_b128 v[170:173], v153 offset:49152
	ds_read_b128 v[182:185], v153 offset:50176
	ds_read_b128 v[190:193], v153 offset:51200
	ds_read_b128 v[194:197], v153 offset:52224
	ds_read_b128 v[198:201], v153 offset:53248
	ds_read_b128 v[202:205], v153 offset:54272
	ds_read_b128 v[206:209], v153 offset:55296
	ds_read_b128 v[210:213], v153 offset:56320
	global_load_lds_dwordx4 v[174:175], off
	v_lshl_add_u64 v[174:175], v[230:231], 0, s[10:11]
	s_mov_b32 m0, s48
	s_nop 0
	global_load_lds_dwordx4 v[174:175], off
	s_waitcnt lgkmcnt(0)
	s_barrier
; __device__ __forceinline__ unsigned cvt_pk_bf16(float lo, float hi) { unsigned r; asm volatile("v_cvt_pk_bf16_f32 %0, %1, %2" : "=v"(r) : "v"(lo), "v"(hi)); return r; }
; #define PG8_STAGE(bufoff, gbase, voff) do { _Pragma("unroll") for (int _i = 0; _i < 2; ++_i) \
;         __builtin_amdgcn_global_load_lds((const unsigned*)((const char*)(gbase) + (voff)[_i]), (PG8_LAS unsigned*)(lds + (bufoff) + ldsw + _i * 8192), 16, 0, 0); } while (0)
; #define PG8_MMA(ai, bj, At, Bt) do { __builtin_amdgcn_s_setprio(1); _Pragma("unroll") for (int m = 0; m < 4; ++m) _Pragma("unroll") for (int n = 0; n < 2; ++n) _Pragma("unroll") for (int k = 0; k < 2; ++k) \
;         acc[ai][bj][m][n] = __builtin_amdgcn_mfma_f32_16x16x32_bf16(Bt[n][k], At[m][k], acc[ai][bj][m][n], 0, 0, 0); __builtin_amdgcn_s_setprio(0); } while (0)
; __device__ __forceinline__ f32x4 sigmoid4(f32x4 x) {
;     f32x4 d;
; #pragma unroll
;     for (int j = 0; j < 4; ++j) d[j] = 1.0f + __expf(-fmaxf(x[j], -20.0f));
;     const float p01 = d[0] * d[1], p23 = d[2] * d[3], r = __builtin_amdgcn_rcpf(p01 * p23), r01 = r * p23, r23 = r * p01;
;     return (f32x4){r01 * d[1], r01 * d[0], r23 * d[3], r23 * d[2]};
; }
;     __device__ __forceinline__ void operator()(const f32x4 (&acc)[2][2][4][2], const Unit& u, int wr, int wc, int fr, int fq) const {
;         const int row0 = u.pm * BM + wr * 64 + fr, col0 = u.pn * HALF + wc * 32 + 8 * fq;
; #pragma unroll
;         for (int ai = 0; ai < 2; ++ai)
; #pragma unroll
;             for (int m = 0; m < 4; ++m) { bf16_t* rowp = O + (size_t)(row0 + ai * HALF + m * 16) * ldc + col0;
;                 f32x4 v0, v1;
; #pragma unroll
;                 for (int j = 0; j < 1; ++j) { v0 = acc[ai][0][m][0] * sigmoid4(acc[ai][0][m][0]) * acc[ai][1][m][0]; v1 = acc[ai][0][m][1] * sigmoid4(acc[ai][0][m][1]) * acc[ai][1][m][1]; }
;                 u32x4 w; w.x = cvt_pk_bf16(v0[0], v0[1]); w.y = cvt_pk_bf16(v0[2], v0[3]); w.z = cvt_pk_bf16(v1[0], v1[1]); w.w = cvt_pk_bf16(v1[2], v1[3]);
;                 *(u32x4*)rowp = w; }
; template <class Epi, class Sched>
; __device__ __forceinline__ void gemm_phase(PG8_LAS unsigned char* lds, const Gemm g, const Sched& S, const Epi& E) {
;     ...
;             PG8_BAR; PG8_WAIT_L(0); PG8_MMA(1, 0, At, B0); PG8_BAR; PG8_SCHED;
;             PG8_STAGE(PG8_SB(1, 1), b3 + hstep, voffB);
;             PG8_WAIT_V(6); PG8_BAR; PG8_MMA(1, 1, At, B1); PG8_BAR;
	v_mfma_f32_16x16x32_bf16 v[60:63], v[144:147], v[170:173], v[60:63]
	v_mfma_f32_16x16x32_bf16 v[56:59], v[160:163], v[170:173], v[56:59]
	v_mfma_f32_16x16x32_bf16 v[44:47], v[144:147], v[190:193], v[44:47]
	v_mfma_f32_16x16x32_bf16 v[40:43], v[160:163], v[190:193], v[40:43]
	v_mfma_f32_16x16x32_bf16 v[28:31], v[144:147], v[198:201], v[28:31]
	v_mfma_f32_16x16x32_bf16 v[24:27], v[160:163], v[198:201], v[24:27]
	v_mfma_f32_16x16x32_bf16 v[12:15], v[144:147], v[206:209], v[12:15]
	v_mfma_f32_16x16x32_bf16 v[8:11], v[160:163], v[206:209], v[8:11]
	v_mfma_f32_16x16x32_bf16 v[60:63], v[156:159], v[182:185], v[60:63]
	v_mfma_f32_16x16x32_bf16 v[56:59], v[166:169], v[182:185], v[56:59]
	v_mfma_f32_16x16x32_bf16 v[44:47], v[156:159], v[194:197], v[44:47]
	v_mfma_f32_16x16x32_bf16 v[40:43], v[166:169], v[194:197], v[40:43]
	v_mfma_f32_16x16x32_bf16 v[28:31], v[156:159], v[202:205], v[28:31]
	v_mfma_f32_16x16x32_bf16 v[24:27], v[166:169], v[202:205], v[24:27]
	v_mfma_f32_16x16x32_bf16 v[12:15], v[156:159], v[210:213], v[12:15]
	v_mfma_f32_16x16x32_bf16 v[8:11], v[166:169], v[210:213], v[8:11]
	s_barrier
	s_add_u32 s30, s30, 0x40080
	s_addc_u32 s31, s31, 0
	s_add_i32 s34, s34, s40
	v_lshl_add_u64 v[144:145], s[30:31], 0, v[132:133]
	s_mov_b32 m0, s34
	s_nop 0
	global_load_lds_dwordx4 v[144:145], off
	v_lshl_add_u64 v[144:145], s[30:31], 0, v[128:129]
	s_add_i32 m0, s34, 0x2000
	s_nop 0
	global_load_lds_dwordx4 v[144:145], off
	s_waitcnt vmcnt(6)
	s_barrier
	v_mfma_f32_16x16x32_bf16 v[52:55], v[214:217], v[170:173], v[52:55]
	v_mfma_f32_16x16x32_bf16 v[48:51], v[222:225], v[170:173], v[48:51]
	v_mfma_f32_16x16x32_bf16 v[36:39], v[214:217], v[190:193], v[36:39]
	v_mfma_f32_16x16x32_bf16 v[32:35], v[222:225], v[190:193], v[32:35]
	v_mfma_f32_16x16x32_bf16 v[20:23], v[214:217], v[198:201], v[20:23]
	v_mfma_f32_16x16x32_bf16 v[16:19], v[222:225], v[198:201], v[16:19]
	v_mfma_f32_16x16x32_bf16 v[4:7], v[214:217], v[206:209], v[4:7]
	v_mfma_f32_16x16x32_bf16 v[0:3], v[222:225], v[206:209], v[0:3]
	v_mfma_f32_16x16x32_bf16 v[52:55], v[218:221], v[182:185], v[52:55]
	v_mfma_f32_16x16x32_bf16 v[48:51], v[226:229], v[182:185], v[48:51]
	v_mfma_f32_16x16x32_bf16 v[36:39], v[218:221], v[194:197], v[36:39]
	v_mfma_f32_16x16x32_bf16 v[32:35], v[226:229], v[194:197], v[32:35]
	v_mfma_f32_16x16x32_bf16 v[20:23], v[218:221], v[202:205], v[20:23]
	v_mfma_f32_16x16x32_bf16 v[16:19], v[226:229], v[202:205], v[16:19]
	v_mfma_f32_16x16x32_bf16 v[4:7], v[218:221], v[210:213], v[4:7]
	v_mfma_f32_16x16x32_bf16 v[0:3], v[226:229], v[210:213], v[0:3]
	s_barrier
	s_add_i32 s58, s58, 2
	s_add_u32 s28, s28, 0x100
	s_addc_u32 s29, s29, 0
	s_add_u32 s56, s56, 0x100
	s_addc_u32 s57, s57, 0
	s_cmp_gt_u32 s58, 13
	s_cbranch_scc0 .LBB0_195
	v_max_f32_e32 v144, v124, v124
	v_max_f32_e32 v144, 0xc1a00000, v144
	v_mul_f32_e32 v144, 0xbfb8aa3b, v144
	v_exp_f32_e32 v157, v144
	v_max_f32_e32 v144, v125, v125
	v_max_f32_e32 v144, 0xc1a00000, v144
	v_mul_f32_e32 v144, 0xbfb8aa3b, v144
	v_exp_f32_e32 v156, v144
	v_max_f32_e32 v144, v126, v126
	v_max_f32_e32 v144, 0xc1a00000, v144
	v_mul_f32_e32 v144, 0xbfb8aa3b, v144
	v_exp_f32_e32 v159, v144
	v_max_f32_e32 v144, v127, v127
	v_max_f32_e32 v144, 0xc1a00000, v144
	v_mul_f32_e32 v144, 0xbfb8aa3b, v144
	v_exp_f32_e32 v158, v144
	v_pk_add_f32 v[156:157], v[156:157], 1.0 op_sel_hi:[1,0]
	v_lshl_or_b32 v146, s53, 7, v150
	v_mov_b32_e32 v160, v157
	v_pk_add_f32 v[158:159], v[158:159], 1.0 op_sel_hi:[1,0]
	v_mov_b32_e32 v162, v156
	v_mov_b32_e32 v161, v159
	v_mov_b32_e32 v163, v158
	v_pk_mul_f32 v[160:161], v[160:161], v[162:163]
	v_lshl_add_u32 v155, s26, 8, v148
	v_mul_f32_e32 v162, v160, v161
	v_rcp_f32_e32 v166, v162
	v_ashrrev_i32_e32 v147, 31, v146
	v_mov_b64_e32 v[144:145], s[4:5]
	v_mad_i64_i32 v[162:163], s[28:29], v155, s52, v[144:145]
	v_mul_f32_e32 v160, v160, v166
	v_mul_f32_e32 v164, v161, v166
	v_pk_mul_f32 v[158:159], v[158:159], v[160:161] op_sel_hi:[1,0]
	v_max_f32_e32 v160, v120, v120
	v_max_f32_e32 v166, v122, v122
	v_max_f32_e32 v160, 0xc1a00000, v160
	v_max_f32_e32 v166, 0xc1a00000, v166
	v_mul_f32_e32 v160, 0xbfb8aa3b, v160
	v_mul_f32_e32 v166, 0xbfb8aa3b, v166
	v_exp_f32_e32 v161, v160
	v_max_f32_e32 v160, v121, v121
	v_exp_f32_e32 v167, v166
	v_max_f32_e32 v166, v123, v123
	v_max_f32_e32 v160, 0xc1a00000, v160
	v_max_f32_e32 v166, 0xc1a00000, v166
	v_mul_f32_e32 v160, 0xbfb8aa3b, v160
	v_mul_f32_e32 v166, 0xbfb8aa3b, v166
	v_exp_f32_e32 v160, v160
	v_exp_f32_e32 v166, v166
	v_pk_mul_f32 v[156:157], v[156:157], v[164:165] op_sel_hi:[1,0]
	v_pk_mul_f32 v[126:127], v[126:127], v[158:159]
	v_pk_mul_f32 v[124:125], v[124:125], v[156:157]
	v_pk_add_f32 v[156:157], v[160:161], 1.0 op_sel_hi:[1,0]
	v_pk_add_f32 v[160:161], v[166:167], 1.0 op_sel_hi:[1,0]
	v_mov_b32_e32 v166, v157
	v_mov_b32_e32 v167, v161
	v_mov_b32_e32 v168, v156
	v_mov_b32_e32 v169, v160
	v_pk_mul_f32 v[166:167], v[166:167], v[168:169]
	v_pk_mul_f32 v[118:119], v[126:127], v[118:119]
	v_mul_f32_e32 v164, v166, v167
	v_rcp_f32_e32 v164, v164
	v_pk_mul_f32 v[116:117], v[124:125], v[116:117]
	v_lshlrev_b64 v[146:147], 1, v[146:147]
	v_lshl_add_u64 v[162:163], v[162:163], 0, v[146:147]
	v_mul_f32_e32 v124, v167, v164
	v_mul_f32_e32 v126, v166, v164
	v_pk_mul_f32 v[126:127], v[160:161], v[126:127] op_sel_hi:[1,0]
	v_pk_mul_f32 v[124:125], v[156:157], v[124:125] op_sel_hi:[1,0]
	v_pk_mul_f32 v[122:123], v[122:123], v[126:127]
	v_pk_mul_f32 v[120:121], v[120:121], v[124:125]
	v_pk_mul_f32 v[122:123], v[122:123], v[114:115]
	v_pk_mul_f32 v[114:115], v[120:121], v[112:113]
	v_cvt_pk_bf16_f32 v112, v116, v117
	v_cvt_pk_bf16_f32 v113, v118, v119
	v_max_f32_e32 v116, v108, v108
; __device__ __forceinline__ unsigned cvt_pk_bf16(float lo, float hi) { unsigned r; asm volatile("v_cvt_pk_bf16_f32 %0, %1, %2" : "=v"(r) : "v"(lo), "v"(hi)); return r; }
; __device__ __forceinline__ f32x4 sigmoid4(f32x4 x) {
;     f32x4 d;
; #pragma unroll
;     for (int j = 0; j < 4; ++j) d[j] = 1.0f + __expf(-fmaxf(x[j], -20.0f));
;     const float p01 = d[0] * d[1], p23 = d[2] * d[3], r = __builtin_amdgcn_rcpf(p01 * p23), r01 = r * p23, r23 = r * p01;
;     return (f32x4){r01 * d[1], r01 * d[0], r23 * d[3], r23 * d[2]};
; }
;     __device__ __forceinline__ void operator()(const f32x4 (&acc)[2][2][4][2], const Unit& u, int wr, int wc, int fr, int fq) const {
;         const int row0 = u.pm * BM + wr * 64 + fr, col0 = u.pn * HALF + wc * 32 + 8 * fq;
; #pragma unroll
;         for (int ai = 0; ai < 2; ++ai)
; #pragma unroll
;             for (int m = 0; m < 4; ++m) { bf16_t* rowp = O + (size_t)(row0 + ai * HALF + m * 16) * ldc + col0;
;                 f32x4 v0, v1;
; #pragma unroll
;                 for (int j = 0; j < 1; ++j) { v0 = acc[ai][0][m][0] * sigmoid4(acc[ai][0][m][0]) * acc[ai][1][m][0]; v1 = acc[ai][0][m][1] * sigmoid4(acc[ai][0][m][1]) * acc[ai][1][m][1]; }
;                 u32x4 w; w.x = cvt_pk_bf16(v0[0], v0[1]); w.y = cvt_pk_bf16(v0[2], v0[3]); w.z = cvt_pk_bf16(v1[0], v1[1]); w.w = cvt_pk_bf16(v1[2], v1[3]);
;                 *(u32x4*)rowp = w; }
	v_max_f32_e32 v118, v110, v110
	v_max_f32_e32 v116, 0xc1a00000, v116
	v_max_f32_e32 v118, 0xc1a00000, v118
	v_mul_f32_e32 v116, 0xbfb8aa3b, v116
	v_mul_f32_e32 v118, 0xbfb8aa3b, v118
	v_exp_f32_e32 v117, v116
	v_max_f32_e32 v116, v109, v109
	v_exp_f32_e32 v119, v118
	v_max_f32_e32 v118, v111, v111
	v_max_f32_e32 v116, 0xc1a00000, v116
	v_max_f32_e32 v118, 0xc1a00000, v118
	v_mul_f32_e32 v116, 0xbfb8aa3b, v116
	v_mul_f32_e32 v118, 0xbfb8aa3b, v118
	v_exp_f32_e32 v116, v116
	v_exp_f32_e32 v118, v118
	v_cvt_pk_bf16_f32 v114, v114, v115
	v_cvt_pk_bf16_f32 v115, v122, v123
	global_store_dwordx4 v[162:163], v[112:115], off
	v_or_b32_e32 v120, 16, v155
	s_and_b64 vcc, exec, s[2:3]
	v_pk_add_f32 v[112:113], v[116:117], 1.0 op_sel_hi:[1,0]
	v_pk_add_f32 v[114:115], v[118:119], 1.0 op_sel_hi:[1,0]
	v_mov_b32_e32 v116, v113
	v_mov_b32_e32 v117, v115
	v_mov_b32_e32 v118, v112
	v_mov_b32_e32 v119, v114
	v_pk_mul_f32 v[116:117], v[116:117], v[118:119]
	s_mov_b32 s53, s14
	v_mul_f32_e32 v118, v116, v117
	v_rcp_f32_e32 v121, v118
	v_mad_i64_i32 v[118:119], s[28:29], v120, s52, v[144:145]
	v_lshl_add_u64 v[118:119], v[118:119], 0, v[146:147]
	v_mul_f32_e32 v116, v116, v121
	v_mul_f32_e32 v120, v117, v121
	v_pk_mul_f32 v[114:115], v[114:115], v[116:117] op_sel_hi:[1,0]
	v_max_f32_e32 v116, v104, v104
	v_max_f32_e32 v121, v106, v106
	v_max_f32_e32 v116, 0xc1a00000, v116
	v_max_f32_e32 v121, 0xc1a00000, v121
	v_mul_f32_e32 v116, 0xbfb8aa3b, v116
	v_mul_f32_e32 v121, 0xbfb8aa3b, v121
	v_exp_f32_e32 v117, v116
	v_max_f32_e32 v116, v105, v105
	v_exp_f32_e32 v123, v121
	v_max_f32_e32 v121, v107, v107
	v_max_f32_e32 v116, 0xc1a00000, v116
	v_max_f32_e32 v121, 0xc1a00000, v121
	v_mul_f32_e32 v116, 0xbfb8aa3b, v116
	v_mul_f32_e32 v121, 0xbfb8aa3b, v121
	v_exp_f32_e32 v116, v116
	v_exp_f32_e32 v122, v121
	v_pk_mul_f32 v[112:113], v[112:113], v[120:121] op_sel_hi:[1,0]
	v_pk_mul_f32 v[110:111], v[110:111], v[114:115]
	v_pk_mul_f32 v[108:109], v[108:109], v[112:113]
	v_pk_add_f32 v[112:113], v[116:117], 1.0 op_sel_hi:[1,0]
	v_pk_add_f32 v[116:117], v[122:123], 1.0 op_sel_hi:[1,0]
	v_mov_b32_e32 v120, v113
	v_mov_b32_e32 v121, v117
	v_mov_b32_e32 v122, v112
	v_mov_b32_e32 v123, v116
	v_pk_mul_f32 v[120:121], v[120:121], v[122:123]
	v_pk_mul_f32 v[102:103], v[110:111], v[102:103]
	v_mul_f32_e32 v122, v120, v121
	v_rcp_f32_e32 v122, v122
	v_pk_mul_f32 v[100:101], v[108:109], v[100:101]
	s_mov_b32 s26, s16
	s_mov_b64 s[30:31], s[24:25]
	v_mul_f32_e32 v108, v121, v122
	v_mul_f32_e32 v110, v120, v122
	v_pk_mul_f32 v[110:111], v[116:117], v[110:111] op_sel_hi:[1,0]
	v_pk_mul_f32 v[108:109], v[112:113], v[108:109] op_sel_hi:[1,0]
	v_pk_mul_f32 v[106:107], v[106:107], v[110:111]
	v_pk_mul_f32 v[104:105], v[104:105], v[108:109]
	v_pk_mul_f32 v[106:107], v[106:107], v[98:99]
	v_pk_mul_f32 v[98:99], v[104:105], v[96:97]
	v_cvt_pk_bf16_f32 v96, v100, v101
	v_cvt_pk_bf16_f32 v97, v102, v103
	v_max_f32_e32 v100, v92, v92
	v_max_f32_e32 v102, v94, v94
	v_max_f32_e32 v100, 0xc1a00000, v100
	v_max_f32_e32 v102, 0xc1a00000, v102
	v_mul_f32_e32 v100, 0xbfb8aa3b, v100
	v_mul_f32_e32 v102, 0xbfb8aa3b, v102
	v_exp_f32_e32 v101, v100
	v_max_f32_e32 v100, v93, v93
	v_exp_f32_e32 v103, v102
	v_max_f32_e32 v102, v95, v95
	v_max_f32_e32 v100, 0xc1a00000, v100
	v_max_f32_e32 v102, 0xc1a00000, v102
	v_mul_f32_e32 v100, 0xbfb8aa3b, v100
	v_mul_f32_e32 v102, 0xbfb8aa3b, v102
	v_exp_f32_e32 v100, v100
	v_exp_f32_e32 v102, v102
	v_cvt_pk_bf16_f32 v98, v98, v99
	v_cvt_pk_bf16_f32 v99, v106, v107
	global_store_dwordx4 v[118:119], v[96:99], off
	v_or_b32_e32 v104, 32, v155
	s_nop 0
	v_pk_add_f32 v[96:97], v[100:101], 1.0 op_sel_hi:[1,0]
	v_pk_add_f32 v[98:99], v[102:103], 1.0 op_sel_hi:[1,0]
	v_mov_b32_e32 v100, v97
	v_mov_b32_e32 v101, v99
	v_mov_b32_e32 v102, v96
	v_mov_b32_e32 v103, v98
	v_pk_mul_f32 v[100:101], v[100:101], v[102:103]
	s_nop 0
	v_mul_f32_e32 v102, v100, v101
	v_rcp_f32_e32 v105, v102
	v_mad_i64_i32 v[102:103], s[28:29], v104, s52, v[144:145]
	v_lshl_add_u64 v[102:103], v[102:103], 0, v[146:147]
	v_mul_f32_e32 v100, v100, v105
	v_mul_f32_e32 v104, v101, v105
	v_pk_mul_f32 v[98:99], v[98:99], v[100:101] op_sel_hi:[1,0]
	v_max_f32_e32 v100, v88, v88
	v_max_f32_e32 v105, v90, v90
	v_max_f32_e32 v100, 0xc1a00000, v100
	v_max_f32_e32 v105, 0xc1a00000, v105
	v_mul_f32_e32 v100, 0xbfb8aa3b, v100
	v_mul_f32_e32 v105, 0xbfb8aa3b, v105
	v_exp_f32_e32 v101, v100
	v_max_f32_e32 v100, v89, v89
	v_exp_f32_e32 v107, v105
	v_max_f32_e32 v105, v91, v91
	v_max_f32_e32 v100, 0xc1a00000, v100
	v_max_f32_e32 v105, 0xc1a00000, v105
	v_mul_f32_e32 v100, 0xbfb8aa3b, v100
	v_mul_f32_e32 v105, 0xbfb8aa3b, v105
	v_exp_f32_e32 v100, v100
	v_exp_f32_e32 v106, v105
	v_pk_mul_f32 v[96:97], v[96:97], v[104:105] op_sel_hi:[1,0]
	v_pk_mul_f32 v[94:95], v[94:95], v[98:99]
	v_pk_mul_f32 v[92:93], v[92:93], v[96:97]
	v_pk_add_f32 v[96:97], v[100:101], 1.0 op_sel_hi:[1,0]
	v_pk_add_f32 v[100:101], v[106:107], 1.0 op_sel_hi:[1,0]
	v_mov_b32_e32 v104, v97
	v_mov_b32_e32 v105, v101
	v_mov_b32_e32 v106, v96
	v_mov_b32_e32 v107, v100
	v_pk_mul_f32 v[104:105], v[104:105], v[106:107]
	v_pk_mul_f32 v[86:87], v[94:95], v[86:87]
	v_mul_f32_e32 v106, v104, v105
	v_rcp_f32_e32 v106, v106
	v_pk_mul_f32 v[84:85], v[92:93], v[84:85]
	v_mul_f32_e32 v92, v105, v106
	v_mul_f32_e32 v94, v104, v106
	v_pk_mul_f32 v[94:95], v[100:101], v[94:95] op_sel_hi:[1,0]
	v_pk_mul_f32 v[92:93], v[96:97], v[92:93] op_sel_hi:[1,0]
	v_pk_mul_f32 v[90:91], v[90:91], v[94:95]
	v_pk_mul_f32 v[88:89], v[88:89], v[92:93]
	v_pk_mul_f32 v[90:91], v[90:91], v[82:83]
	v_pk_mul_f32 v[82:83], v[88:89], v[80:81]
	v_cvt_pk_bf16_f32 v80, v84, v85
	v_cvt_pk_bf16_f32 v81, v86, v87
; __device__ __forceinline__ unsigned cvt_pk_bf16(float lo, float hi) { unsigned r; asm volatile("v_cvt_pk_bf16_f32 %0, %1, %2" : "=v"(r) : "v"(lo), "v"(hi)); return r; }
; __device__ __forceinline__ f32x4 sigmoid4(f32x4 x) {
;     f32x4 d;
; #pragma unroll
;     for (int j = 0; j < 4; ++j) d[j] = 1.0f + __expf(-fmaxf(x[j], -20.0f));
;     const float p01 = d[0] * d[1], p23 = d[2] * d[3], r = __builtin_amdgcn_rcpf(p01 * p23), r01 = r * p23, r23 = r * p01;
;     return (f32x4){r01 * d[1], r01 * d[0], r23 * d[3], r23 * d[2]};
; }
;     __device__ __forceinline__ void operator()(const f32x4 (&acc)[2][2][4][2], const Unit& u, int wr, int wc, int fr, int fq) const {
;         const int row0 = u.pm * BM + wr * 64 + fr, col0 = u.pn * HALF + wc * 32 + 8 * fq;
; #pragma unroll
;         for (int ai = 0; ai < 2; ++ai)
; #pragma unroll
;             for (int m = 0; m < 4; ++m) { bf16_t* rowp = O + (size_t)(row0 + ai * HALF + m * 16) * ldc + col0;
;                 f32x4 v0, v1;
; #pragma unroll
;                 for (int j = 0; j < 1; ++j) { v0 = acc[ai][0][m][0] * sigmoid4(acc[ai][0][m][0]) * acc[ai][1][m][0]; v1 = acc[ai][0][m][1] * sigmoid4(acc[ai][0][m][1]) * acc[ai][1][m][1]; }
;                 u32x4 w; w.x = cvt_pk_bf16(v0[0], v0[1]); w.y = cvt_pk_bf16(v0[2], v0[3]); w.z = cvt_pk_bf16(v1[0], v1[1]); w.w = cvt_pk_bf16(v1[2], v1[3]);
;                 *(u32x4*)rowp = w; }
	v_max_f32_e32 v84, v76, v76
	v_max_f32_e32 v86, v78, v78
	v_max_f32_e32 v84, 0xc1a00000, v84
	v_max_f32_e32 v86, 0xc1a00000, v86
	v_mul_f32_e32 v84, 0xbfb8aa3b, v84
	v_mul_f32_e32 v86, 0xbfb8aa3b, v86
	v_exp_f32_e32 v85, v84
	v_max_f32_e32 v84, v77, v77
	v_exp_f32_e32 v87, v86
	v_max_f32_e32 v86, v79, v79
	v_max_f32_e32 v84, 0xc1a00000, v84
	v_max_f32_e32 v86, 0xc1a00000, v86
	v_mul_f32_e32 v84, 0xbfb8aa3b, v84
	v_mul_f32_e32 v86, 0xbfb8aa3b, v86
	v_exp_f32_e32 v84, v84
	v_exp_f32_e32 v86, v86
	v_cvt_pk_bf16_f32 v82, v82, v83
	v_cvt_pk_bf16_f32 v83, v90, v91
	global_store_dwordx4 v[102:103], v[80:83], off
	v_or_b32_e32 v88, 48, v155
	s_nop 0
	v_pk_add_f32 v[80:81], v[84:85], 1.0 op_sel_hi:[1,0]
	v_pk_add_f32 v[82:83], v[86:87], 1.0 op_sel_hi:[1,0]
	v_mov_b32_e32 v84, v81
	v_mov_b32_e32 v85, v83
	v_mov_b32_e32 v86, v80
	v_mov_b32_e32 v87, v82
	v_pk_mul_f32 v[84:85], v[84:85], v[86:87]
	s_nop 0
	v_mul_f32_e32 v86, v84, v85
	v_rcp_f32_e32 v89, v86
	v_mad_i64_i32 v[86:87], s[28:29], v88, s52, v[144:145]
	v_lshl_add_u64 v[86:87], v[86:87], 0, v[146:147]
	v_mul_f32_e32 v84, v84, v89
	v_mul_f32_e32 v88, v85, v89
	v_pk_mul_f32 v[82:83], v[82:83], v[84:85] op_sel_hi:[1,0]
	v_max_f32_e32 v84, v72, v72
	v_max_f32_e32 v89, v74, v74
	v_max_f32_e32 v84, 0xc1a00000, v84
	v_max_f32_e32 v89, 0xc1a00000, v89
	v_mul_f32_e32 v84, 0xbfb8aa3b, v84
	v_mul_f32_e32 v89, 0xbfb8aa3b, v89
	v_exp_f32_e32 v85, v84
	v_max_f32_e32 v84, v73, v73
	v_exp_f32_e32 v91, v89
	v_max_f32_e32 v89, v75, v75
	v_max_f32_e32 v84, 0xc1a00000, v84
	v_max_f32_e32 v89, 0xc1a00000, v89
	v_mul_f32_e32 v84, 0xbfb8aa3b, v84
	v_mul_f32_e32 v89, 0xbfb8aa3b, v89
	v_exp_f32_e32 v84, v84
	v_exp_f32_e32 v90, v89
	v_pk_mul_f32 v[80:81], v[80:81], v[88:89] op_sel_hi:[1,0]
	v_pk_mul_f32 v[78:79], v[78:79], v[82:83]
	v_pk_mul_f32 v[76:77], v[76:77], v[80:81]
	v_pk_add_f32 v[80:81], v[84:85], 1.0 op_sel_hi:[1,0]
	v_pk_add_f32 v[84:85], v[90:91], 1.0 op_sel_hi:[1,0]
	v_mov_b32_e32 v88, v81
	v_mov_b32_e32 v89, v85
	v_mov_b32_e32 v90, v80
	v_mov_b32_e32 v91, v84
	v_pk_mul_f32 v[88:89], v[88:89], v[90:91]
	v_pk_mul_f32 v[70:71], v[78:79], v[70:71]
	v_mul_f32_e32 v90, v88, v89
	v_rcp_f32_e32 v90, v90
	v_pk_mul_f32 v[68:69], v[76:77], v[68:69]
	v_mul_f32_e32 v76, v89, v90
	v_mul_f32_e32 v78, v88, v90
	v_pk_mul_f32 v[78:79], v[84:85], v[78:79] op_sel_hi:[1,0]
	v_pk_mul_f32 v[76:77], v[80:81], v[76:77] op_sel_hi:[1,0]
	v_pk_mul_f32 v[74:75], v[74:75], v[78:79]
	v_pk_mul_f32 v[72:73], v[72:73], v[76:77]
	v_pk_mul_f32 v[74:75], v[74:75], v[66:67]
	v_pk_mul_f32 v[66:67], v[72:73], v[64:65]
	v_cvt_pk_bf16_f32 v64, v68, v69
	v_cvt_pk_bf16_f32 v65, v70, v71
	v_max_f32_e32 v68, v60, v60
	v_max_f32_e32 v70, v62, v62
	v_max_f32_e32 v68, 0xc1a00000, v68
	v_max_f32_e32 v70, 0xc1a00000, v70
	v_mul_f32_e32 v68, 0xbfb8aa3b, v68
	v_mul_f32_e32 v70, 0xbfb8aa3b, v70
	v_exp_f32_e32 v69, v68
	v_max_f32_e32 v68, v61, v61
	v_exp_f32_e32 v71, v70
	v_max_f32_e32 v70, v63, v63
	v_max_f32_e32 v68, 0xc1a00000, v68
	v_max_f32_e32 v70, 0xc1a00000, v70
	v_mul_f32_e32 v68, 0xbfb8aa3b, v68
	v_mul_f32_e32 v70, 0xbfb8aa3b, v70
	v_exp_f32_e32 v68, v68
	v_exp_f32_e32 v70, v70
	v_cvt_pk_bf16_f32 v66, v66, v67
	v_cvt_pk_bf16_f32 v67, v74, v75
	global_store_dwordx4 v[86:87], v[64:67], off
	v_add_u32_e32 v72, 0x80, v155
	s_nop 0
	v_pk_add_f32 v[64:65], v[68:69], 1.0 op_sel_hi:[1,0]
	v_pk_add_f32 v[66:67], v[70:71], 1.0 op_sel_hi:[1,0]
	v_mov_b32_e32 v68, v65
	v_mov_b32_e32 v69, v67
	v_mov_b32_e32 v70, v64
	v_mov_b32_e32 v71, v66
	v_pk_mul_f32 v[68:69], v[68:69], v[70:71]
	s_nop 0
	v_mul_f32_e32 v70, v68, v69
	v_rcp_f32_e32 v73, v70
	v_mad_i64_i32 v[70:71], s[28:29], v72, s52, v[144:145]
	v_lshl_add_u64 v[70:71], v[70:71], 0, v[146:147]
	v_mul_f32_e32 v68, v68, v73
	v_mul_f32_e32 v72, v69, v73
	v_pk_mul_f32 v[66:67], v[66:67], v[68:69] op_sel_hi:[1,0]
	v_max_f32_e32 v68, v56, v56
	v_max_f32_e32 v73, v58, v58
	v_max_f32_e32 v68, 0xc1a00000, v68
	v_max_f32_e32 v73, 0xc1a00000, v73
	v_mul_f32_e32 v68, 0xbfb8aa3b, v68
	v_mul_f32_e32 v73, 0xbfb8aa3b, v73
	v_exp_f32_e32 v69, v68
	v_max_f32_e32 v68, v57, v57
	v_exp_f32_e32 v75, v73
	v_max_f32_e32 v73, v59, v59
	v_max_f32_e32 v68, 0xc1a00000, v68
	v_max_f32_e32 v73, 0xc1a00000, v73
	v_mul_f32_e32 v68, 0xbfb8aa3b, v68
	v_mul_f32_e32 v73, 0xbfb8aa3b, v73
	v_exp_f32_e32 v68, v68
	v_exp_f32_e32 v74, v73
	v_pk_mul_f32 v[64:65], v[64:65], v[72:73] op_sel_hi:[1,0]
	v_pk_mul_f32 v[62:63], v[62:63], v[66:67]
	v_pk_mul_f32 v[60:61], v[60:61], v[64:65]
	v_pk_add_f32 v[64:65], v[68:69], 1.0 op_sel_hi:[1,0]
	v_pk_add_f32 v[68:69], v[74:75], 1.0 op_sel_hi:[1,0]
	v_mov_b32_e32 v72, v65
	v_mov_b32_e32 v73, v69
	v_mov_b32_e32 v74, v64
	v_mov_b32_e32 v75, v68
	v_pk_mul_f32 v[72:73], v[72:73], v[74:75]
	v_pk_mul_f32 v[54:55], v[62:63], v[54:55]
	v_mul_f32_e32 v74, v72, v73
	v_rcp_f32_e32 v74, v74
	v_pk_mul_f32 v[52:53], v[60:61], v[52:53]
	v_mul_f32_e32 v60, v73, v74
	v_mul_f32_e32 v62, v72, v74
	v_pk_mul_f32 v[62:63], v[68:69], v[62:63] op_sel_hi:[1,0]
	v_pk_mul_f32 v[60:61], v[64:65], v[60:61] op_sel_hi:[1,0]
	v_pk_mul_f32 v[58:59], v[58:59], v[62:63]
	v_pk_mul_f32 v[56:57], v[56:57], v[60:61]
	v_pk_mul_f32 v[58:59], v[58:59], v[50:51]
	v_pk_mul_f32 v[50:51], v[56:57], v[48:49]
	v_cvt_pk_bf16_f32 v48, v52, v53
	v_cvt_pk_bf16_f32 v49, v54, v55
	v_max_f32_e32 v52, v44, v44
	v_max_f32_e32 v54, v46, v46
	v_max_f32_e32 v52, 0xc1a00000, v52
	v_max_f32_e32 v54, 0xc1a00000, v54
	v_mul_f32_e32 v52, 0xbfb8aa3b, v52
	v_mul_f32_e32 v54, 0xbfb8aa3b, v54
	v_exp_f32_e32 v53, v52
	v_max_f32_e32 v52, v45, v45
	v_exp_f32_e32 v55, v54
	v_max_f32_e32 v54, v47, v47
	v_max_f32_e32 v52, 0xc1a00000, v52
	v_max_f32_e32 v54, 0xc1a00000, v54
; __device__ __forceinline__ unsigned cvt_pk_bf16(float lo, float hi) { unsigned r; asm volatile("v_cvt_pk_bf16_f32 %0, %1, %2" : "=v"(r) : "v"(lo), "v"(hi)); return r; }
; __device__ __forceinline__ f32x4 sigmoid4(f32x4 x) {
;     f32x4 d;
; #pragma unroll
;     for (int j = 0; j < 4; ++j) d[j] = 1.0f + __expf(-fmaxf(x[j], -20.0f));
;     const float p01 = d[0] * d[1], p23 = d[2] * d[3], r = __builtin_amdgcn_rcpf(p01 * p23), r01 = r * p23, r23 = r * p01;
;     return (f32x4){r01 * d[1], r01 * d[0], r23 * d[3], r23 * d[2]};
; }
;     __device__ __forceinline__ void operator()(const f32x4 (&acc)[2][2][4][2], const Unit& u, int wr, int wc, int fr, int fq) const {
;         const int row0 = u.pm * BM + wr * 64 + fr, col0 = u.pn * HALF + wc * 32 + 8 * fq;
; #pragma unroll
;         for (int ai = 0; ai < 2; ++ai)
; #pragma unroll
;             for (int m = 0; m < 4; ++m) { bf16_t* rowp = O + (size_t)(row0 + ai * HALF + m * 16) * ldc + col0;
;                 f32x4 v0, v1;
; #pragma unroll
;                 for (int j = 0; j < 1; ++j) { v0 = acc[ai][0][m][0] * sigmoid4(acc[ai][0][m][0]) * acc[ai][1][m][0]; v1 = acc[ai][0][m][1] * sigmoid4(acc[ai][0][m][1]) * acc[ai][1][m][1]; }
;                 u32x4 w; w.x = cvt_pk_bf16(v0[0], v0[1]); w.y = cvt_pk_bf16(v0[2], v0[3]); w.z = cvt_pk_bf16(v1[0], v1[1]); w.w = cvt_pk_bf16(v1[2], v1[3]);
;                 *(u32x4*)rowp = w; }
	v_mul_f32_e32 v52, 0xbfb8aa3b, v52
	v_mul_f32_e32 v54, 0xbfb8aa3b, v54
	v_exp_f32_e32 v52, v52
	v_exp_f32_e32 v54, v54
	v_cvt_pk_bf16_f32 v50, v50, v51
	v_cvt_pk_bf16_f32 v51, v58, v59
	global_store_dwordx4 v[70:71], v[48:51], off
	v_add_u32_e32 v56, 0x90, v155
	s_nop 0
	v_pk_add_f32 v[48:49], v[52:53], 1.0 op_sel_hi:[1,0]
	v_pk_add_f32 v[50:51], v[54:55], 1.0 op_sel_hi:[1,0]
	v_mov_b32_e32 v52, v49
	v_mov_b32_e32 v53, v51
	v_mov_b32_e32 v54, v48
	v_mov_b32_e32 v55, v50
	v_pk_mul_f32 v[52:53], v[52:53], v[54:55]
	s_nop 0
	v_mul_f32_e32 v54, v52, v53
	v_rcp_f32_e32 v57, v54
	v_mad_i64_i32 v[54:55], s[28:29], v56, s52, v[144:145]
	v_lshl_add_u64 v[54:55], v[54:55], 0, v[146:147]
	v_mul_f32_e32 v52, v52, v57
	v_mul_f32_e32 v56, v53, v57
	v_pk_mul_f32 v[50:51], v[50:51], v[52:53] op_sel_hi:[1,0]
	v_max_f32_e32 v52, v40, v40
	v_max_f32_e32 v57, v42, v42
	v_max_f32_e32 v52, 0xc1a00000, v52
	v_max_f32_e32 v57, 0xc1a00000, v57
	v_mul_f32_e32 v52, 0xbfb8aa3b, v52
	v_mul_f32_e32 v57, 0xbfb8aa3b, v57
	v_exp_f32_e32 v53, v52
	v_max_f32_e32 v52, v41, v41
	v_exp_f32_e32 v59, v57
	v_max_f32_e32 v57, v43, v43
	v_max_f32_e32 v52, 0xc1a00000, v52
	v_max_f32_e32 v57, 0xc1a00000, v57
	v_mul_f32_e32 v52, 0xbfb8aa3b, v52
	v_mul_f32_e32 v57, 0xbfb8aa3b, v57
	v_exp_f32_e32 v52, v52
	v_exp_f32_e32 v58, v57
	v_pk_mul_f32 v[48:49], v[48:49], v[56:57] op_sel_hi:[1,0]
	v_pk_mul_f32 v[46:47], v[46:47], v[50:51]
	v_pk_mul_f32 v[44:45], v[44:45], v[48:49]
	v_pk_add_f32 v[48:49], v[52:53], 1.0 op_sel_hi:[1,0]
	v_pk_add_f32 v[52:53], v[58:59], 1.0 op_sel_hi:[1,0]
	v_mov_b32_e32 v56, v49
	v_mov_b32_e32 v57, v53
	v_mov_b32_e32 v58, v48
	v_mov_b32_e32 v59, v52
	v_pk_mul_f32 v[56:57], v[56:57], v[58:59]
	v_pk_mul_f32 v[38:39], v[46:47], v[38:39]
	v_mul_f32_e32 v58, v56, v57
	v_rcp_f32_e32 v58, v58
	v_pk_mul_f32 v[36:37], v[44:45], v[36:37]
	v_mul_f32_e32 v44, v57, v58
	v_mul_f32_e32 v46, v56, v58
	v_pk_mul_f32 v[46:47], v[52:53], v[46:47] op_sel_hi:[1,0]
	v_pk_mul_f32 v[44:45], v[48:49], v[44:45] op_sel_hi:[1,0]
	v_pk_mul_f32 v[42:43], v[42:43], v[46:47]
	v_pk_mul_f32 v[40:41], v[40:41], v[44:45]
	v_pk_mul_f32 v[42:43], v[42:43], v[34:35]
	v_pk_mul_f32 v[34:35], v[40:41], v[32:33]
	v_cvt_pk_bf16_f32 v32, v36, v37
	v_cvt_pk_bf16_f32 v33, v38, v39
	v_max_f32_e32 v36, v28, v28
	v_max_f32_e32 v38, v30, v30
	v_max_f32_e32 v36, 0xc1a00000, v36
	v_max_f32_e32 v38, 0xc1a00000, v38
	v_mul_f32_e32 v36, 0xbfb8aa3b, v36
	v_mul_f32_e32 v38, 0xbfb8aa3b, v38
	v_exp_f32_e32 v37, v36
	v_max_f32_e32 v36, v29, v29
	v_exp_f32_e32 v39, v38
	v_max_f32_e32 v38, v31, v31
	v_max_f32_e32 v36, 0xc1a00000, v36
	v_max_f32_e32 v38, 0xc1a00000, v38
	v_mul_f32_e32 v36, 0xbfb8aa3b, v36
	v_mul_f32_e32 v38, 0xbfb8aa3b, v38
	v_exp_f32_e32 v36, v36
	v_exp_f32_e32 v38, v38
	v_cvt_pk_bf16_f32 v34, v34, v35
	v_cvt_pk_bf16_f32 v35, v42, v43
	global_store_dwordx4 v[54:55], v[32:35], off
	v_add_u32_e32 v40, 0xa0, v155
	s_nop 0
	v_pk_add_f32 v[32:33], v[36:37], 1.0 op_sel_hi:[1,0]
	v_pk_add_f32 v[34:35], v[38:39], 1.0 op_sel_hi:[1,0]
	v_mov_b32_e32 v36, v33
	v_mov_b32_e32 v37, v35
	v_mov_b32_e32 v38, v32
	v_mov_b32_e32 v39, v34
	v_pk_mul_f32 v[36:37], v[36:37], v[38:39]
	s_nop 0
	v_mul_f32_e32 v38, v36, v37
	v_rcp_f32_e32 v41, v38
	v_mad_i64_i32 v[38:39], s[28:29], v40, s52, v[144:145]
	v_lshl_add_u64 v[38:39], v[38:39], 0, v[146:147]
	v_mul_f32_e32 v36, v36, v41
	v_mul_f32_e32 v40, v37, v41
	v_pk_mul_f32 v[34:35], v[34:35], v[36:37] op_sel_hi:[1,0]
	v_max_f32_e32 v36, v24, v24
	v_max_f32_e32 v41, v26, v26
	v_max_f32_e32 v36, 0xc1a00000, v36
	v_max_f32_e32 v41, 0xc1a00000, v41
	v_mul_f32_e32 v36, 0xbfb8aa3b, v36
	v_mul_f32_e32 v41, 0xbfb8aa3b, v41
	v_exp_f32_e32 v37, v36
	v_max_f32_e32 v36, v25, v25
	v_exp_f32_e32 v43, v41
	v_max_f32_e32 v41, v27, v27
	v_max_f32_e32 v36, 0xc1a00000, v36
	v_max_f32_e32 v41, 0xc1a00000, v41
	v_mul_f32_e32 v36, 0xbfb8aa3b, v36
; __device__ __forceinline__ unsigned cvt_pk_bf16(float lo, float hi) { unsigned r; asm volatile("v_cvt_pk_bf16_f32 %0, %1, %2" : "=v"(r) : "v"(lo), "v"(hi)); return r; }
; #define PG8_WAIT_V(n) asm volatile("s_waitcnt vmcnt(" #n ")" ::: "memory")
; #define PG8_BAR __builtin_amdgcn_s_barrier()
;     __device__ __forceinline__ void operator()(const f32x4 (&acc)[2][2][4][2], const Unit& u, int wr, int wc, int fr, int fq) const {
;         const int row0 = u.pm * BM + wr * 64 + fr, col0 = u.pn * HALF + wc * 32 + 8 * fq;
; #pragma unroll
;         for (int ai = 0; ai < 2; ++ai)
; #pragma unroll
;             for (int m = 0; m < 4; ++m) { bf16_t* rowp = O + (size_t)(row0 + ai * HALF + m * 16) * ldc + col0;
;                 f32x4 v0, v1;
; #pragma unroll
;                 for (int j = 0; j < 1; ++j) { v0 = acc[ai][0][m][0] * sigmoid4(acc[ai][0][m][0]) * acc[ai][1][m][0]; v1 = acc[ai][0][m][1] * sigmoid4(acc[ai][0][m][1]) * acc[ai][1][m][1]; }
;                 u32x4 w; w.x = cvt_pk_bf16(v0[0], v0[1]); w.y = cvt_pk_bf16(v0[2], v0[3]); w.z = cvt_pk_bf16(v1[0], v1[1]); w.w = cvt_pk_bf16(v1[2], v1[3]);
;                 *(u32x4*)rowp = w; }
; template <class Epi, class Sched>
; __device__ __forceinline__ void gemm_phase(PG8_LAS unsigned char* lds, const Gemm g, const Sched& S, const Epi& E) {
;     ...
;         if (!has_next) break;
; #pragma unroll
;         for (int a = 0; a < 2; ++a)
; #pragma unroll
;             for (int b = 0; b < 2; ++b)
; #pragma unroll
;                 for (int m = 0; m < 4; ++m)
; #pragma unroll
;                     for (int n = 0; n < 2; ++n) acc[a][b][m][n] = (f32x4){0.f, 0.f, 0.f, 0.f};
;         cur = nxt; cA = nA; cB = nB; ++ui;
;     }
;     PG8_WAIT_V(0);
;     if (wr == 0) PG8_BAR;
;     PG8_BAR;
	v_mul_f32_e32 v41, 0xbfb8aa3b, v41
	v_exp_f32_e32 v36, v36
	v_exp_f32_e32 v42, v41
	v_pk_mul_f32 v[32:33], v[32:33], v[40:41] op_sel_hi:[1,0]
	v_pk_mul_f32 v[30:31], v[30:31], v[34:35]
	v_pk_mul_f32 v[28:29], v[28:29], v[32:33]
	v_pk_add_f32 v[32:33], v[36:37], 1.0 op_sel_hi:[1,0]
	v_pk_add_f32 v[36:37], v[42:43], 1.0 op_sel_hi:[1,0]
	v_mov_b32_e32 v40, v33
	v_mov_b32_e32 v41, v37
	v_mov_b32_e32 v42, v32
	v_mov_b32_e32 v43, v36
	v_pk_mul_f32 v[40:41], v[40:41], v[42:43]
	v_pk_mul_f32 v[22:23], v[30:31], v[22:23]
	v_mul_f32_e32 v42, v40, v41
	v_rcp_f32_e32 v42, v42
	v_pk_mul_f32 v[20:21], v[28:29], v[20:21]
	v_mul_f32_e32 v28, v41, v42
	v_mul_f32_e32 v30, v40, v42
	v_pk_mul_f32 v[30:31], v[36:37], v[30:31] op_sel_hi:[1,0]
	v_pk_mul_f32 v[28:29], v[32:33], v[28:29] op_sel_hi:[1,0]
	v_pk_mul_f32 v[26:27], v[26:27], v[30:31]
	v_pk_mul_f32 v[24:25], v[24:25], v[28:29]
	v_pk_mul_f32 v[26:27], v[26:27], v[18:19]
	v_pk_mul_f32 v[18:19], v[24:25], v[16:17]
	v_cvt_pk_bf16_f32 v16, v20, v21
	v_cvt_pk_bf16_f32 v17, v22, v23
	v_max_f32_e32 v20, v12, v12
	v_max_f32_e32 v22, v14, v14
	v_max_f32_e32 v20, 0xc1a00000, v20
	v_max_f32_e32 v22, 0xc1a00000, v22
	v_mul_f32_e32 v20, 0xbfb8aa3b, v20
	v_mul_f32_e32 v22, 0xbfb8aa3b, v22
	v_exp_f32_e32 v21, v20
	v_max_f32_e32 v20, v13, v13
	v_exp_f32_e32 v23, v22
	v_max_f32_e32 v22, v15, v15
	v_max_f32_e32 v20, 0xc1a00000, v20
	v_max_f32_e32 v22, 0xc1a00000, v22
	v_mul_f32_e32 v20, 0xbfb8aa3b, v20
	v_mul_f32_e32 v22, 0xbfb8aa3b, v22
	v_exp_f32_e32 v20, v20
	v_exp_f32_e32 v22, v22
	v_cvt_pk_bf16_f32 v18, v18, v19
	v_cvt_pk_bf16_f32 v19, v26, v27
	global_store_dwordx4 v[38:39], v[16:19], off
	v_add_u32_e32 v24, 0xb0, v155
	s_nop 0
	v_pk_add_f32 v[16:17], v[20:21], 1.0 op_sel_hi:[1,0]
	v_pk_add_f32 v[18:19], v[22:23], 1.0 op_sel_hi:[1,0]
	v_mov_b32_e32 v20, v17
	v_mov_b32_e32 v21, v19
	v_mov_b32_e32 v22, v16
	v_mov_b32_e32 v23, v18
	v_pk_mul_f32 v[20:21], v[20:21], v[22:23]
	s_nop 0
	v_mul_f32_e32 v22, v20, v21
	v_rcp_f32_e32 v25, v22
	v_mad_i64_i32 v[22:23], s[28:29], v24, s52, v[144:145]
	v_lshl_add_u64 v[22:23], v[22:23], 0, v[146:147]
	v_mul_f32_e32 v20, v20, v25
	v_mul_f32_e32 v24, v21, v25
	v_pk_mul_f32 v[18:19], v[18:19], v[20:21] op_sel_hi:[1,0]
	v_max_f32_e32 v20, v8, v8
	v_max_f32_e32 v25, v10, v10
	v_max_f32_e32 v20, 0xc1a00000, v20
	v_max_f32_e32 v25, 0xc1a00000, v25
	v_mul_f32_e32 v20, 0xbfb8aa3b, v20
	v_mul_f32_e32 v25, 0xbfb8aa3b, v25
	v_exp_f32_e32 v21, v20
	v_max_f32_e32 v20, v9, v9
	v_exp_f32_e32 v27, v25
	v_max_f32_e32 v25, v11, v11
	v_max_f32_e32 v20, 0xc1a00000, v20
	v_max_f32_e32 v25, 0xc1a00000, v25
	v_mul_f32_e32 v20, 0xbfb8aa3b, v20
	v_mul_f32_e32 v25, 0xbfb8aa3b, v25
	v_exp_f32_e32 v20, v20
	v_exp_f32_e32 v26, v25
	v_pk_mul_f32 v[16:17], v[16:17], v[24:25] op_sel_hi:[1,0]
	v_pk_mul_f32 v[14:15], v[14:15], v[18:19]
	v_pk_mul_f32 v[12:13], v[12:13], v[16:17]
	v_pk_add_f32 v[16:17], v[20:21], 1.0 op_sel_hi:[1,0]
	v_pk_add_f32 v[20:21], v[26:27], 1.0 op_sel_hi:[1,0]
	v_mov_b32_e32 v24, v17
	v_mov_b32_e32 v25, v21
	v_mov_b32_e32 v26, v16
	v_mov_b32_e32 v27, v20
	v_pk_mul_f32 v[24:25], v[24:25], v[26:27]
	v_pk_mul_f32 v[6:7], v[14:15], v[6:7]
	v_mul_f32_e32 v26, v24, v25
	v_rcp_f32_e32 v26, v26
	v_pk_mul_f32 v[4:5], v[12:13], v[4:5]
	s_mov_b64 s[28:29], s[18:19]
	v_mul_f32_e32 v12, v25, v26
	v_mul_f32_e32 v14, v24, v26
	v_pk_mul_f32 v[14:15], v[20:21], v[14:15] op_sel_hi:[1,0]
	v_pk_mul_f32 v[12:13], v[16:17], v[12:13] op_sel_hi:[1,0]
	v_pk_mul_f32 v[10:11], v[10:11], v[14:15]
	v_pk_mul_f32 v[8:9], v[8:9], v[12:13]
	v_pk_mul_f32 v[10:11], v[10:11], v[2:3]
	v_pk_mul_f32 v[2:3], v[8:9], v[0:1]
	v_cvt_pk_bf16_f32 v0, v4, v5
	v_cvt_pk_bf16_f32 v1, v6, v7
	s_nop 0
	v_cvt_pk_bf16_f32 v2, v2, v3
	v_cvt_pk_bf16_f32 v3, v10, v11
	global_store_dwordx4 v[22:23], v[0:3], off
	s_cbranch_vccz .LBB0_192
	s_waitcnt vmcnt(0)
	s_cmpk_gt_u32 s37, 0xff
	s_cbranch_scc1 .LBB0_199
	s_barrier

; #define PG8_STAGE(bufoff, gbase, voff) do { _Pragma("unroll") for (int _i = 0; _i < 2; ++_i) \
;         __builtin_amdgcn_global_load_lds((const unsigned*)((const char*)(gbase) + (voff)[_i]), (PG8_LAS unsigned*)(lds + (bufoff) + ldsw + _i * 8192), 16, 0, 0); } while (0)
; #define PG8_LDA(dst, b, h) do { _Pragma("unroll") for (int m = 0; m < 4; ++m) _Pragma("unroll") for (int k = 0; k < 2; ++k) dst[m][k] = *(const PG8_LAS bf16x8*)(lds + PG8_SA(b, h) + aoff + m * 2048 + k * 1024); } while (0)
; #define PG8_LDB(dst, b, h) do { _Pragma("unroll") for (int n = 0; n < 2; ++n) _Pragma("unroll") for (int k = 0; k < 2; ++k) dst[n][k] = *(const PG8_LAS bf16x8*)(lds + PG8_SB(b, h) + boff + n * 2048 + k * 1024); } while (0)
; #define PG8_MMA(ai, bj, At, Bt) do { __builtin_amdgcn_s_setprio(1); _Pragma("unroll") for (int m = 0; m < 4; ++m) _Pragma("unroll") for (int n = 0; n < 2; ++n) _Pragma("unroll") for (int k = 0; k < 2; ++k) \
;         acc[ai][bj][m][n] = __builtin_amdgcn_mfma_f32_16x16x32_bf16(Bt[n][k], At[m][k], acc[ai][bj][m][n], 0, 0, 0); __builtin_amdgcn_s_setprio(0); } while (0)
; #define PG8_WAIT_L(n) asm volatile("s_waitcnt lgkmcnt(" #n ")" ::: "memory")
; #define PG8_BAR __builtin_amdgcn_s_barrier()
; #define PG8_SCHED __builtin_amdgcn_sched_barrier(0)
; template <class Epi, class Sched>
; __device__ __forceinline__ void gemm_phase(PG8_LAS unsigned char* lds, const Gemm g, const Sched& S, const Epi& E) {
;     ...
;             const bool last = (t == nt - 2);
;             const char* a1 = cA + (size_t)(t + 1) * kstep;
;             const char* a2 = last ? nA : cA + (size_t)(t + 2) * kstep; const char* b2 = last ? nB : cB + (size_t)(t + 2) * kstep;
;             const char* a3 = a2 + kstep; const char* b3 = b2 + kstep;
;             if (last && has_next) S.a_ready(nxt);
;             PG8_LDB(B0, 0, 0); PG8_SCHED; PG8_LDA(At, 0, 0); PG8_STAGE(PG8_SA(1, 1), a1 + hstep, voffA);
;             PG8_WAIT_L(8); PG8_BAR; PG8_WAIT_L(0); PG8_MMA(0, 0, At, B0); PG8_BAR; PG8_SCHED;
;             PG8_LDB(B1, 0, 1); PG8_STAGE(PG8_SB(0, 0), b2, voffB);
;             PG8_BAR; PG8_WAIT_L(0); PG8_MMA(0, 1, At, B1); PG8_BAR;
;             PG8_LDA(At, 0, 1); PG8_STAGE(PG8_SA(0, 0), a2, voffA);
;             PG8_BAR; PG8_WAIT_L(0); PG8_MMA(1, 0, At, B0); PG8_BAR; PG8_SCHED;
.LBB0_286:
	ds_read_b128 v[154:157], v149
	ds_read_b128 v[158:161], v149 offset:1024
	ds_read_b128 v[166:169], v149 offset:2048
	ds_read_b128 v[170:173], v149 offset:3072
	ds_read_b128 v[182:185], v150
	ds_read_b128 v[190:193], v150 offset:1024
	ds_read_b128 v[194:197], v150 offset:2048
	ds_read_b128 v[198:201], v150 offset:3072
	ds_read_b128 v[202:205], v150 offset:4096
	ds_read_b128 v[206:209], v150 offset:5120
	ds_read_b128 v[210:213], v150 offset:6144
	ds_read_b128 v[214:217], v150 offset:7168
	s_add_u32 s24, s22, 0x100
	s_addc_u32 s25, s23, 0
	s_cmp_eq_u32 s57, 40
	s_cselect_b32 s29, s1, s25
	s_cselect_b32 s28, s0, s24
	s_cselect_b32 s27, s5, s56
	s_cselect_b32 s26, s4, s55
	v_lshl_add_u64 v[144:145], s[22:23], 0, v[136:137]
	s_add_i32 m0, s38, 0xc000
	s_nop 0
	global_load_lds_dwordx4 v[144:145], off
	v_lshl_add_u64 v[144:145], s[22:23], 0, v[138:139]
	s_add_i32 m0, s38, 0xe000
	s_nop 0
	global_load_lds_dwordx4 v[144:145], off
	s_waitcnt lgkmcnt(0)
	s_barrier
	v_mfma_f32_16x16x32_bf16 v[124:127], v[154:157], v[182:185], v[124:127]
	v_mfma_f32_16x16x32_bf16 v[120:123], v[166:169], v[182:185], v[120:123]
	v_mfma_f32_16x16x32_bf16 v[108:111], v[154:157], v[194:197], v[108:111]
	v_mfma_f32_16x16x32_bf16 v[104:107], v[166:169], v[194:197], v[104:107]
	v_mfma_f32_16x16x32_bf16 v[92:95], v[154:157], v[202:205], v[92:95]
	v_mfma_f32_16x16x32_bf16 v[88:91], v[166:169], v[202:205], v[88:91]
	v_mfma_f32_16x16x32_bf16 v[76:79], v[154:157], v[210:213], v[76:79]
	v_mfma_f32_16x16x32_bf16 v[72:75], v[166:169], v[210:213], v[72:75]
	v_mfma_f32_16x16x32_bf16 v[124:127], v[158:161], v[190:193], v[124:127]
	v_mfma_f32_16x16x32_bf16 v[120:123], v[170:173], v[190:193], v[120:123]
	v_mfma_f32_16x16x32_bf16 v[108:111], v[158:161], v[198:201], v[108:111]
	v_mfma_f32_16x16x32_bf16 v[104:107], v[170:173], v[198:201], v[104:107]
	v_mfma_f32_16x16x32_bf16 v[92:95], v[158:161], v[206:209], v[92:95]
	v_mfma_f32_16x16x32_bf16 v[88:91], v[170:173], v[206:209], v[88:91]
	v_mfma_f32_16x16x32_bf16 v[76:79], v[158:161], v[214:217], v[76:79]
	v_mfma_f32_16x16x32_bf16 v[72:75], v[170:173], v[214:217], v[72:75]
	s_barrier
	ds_read_b128 v[218:221], v151
	ds_read_b128 v[222:225], v151 offset:1024
	ds_read_b128 v[226:229], v151 offset:2048
	ds_read_b128 v[230:233], v151 offset:3072
	s_add_i32 s22, s46, s37
	v_lshl_add_u64 v[144:145], s[26:27], 0, v[130:131]
	s_mov_b32 m0, s22
	s_nop 0
	global_load_lds_dwordx4 v[144:145], off
	v_lshl_add_u64 v[162:163], s[26:27], 0, v[134:135]
	s_add_i32 m0, s22, 0x2000
	s_nop 0
	global_load_lds_dwordx4 v[162:163], off
	s_waitcnt lgkmcnt(0)
	s_barrier
	v_mfma_f32_16x16x32_bf16 v[116:119], v[218:221], v[182:185], v[116:119]
	v_mfma_f32_16x16x32_bf16 v[112:115], v[226:229], v[182:185], v[112:115]
	v_mfma_f32_16x16x32_bf16 v[100:103], v[218:221], v[194:197], v[100:103]
	v_mfma_f32_16x16x32_bf16 v[96:99], v[226:229], v[194:197], v[96:99]
	v_mfma_f32_16x16x32_bf16 v[84:87], v[218:221], v[202:205], v[84:87]
	v_mfma_f32_16x16x32_bf16 v[80:83], v[226:229], v[202:205], v[80:83]
	v_mfma_f32_16x16x32_bf16 v[68:71], v[218:221], v[210:213], v[68:71]
	v_mfma_f32_16x16x32_bf16 v[64:67], v[226:229], v[210:213], v[64:67]
	v_mfma_f32_16x16x32_bf16 v[116:119], v[222:225], v[190:193], v[116:119]
	v_mfma_f32_16x16x32_bf16 v[112:115], v[230:233], v[190:193], v[112:115]
	v_mfma_f32_16x16x32_bf16 v[100:103], v[222:225], v[198:201], v[100:103]
	v_mfma_f32_16x16x32_bf16 v[96:99], v[230:233], v[198:201], v[96:99]
	v_mfma_f32_16x16x32_bf16 v[84:87], v[222:225], v[206:209], v[84:87]
	v_mfma_f32_16x16x32_bf16 v[80:83], v[230:233], v[206:209], v[80:83]
	v_mfma_f32_16x16x32_bf16 v[68:71], v[222:225], v[214:217], v[68:71]
	v_mfma_f32_16x16x32_bf16 v[64:67], v[230:233], v[214:217], v[64:67]
	s_barrier
	s_mov_b32 m0, s38
	v_lshl_add_u64 v[174:175], s[28:29], 0, v[128:129]
	ds_read_b128 v[182:185], v150 offset:16384
	ds_read_b128 v[190:193], v150 offset:17408
	ds_read_b128 v[194:197], v150 offset:18432
	ds_read_b128 v[198:201], v150 offset:19456
	ds_read_b128 v[202:205], v150 offset:20480
	ds_read_b128 v[206:209], v150 offset:21504
	ds_read_b128 v[210:213], v150 offset:22528
	ds_read_b128 v[214:217], v150 offset:23552
	global_load_lds_dwordx4 v[174:175], off
	v_lshl_add_u64 v[178:179], s[28:29], 0, v[132:133]
	s_mov_b32 m0, s39
	s_nop 0
	global_load_lds_dwordx4 v[178:179], off
	s_waitcnt lgkmcnt(0)
	s_barrier
	v_mfma_f32_16x16x32_bf16 v[60:63], v[154:157], v[182:185], v[60:63]
	v_mfma_f32_16x16x32_bf16 v[56:59], v[166:169], v[182:185], v[56:59]
	v_mfma_f32_16x16x32_bf16 v[48:51], v[154:157], v[194:197], v[48:51]
	v_mfma_f32_16x16x32_bf16 v[40:43], v[166:169], v[194:197], v[40:43]
	v_mfma_f32_16x16x32_bf16 v[32:35], v[154:157], v[202:205], v[32:35]
	v_mfma_f32_16x16x32_bf16 v[24:27], v[166:169], v[202:205], v[24:27]
	v_mfma_f32_16x16x32_bf16 v[16:19], v[154:157], v[210:213], v[16:19]
	v_mfma_f32_16x16x32_bf16 v[8:11], v[166:169], v[210:213], v[8:11]
	v_mfma_f32_16x16x32_bf16 v[60:63], v[158:161], v[190:193], v[60:63]
	v_mfma_f32_16x16x32_bf16 v[56:59], v[170:173], v[190:193], v[56:59]
	v_mfma_f32_16x16x32_bf16 v[48:51], v[158:161], v[198:201], v[48:51]
	v_mfma_f32_16x16x32_bf16 v[40:43], v[170:173], v[198:201], v[40:43]
	v_mfma_f32_16x16x32_bf16 v[32:35], v[158:161], v[206:209], v[32:35]
	v_mfma_f32_16x16x32_bf16 v[24:27], v[170:173], v[206:209], v[24:27]
	v_mfma_f32_16x16x32_bf16 v[16:19], v[158:161], v[214:217], v[16:19]
	v_mfma_f32_16x16x32_bf16 v[8:11], v[170:173], v[214:217], v[8:11]
	s_barrier
; #define PG8_STAGE(bufoff, gbase, voff) do { _Pragma("unroll") for (int _i = 0; _i < 2; ++_i) \
;         __builtin_amdgcn_global_load_lds((const unsigned*)((const char*)(gbase) + (voff)[_i]), (PG8_LAS unsigned*)(lds + (bufoff) + ldsw + _i * 8192), 16, 0, 0); } while (0)
; #define PG8_LDA(dst, b, h) do { _Pragma("unroll") for (int m = 0; m < 4; ++m) _Pragma("unroll") for (int k = 0; k < 2; ++k) dst[m][k] = *(const PG8_LAS bf16x8*)(lds + PG8_SA(b, h) + aoff + m * 2048 + k * 1024); } while (0)
; #define PG8_LDB(dst, b, h) do { _Pragma("unroll") for (int n = 0; n < 2; ++n) _Pragma("unroll") for (int k = 0; k < 2; ++k) dst[n][k] = *(const PG8_LAS bf16x8*)(lds + PG8_SB(b, h) + boff + n * 2048 + k * 1024); } while (0)
; #define PG8_MMA(ai, bj, At, Bt) do { __builtin_amdgcn_s_setprio(1); _Pragma("unroll") for (int m = 0; m < 4; ++m) _Pragma("unroll") for (int n = 0; n < 2; ++n) _Pragma("unroll") for (int k = 0; k < 2; ++k) \
;         acc[ai][bj][m][n] = __builtin_amdgcn_mfma_f32_16x16x32_bf16(Bt[n][k], At[m][k], acc[ai][bj][m][n], 0, 0, 0); __builtin_amdgcn_s_setprio(0); } while (0)
; #define PG8_WAIT_V(n) asm volatile("s_waitcnt vmcnt(" #n ")" ::: "memory")
; #define PG8_WAIT_L(n) asm volatile("s_waitcnt lgkmcnt(" #n ")" ::: "memory")
; #define PG8_BAR __builtin_amdgcn_s_barrier()
; #define PG8_SCHED __builtin_amdgcn_sched_barrier(0)
; template <class Epi, class Sched>
; __device__ __forceinline__ void gemm_phase(PG8_LAS unsigned char* lds, const Gemm g, const Sched& S, const Epi& E) {
;     ...
;             PG8_STAGE(PG8_SB(0, 1), b2 + hstep, voffB);
;             PG8_WAIT_V(6); PG8_BAR; PG8_MMA(1, 1, At, B1); PG8_BAR;
;             PG8_LDB(B0, 1, 0); PG8_SCHED; PG8_LDA(At, 1, 0); PG8_STAGE(PG8_SA(0, 1), a2 + hstep, voffA);
;             PG8_WAIT_L(8); PG8_BAR; PG8_WAIT_L(0); PG8_MMA(0, 0, At, B0); PG8_BAR; PG8_SCHED;
;             PG8_LDB(B1, 1, 1); PG8_STAGE(PG8_SB(1, 0), b3, voffB);
;             PG8_BAR; PG8_WAIT_L(0); PG8_MMA(0, 1, At, B1); PG8_BAR;
;             PG8_LDA(At, 1, 1); PG8_STAGE(PG8_SA(1, 0), a3, voffA);
;             PG8_BAR; PG8_WAIT_L(0); PG8_MMA(1, 0, At, B0); PG8_BAR; PG8_SCHED;
	s_add_u32 s22, s26, 0xb0000
	s_addc_u32 s23, s27, 0
	s_add_i32 s58, s47, s37
	v_lshl_add_u64 v[154:155], s[22:23], 0, v[130:131]
	s_mov_b32 m0, s58
	s_nop 0
	global_load_lds_dwordx4 v[154:155], off
	v_lshl_add_u64 v[154:155], s[22:23], 0, v[134:135]
	s_add_i32 m0, s58, 0x2000
	s_nop 0
	global_load_lds_dwordx4 v[154:155], off
	s_waitcnt vmcnt(6)
	s_barrier
	v_mfma_f32_16x16x32_bf16 v[52:55], v[218:221], v[182:185], v[52:55]
	v_mfma_f32_16x16x32_bf16 v[44:47], v[226:229], v[182:185], v[44:47]
	v_mfma_f32_16x16x32_bf16 v[36:39], v[218:221], v[194:197], v[36:39]
	v_mfma_f32_16x16x32_bf16 v[28:31], v[226:229], v[194:197], v[28:31]
	v_mfma_f32_16x16x32_bf16 v[20:23], v[218:221], v[202:205], v[20:23]
	v_mfma_f32_16x16x32_bf16 v[12:15], v[226:229], v[202:205], v[12:15]
	v_mfma_f32_16x16x32_bf16 v[4:7], v[218:221], v[210:213], v[4:7]
	v_mfma_f32_16x16x32_bf16 v[0:3], v[226:229], v[210:213], v[0:3]
	v_mfma_f32_16x16x32_bf16 v[52:55], v[222:225], v[190:193], v[52:55]
	v_mfma_f32_16x16x32_bf16 v[44:47], v[230:233], v[190:193], v[44:47]
	v_mfma_f32_16x16x32_bf16 v[36:39], v[222:225], v[198:201], v[36:39]
	v_mfma_f32_16x16x32_bf16 v[28:31], v[230:233], v[198:201], v[28:31]
	v_mfma_f32_16x16x32_bf16 v[20:23], v[222:225], v[206:209], v[20:23]
	v_mfma_f32_16x16x32_bf16 v[12:15], v[230:233], v[206:209], v[12:15]
	v_mfma_f32_16x16x32_bf16 v[4:7], v[222:225], v[214:217], v[4:7]
	v_mfma_f32_16x16x32_bf16 v[0:3], v[230:233], v[214:217], v[0:3]
	s_barrier
	s_add_i32 s58, 0, 0x18000
	v_add_u32_e32 v153, s58, v147
	ds_read_b128 v[154:157], v153
	ds_read_b128 v[158:161], v153 offset:1024
	ds_read_b128 v[166:169], v153 offset:2048
	ds_read_b128 v[170:173], v153 offset:3072
	ds_read_b128 v[182:185], v150 offset:32768
	ds_read_b128 v[190:193], v150 offset:33792
	ds_read_b128 v[194:197], v150 offset:34816
	ds_read_b128 v[198:201], v150 offset:35840
	ds_read_b128 v[202:205], v150 offset:36864
	ds_read_b128 v[206:209], v150 offset:37888
	ds_read_b128 v[210:213], v150 offset:38912
	ds_read_b128 v[214:217], v150 offset:39936
	s_add_u32 s22, s28, 0xb0000
	s_addc_u32 s23, s29, 0
	s_mov_b32 m0, s40
	v_lshl_add_u64 v[186:187], s[22:23], 0, v[128:129]
	global_load_lds_dwordx4 v[186:187], off
	v_lshl_add_u64 v[186:187], s[22:23], 0, v[132:133]
	s_mov_b32 m0, s41
	s_nop 0
	global_load_lds_dwordx4 v[186:187], off
	s_waitcnt lgkmcnt(0)
	s_barrier
	v_mfma_f32_16x16x32_bf16 v[124:127], v[154:157], v[182:185], v[124:127]
	v_mfma_f32_16x16x32_bf16 v[120:123], v[166:169], v[182:185], v[120:123]
	v_mfma_f32_16x16x32_bf16 v[108:111], v[154:157], v[194:197], v[108:111]
	v_mfma_f32_16x16x32_bf16 v[104:107], v[166:169], v[194:197], v[104:107]
	v_mfma_f32_16x16x32_bf16 v[92:95], v[154:157], v[202:205], v[92:95]
	v_mfma_f32_16x16x32_bf16 v[88:91], v[166:169], v[202:205], v[88:91]
	v_mfma_f32_16x16x32_bf16 v[76:79], v[154:157], v[210:213], v[76:79]
	v_mfma_f32_16x16x32_bf16 v[72:75], v[166:169], v[210:213], v[72:75]
	v_mfma_f32_16x16x32_bf16 v[124:127], v[158:161], v[190:193], v[124:127]
	v_mfma_f32_16x16x32_bf16 v[120:123], v[170:173], v[190:193], v[120:123]
	v_mfma_f32_16x16x32_bf16 v[108:111], v[158:161], v[198:201], v[108:111]
	v_mfma_f32_16x16x32_bf16 v[104:107], v[170:173], v[198:201], v[104:107]
	v_mfma_f32_16x16x32_bf16 v[92:95], v[158:161], v[206:209], v[92:95]
	v_mfma_f32_16x16x32_bf16 v[88:91], v[170:173], v[206:209], v[88:91]
	v_mfma_f32_16x16x32_bf16 v[76:79], v[158:161], v[214:217], v[76:79]
	v_mfma_f32_16x16x32_bf16 v[72:75], v[170:173], v[214:217], v[72:75]
	s_barrier
	s_add_i32 s28, 0, 0x1c000
	v_add_u32_e32 v153, s28, v147
	ds_read_b128 v[218:221], v153
	ds_read_b128 v[222:225], v153 offset:1024
	ds_read_b128 v[226:229], v153 offset:2048
	ds_read_b128 v[230:233], v153 offset:3072
	s_add_i32 s22, s58, s37
	v_lshl_add_u64 v[144:145], v[144:145], 0, s[14:15]
	s_mov_b32 m0, s22
	s_nop 0
	global_load_lds_dwordx4 v[144:145], off
	v_lshl_add_u64 v[144:145], v[162:163], 0, s[14:15]
	s_add_i32 m0, s22, 0x2000
	s_nop 0
	global_load_lds_dwordx4 v[144:145], off
	s_waitcnt lgkmcnt(0)
	s_barrier
	v_mfma_f32_16x16x32_bf16 v[116:119], v[218:221], v[182:185], v[116:119]
	v_mfma_f32_16x16x32_bf16 v[112:115], v[226:229], v[182:185], v[112:115]
	v_mfma_f32_16x16x32_bf16 v[100:103], v[218:221], v[194:197], v[100:103]
	v_mfma_f32_16x16x32_bf16 v[96:99], v[226:229], v[194:197], v[96:99]
	v_mfma_f32_16x16x32_bf16 v[84:87], v[218:221], v[202:205], v[84:87]
	v_mfma_f32_16x16x32_bf16 v[80:83], v[226:229], v[202:205], v[80:83]
	v_mfma_f32_16x16x32_bf16 v[68:71], v[218:221], v[210:213], v[68:71]
	v_mfma_f32_16x16x32_bf16 v[64:67], v[226:229], v[210:213], v[64:67]
	v_mfma_f32_16x16x32_bf16 v[116:119], v[222:225], v[190:193], v[116:119]
	v_mfma_f32_16x16x32_bf16 v[112:115], v[230:233], v[190:193], v[112:115]
	v_mfma_f32_16x16x32_bf16 v[100:103], v[222:225], v[198:201], v[100:103]
	v_mfma_f32_16x16x32_bf16 v[96:99], v[230:233], v[198:201], v[96:99]
	v_mfma_f32_16x16x32_bf16 v[84:87], v[222:225], v[206:209], v[84:87]
	v_mfma_f32_16x16x32_bf16 v[80:83], v[230:233], v[206:209], v[80:83]
	v_mfma_f32_16x16x32_bf16 v[68:71], v[222:225], v[214:217], v[68:71]
	v_mfma_f32_16x16x32_bf16 v[64:67], v[230:233], v[214:217], v[64:67]
	s_barrier
	s_mov_b32 m0, s43
	v_lshl_add_u64 v[144:145], v[174:175], 0, s[14:15]
	ds_read_b128 v[182:185], v150 offset:49152
	ds_read_b128 v[190:193], v150 offset:50176
	ds_read_b128 v[194:197], v150 offset:51200
	ds_read_b128 v[198:201], v150 offset:52224
	ds_read_b128 v[202:205], v150 offset:53248
	ds_read_b128 v[206:209], v150 offset:54272
	ds_read_b128 v[210:213], v150 offset:55296
	ds_read_b128 v[214:217], v150 offset:56320
	global_load_lds_dwordx4 v[144:145], off
	v_lshl_add_u64 v[144:145], v[178:179], 0, s[14:15]
	s_mov_b32 m0, s44
	s_nop 0
	global_load_lds_dwordx4 v[144:145], off
	s_waitcnt lgkmcnt(0)
	s_barrier
; __device__ __forceinline__ unsigned cvt_pk_bf16(float lo, float hi) { unsigned r; asm volatile("v_cvt_pk_bf16_f32 %0, %1, %2" : "=v"(r) : "v"(lo), "v"(hi)); return r; }
; __device__ __forceinline__ float flogsig16(float x) { return (fminf(x, 0.f) - __logf(1.0f + __expf(-fabsf(x)))) * 0.0625f; }
; #define PG8_STAGE(bufoff, gbase, voff) do { _Pragma("unroll") for (int _i = 0; _i < 2; ++_i) \
;         __builtin_amdgcn_global_load_lds((const unsigned*)((const char*)(gbase) + (voff)[_i]), (PG8_LAS unsigned*)(lds + (bufoff) + ldsw + _i * 8192), 16, 0, 0); } while (0)
; #define PG8_WAIT_V(n) asm volatile("s_waitcnt vmcnt(" #n ")" ::: "memory")
; #define PG8_WAIT_L(n) asm volatile("s_waitcnt lgkmcnt(" #n ")" ::: "memory")
; #define PG8_BAR __builtin_amdgcn_s_barrier()
; #define PG8_SCHED __builtin_amdgcn_sched_barrier(0)
;     __device__ __forceinline__ void operator()(const f32x4 (&acc)[2][2][4][2], const Unit& u, int wr, int wc, int fr, int fq) const {
;     ...
;             for (int m = 0; m < 4; ++m) { bf16_t* rowp = O + (size_t)(row0 + ai * HALF + m * 16) * ldc + col0;
; #pragma unroll
;                 for (int bj = 0; bj < 2; ++bj) { f32x4 v0 = acc[ai][bj][m][0] + bv[bj][0], v1 = acc[ai][bj][m][1] + bv[bj][1];
;                     if (act == 1) {
; #pragma unroll
;                         for (int j = 0; j < 1; ++j) { v0 = v0 * sigmoid4(v0); v1 = v1 * sigmoid4(v1); } }
;                     else if (act == 2) {
; #pragma unroll
;                         for (int j = 0; j < 1; ++j) { v0 = sigmoid4(v0); v1 = sigmoid4(v1); } }
;                     else if (act == 3) {
; #pragma unroll
;                         for (int j = 0; j < 4; ++j) { v0[j] = flogsig16(v0[j]); v1[j] = flogsig16(v1[j]); } }
;                     u32x4 w; w.x = cvt_pk_bf16(v0[0], v0[1]); w.y = cvt_pk_bf16(v0[2], v0[3]); w.z = cvt_pk_bf16(v1[0], v1[1]); w.w = cvt_pk_bf16(v1[2], v1[3]);
;                     *(u32x4*)(rowp + bj * HALF) = w; } }
; template <class Epi, class Sched>
; __device__ __forceinline__ void gemm_phase(PG8_LAS unsigned char* lds, const Gemm g, const Sched& S, const Epi& E) {
;     ...
;             PG8_BAR; PG8_WAIT_L(0); PG8_MMA(1, 0, At, B0); PG8_BAR; PG8_SCHED;
;             PG8_STAGE(PG8_SB(1, 1), b3 + hstep, voffB);
;             PG8_WAIT_V(6); PG8_BAR; PG8_MMA(1, 1, At, B1); PG8_BAR;
;         }
	v_mfma_f32_16x16x32_bf16 v[60:63], v[154:157], v[182:185], v[60:63]
	v_mfma_f32_16x16x32_bf16 v[56:59], v[166:169], v[182:185], v[56:59]
	v_mfma_f32_16x16x32_bf16 v[48:51], v[154:157], v[194:197], v[48:51]
	v_mfma_f32_16x16x32_bf16 v[40:43], v[166:169], v[194:197], v[40:43]
	v_mfma_f32_16x16x32_bf16 v[32:35], v[154:157], v[202:205], v[32:35]
	v_mfma_f32_16x16x32_bf16 v[24:27], v[166:169], v[202:205], v[24:27]
	v_mfma_f32_16x16x32_bf16 v[16:19], v[154:157], v[210:213], v[16:19]
	v_mfma_f32_16x16x32_bf16 v[8:11], v[166:169], v[210:213], v[8:11]
	v_mfma_f32_16x16x32_bf16 v[60:63], v[158:161], v[190:193], v[60:63]
	v_mfma_f32_16x16x32_bf16 v[56:59], v[170:173], v[190:193], v[56:59]
	v_mfma_f32_16x16x32_bf16 v[48:51], v[158:161], v[198:201], v[48:51]
	v_mfma_f32_16x16x32_bf16 v[40:43], v[170:173], v[198:201], v[40:43]
	v_mfma_f32_16x16x32_bf16 v[32:35], v[158:161], v[206:209], v[32:35]
	v_mfma_f32_16x16x32_bf16 v[24:27], v[170:173], v[206:209], v[24:27]
	v_mfma_f32_16x16x32_bf16 v[16:19], v[158:161], v[214:217], v[16:19]
	v_mfma_f32_16x16x32_bf16 v[8:11], v[170:173], v[214:217], v[8:11]
	s_barrier
	s_add_u32 s22, s26, 0xb0080
	s_addc_u32 s23, s27, 0
	s_add_i32 s26, s28, s37
	v_lshl_add_u64 v[144:145], s[22:23], 0, v[130:131]
	s_mov_b32 m0, s26
	s_nop 0
	global_load_lds_dwordx4 v[144:145], off
	v_lshl_add_u64 v[144:145], s[22:23], 0, v[134:135]
	s_add_i32 m0, s26, 0x2000
	s_nop 0
	global_load_lds_dwordx4 v[144:145], off
	s_waitcnt vmcnt(6)
	s_barrier
	v_mfma_f32_16x16x32_bf16 v[52:55], v[218:221], v[182:185], v[52:55]
	v_mfma_f32_16x16x32_bf16 v[44:47], v[226:229], v[182:185], v[44:47]
	v_mfma_f32_16x16x32_bf16 v[36:39], v[218:221], v[194:197], v[36:39]
	v_mfma_f32_16x16x32_bf16 v[28:31], v[226:229], v[194:197], v[28:31]
	v_mfma_f32_16x16x32_bf16 v[20:23], v[218:221], v[202:205], v[20:23]
	v_mfma_f32_16x16x32_bf16 v[12:15], v[226:229], v[202:205], v[12:15]
	v_mfma_f32_16x16x32_bf16 v[4:7], v[218:221], v[210:213], v[4:7]
	v_mfma_f32_16x16x32_bf16 v[0:3], v[226:229], v[210:213], v[0:3]
	v_mfma_f32_16x16x32_bf16 v[52:55], v[222:225], v[190:193], v[52:55]
	v_mfma_f32_16x16x32_bf16 v[44:47], v[230:233], v[190:193], v[44:47]
	v_mfma_f32_16x16x32_bf16 v[36:39], v[222:225], v[198:201], v[36:39]
	v_mfma_f32_16x16x32_bf16 v[28:31], v[230:233], v[198:201], v[28:31]
	v_mfma_f32_16x16x32_bf16 v[20:23], v[222:225], v[206:209], v[20:23]
	v_mfma_f32_16x16x32_bf16 v[12:15], v[230:233], v[206:209], v[12:15]
	v_mfma_f32_16x16x32_bf16 v[4:7], v[222:225], v[214:217], v[4:7]
	v_mfma_f32_16x16x32_bf16 v[0:3], v[230:233], v[214:217], v[0:3]
	s_add_i32 s57, s57, 2
	s_add_u32 s55, s55, 0x100
	s_addc_u32 s56, s56, 0
	s_cmp_gt_u32 s57, 41
	s_mov_b64 s[22:23], s[24:25]
	s_barrier
	s_cbranch_scc0 .LBB0_286
	v_lshl_add_u32 v154, s53, 8, v146
	v_lshl_or_b32 v144, s54, 8, v148
	v_ashrrev_i32_e32 v155, 31, v154
	v_ashrrev_i32_e32 v145, 31, v144
	v_lshlrev_b64 v[156:157], 11, v[154:155]
	v_lshl_add_u64 v[156:157], s[10:11], 0, v[156:157]
	v_lshlrev_b64 v[158:159], 1, v[144:145]
	v_lshl_add_u64 v[144:145], v[156:157], 0, v[158:159]
	v_pk_add_f32 v[126:127], v[126:127], 0 op_sel_hi:[1,0]
	v_pk_add_f32 v[124:125], v[124:125], 0 op_sel_hi:[1,0]
	v_pk_add_f32 v[156:157], v[122:123], 0 op_sel_hi:[1,0]
	v_pk_add_f32 v[122:123], v[120:121], 0 op_sel_hi:[1,0]
	v_cvt_pk_bf16_f32 v120, v124, v125
	v_cvt_pk_bf16_f32 v121, v126, v127
	v_pk_add_f32 v[116:117], v[116:117], 0 op_sel_hi:[1,0]
	v_cvt_pk_bf16_f32 v122, v122, v123
	v_cvt_pk_bf16_f32 v123, v156, v157
	global_store_dwordx4 v[144:145], v[120:123], off
	v_pk_add_f32 v[118:119], v[118:119], 0 op_sel_hi:[1,0]
	v_pk_add_f32 v[110:111], v[110:111], 0 op_sel_hi:[1,0]
	v_pk_add_f32 v[120:121], v[114:115], 0 op_sel_hi:[1,0]
	v_pk_add_f32 v[114:115], v[112:113], 0 op_sel_hi:[1,0]
	v_cvt_pk_bf16_f32 v112, v116, v117
	v_cvt_pk_bf16_f32 v113, v118, v119
	v_pk_add_f32 v[108:109], v[108:109], 0 op_sel_hi:[1,0]
	v_cvt_pk_bf16_f32 v114, v114, v115
	v_cvt_pk_bf16_f32 v115, v120, v121
	global_store_dwordx4 v[144:145], v[112:115], off offset:256
	v_pk_add_f32 v[100:101], v[100:101], 0 op_sel_hi:[1,0]
	v_pk_add_f32 v[102:103], v[102:103], 0 op_sel_hi:[1,0]
	v_or_b32_e32 v112, 16, v154
	v_ashrrev_i32_e32 v113, 31, v112
	v_lshlrev_b64 v[112:113], 11, v[112:113]
	v_lshl_add_u64 v[112:113], s[10:11], 0, v[112:113]
	v_lshl_add_u64 v[112:113], v[112:113], 0, v[158:159]
	v_pk_add_f32 v[114:115], v[106:107], 0 op_sel_hi:[1,0]
	v_pk_add_f32 v[106:107], v[104:105], 0 op_sel_hi:[1,0]
	v_cvt_pk_bf16_f32 v104, v108, v109
	v_cvt_pk_bf16_f32 v105, v110, v111
	v_pk_add_f32 v[94:95], v[94:95], 0 op_sel_hi:[1,0]
	v_cvt_pk_bf16_f32 v106, v106, v107
	v_cvt_pk_bf16_f32 v107, v114, v115
	global_store_dwordx4 v[112:113], v[104:107], off
	v_pk_add_f32 v[92:93], v[92:93], 0 op_sel_hi:[1,0]
	v_pk_add_f32 v[84:85], v[84:85], 0 op_sel_hi:[1,0]
	v_pk_add_f32 v[104:105], v[98:99], 0 op_sel_hi:[1,0]
	v_pk_add_f32 v[98:99], v[96:97], 0 op_sel_hi:[1,0]
	v_cvt_pk_bf16_f32 v96, v100, v101
	v_cvt_pk_bf16_f32 v97, v102, v103
	v_pk_add_f32 v[86:87], v[86:87], 0 op_sel_hi:[1,0]
	v_cvt_pk_bf16_f32 v98, v98, v99
	v_cvt_pk_bf16_f32 v99, v104, v105
	global_store_dwordx4 v[112:113], v[96:99], off offset:256
	v_pk_add_f32 v[78:79], v[78:79], 0 op_sel_hi:[1,0]
	v_pk_add_f32 v[76:77], v[76:77], 0 op_sel_hi:[1,0]
	v_or_b32_e32 v96, 32, v154
	v_ashrrev_i32_e32 v97, 31, v96
	v_lshlrev_b64 v[96:97], 11, v[96:97]
	v_lshl_add_u64 v[96:97], s[10:11], 0, v[96:97]
	v_lshl_add_u64 v[96:97], v[96:97], 0, v[158:159]
; __device__ __forceinline__ unsigned cvt_pk_bf16(float lo, float hi) { unsigned r; asm volatile("v_cvt_pk_bf16_f32 %0, %1, %2" : "=v"(r) : "v"(lo), "v"(hi)); return r; }
; __device__ __forceinline__ float flogsig16(float x) { return (fminf(x, 0.f) - __logf(1.0f + __expf(-fabsf(x)))) * 0.0625f; }
; #define PG8_WAIT_V(n) asm volatile("s_waitcnt vmcnt(" #n ")" ::: "memory")
; #define PG8_BAR __builtin_amdgcn_s_barrier()
;     __device__ __forceinline__ void operator()(const f32x4 (&acc)[2][2][4][2], const Unit& u, int wr, int wc, int fr, int fq) const {
;     ...
;             for (int m = 0; m < 4; ++m) { bf16_t* rowp = O + (size_t)(row0 + ai * HALF + m * 16) * ldc + col0;
; #pragma unroll
;                 for (int bj = 0; bj < 2; ++bj) { f32x4 v0 = acc[ai][bj][m][0] + bv[bj][0], v1 = acc[ai][bj][m][1] + bv[bj][1];
;                     if (act == 1) {
; #pragma unroll
;                         for (int j = 0; j < 1; ++j) { v0 = v0 * sigmoid4(v0); v1 = v1 * sigmoid4(v1); } }
;                     else if (act == 2) {
; #pragma unroll
;                         for (int j = 0; j < 1; ++j) { v0 = sigmoid4(v0); v1 = sigmoid4(v1); } }
;                     else if (act == 3) {
; #pragma unroll
;                         for (int j = 0; j < 4; ++j) { v0[j] = flogsig16(v0[j]); v1[j] = flogsig16(v1[j]); } }
;                     u32x4 w; w.x = cvt_pk_bf16(v0[0], v0[1]); w.y = cvt_pk_bf16(v0[2], v0[3]); w.z = cvt_pk_bf16(v1[0], v1[1]); w.w = cvt_pk_bf16(v1[2], v1[3]);
;                     *(u32x4*)(rowp + bj * HALF) = w; } }
; template <class Epi, class Sched>
; __device__ __forceinline__ void gemm_phase(PG8_LAS unsigned char* lds, const Gemm g, const Sched& S, const Epi& E) {
;     ...
;         if (!has_next) break;
; #pragma unroll
;         for (int a = 0; a < 2; ++a)
; #pragma unroll
;             for (int b = 0; b < 2; ++b)
; #pragma unroll
;                 for (int m = 0; m < 4; ++m)
; #pragma unroll
;                     for (int n = 0; n < 2; ++n) acc[a][b][m][n] = (f32x4){0.f, 0.f, 0.f, 0.f};
;         cur = nxt; cA = nA; cB = nB; ++ui;
;     }
;     PG8_WAIT_V(0);
;     if (wr == 0) PG8_BAR;
;     PG8_BAR;
	v_pk_add_f32 v[98:99], v[90:91], 0 op_sel_hi:[1,0]
	v_pk_add_f32 v[90:91], v[88:89], 0 op_sel_hi:[1,0]
	v_cvt_pk_bf16_f32 v88, v92, v93
	v_cvt_pk_bf16_f32 v89, v94, v95
	v_pk_add_f32 v[70:71], v[70:71], 0 op_sel_hi:[1,0]
	v_cvt_pk_bf16_f32 v90, v90, v91
	v_cvt_pk_bf16_f32 v91, v98, v99
	global_store_dwordx4 v[96:97], v[88:91], off
	v_pk_add_f32 v[68:69], v[68:69], 0 op_sel_hi:[1,0]
	s_mov_b64 s[22:23], 0x40000
	v_pk_add_f32 v[88:89], v[82:83], 0 op_sel_hi:[1,0]
	v_pk_add_f32 v[82:83], v[80:81], 0 op_sel_hi:[1,0]
	v_cvt_pk_bf16_f32 v80, v84, v85
	v_cvt_pk_bf16_f32 v81, v86, v87
	v_pk_add_f32 v[60:61], v[60:61], 0 op_sel_hi:[1,0]
	v_cvt_pk_bf16_f32 v82, v82, v83
	v_cvt_pk_bf16_f32 v83, v88, v89
	global_store_dwordx4 v[96:97], v[80:83], off offset:256
	v_pk_add_f32 v[62:63], v[62:63], 0 op_sel_hi:[1,0]
	v_pk_add_f32 v[54:55], v[54:55], 0 op_sel_hi:[1,0]
	v_or_b32_e32 v80, 48, v154
	v_ashrrev_i32_e32 v81, 31, v80
	v_lshlrev_b64 v[80:81], 11, v[80:81]
	v_lshl_add_u64 v[80:81], s[10:11], 0, v[80:81]
	v_lshl_add_u64 v[80:81], v[80:81], 0, v[158:159]
	v_pk_add_f32 v[82:83], v[74:75], 0 op_sel_hi:[1,0]
	v_pk_add_f32 v[74:75], v[72:73], 0 op_sel_hi:[1,0]
	v_cvt_pk_bf16_f32 v72, v76, v77
	v_cvt_pk_bf16_f32 v73, v78, v79
	v_pk_add_f32 v[52:53], v[52:53], 0 op_sel_hi:[1,0]
	v_cvt_pk_bf16_f32 v74, v74, v75
	v_cvt_pk_bf16_f32 v75, v82, v83
	global_store_dwordx4 v[80:81], v[72:75], off
	v_pk_add_f32 v[48:49], v[48:49], 0 op_sel_hi:[1,0]
	v_pk_add_f32 v[38:39], v[38:39], 0 op_sel_hi:[1,0]
	v_pk_add_f32 v[72:73], v[66:67], 0 op_sel_hi:[1,0]
	v_pk_add_f32 v[66:67], v[64:65], 0 op_sel_hi:[1,0]
	v_cvt_pk_bf16_f32 v64, v68, v69
	v_cvt_pk_bf16_f32 v65, v70, v71
	v_pk_add_f32 v[36:37], v[36:37], 0 op_sel_hi:[1,0]
	v_cvt_pk_bf16_f32 v66, v66, v67
	v_cvt_pk_bf16_f32 v67, v72, v73
	global_store_dwordx4 v[80:81], v[64:67], off offset:256
	v_pk_add_f32 v[32:33], v[32:33], 0 op_sel_hi:[1,0]
	v_pk_add_f32 v[22:23], v[22:23], 0 op_sel_hi:[1,0]
	v_lshl_add_u64 v[64:65], v[144:145], 0, s[22:23]
	s_mov_b32 s22, 0x40000
	v_pk_add_f32 v[66:67], v[58:59], 0 op_sel_hi:[1,0]
	v_pk_add_f32 v[58:59], v[56:57], 0 op_sel_hi:[1,0]
	v_cvt_pk_bf16_f32 v56, v60, v61
	v_add_co_u32_e32 v60, vcc, s22, v144
	v_cvt_pk_bf16_f32 v57, v62, v63
	v_cvt_pk_bf16_f32 v58, v58, v59
	v_cvt_pk_bf16_f32 v59, v66, v67
	s_mov_b64 s[22:23], 0x48000
	s_nop 0
	v_addc_co_u32_e32 v61, vcc, 0, v145, vcc
	global_store_dwordx4 v[60:61], v[56:59], off
	v_pk_add_f32 v[20:21], v[20:21], 0 op_sel_hi:[1,0]
	v_pk_add_f32 v[16:17], v[16:17], 0 op_sel_hi:[1,0]
	v_pk_add_f32 v[56:57], v[46:47], 0 op_sel_hi:[1,0]
	v_pk_add_f32 v[46:47], v[44:45], 0 op_sel_hi:[1,0]
	v_cvt_pk_bf16_f32 v44, v52, v53
	v_cvt_pk_bf16_f32 v45, v54, v55
	s_mov_b32 s54, s51
	v_cvt_pk_bf16_f32 v46, v46, v47
	v_cvt_pk_bf16_f32 v47, v56, v57
	global_store_dwordx4 v[64:65], v[44:47], off offset:256
	s_mov_b32 s53, s52
	s_mov_b64 s[24:25], s[4:5]
	v_pk_add_f32 v[46:47], v[50:51], 0 op_sel_hi:[1,0]
	v_pk_add_f32 v[50:51], v[42:43], 0 op_sel_hi:[1,0]
	v_pk_add_f32 v[42:43], v[40:41], 0 op_sel_hi:[1,0]
	v_cvt_pk_bf16_f32 v40, v48, v49
	v_cvt_pk_bf16_f32 v41, v46, v47
	v_add_co_u32_e32 v46, vcc, s48, v144
	v_cvt_pk_bf16_f32 v42, v42, v43
	v_cvt_pk_bf16_f32 v43, v50, v51
	v_lshl_add_u64 v[44:45], v[144:145], 0, s[22:23]
	s_nop 0
	v_addc_co_u32_e32 v47, vcc, 0, v145, vcc
	global_store_dwordx4 v[46:47], v[40:43], off
	s_mov_b64 s[22:23], s[0:1]
	v_pk_add_f32 v[6:7], v[6:7], 0 op_sel_hi:[1,0]
	v_pk_add_f32 v[40:41], v[30:31], 0 op_sel_hi:[1,0]
	v_pk_add_f32 v[30:31], v[28:29], 0 op_sel_hi:[1,0]
	v_cvt_pk_bf16_f32 v28, v36, v37
	v_cvt_pk_bf16_f32 v29, v38, v39
	v_pk_add_f32 v[4:5], v[4:5], 0 op_sel_hi:[1,0]
	v_cvt_pk_bf16_f32 v30, v30, v31
	v_cvt_pk_bf16_f32 v31, v40, v41
	global_store_dwordx4 v[44:45], v[28:31], off offset:256
	s_nop 1
	v_pk_add_f32 v[30:31], v[34:35], 0 op_sel_hi:[1,0]
	v_pk_add_f32 v[34:35], v[26:27], 0 op_sel_hi:[1,0]
	v_pk_add_f32 v[26:27], v[24:25], 0 op_sel_hi:[1,0]
	v_cvt_pk_bf16_f32 v24, v32, v33
	v_cvt_pk_bf16_f32 v25, v30, v31
	v_add_co_u32_e32 v30, vcc, s49, v144
	v_cvt_pk_bf16_f32 v26, v26, v27
	v_cvt_pk_bf16_f32 v27, v34, v35
	v_lshl_add_u64 v[28:29], v[144:145], 0, s[16:17]
	s_nop 0
	v_addc_co_u32_e32 v31, vcc, 0, v145, vcc
	global_store_dwordx4 v[30:31], v[24:27], off
	s_nop 1
	v_pk_add_f32 v[24:25], v[14:15], 0 op_sel_hi:[1,0]
	v_pk_add_f32 v[14:15], v[12:13], 0 op_sel_hi:[1,0]
	v_cvt_pk_bf16_f32 v12, v20, v21
	v_cvt_pk_bf16_f32 v13, v22, v23
	s_nop 0
	v_cvt_pk_bf16_f32 v14, v14, v15
	v_cvt_pk_bf16_f32 v15, v24, v25
	global_store_dwordx4 v[28:29], v[12:15], off offset:256
	s_nop 1
	v_pk_add_f32 v[14:15], v[18:19], 0 op_sel_hi:[1,0]
	v_pk_add_f32 v[18:19], v[10:11], 0 op_sel_hi:[1,0]
	v_pk_add_f32 v[10:11], v[8:9], 0 op_sel_hi:[1,0]
	v_cvt_pk_bf16_f32 v8, v16, v17
	v_cvt_pk_bf16_f32 v9, v14, v15
	v_add_co_u32_e32 v14, vcc, s50, v144
	v_lshl_add_u64 v[12:13], v[144:145], 0, s[18:19]
	s_nop 0
	v_addc_co_u32_e32 v15, vcc, 0, v145, vcc
	v_cvt_pk_bf16_f32 v10, v10, v11
	v_cvt_pk_bf16_f32 v11, v18, v19
	global_store_dwordx4 v[14:15], v[8:11], off
	s_and_b64 vcc, exec, s[2:3]
	s_nop 0
	v_pk_add_f32 v[8:9], v[2:3], 0 op_sel_hi:[1,0]
	v_pk_add_f32 v[2:3], v[0:1], 0 op_sel_hi:[1,0]
	v_cvt_pk_bf16_f32 v0, v4, v5
	v_cvt_pk_bf16_f32 v1, v6, v7
	s_nop 0
	v_cvt_pk_bf16_f32 v2, v2, v3
	v_cvt_pk_bf16_f32 v3, v8, v9
	global_store_dwordx4 v[12:13], v[0:3], off offset:256
	s_cbranch_vccz .LBB0_275
	s_waitcnt vmcnt(0)
	s_cmpk_gt_u32 s31, 0xff
	s_cbranch_scc1 .LBB0_290
	s_barrier

; #define PG8_STAGE(bufoff, gbase, voff) do { _Pragma("unroll") for (int _i = 0; _i < 2; ++_i) \
;         __builtin_amdgcn_global_load_lds((const unsigned*)((const char*)(gbase) + (voff)[_i]), (PG8_LAS unsigned*)(lds + (bufoff) + ldsw + _i * 8192), 16, 0, 0); } while (0)
; #define PG8_LDA(dst, b, h) do { _Pragma("unroll") for (int m = 0; m < 4; ++m) _Pragma("unroll") for (int k = 0; k < 2; ++k) dst[m][k] = *(const PG8_LAS bf16x8*)(lds + PG8_SA(b, h) + aoff + m * 2048 + k * 1024); } while (0)
; #define PG8_LDB(dst, b, h) do { _Pragma("unroll") for (int n = 0; n < 2; ++n) _Pragma("unroll") for (int k = 0; k < 2; ++k) dst[n][k] = *(const PG8_LAS bf16x8*)(lds + PG8_SB(b, h) + boff + n * 2048 + k * 1024); } while (0)
; #define PG8_WAIT_V(n) asm volatile("s_waitcnt vmcnt(" #n ")" ::: "memory")
; #define PG8_WAIT_L(n) asm volatile("s_waitcnt lgkmcnt(" #n ")" ::: "memory")
; #define PG8_BAR __builtin_amdgcn_s_barrier()
; #define PG8_SCHED __builtin_amdgcn_sched_barrier(0)
; template <class Epi, class Sched>
; __device__ __forceinline__ void gemm_phase(PG8_LAS unsigned char* lds, const Gemm g, const Sched& S, const Epi& E) {
;     ...
;             const bool last = (t == nt - 2);
;             const char* a1 = cA + (size_t)(t + 1) * kstep;
;             const char* a2 = last ? nA : cA + (size_t)(t + 2) * kstep; const char* b2 = last ? nB : cB + (size_t)(t + 2) * kstep;
;             const char* a3 = a2 + kstep; const char* b3 = b2 + kstep;
;             if (last && has_next) S.a_ready(nxt);
;             PG8_LDB(B0, 0, 0); PG8_SCHED; PG8_LDA(At, 0, 0); PG8_STAGE(PG8_SA(1, 1), a1 + hstep, voffA);
;             PG8_WAIT_L(8); PG8_BAR; PG8_WAIT_L(0); PG8_MMA(0, 0, At, B0); PG8_BAR; PG8_SCHED;
;             PG8_LDB(B1, 0, 1); PG8_STAGE(PG8_SB(0, 0), b2, voffB);
;             PG8_BAR; PG8_WAIT_L(0); PG8_MMA(0, 1, At, B1); PG8_BAR;
;             PG8_LDA(At, 0, 1); PG8_STAGE(PG8_SA(0, 0), a2, voffA);
;             PG8_BAR; PG8_WAIT_L(0); PG8_MMA(1, 0, At, B0); PG8_BAR; PG8_SCHED;
;             PG8_STAGE(PG8_SB(0, 1), b2 + hstep, voffB);
;             PG8_WAIT_V(6); PG8_BAR; PG8_MMA(1, 1, At, B1); PG8_BAR;
;             PG8_LDB(B0, 1, 0); PG8_SCHED; PG8_LDA(At, 1, 0); PG8_STAGE(PG8_SA(0, 1), a2 + hstep, voffA);
;             PG8_WAIT_L(8); PG8_BAR; PG8_WAIT_L(0); PG8_MMA(0, 0, At, B0); PG8_BAR; PG8_SCHED;
.LBB0_416:
	ds_read_b128 v[24:27], v186
	ds_read_b128 v[28:31], v186 offset:1024
	ds_read_b128 v[40:43], v186 offset:2048
	ds_read_b128 v[44:47], v186 offset:3072
	ds_read_b128 v[144:147], v187
	ds_read_b128 v[148:151], v187 offset:1024
	ds_read_b128 v[182:185], v187 offset:2048
	ds_read_b128 v[192:195], v187 offset:3072
	ds_read_b128 v[196:199], v187 offset:4096
	ds_read_b128 v[200:203], v187 offset:5120
	ds_read_b128 v[204:207], v187 offset:6144
	ds_read_b128 v[208:211], v187 offset:7168
	s_add_u32 s4, s0, 0xfffc0080
	s_addc_u32 s5, s1, -1
	s_cmp_eq_u32 s53, 12
	s_cselect_b32 s29, s7, s5
	s_cselect_b32 s28, s10, s4
	s_cselect_b32 s5, s19, s52
	s_cselect_b32 s4, s21, s51
	v_lshl_add_u64 v[174:175], s[0:1], 0, v[166:167]
	s_add_i32 m0, s27, 0xc000
	s_nop 0
	global_load_lds_dwordx4 v[174:175], off
	v_lshl_add_u64 v[174:175], s[0:1], 0, v[168:169]
	s_add_i32 m0, s27, 0xe000
	s_nop 0
	global_load_lds_dwordx4 v[174:175], off
	s_waitcnt lgkmcnt(0)
	s_barrier
	v_mfma_f32_16x16x32_bf16 v[140:143], v[24:27], v[144:147], v[140:143]
	v_mfma_f32_16x16x32_bf16 v[136:139], v[40:43], v[144:147], v[136:139]
	v_mfma_f32_16x16x32_bf16 v[124:127], v[24:27], v[182:185], v[124:127]
	v_mfma_f32_16x16x32_bf16 v[120:123], v[40:43], v[182:185], v[120:123]
	v_mfma_f32_16x16x32_bf16 v[108:111], v[24:27], v[196:199], v[108:111]
	v_mfma_f32_16x16x32_bf16 v[104:107], v[40:43], v[196:199], v[104:107]
	v_mfma_f32_16x16x32_bf16 v[92:95], v[24:27], v[204:207], v[92:95]
	v_mfma_f32_16x16x32_bf16 v[88:91], v[40:43], v[204:207], v[88:91]
	v_mfma_f32_16x16x32_bf16 v[140:143], v[28:31], v[148:151], v[140:143]
	v_mfma_f32_16x16x32_bf16 v[136:139], v[44:47], v[148:151], v[136:139]
	v_mfma_f32_16x16x32_bf16 v[124:127], v[28:31], v[192:195], v[124:127]
	v_mfma_f32_16x16x32_bf16 v[120:123], v[44:47], v[192:195], v[120:123]
	v_mfma_f32_16x16x32_bf16 v[108:111], v[28:31], v[200:203], v[108:111]
	v_mfma_f32_16x16x32_bf16 v[104:107], v[44:47], v[200:203], v[104:107]
	v_mfma_f32_16x16x32_bf16 v[92:95], v[28:31], v[208:211], v[92:95]
	v_mfma_f32_16x16x32_bf16 v[88:91], v[44:47], v[208:211], v[88:91]
	s_barrier
	ds_read_b128 v[212:215], v189
	ds_read_b128 v[216:219], v189 offset:1024
	ds_read_b128 v[220:223], v189 offset:2048
	ds_read_b128 v[224:227], v189 offset:3072
	s_add_i32 s54, s43, s35
	v_lshl_add_u64 v[174:175], s[4:5], 0, v[156:157]
	s_mov_b32 m0, s54
	s_nop 0
	global_load_lds_dwordx4 v[174:175], off
	v_lshl_add_u64 v[228:229], s[4:5], 0, v[160:161]
	s_add_i32 m0, s54, 0x2000
	s_nop 0
	global_load_lds_dwordx4 v[228:229], off
	s_waitcnt lgkmcnt(0)
	s_barrier
	v_mfma_f32_16x16x32_bf16 v[132:135], v[212:215], v[144:147], v[132:135]
	v_mfma_f32_16x16x32_bf16 v[128:131], v[220:223], v[144:147], v[128:131]
	v_mfma_f32_16x16x32_bf16 v[116:119], v[212:215], v[182:185], v[116:119]
	v_mfma_f32_16x16x32_bf16 v[112:115], v[220:223], v[182:185], v[112:115]
	v_mfma_f32_16x16x32_bf16 v[100:103], v[212:215], v[196:199], v[100:103]
	v_mfma_f32_16x16x32_bf16 v[96:99], v[220:223], v[196:199], v[96:99]
	v_mfma_f32_16x16x32_bf16 v[84:87], v[212:215], v[204:207], v[84:87]
	v_mfma_f32_16x16x32_bf16 v[80:83], v[220:223], v[204:207], v[80:83]
	v_mfma_f32_16x16x32_bf16 v[132:135], v[216:219], v[148:151], v[132:135]
	v_mfma_f32_16x16x32_bf16 v[128:131], v[224:227], v[148:151], v[128:131]
	v_mfma_f32_16x16x32_bf16 v[116:119], v[216:219], v[192:195], v[116:119]
	v_mfma_f32_16x16x32_bf16 v[112:115], v[224:227], v[192:195], v[112:115]
	v_mfma_f32_16x16x32_bf16 v[100:103], v[216:219], v[200:203], v[100:103]
	v_mfma_f32_16x16x32_bf16 v[96:99], v[224:227], v[200:203], v[96:99]
	v_mfma_f32_16x16x32_bf16 v[84:87], v[216:219], v[208:211], v[84:87]
	v_mfma_f32_16x16x32_bf16 v[80:83], v[224:227], v[208:211], v[80:83]
	s_barrier
	s_mov_b32 m0, s27
	v_lshl_add_u64 v[230:231], s[28:29], 0, v[154:155]
	ds_read_b128 v[144:147], v187 offset:16384
	ds_read_b128 v[148:151], v187 offset:17408
	ds_read_b128 v[182:185], v187 offset:18432
	ds_read_b128 v[192:195], v187 offset:19456
	ds_read_b128 v[196:199], v187 offset:20480
	ds_read_b128 v[200:203], v187 offset:21504
	ds_read_b128 v[204:207], v187 offset:22528
	ds_read_b128 v[208:211], v187 offset:23552
	global_load_lds_dwordx4 v[230:231], off
	v_lshl_add_u64 v[232:233], s[28:29], 0, v[158:159]
	s_mov_b32 m0, s36
	s_nop 0
	global_load_lds_dwordx4 v[232:233], off
	s_waitcnt lgkmcnt(0)
	s_barrier
	v_mfma_f32_16x16x32_bf16 v[76:79], v[24:27], v[144:147], v[76:79]
	v_mfma_f32_16x16x32_bf16 v[72:75], v[40:43], v[144:147], v[72:75]
	v_mfma_f32_16x16x32_bf16 v[60:63], v[24:27], v[182:185], v[60:63]
	v_mfma_f32_16x16x32_bf16 v[56:59], v[40:43], v[182:185], v[56:59]
	v_mfma_f32_16x16x32_bf16 v[36:39], v[24:27], v[196:199], v[36:39]
	v_mfma_f32_16x16x32_bf16 v[32:35], v[40:43], v[196:199], v[32:35]
	v_mfma_f32_16x16x32_bf16 v[12:15], v[24:27], v[204:207], v[12:15]
	v_mfma_f32_16x16x32_bf16 v[8:11], v[40:43], v[204:207], v[8:11]
	v_mfma_f32_16x16x32_bf16 v[76:79], v[28:31], v[148:151], v[76:79]
	v_mfma_f32_16x16x32_bf16 v[72:75], v[44:47], v[148:151], v[72:75]
	v_mfma_f32_16x16x32_bf16 v[60:63], v[28:31], v[192:195], v[60:63]
	v_mfma_f32_16x16x32_bf16 v[56:59], v[44:47], v[192:195], v[56:59]
	v_mfma_f32_16x16x32_bf16 v[36:39], v[28:31], v[200:203], v[36:39]
	v_mfma_f32_16x16x32_bf16 v[32:35], v[44:47], v[200:203], v[32:35]
	v_mfma_f32_16x16x32_bf16 v[12:15], v[28:31], v[208:211], v[12:15]
	v_mfma_f32_16x16x32_bf16 v[8:11], v[44:47], v[208:211], v[8:11]
	s_barrier
	s_add_u32 s54, s4, 0x40000
	s_addc_u32 s55, s5, 0
	s_add_i32 s56, s44, s35
	v_lshl_add_u64 v[24:25], s[54:55], 0, v[156:157]
	s_mov_b32 m0, s56
	s_nop 0
	global_load_lds_dwordx4 v[24:25], off
	v_lshl_add_u64 v[24:25], s[54:55], 0, v[160:161]
	s_add_i32 m0, s56, 0x2000
	s_nop 0
	global_load_lds_dwordx4 v[24:25], off
	s_waitcnt vmcnt(6)
	s_barrier
; #define PG8_STAGE(bufoff, gbase, voff) do { _Pragma("unroll") for (int _i = 0; _i < 2; ++_i) \
;         __builtin_amdgcn_global_load_lds((const unsigned*)((const char*)(gbase) + (voff)[_i]), (PG8_LAS unsigned*)(lds + (bufoff) + ldsw + _i * 8192), 16, 0, 0); } while (0)
; #define PG8_LDA(dst, b, h) do { _Pragma("unroll") for (int m = 0; m < 4; ++m) _Pragma("unroll") for (int k = 0; k < 2; ++k) dst[m][k] = *(const PG8_LAS bf16x8*)(lds + PG8_SA(b, h) + aoff + m * 2048 + k * 1024); } while (0)
; #define PG8_LDB(dst, b, h) do { _Pragma("unroll") for (int n = 0; n < 2; ++n) _Pragma("unroll") for (int k = 0; k < 2; ++k) dst[n][k] = *(const PG8_LAS bf16x8*)(lds + PG8_SB(b, h) + boff + n * 2048 + k * 1024); } while (0)
; #define PG8_MMA(ai, bj, At, Bt) do { __builtin_amdgcn_s_setprio(1); _Pragma("unroll") for (int m = 0; m < 4; ++m) _Pragma("unroll") for (int n = 0; n < 2; ++n) _Pragma("unroll") for (int k = 0; k < 2; ++k) \
;         acc[ai][bj][m][n] = __builtin_amdgcn_mfma_f32_16x16x32_bf16(Bt[n][k], At[m][k], acc[ai][bj][m][n], 0, 0, 0); __builtin_amdgcn_s_setprio(0); } while (0)
; #define PG8_WAIT_V(n) asm volatile("s_waitcnt vmcnt(" #n ")" ::: "memory")
; #define PG8_WAIT_L(n) asm volatile("s_waitcnt lgkmcnt(" #n ")" ::: "memory")
; #define PG8_BAR __builtin_amdgcn_s_barrier()
; #define PG8_SCHED __builtin_amdgcn_sched_barrier(0)
; template <class Epi, class Sched>
; __device__ __forceinline__ void gemm_phase(PG8_LAS unsigned char* lds, const Gemm g, const Sched& S, const Epi& E) {
;     ...
;             PG8_WAIT_V(6); PG8_BAR; PG8_MMA(1, 1, At, B1); PG8_BAR;
;             PG8_LDB(B0, 1, 0); PG8_SCHED; PG8_LDA(At, 1, 0); PG8_STAGE(PG8_SA(0, 1), a2 + hstep, voffA);
;             PG8_WAIT_L(8); PG8_BAR; PG8_WAIT_L(0); PG8_MMA(0, 0, At, B0); PG8_BAR; PG8_SCHED;
;             PG8_LDB(B1, 1, 1); PG8_STAGE(PG8_SB(1, 0), b3, voffB);
;             PG8_BAR; PG8_WAIT_L(0); PG8_MMA(0, 1, At, B1); PG8_BAR;
	v_mfma_f32_16x16x32_bf16 v[20:23], v[212:215], v[196:199], v[20:23]
	v_mfma_f32_16x16x32_bf16 v[16:19], v[220:223], v[196:199], v[16:19]
	v_mfma_f32_16x16x32_bf16 v[4:7], v[212:215], v[204:207], v[4:7]
	v_mfma_f32_16x16x32_bf16 v[0:3], v[220:223], v[204:207], v[0:3]
	v_mfma_f32_16x16x32_bf16 v[24:27], v[212:215], v[144:147], v[68:71]
	v_mfma_f32_16x16x32_bf16 v[28:31], v[220:223], v[144:147], v[64:67]
	v_mfma_f32_16x16x32_bf16 v[40:43], v[212:215], v[182:185], v[52:55]
	v_mfma_f32_16x16x32_bf16 v[44:47], v[220:223], v[182:185], v[48:51]
	v_mfma_f32_16x16x32_bf16 v[20:23], v[216:219], v[200:203], v[20:23]
	v_mfma_f32_16x16x32_bf16 v[16:19], v[224:227], v[200:203], v[16:19]
	v_mfma_f32_16x16x32_bf16 v[4:7], v[216:219], v[208:211], v[4:7]
	v_mfma_f32_16x16x32_bf16 v[0:3], v[224:227], v[208:211], v[0:3]
	v_mfma_f32_16x16x32_bf16 v[24:27], v[216:219], v[148:151], v[24:27]
	v_mfma_f32_16x16x32_bf16 v[28:31], v[224:227], v[148:151], v[28:31]
	v_mfma_f32_16x16x32_bf16 v[40:43], v[216:219], v[192:195], v[40:43]
	v_mfma_f32_16x16x32_bf16 v[44:47], v[224:227], v[192:195], v[44:47]
	s_barrier
	s_add_i32 s54, 0, 0x18000
	v_add_u32_e32 v68, s54, v179
	ds_read_b128 v[48:51], v68
	ds_read_b128 v[52:55], v68 offset:1024
	ds_read_b128 v[64:67], v68 offset:2048
	ds_read_b128 v[68:71], v68 offset:3072
	ds_read_b128 v[144:147], v187 offset:32768
	ds_read_b128 v[148:151], v187 offset:33792
	ds_read_b128 v[182:185], v187 offset:34816
	ds_read_b128 v[192:195], v187 offset:35840
	ds_read_b128 v[196:199], v187 offset:36864
	ds_read_b128 v[200:203], v187 offset:37888
	ds_read_b128 v[204:207], v187 offset:38912
	ds_read_b128 v[208:211], v187 offset:39936
	s_add_u32 s28, s28, 0x40000
	s_addc_u32 s29, s29, 0
	s_mov_b32 m0, s37
	v_lshl_add_u64 v[212:213], s[28:29], 0, v[154:155]
	global_load_lds_dwordx4 v[212:213], off
	v_lshl_add_u64 v[212:213], s[28:29], 0, v[158:159]
	s_mov_b32 m0, s38
	s_nop 0
	global_load_lds_dwordx4 v[212:213], off
	s_waitcnt lgkmcnt(0)
	s_barrier
	v_mfma_f32_16x16x32_bf16 v[140:143], v[48:51], v[144:147], v[140:143]
	v_mfma_f32_16x16x32_bf16 v[136:139], v[64:67], v[144:147], v[136:139]
	v_mfma_f32_16x16x32_bf16 v[124:127], v[48:51], v[182:185], v[124:127]
	v_mfma_f32_16x16x32_bf16 v[120:123], v[64:67], v[182:185], v[120:123]
	v_mfma_f32_16x16x32_bf16 v[108:111], v[48:51], v[196:199], v[108:111]
	v_mfma_f32_16x16x32_bf16 v[104:107], v[64:67], v[196:199], v[104:107]
	v_mfma_f32_16x16x32_bf16 v[92:95], v[48:51], v[204:207], v[92:95]
	v_mfma_f32_16x16x32_bf16 v[88:91], v[64:67], v[204:207], v[88:91]
	v_mfma_f32_16x16x32_bf16 v[140:143], v[52:55], v[148:151], v[140:143]
	v_mfma_f32_16x16x32_bf16 v[136:139], v[68:71], v[148:151], v[136:139]
	v_mfma_f32_16x16x32_bf16 v[124:127], v[52:55], v[192:195], v[124:127]
	v_mfma_f32_16x16x32_bf16 v[120:123], v[68:71], v[192:195], v[120:123]
	v_mfma_f32_16x16x32_bf16 v[108:111], v[52:55], v[200:203], v[108:111]
	v_mfma_f32_16x16x32_bf16 v[104:107], v[68:71], v[200:203], v[104:107]
	v_mfma_f32_16x16x32_bf16 v[92:95], v[52:55], v[208:211], v[92:95]
	v_mfma_f32_16x16x32_bf16 v[88:91], v[68:71], v[208:211], v[88:91]
	s_barrier
	s_add_i32 s28, 0, 0x1c000
	v_add_u32_e32 v162, s28, v179
	ds_read_b128 v[212:215], v162
	ds_read_b128 v[216:219], v162 offset:1024
	ds_read_b128 v[220:223], v162 offset:2048
	ds_read_b128 v[224:227], v162 offset:3072
	s_add_i32 s29, s54, s35
	v_lshl_add_u64 v[174:175], v[174:175], 0, s[14:15]
	s_mov_b32 m0, s29
	s_nop 0
	global_load_lds_dwordx4 v[174:175], off
	v_lshl_add_u64 v[174:175], v[228:229], 0, s[14:15]
	s_add_i32 m0, s29, 0x2000
	s_nop 0
	global_load_lds_dwordx4 v[174:175], off
	s_waitcnt lgkmcnt(0)
	s_barrier
	v_mfma_f32_16x16x32_bf16 v[132:135], v[212:215], v[144:147], v[132:135]
	v_mfma_f32_16x16x32_bf16 v[128:131], v[220:223], v[144:147], v[128:131]
	v_mfma_f32_16x16x32_bf16 v[116:119], v[212:215], v[182:185], v[116:119]
	v_mfma_f32_16x16x32_bf16 v[112:115], v[220:223], v[182:185], v[112:115]
	v_mfma_f32_16x16x32_bf16 v[100:103], v[212:215], v[196:199], v[100:103]
	v_mfma_f32_16x16x32_bf16 v[96:99], v[220:223], v[196:199], v[96:99]
	v_mfma_f32_16x16x32_bf16 v[84:87], v[212:215], v[204:207], v[84:87]
	v_mfma_f32_16x16x32_bf16 v[80:83], v[220:223], v[204:207], v[80:83]
	v_mfma_f32_16x16x32_bf16 v[132:135], v[216:219], v[148:151], v[132:135]
	v_mfma_f32_16x16x32_bf16 v[128:131], v[224:227], v[148:151], v[128:131]
	v_mfma_f32_16x16x32_bf16 v[116:119], v[216:219], v[192:195], v[116:119]
	v_mfma_f32_16x16x32_bf16 v[112:115], v[224:227], v[192:195], v[112:115]
	v_mfma_f32_16x16x32_bf16 v[100:103], v[216:219], v[200:203], v[100:103]
	v_mfma_f32_16x16x32_bf16 v[96:99], v[224:227], v[200:203], v[96:99]
	v_mfma_f32_16x16x32_bf16 v[84:87], v[216:219], v[208:211], v[84:87]
	v_mfma_f32_16x16x32_bf16 v[80:83], v[224:227], v[208:211], v[80:83]
	s_barrier
; #define PG8_STAGE(bufoff, gbase, voff) do { _Pragma("unroll") for (int _i = 0; _i < 2; ++_i) \
;         __builtin_amdgcn_global_load_lds((const unsigned*)((const char*)(gbase) + (voff)[_i]), (PG8_LAS unsigned*)(lds + (bufoff) + ldsw + _i * 8192), 16, 0, 0); } while (0)
; #define PG8_LDA(dst, b, h) do { _Pragma("unroll") for (int m = 0; m < 4; ++m) _Pragma("unroll") for (int k = 0; k < 2; ++k) dst[m][k] = *(const PG8_LAS bf16x8*)(lds + PG8_SA(b, h) + aoff + m * 2048 + k * 1024); } while (0)
; #define PG8_MMA(ai, bj, At, Bt) do { __builtin_amdgcn_s_setprio(1); _Pragma("unroll") for (int m = 0; m < 4; ++m) _Pragma("unroll") for (int n = 0; n < 2; ++n) _Pragma("unroll") for (int k = 0; k < 2; ++k) \
;         acc[ai][bj][m][n] = __builtin_amdgcn_mfma_f32_16x16x32_bf16(Bt[n][k], At[m][k], acc[ai][bj][m][n], 0, 0, 0); __builtin_amdgcn_s_setprio(0); } while (0)
; #define PG8_WAIT_V(n) asm volatile("s_waitcnt vmcnt(" #n ")" ::: "memory")
; #define PG8_WAIT_L(n) asm volatile("s_waitcnt lgkmcnt(" #n ")" ::: "memory")
; #define PG8_BAR __builtin_amdgcn_s_barrier()
; #define PG8_SCHED __builtin_amdgcn_sched_barrier(0)
;     __device__ __forceinline__ void operator()(const f32x4 (&acc)[2][2][4][2], const Unit& u, int wr, int wc, int fr, int fq) const {
;         int act = 0; const float* bias = nullptr;
;         if (mode == 1) { if (u.pn >= 8 && u.pn < 12) act = 1; else if (u.pn >= 12) { act = 3; bias = (u.pn >= 14) ? bias_b + (u.pn - 14) * 256 : bias_f + (u.pn - 12) * 256; } }
;         else if (mode == 2) { if (u.pn >= 6) act = 2; }
;         const int row0 = u.pm * BM + wr * 64 + fr, col0 = u.pn * BM + wc * 32 + 8 * fq, bcol0 = wc * 32 + 8 * fq;
;         f32x4 bv[2][2];
; #pragma unroll
;         for (int bj = 0; bj < 2; ++bj)
; #pragma unroll
;             for (int n = 0; n < 2; ++n) bv[bj][n] = bias ? *(const f32x4*)(bias + bcol0 + bj * HALF + 4 * n) : (f32x4){0.f, 0.f, 0.f, 0.f};
; template <class Epi, class Sched>
; __device__ __forceinline__ void gemm_phase(PG8_LAS unsigned char* lds, const Gemm g, const Sched& S, const Epi& E) {
;     ...
;             PG8_LDA(At, 1, 1); PG8_STAGE(PG8_SA(1, 0), a3, voffA);
;             PG8_BAR; PG8_WAIT_L(0); PG8_MMA(1, 0, At, B0); PG8_BAR; PG8_SCHED;
;             PG8_STAGE(PG8_SB(1, 1), b3 + hstep, voffB);
;             PG8_WAIT_V(6); PG8_BAR; PG8_MMA(1, 1, At, B1); PG8_BAR;
;         }
	s_mov_b32 m0, s39
	v_lshl_add_u64 v[174:175], v[230:231], 0, s[14:15]
	ds_read_b128 v[144:147], v187 offset:49152
	ds_read_b128 v[148:151], v187 offset:50176
	ds_read_b128 v[182:185], v187 offset:51200
	ds_read_b128 v[192:195], v187 offset:52224
	ds_read_b128 v[196:199], v187 offset:53248
	ds_read_b128 v[200:203], v187 offset:54272
	ds_read_b128 v[204:207], v187 offset:55296
	ds_read_b128 v[208:211], v187 offset:56320
	global_load_lds_dwordx4 v[174:175], off
	v_lshl_add_u64 v[174:175], v[232:233], 0, s[14:15]
	s_mov_b32 m0, s40
	s_nop 0
	global_load_lds_dwordx4 v[174:175], off
	s_waitcnt lgkmcnt(0)
	s_barrier
	v_mfma_f32_16x16x32_bf16 v[76:79], v[48:51], v[144:147], v[76:79]
	v_mfma_f32_16x16x32_bf16 v[72:75], v[64:67], v[144:147], v[72:75]
	v_mfma_f32_16x16x32_bf16 v[60:63], v[48:51], v[182:185], v[60:63]
	v_mfma_f32_16x16x32_bf16 v[56:59], v[64:67], v[182:185], v[56:59]
	v_mfma_f32_16x16x32_bf16 v[36:39], v[48:51], v[196:199], v[36:39]
	v_mfma_f32_16x16x32_bf16 v[32:35], v[64:67], v[196:199], v[32:35]
	v_mfma_f32_16x16x32_bf16 v[12:15], v[48:51], v[204:207], v[12:15]
	v_mfma_f32_16x16x32_bf16 v[8:11], v[64:67], v[204:207], v[8:11]
	v_mfma_f32_16x16x32_bf16 v[76:79], v[52:55], v[148:151], v[76:79]
	v_mfma_f32_16x16x32_bf16 v[72:75], v[68:71], v[148:151], v[72:75]
	v_mfma_f32_16x16x32_bf16 v[60:63], v[52:55], v[192:195], v[60:63]
	v_mfma_f32_16x16x32_bf16 v[56:59], v[68:71], v[192:195], v[56:59]
	v_mfma_f32_16x16x32_bf16 v[36:39], v[52:55], v[200:203], v[36:39]
	v_mfma_f32_16x16x32_bf16 v[32:35], v[68:71], v[200:203], v[32:35]
	v_mfma_f32_16x16x32_bf16 v[12:15], v[52:55], v[208:211], v[12:15]
	v_mfma_f32_16x16x32_bf16 v[8:11], v[68:71], v[208:211], v[8:11]
	s_barrier
	s_add_u32 s4, s4, 0x40080
	s_addc_u32 s5, s5, 0
	s_add_i32 s28, s28, s35
	v_lshl_add_u64 v[48:49], s[4:5], 0, v[156:157]
	s_mov_b32 m0, s28
	s_nop 0
	global_load_lds_dwordx4 v[48:49], off
	v_lshl_add_u64 v[48:49], s[4:5], 0, v[160:161]
	s_add_i32 m0, s28, 0x2000
	s_nop 0
	global_load_lds_dwordx4 v[48:49], off
	s_waitcnt vmcnt(6)
	s_barrier
	v_mfma_f32_16x16x32_bf16 v[24:27], v[212:215], v[144:147], v[24:27]
	v_mfma_f32_16x16x32_bf16 v[68:71], v[216:219], v[148:151], v[24:27]
	v_mfma_f32_16x16x32_bf16 v[24:27], v[220:223], v[144:147], v[28:31]
	v_mfma_f32_16x16x32_bf16 v[64:67], v[224:227], v[148:151], v[24:27]
	v_mfma_f32_16x16x32_bf16 v[24:27], v[212:215], v[182:185], v[40:43]
	v_mfma_f32_16x16x32_bf16 v[52:55], v[216:219], v[192:195], v[24:27]
	v_mfma_f32_16x16x32_bf16 v[24:27], v[220:223], v[182:185], v[44:47]
	v_mfma_f32_16x16x32_bf16 v[20:23], v[212:215], v[196:199], v[20:23]
	v_mfma_f32_16x16x32_bf16 v[16:19], v[220:223], v[196:199], v[16:19]
	v_mfma_f32_16x16x32_bf16 v[4:7], v[212:215], v[204:207], v[4:7]
	v_mfma_f32_16x16x32_bf16 v[0:3], v[220:223], v[204:207], v[0:3]
	v_mfma_f32_16x16x32_bf16 v[48:51], v[224:227], v[192:195], v[24:27]
	v_mfma_f32_16x16x32_bf16 v[20:23], v[216:219], v[200:203], v[20:23]
	v_mfma_f32_16x16x32_bf16 v[16:19], v[224:227], v[200:203], v[16:19]
	v_mfma_f32_16x16x32_bf16 v[4:7], v[216:219], v[208:211], v[4:7]
	v_mfma_f32_16x16x32_bf16 v[0:3], v[224:227], v[208:211], v[0:3]
	s_barrier
	s_add_i32 s53, s53, 2
	s_add_u32 s0, s0, 0x100
	s_addc_u32 s1, s1, 0
	s_add_u32 s51, s51, 0x100
	s_addc_u32 s52, s52, 0
	s_cmp_gt_u32 s53, 13
	s_cbranch_scc0 .LBB0_416
	s_cmp_gt_i32 s26, 11
	s_cselect_b64 s[4:5], -1, 0
	s_cmp_lt_i32 s26, 12
	s_mov_b64 s[0:1], 0
	s_cbranch_scc1 .LBB0_422
	s_lshl_b32 s10, s26, 8
	s_cmp_lt_u32 s26, 14
	s_mov_b64 s[28:29], -1
	s_cbranch_scc0 .LBB0_420
	s_lshl_b64 s[0:1], s[10:11], 2
	v_readlane_b32 s52, v245, 0
	v_readlane_b32 s53, v245, 1
	s_add_u32 s0, s52, s0
	s_addc_u32 s1, s53, s1
	s_add_u32 s0, s0, 0xffffd000
	v_readlane_b32 s54, v245, 2
	v_readlane_b32 s55, v245, 3
	v_readlane_b32 s56, v245, 4
	v_readlane_b32 s57, v245, 5
	v_readlane_b32 s58, v245, 6
	v_readlane_b32 s59, v245, 7
	v_readlane_b32 s60, v245, 8
	v_readlane_b32 s61, v245, 9
	v_readlane_b32 s62, v245, 10
	v_readlane_b32 s63, v245, 11
	v_readlane_b32 s64, v245, 12
	v_readlane_b32 s65, v245, 13
	v_readlane_b32 s66, v245, 14
	v_readlane_b32 s67, v245, 15
	s_addc_u32 s1, s1, -1
	s_mov_b64 s[28:29], 0

; #define PG8_STAGE(bufoff, gbase, voff) do { _Pragma("unroll") for (int _i = 0; _i < 2; ++_i) \
;         __builtin_amdgcn_global_load_lds((const unsigned*)((const char*)(gbase) + (voff)[_i]), (PG8_LAS unsigned*)(lds + (bufoff) + ldsw + _i * 8192), 16, 0, 0); } while (0)
; #define PG8_LDA(dst, b, h) do { _Pragma("unroll") for (int m = 0; m < 4; ++m) _Pragma("unroll") for (int k = 0; k < 2; ++k) dst[m][k] = *(const PG8_LAS bf16x8*)(lds + PG8_SA(b, h) + aoff + m * 2048 + k * 1024); } while (0)
; #define PG8_LDB(dst, b, h) do { _Pragma("unroll") for (int n = 0; n < 2; ++n) _Pragma("unroll") for (int k = 0; k < 2; ++k) dst[n][k] = *(const PG8_LAS bf16x8*)(lds + PG8_SB(b, h) + boff + n * 2048 + k * 1024); } while (0)
; #define PG8_MMA(ai, bj, At, Bt) do { __builtin_amdgcn_s_setprio(1); _Pragma("unroll") for (int m = 0; m < 4; ++m) _Pragma("unroll") for (int n = 0; n < 2; ++n) _Pragma("unroll") for (int k = 0; k < 2; ++k) \
;         acc[ai][bj][m][n] = __builtin_amdgcn_mfma_f32_16x16x32_bf16(Bt[n][k], At[m][k], acc[ai][bj][m][n], 0, 0, 0); __builtin_amdgcn_s_setprio(0); } while (0)
; #define PG8_WAIT_L(n) asm volatile("s_waitcnt lgkmcnt(" #n ")" ::: "memory")
; #define PG8_BAR __builtin_amdgcn_s_barrier()
; #define PG8_SCHED __builtin_amdgcn_sched_barrier(0)
; template <class Epi, class Sched>
; __device__ __forceinline__ void gemm_phase(PG8_LAS unsigned char* lds, const Gemm g, const Sched& S, const Epi& E) {
;     ...
;             const bool last = (t == nt - 2);
;             const char* a1 = cA + (size_t)(t + 1) * kstep;
;             const char* a2 = last ? nA : cA + (size_t)(t + 2) * kstep; const char* b2 = last ? nB : cB + (size_t)(t + 2) * kstep;
;             const char* a3 = a2 + kstep; const char* b3 = b2 + kstep;
;             if (last && has_next) S.a_ready(nxt);
;             PG8_LDB(B0, 0, 0); PG8_SCHED; PG8_LDA(At, 0, 0); PG8_STAGE(PG8_SA(1, 1), a1 + hstep, voffA);
;             PG8_WAIT_L(8); PG8_BAR; PG8_WAIT_L(0); PG8_MMA(0, 0, At, B0); PG8_BAR; PG8_SCHED;
;             PG8_LDB(B1, 0, 1); PG8_STAGE(PG8_SB(0, 0), b2, voffB);
;             PG8_BAR; PG8_WAIT_L(0); PG8_MMA(0, 1, At, B1); PG8_BAR;
;             PG8_LDA(At, 0, 1); PG8_STAGE(PG8_SA(0, 0), a2, voffA);
;             PG8_BAR; PG8_WAIT_L(0); PG8_MMA(1, 0, At, B0); PG8_BAR; PG8_SCHED;
.LBB0_724:
	ds_read_b128 v[144:147], v151
	ds_read_b128 v[156:159], v151 offset:1024
	ds_read_b128 v[160:163], v151 offset:2048
	ds_read_b128 v[166:169], v151 offset:3072
	ds_read_b128 v[170:173], v153
	ds_read_b128 v[182:185], v153 offset:1024
	ds_read_b128 v[190:193], v153 offset:2048
	ds_read_b128 v[194:197], v153 offset:3072
	ds_read_b128 v[198:201], v153 offset:4096
	ds_read_b128 v[202:205], v153 offset:5120
	ds_read_b128 v[206:209], v153 offset:6144
	ds_read_b128 v[210:213], v153 offset:7168
	s_add_u32 s20, s18, 0xfffc0080
	s_addc_u32 s21, s19, -1
	s_cmp_eq_u32 s48, 12
	s_cselect_b32 s23, s5, s21
	s_cselect_b32 s22, s11, s20
	s_cselect_b32 s21, s9, s47
	s_cselect_b32 s20, s45, s46
	v_lshl_add_u64 v[174:175], s[18:19], 0, v[136:137]
	s_add_i32 m0, s17, 0xc000
	s_nop 0
	global_load_lds_dwordx4 v[174:175], off
	v_lshl_add_u64 v[174:175], s[18:19], 0, v[138:139]
	s_add_i32 m0, s17, 0xe000
	s_nop 0
	global_load_lds_dwordx4 v[174:175], off
	s_waitcnt lgkmcnt(0)
	s_barrier
	v_mfma_f32_16x16x32_bf16 v[124:127], v[144:147], v[170:173], v[124:127]
	v_mfma_f32_16x16x32_bf16 v[120:123], v[160:163], v[170:173], v[120:123]
	v_mfma_f32_16x16x32_bf16 v[108:111], v[144:147], v[190:193], v[108:111]
	v_mfma_f32_16x16x32_bf16 v[104:107], v[160:163], v[190:193], v[104:107]
	v_mfma_f32_16x16x32_bf16 v[92:95], v[144:147], v[198:201], v[92:95]
	v_mfma_f32_16x16x32_bf16 v[88:91], v[160:163], v[198:201], v[88:91]
	v_mfma_f32_16x16x32_bf16 v[76:79], v[144:147], v[206:209], v[76:79]
	v_mfma_f32_16x16x32_bf16 v[72:75], v[160:163], v[206:209], v[72:75]
	v_mfma_f32_16x16x32_bf16 v[124:127], v[156:159], v[182:185], v[124:127]
	v_mfma_f32_16x16x32_bf16 v[120:123], v[166:169], v[182:185], v[120:123]
	v_mfma_f32_16x16x32_bf16 v[108:111], v[156:159], v[194:197], v[108:111]
	v_mfma_f32_16x16x32_bf16 v[104:107], v[166:169], v[194:197], v[104:107]
	v_mfma_f32_16x16x32_bf16 v[92:95], v[156:159], v[202:205], v[92:95]
	v_mfma_f32_16x16x32_bf16 v[88:91], v[166:169], v[202:205], v[88:91]
	v_mfma_f32_16x16x32_bf16 v[76:79], v[156:159], v[210:213], v[76:79]
	v_mfma_f32_16x16x32_bf16 v[72:75], v[166:169], v[210:213], v[72:75]
	s_barrier
	ds_read_b128 v[214:217], v154
	ds_read_b128 v[218:221], v154 offset:1024
	ds_read_b128 v[222:225], v154 offset:2048
	ds_read_b128 v[226:229], v154 offset:3072
	s_add_i32 s49, s42, s30
	v_lshl_add_u64 v[174:175], s[20:21], 0, v[130:131]
	s_mov_b32 m0, s49
	s_nop 0
	global_load_lds_dwordx4 v[174:175], off
	v_lshl_add_u64 v[186:187], s[20:21], 0, v[134:135]
	s_add_i32 m0, s49, 0x2000
	s_nop 0
	global_load_lds_dwordx4 v[186:187], off
	s_waitcnt lgkmcnt(0)
	s_barrier
	v_mfma_f32_16x16x32_bf16 v[116:119], v[214:217], v[170:173], v[116:119]
	v_mfma_f32_16x16x32_bf16 v[112:115], v[222:225], v[170:173], v[112:115]
	v_mfma_f32_16x16x32_bf16 v[100:103], v[214:217], v[190:193], v[100:103]
	v_mfma_f32_16x16x32_bf16 v[96:99], v[222:225], v[190:193], v[96:99]
	v_mfma_f32_16x16x32_bf16 v[84:87], v[214:217], v[198:201], v[84:87]
	v_mfma_f32_16x16x32_bf16 v[80:83], v[222:225], v[198:201], v[80:83]
	v_mfma_f32_16x16x32_bf16 v[68:71], v[214:217], v[206:209], v[68:71]
	v_mfma_f32_16x16x32_bf16 v[64:67], v[222:225], v[206:209], v[64:67]
	v_mfma_f32_16x16x32_bf16 v[116:119], v[218:221], v[182:185], v[116:119]
	v_mfma_f32_16x16x32_bf16 v[112:115], v[226:229], v[182:185], v[112:115]
	v_mfma_f32_16x16x32_bf16 v[100:103], v[218:221], v[194:197], v[100:103]
	v_mfma_f32_16x16x32_bf16 v[96:99], v[226:229], v[194:197], v[96:99]
	v_mfma_f32_16x16x32_bf16 v[84:87], v[218:221], v[202:205], v[84:87]
	v_mfma_f32_16x16x32_bf16 v[80:83], v[226:229], v[202:205], v[80:83]
	v_mfma_f32_16x16x32_bf16 v[68:71], v[218:221], v[210:213], v[68:71]
	v_mfma_f32_16x16x32_bf16 v[64:67], v[226:229], v[210:213], v[64:67]
	s_barrier
	s_mov_b32 m0, s17
	v_lshl_add_u64 v[230:231], s[22:23], 0, v[128:129]
	ds_read_b128 v[170:173], v153 offset:16384
	ds_read_b128 v[182:185], v153 offset:17408
	ds_read_b128 v[190:193], v153 offset:18432
	ds_read_b128 v[194:197], v153 offset:19456
	ds_read_b128 v[198:201], v153 offset:20480
	ds_read_b128 v[202:205], v153 offset:21504
	ds_read_b128 v[206:209], v153 offset:22528
	ds_read_b128 v[210:213], v153 offset:23552
	global_load_lds_dwordx4 v[230:231], off
	v_lshl_add_u64 v[232:233], s[22:23], 0, v[132:133]
	s_mov_b32 m0, s31
	s_nop 0
	global_load_lds_dwordx4 v[232:233], off
	s_waitcnt lgkmcnt(0)
	s_barrier
	v_mfma_f32_16x16x32_bf16 v[60:63], v[144:147], v[170:173], v[60:63]
	v_mfma_f32_16x16x32_bf16 v[56:59], v[160:163], v[170:173], v[56:59]
	v_mfma_f32_16x16x32_bf16 v[44:47], v[144:147], v[190:193], v[44:47]
	v_mfma_f32_16x16x32_bf16 v[40:43], v[160:163], v[190:193], v[40:43]
	v_mfma_f32_16x16x32_bf16 v[28:31], v[144:147], v[198:201], v[28:31]
	v_mfma_f32_16x16x32_bf16 v[24:27], v[160:163], v[198:201], v[24:27]
	v_mfma_f32_16x16x32_bf16 v[12:15], v[144:147], v[206:209], v[12:15]
	v_mfma_f32_16x16x32_bf16 v[8:11], v[160:163], v[206:209], v[8:11]
	v_mfma_f32_16x16x32_bf16 v[60:63], v[156:159], v[182:185], v[60:63]
	v_mfma_f32_16x16x32_bf16 v[56:59], v[166:169], v[182:185], v[56:59]
	v_mfma_f32_16x16x32_bf16 v[44:47], v[156:159], v[194:197], v[44:47]
	v_mfma_f32_16x16x32_bf16 v[40:43], v[166:169], v[194:197], v[40:43]
	v_mfma_f32_16x16x32_bf16 v[28:31], v[156:159], v[202:205], v[28:31]
	v_mfma_f32_16x16x32_bf16 v[24:27], v[166:169], v[202:205], v[24:27]
	v_mfma_f32_16x16x32_bf16 v[12:15], v[156:159], v[210:213], v[12:15]
	v_mfma_f32_16x16x32_bf16 v[8:11], v[166:169], v[210:213], v[8:11]
	s_barrier
; #define PG8_STAGE(bufoff, gbase, voff) do { _Pragma("unroll") for (int _i = 0; _i < 2; ++_i) \
;         __builtin_amdgcn_global_load_lds((const unsigned*)((const char*)(gbase) + (voff)[_i]), (PG8_LAS unsigned*)(lds + (bufoff) + ldsw + _i * 8192), 16, 0, 0); } while (0)
; #define PG8_LDA(dst, b, h) do { _Pragma("unroll") for (int m = 0; m < 4; ++m) _Pragma("unroll") for (int k = 0; k < 2; ++k) dst[m][k] = *(const PG8_LAS bf16x8*)(lds + PG8_SA(b, h) + aoff + m * 2048 + k * 1024); } while (0)
; #define PG8_LDB(dst, b, h) do { _Pragma("unroll") for (int n = 0; n < 2; ++n) _Pragma("unroll") for (int k = 0; k < 2; ++k) dst[n][k] = *(const PG8_LAS bf16x8*)(lds + PG8_SB(b, h) + boff + n * 2048 + k * 1024); } while (0)
; #define PG8_MMA(ai, bj, At, Bt) do { __builtin_amdgcn_s_setprio(1); _Pragma("unroll") for (int m = 0; m < 4; ++m) _Pragma("unroll") for (int n = 0; n < 2; ++n) _Pragma("unroll") for (int k = 0; k < 2; ++k) \
;         acc[ai][bj][m][n] = __builtin_amdgcn_mfma_f32_16x16x32_bf16(Bt[n][k], At[m][k], acc[ai][bj][m][n], 0, 0, 0); __builtin_amdgcn_s_setprio(0); } while (0)
; #define PG8_WAIT_V(n) asm volatile("s_waitcnt vmcnt(" #n ")" ::: "memory")
; #define PG8_WAIT_L(n) asm volatile("s_waitcnt lgkmcnt(" #n ")" ::: "memory")
; #define PG8_BAR __builtin_amdgcn_s_barrier()
; #define PG8_SCHED __builtin_amdgcn_sched_barrier(0)
; template <class Epi, class Sched>
; __device__ __forceinline__ void gemm_phase(PG8_LAS unsigned char* lds, const Gemm g, const Sched& S, const Epi& E) {
;     ...
;             PG8_STAGE(PG8_SB(0, 1), b2 + hstep, voffB);
;             PG8_WAIT_V(6); PG8_BAR; PG8_MMA(1, 1, At, B1); PG8_BAR;
;             PG8_LDB(B0, 1, 0); PG8_SCHED; PG8_LDA(At, 1, 0); PG8_STAGE(PG8_SA(0, 1), a2 + hstep, voffA);
;             PG8_WAIT_L(8); PG8_BAR; PG8_WAIT_L(0); PG8_MMA(0, 0, At, B0); PG8_BAR; PG8_SCHED;
;             PG8_LDB(B1, 1, 1); PG8_STAGE(PG8_SB(1, 0), b3, voffB);
;             PG8_BAR; PG8_WAIT_L(0); PG8_MMA(0, 1, At, B1); PG8_BAR;
;             PG8_LDA(At, 1, 1); PG8_STAGE(PG8_SA(1, 0), a3, voffA);
;             PG8_BAR; PG8_WAIT_L(0); PG8_MMA(1, 0, At, B0); PG8_BAR; PG8_SCHED;
	s_add_u32 s50, s20, 0x40000
	s_addc_u32 s51, s21, 0
	s_add_i32 s49, s43, s30
	v_lshl_add_u64 v[144:145], s[50:51], 0, v[130:131]
	s_mov_b32 m0, s49
	s_nop 0
	global_load_lds_dwordx4 v[144:145], off
	v_lshl_add_u64 v[144:145], s[50:51], 0, v[134:135]
	s_add_i32 m0, s49, 0x2000
	s_nop 0
	global_load_lds_dwordx4 v[144:145], off
	s_waitcnt vmcnt(6)
	s_barrier
	v_mfma_f32_16x16x32_bf16 v[52:55], v[214:217], v[170:173], v[52:55]
	v_mfma_f32_16x16x32_bf16 v[48:51], v[222:225], v[170:173], v[48:51]
	v_mfma_f32_16x16x32_bf16 v[36:39], v[214:217], v[190:193], v[36:39]
	v_mfma_f32_16x16x32_bf16 v[32:35], v[222:225], v[190:193], v[32:35]
	v_mfma_f32_16x16x32_bf16 v[20:23], v[214:217], v[198:201], v[20:23]
	v_mfma_f32_16x16x32_bf16 v[16:19], v[222:225], v[198:201], v[16:19]
	v_mfma_f32_16x16x32_bf16 v[4:7], v[214:217], v[206:209], v[4:7]
	v_mfma_f32_16x16x32_bf16 v[0:3], v[222:225], v[206:209], v[0:3]
	v_mfma_f32_16x16x32_bf16 v[52:55], v[218:221], v[182:185], v[52:55]
	v_mfma_f32_16x16x32_bf16 v[48:51], v[226:229], v[182:185], v[48:51]
	v_mfma_f32_16x16x32_bf16 v[36:39], v[218:221], v[194:197], v[36:39]
	v_mfma_f32_16x16x32_bf16 v[32:35], v[226:229], v[194:197], v[32:35]
	v_mfma_f32_16x16x32_bf16 v[20:23], v[218:221], v[202:205], v[20:23]
	v_mfma_f32_16x16x32_bf16 v[16:19], v[226:229], v[202:205], v[16:19]
	v_mfma_f32_16x16x32_bf16 v[4:7], v[218:221], v[210:213], v[4:7]
	v_mfma_f32_16x16x32_bf16 v[0:3], v[226:229], v[210:213], v[0:3]
	s_barrier
	s_add_i32 s49, 0, 0x18000
	v_add_u32_e32 v155, s49, v149
	ds_read_b128 v[144:147], v155
	ds_read_b128 v[156:159], v155 offset:1024
	ds_read_b128 v[160:163], v155 offset:2048
	ds_read_b128 v[166:169], v155 offset:3072
	ds_read_b128 v[170:173], v153 offset:32768
	ds_read_b128 v[182:185], v153 offset:33792
	ds_read_b128 v[190:193], v153 offset:34816
	ds_read_b128 v[194:197], v153 offset:35840
	ds_read_b128 v[198:201], v153 offset:36864
	ds_read_b128 v[202:205], v153 offset:37888
	ds_read_b128 v[206:209], v153 offset:38912
	ds_read_b128 v[210:213], v153 offset:39936
	s_add_u32 s22, s22, 0x40000
	s_addc_u32 s23, s23, 0
	s_mov_b32 m0, s34
	v_lshl_add_u64 v[214:215], s[22:23], 0, v[128:129]
	global_load_lds_dwordx4 v[214:215], off
	v_lshl_add_u64 v[214:215], s[22:23], 0, v[132:133]
	s_mov_b32 m0, s35
	s_nop 0
	global_load_lds_dwordx4 v[214:215], off
	s_waitcnt lgkmcnt(0)
	s_barrier
	v_mfma_f32_16x16x32_bf16 v[124:127], v[144:147], v[170:173], v[124:127]
	v_mfma_f32_16x16x32_bf16 v[120:123], v[160:163], v[170:173], v[120:123]
	v_mfma_f32_16x16x32_bf16 v[108:111], v[144:147], v[190:193], v[108:111]
	v_mfma_f32_16x16x32_bf16 v[104:107], v[160:163], v[190:193], v[104:107]
	v_mfma_f32_16x16x32_bf16 v[92:95], v[144:147], v[198:201], v[92:95]
	v_mfma_f32_16x16x32_bf16 v[88:91], v[160:163], v[198:201], v[88:91]
	v_mfma_f32_16x16x32_bf16 v[76:79], v[144:147], v[206:209], v[76:79]
	v_mfma_f32_16x16x32_bf16 v[72:75], v[160:163], v[206:209], v[72:75]
	v_mfma_f32_16x16x32_bf16 v[124:127], v[156:159], v[182:185], v[124:127]
	v_mfma_f32_16x16x32_bf16 v[120:123], v[166:169], v[182:185], v[120:123]
	v_mfma_f32_16x16x32_bf16 v[108:111], v[156:159], v[194:197], v[108:111]
	v_mfma_f32_16x16x32_bf16 v[104:107], v[166:169], v[194:197], v[104:107]
	v_mfma_f32_16x16x32_bf16 v[92:95], v[156:159], v[202:205], v[92:95]
	v_mfma_f32_16x16x32_bf16 v[88:91], v[166:169], v[202:205], v[88:91]
	v_mfma_f32_16x16x32_bf16 v[76:79], v[156:159], v[210:213], v[76:79]
	v_mfma_f32_16x16x32_bf16 v[72:75], v[166:169], v[210:213], v[72:75]
	s_barrier
	s_add_i32 s22, 0, 0x1c000
	v_add_u32_e32 v155, s22, v149
	ds_read_b128 v[214:217], v155
	ds_read_b128 v[218:221], v155 offset:1024
	ds_read_b128 v[222:225], v155 offset:2048
	ds_read_b128 v[226:229], v155 offset:3072
	s_add_i32 s23, s49, s30
	v_lshl_add_u64 v[174:175], v[174:175], 0, s[6:7]
	s_mov_b32 m0, s23
	s_nop 0
	global_load_lds_dwordx4 v[174:175], off
	v_lshl_add_u64 v[174:175], v[186:187], 0, s[6:7]
	s_add_i32 m0, s23, 0x2000
	s_nop 0
	global_load_lds_dwordx4 v[174:175], off
	s_waitcnt lgkmcnt(0)
	s_barrier
	v_mfma_f32_16x16x32_bf16 v[116:119], v[214:217], v[170:173], v[116:119]
	v_mfma_f32_16x16x32_bf16 v[112:115], v[222:225], v[170:173], v[112:115]
	v_mfma_f32_16x16x32_bf16 v[100:103], v[214:217], v[190:193], v[100:103]
	v_mfma_f32_16x16x32_bf16 v[96:99], v[222:225], v[190:193], v[96:99]
	v_mfma_f32_16x16x32_bf16 v[84:87], v[214:217], v[198:201], v[84:87]
	v_mfma_f32_16x16x32_bf16 v[80:83], v[222:225], v[198:201], v[80:83]
	v_mfma_f32_16x16x32_bf16 v[68:71], v[214:217], v[206:209], v[68:71]
	v_mfma_f32_16x16x32_bf16 v[64:67], v[222:225], v[206:209], v[64:67]
	v_mfma_f32_16x16x32_bf16 v[116:119], v[218:221], v[182:185], v[116:119]
	v_mfma_f32_16x16x32_bf16 v[112:115], v[226:229], v[182:185], v[112:115]
	v_mfma_f32_16x16x32_bf16 v[100:103], v[218:221], v[194:197], v[100:103]
	v_mfma_f32_16x16x32_bf16 v[96:99], v[226:229], v[194:197], v[96:99]
	v_mfma_f32_16x16x32_bf16 v[84:87], v[218:221], v[202:205], v[84:87]
	v_mfma_f32_16x16x32_bf16 v[80:83], v[226:229], v[202:205], v[80:83]
	v_mfma_f32_16x16x32_bf16 v[68:71], v[218:221], v[210:213], v[68:71]
	v_mfma_f32_16x16x32_bf16 v[64:67], v[226:229], v[210:213], v[64:67]
	s_barrier
	s_mov_b32 m0, s37
	v_lshl_add_u64 v[174:175], v[230:231], 0, s[6:7]
	ds_read_b128 v[170:173], v153 offset:49152
	ds_read_b128 v[182:185], v153 offset:50176
	ds_read_b128 v[190:193], v153 offset:51200
	ds_read_b128 v[194:197], v153 offset:52224
	ds_read_b128 v[198:201], v153 offset:53248
	ds_read_b128 v[202:205], v153 offset:54272
	ds_read_b128 v[206:209], v153 offset:55296
	ds_read_b128 v[210:213], v153 offset:56320
	global_load_lds_dwordx4 v[174:175], off
	v_lshl_add_u64 v[174:175], v[232:233], 0, s[6:7]
	s_mov_b32 m0, s38
	s_nop 0
	global_load_lds_dwordx4 v[174:175], off
	s_waitcnt lgkmcnt(0)
	s_barrier
; __device__ __forceinline__ f32x4 sigmoid4(f32x4 x) {
;     f32x4 d;
; #pragma unroll
;     for (int j = 0; j < 4; ++j) d[j] = 1.0f + __expf(-fmaxf(x[j], -20.0f));
;     const float p01 = d[0] * d[1], p23 = d[2] * d[3], r = __builtin_amdgcn_rcpf(p01 * p23), r01 = r * p23, r23 = r * p01;
;     return (f32x4){r01 * d[1], r01 * d[0], r23 * d[3], r23 * d[2]};
; }
; __device__ __forceinline__ float flogsig16(float x) { return (fminf(x, 0.f) - __logf(1.0f + __expf(-fabsf(x)))) * 0.0625f; }
; __device__ __forceinline__ float bf_lo(unsigned u) { return __uint_as_float(u << 16); }
; __device__ __forceinline__ float bf_hi(unsigned u) { return __uint_as_float(u & 0xffff0000u); }
;     __device__ __forceinline__ void operator()(const f32x4 (&acc)[2][2][4][2], const Unit& u, int wr, int wc, int fr, int fq) const {
;         int act = 0; const float* bias = nullptr;
;         if (mode == 1) { if (u.pn >= 8 && u.pn < 12) act = 1; else if (u.pn >= 12) { act = 3; bias = (u.pn >= 14) ? bias_b + (u.pn - 14) * 256 : bias_f + (u.pn - 12) * 256; } }
;         else if (mode == 2) { if (u.pn >= 6) act = 2; }
;         const int row0 = u.pm * BM + wr * 64 + fr, col0 = u.pn * BM + wc * 32 + 8 * fq, bcol0 = wc * 32 + 8 * fq;
;         f32x4 bv[2][2];
; #pragma unroll
;         for (int bj = 0; bj < 2; ++bj)
; #pragma unroll
;             for (int n = 0; n < 2; ++n) bv[bj][n] = bias ? *(const f32x4*)(bias + bcol0 + bj * HALF + 4 * n) : (f32x4){0.f, 0.f, 0.f, 0.f};
; #pragma unroll
;         for (int ai = 0; ai < 2; ++ai)
; #pragma unroll
;             for (int m = 0; m < 4; ++m) { bf16_t* rowp = O + (size_t)(row0 + ai * HALF + m * 16) * ldc + col0;
; #pragma unroll
;                 for (int bj = 0; bj < 2; ++bj) { f32x4 v0 = acc[ai][bj][m][0] + bv[bj][0], v1 = acc[ai][bj][m][1] + bv[bj][1];
;                     if (act == 1) {
; #pragma unroll
;                         for (int j = 0; j < 1; ++j) { v0 = v0 * sigmoid4(v0); v1 = v1 * sigmoid4(v1); } }
;                     else if (act == 2) {
; #pragma unroll
; template <class Epi, class Sched>
; __device__ __forceinline__ void gemm_phase(PG8_LAS unsigned char* lds, const Gemm g, const Sched& S, const Epi& E) {
;     ...
;             PG8_BAR; PG8_WAIT_L(0); PG8_MMA(1, 0, At, B0); PG8_BAR; PG8_SCHED;
;             PG8_STAGE(PG8_SB(1, 1), b3 + hstep, voffB);
;             PG8_WAIT_V(6); PG8_BAR; PG8_MMA(1, 1, At, B1); PG8_BAR;
;         }
	v_mfma_f32_16x16x32_bf16 v[60:63], v[144:147], v[170:173], v[60:63]
	v_mfma_f32_16x16x32_bf16 v[56:59], v[160:163], v[170:173], v[56:59]
	v_mfma_f32_16x16x32_bf16 v[44:47], v[144:147], v[190:193], v[44:47]
	v_mfma_f32_16x16x32_bf16 v[40:43], v[160:163], v[190:193], v[40:43]
	v_mfma_f32_16x16x32_bf16 v[28:31], v[144:147], v[198:201], v[28:31]
	v_mfma_f32_16x16x32_bf16 v[24:27], v[160:163], v[198:201], v[24:27]
	v_mfma_f32_16x16x32_bf16 v[12:15], v[144:147], v[206:209], v[12:15]
	v_mfma_f32_16x16x32_bf16 v[8:11], v[160:163], v[206:209], v[8:11]
	v_mfma_f32_16x16x32_bf16 v[60:63], v[156:159], v[182:185], v[60:63]
	v_mfma_f32_16x16x32_bf16 v[56:59], v[166:169], v[182:185], v[56:59]
	v_mfma_f32_16x16x32_bf16 v[44:47], v[156:159], v[194:197], v[44:47]
	v_mfma_f32_16x16x32_bf16 v[40:43], v[166:169], v[194:197], v[40:43]
	v_mfma_f32_16x16x32_bf16 v[28:31], v[156:159], v[202:205], v[28:31]
	v_mfma_f32_16x16x32_bf16 v[24:27], v[166:169], v[202:205], v[24:27]
	v_mfma_f32_16x16x32_bf16 v[12:15], v[156:159], v[210:213], v[12:15]
	v_mfma_f32_16x16x32_bf16 v[8:11], v[166:169], v[210:213], v[8:11]
	s_barrier
	s_add_u32 s20, s20, 0x40080
	s_addc_u32 s21, s21, 0
	s_add_i32 s22, s22, s30
	v_lshl_add_u64 v[144:145], s[20:21], 0, v[130:131]
	s_mov_b32 m0, s22
	s_nop 0
	global_load_lds_dwordx4 v[144:145], off
	v_lshl_add_u64 v[144:145], s[20:21], 0, v[134:135]
	s_add_i32 m0, s22, 0x2000
	s_nop 0
	global_load_lds_dwordx4 v[144:145], off
	s_waitcnt vmcnt(6)
	s_barrier
	v_mfma_f32_16x16x32_bf16 v[52:55], v[214:217], v[170:173], v[52:55]
	v_mfma_f32_16x16x32_bf16 v[48:51], v[222:225], v[170:173], v[48:51]
	v_mfma_f32_16x16x32_bf16 v[36:39], v[214:217], v[190:193], v[36:39]
	v_mfma_f32_16x16x32_bf16 v[32:35], v[222:225], v[190:193], v[32:35]
	v_mfma_f32_16x16x32_bf16 v[20:23], v[214:217], v[198:201], v[20:23]
	v_mfma_f32_16x16x32_bf16 v[16:19], v[222:225], v[198:201], v[16:19]
	v_mfma_f32_16x16x32_bf16 v[4:7], v[214:217], v[206:209], v[4:7]
	v_mfma_f32_16x16x32_bf16 v[0:3], v[222:225], v[206:209], v[0:3]
	v_mfma_f32_16x16x32_bf16 v[52:55], v[218:221], v[182:185], v[52:55]
	v_mfma_f32_16x16x32_bf16 v[48:51], v[226:229], v[182:185], v[48:51]
	v_mfma_f32_16x16x32_bf16 v[36:39], v[218:221], v[194:197], v[36:39]
	v_mfma_f32_16x16x32_bf16 v[32:35], v[226:229], v[194:197], v[32:35]
	v_mfma_f32_16x16x32_bf16 v[20:23], v[218:221], v[202:205], v[20:23]
	v_mfma_f32_16x16x32_bf16 v[16:19], v[226:229], v[202:205], v[16:19]
	v_mfma_f32_16x16x32_bf16 v[4:7], v[218:221], v[210:213], v[4:7]
	v_mfma_f32_16x16x32_bf16 v[0:3], v[226:229], v[210:213], v[0:3]
	s_barrier
	s_add_i32 s48, s48, 2
	s_add_u32 s18, s18, 0x100
	s_addc_u32 s19, s19, 0
	s_add_u32 s46, s46, 0x100
	s_addc_u32 s47, s47, 0
	s_cmp_gt_u32 s48, 13
	s_cbranch_scc0 .LBB0_724
	s_cmp_gt_i32 s4, 5
	s_cselect_b64 s[18:19], -1, 0
	s_cmp_lt_i32 s4, 6
	v_pk_add_f32 v[144:145], v[126:127], 0 op_sel_hi:[1,0]
	v_pk_add_f32 v[146:147], v[124:125], 0 op_sel_hi:[1,0]
	v_pk_add_f32 v[124:125], v[122:123], 0 op_sel_hi:[1,0]
	v_pk_add_f32 v[126:127], v[120:121], 0 op_sel_hi:[1,0]
	s_cbranch_scc1 .LBB0_727
	v_max_f32_e32 v122, v144, v144
	v_max_f32_e32 v122, 0xc1a00000, v122
	v_mul_f32_e32 v122, 0xbfb8aa3b, v122
	v_max_f32_e32 v120, v146, v146
	v_max_f32_e32 v121, v147, v147
	v_exp_f32_e32 v123, v122
	v_max_f32_e32 v122, v145, v145
	v_max_f32_e32 v120, 0xc1a00000, v120
	v_max_f32_e32 v121, 0xc1a00000, v121
	v_max_f32_e32 v122, 0xc1a00000, v122
	v_mul_f32_e32 v120, 0xbfb8aa3b, v120
	v_mul_f32_e32 v121, 0xbfb8aa3b, v121
	v_mul_f32_e32 v122, 0xbfb8aa3b, v122
	v_exp_f32_e32 v120, v120
	v_exp_f32_e32 v121, v121
	v_exp_f32_e32 v122, v122
	v_max_f32_e32 v124, v124, v124
	v_max_f32_e32 v124, 0xc1a00000, v124
	v_pk_add_f32 v[120:121], v[120:121], 1.0 op_sel_hi:[1,0]
	v_pk_add_f32 v[122:123], v[122:123], 1.0 op_sel_hi:[1,0]
	v_mov_b32_e32 v144, v120
	v_mov_b32_e32 v145, v123
	v_pk_mov_b32 v[146:147], v[120:121], v[122:123] op_sel:[1,0]
	v_mul_f32_e32 v124, 0xbfb8aa3b, v124
	v_pk_mul_f32 v[144:145], v[144:145], v[146:147]
	v_max_f32_e32 v126, v126, v126
	v_max_f32_e32 v127, v127, v127
	v_exp_f32_e32 v147, v124
	v_max_f32_e32 v124, v125, v125
	v_max_f32_e32 v126, 0xc1a00000, v126
	v_max_f32_e32 v127, 0xc1a00000, v127
	v_max_f32_e32 v124, 0xc1a00000, v124
	v_mul_f32_e32 v146, v144, v145
	v_mul_f32_e32 v126, 0xbfb8aa3b, v126
	v_mul_f32_e32 v127, 0xbfb8aa3b, v127
	v_mul_f32_e32 v124, 0xbfb8aa3b, v124
	v_rcp_f32_e32 v155, v146
	v_exp_f32_e32 v126, v126
	v_exp_f32_e32 v127, v127
	v_exp_f32_e32 v146, v124
	v_mul_f32_e32 v124, v145, v155
	v_mul_f32_e32 v144, v144, v155
	v_pk_add_f32 v[126:127], v[126:127], 1.0 op_sel_hi:[1,0]
	v_pk_add_f32 v[156:157], v[146:147], 1.0 op_sel_hi:[1,0]
	v_mov_b32_e32 v146, v126
	v_mov_b32_e32 v147, v157
	v_pk_mov_b32 v[158:159], v[126:127], v[156:157] op_sel:[1,0]
	v_pk_mul_f32 v[144:145], v[122:123], v[144:145] op_sel_hi:[1,0]
	v_pk_mul_f32 v[158:159], v[146:147], v[158:159]
	s_nop 0
	v_mul_f32_e32 v125, v158, v159
	v_rcp_f32_e32 v125, v125
	s_nop 0
	v_pk_mul_f32 v[146:147], v[120:121], v[124:125] op_sel:[1,0] op_sel_hi:[0,0]
	v_mul_f32_e32 v120, v159, v125
	v_mul_f32_e32 v122, v158, v125
	v_pk_mul_f32 v[124:125], v[156:157], v[122:123] op_sel_hi:[1,0]
	v_pk_mul_f32 v[126:127], v[126:127], v[120:121] op_sel:[1,0] op_sel_hi:[0,0]

; #define PG8_STAGE(bufoff, gbase, voff) do { _Pragma("unroll") for (int _i = 0; _i < 2; ++_i) \
;         __builtin_amdgcn_global_load_lds((const unsigned*)((const char*)(gbase) + (voff)[_i]), (PG8_LAS unsigned*)(lds + (bufoff) + ldsw + _i * 8192), 16, 0, 0); } while (0)
; #define PG8_LDA(dst, b, h) do { _Pragma("unroll") for (int m = 0; m < 4; ++m) _Pragma("unroll") for (int k = 0; k < 2; ++k) dst[m][k] = *(const PG8_LAS bf16x8*)(lds + PG8_SA(b, h) + aoff + m * 2048 + k * 1024); } while (0)
; #define PG8_LDB(dst, b, h) do { _Pragma("unroll") for (int n = 0; n < 2; ++n) _Pragma("unroll") for (int k = 0; k < 2; ++k) dst[n][k] = *(const PG8_LAS bf16x8*)(lds + PG8_SB(b, h) + boff + n * 2048 + k * 1024); } while (0)
; #define PG8_MMA(ai, bj, At, Bt) do { __builtin_amdgcn_s_setprio(1); _Pragma("unroll") for (int m = 0; m < 4; ++m) _Pragma("unroll") for (int n = 0; n < 2; ++n) _Pragma("unroll") for (int k = 0; k < 2; ++k) \
;         acc[ai][bj][m][n] = __builtin_amdgcn_mfma_f32_16x16x32_bf16(Bt[n][k], At[m][k], acc[ai][bj][m][n], 0, 0, 0); __builtin_amdgcn_s_setprio(0); } while (0)
; #define PG8_WAIT_L(n) asm volatile("s_waitcnt lgkmcnt(" #n ")" ::: "memory")
; #define PG8_BAR __builtin_amdgcn_s_barrier()
; #define PG8_SCHED __builtin_amdgcn_sched_barrier(0)
; template <class Epi, class Sched>
; __device__ __forceinline__ void gemm_phase(PG8_LAS unsigned char* lds, const Gemm g, const Sched& S, const Epi& E) {
;     ...
;             const bool last = (t == nt - 2);
;             const char* a1 = cA + (size_t)(t + 1) * kstep;
;             const char* a2 = last ? nA : cA + (size_t)(t + 2) * kstep; const char* b2 = last ? nB : cB + (size_t)(t + 2) * kstep;
;             const char* a3 = a2 + kstep; const char* b3 = b2 + kstep;
;             if (last && has_next) S.a_ready(nxt);
;             PG8_LDB(B0, 0, 0); PG8_SCHED; PG8_LDA(At, 0, 0); PG8_STAGE(PG8_SA(1, 1), a1 + hstep, voffA);
;             PG8_WAIT_L(8); PG8_BAR; PG8_WAIT_L(0); PG8_MMA(0, 0, At, B0); PG8_BAR; PG8_SCHED;
;             PG8_LDB(B1, 0, 1); PG8_STAGE(PG8_SB(0, 0), b2, voffB);
;             PG8_BAR; PG8_WAIT_L(0); PG8_MMA(0, 1, At, B1); PG8_BAR;
;             PG8_LDA(At, 0, 1); PG8_STAGE(PG8_SA(0, 0), a2, voffA);
;             PG8_BAR; PG8_WAIT_L(0); PG8_MMA(1, 0, At, B0); PG8_BAR; PG8_SCHED;
.LBB0_991:
	ds_read_b128 v[144:147], v153
	ds_read_b128 v[156:159], v153 offset:1024
	ds_read_b128 v[160:163], v153 offset:2048
	ds_read_b128 v[164:167], v153 offset:3072
	ds_read_b128 v[168:171], v154
	ds_read_b128 v[172:175], v154 offset:1024
	ds_read_b128 v[182:185], v154 offset:2048
	ds_read_b128 v[190:193], v154 offset:3072
	ds_read_b128 v[194:197], v154 offset:4096
	ds_read_b128 v[198:201], v154 offset:5120
	ds_read_b128 v[202:205], v154 offset:6144
	ds_read_b128 v[206:209], v154 offset:7168
	s_add_u32 s20, s18, 0xfffc0080
	s_addc_u32 s21, s19, -1
	s_cmp_eq_u32 s47, 12
	s_cselect_b32 s23, s11, s21
	s_cselect_b32 s22, s43, s20
	s_cselect_b32 s21, s9, s46
	s_cselect_b32 s20, s44, s45
	v_lshl_add_u64 v[148:149], s[18:19], 0, v[136:137]
	s_add_i32 m0, s17, 0xc000
	s_nop 0
	global_load_lds_dwordx4 v[148:149], off
	v_lshl_add_u64 v[148:149], s[18:19], 0, v[138:139]
	s_add_i32 m0, s17, 0xe000
	s_nop 0
	global_load_lds_dwordx4 v[148:149], off
	s_waitcnt lgkmcnt(0)
	s_barrier
	v_mfma_f32_16x16x32_bf16 v[124:127], v[144:147], v[168:171], v[124:127]
	v_mfma_f32_16x16x32_bf16 v[120:123], v[160:163], v[168:171], v[120:123]
	v_mfma_f32_16x16x32_bf16 v[112:115], v[144:147], v[182:185], v[112:115]
	v_mfma_f32_16x16x32_bf16 v[104:107], v[160:163], v[182:185], v[104:107]
	v_mfma_f32_16x16x32_bf16 v[96:99], v[144:147], v[194:197], v[96:99]
	v_mfma_f32_16x16x32_bf16 v[88:91], v[160:163], v[194:197], v[88:91]
	v_mfma_f32_16x16x32_bf16 v[80:83], v[144:147], v[202:205], v[80:83]
	v_mfma_f32_16x16x32_bf16 v[72:75], v[160:163], v[202:205], v[72:75]
	v_mfma_f32_16x16x32_bf16 v[124:127], v[156:159], v[172:175], v[124:127]
	v_mfma_f32_16x16x32_bf16 v[120:123], v[164:167], v[172:175], v[120:123]
	v_mfma_f32_16x16x32_bf16 v[112:115], v[156:159], v[190:193], v[112:115]
	v_mfma_f32_16x16x32_bf16 v[104:107], v[164:167], v[190:193], v[104:107]
	v_mfma_f32_16x16x32_bf16 v[96:99], v[156:159], v[198:201], v[96:99]
	v_mfma_f32_16x16x32_bf16 v[88:91], v[164:167], v[198:201], v[88:91]
	v_mfma_f32_16x16x32_bf16 v[80:83], v[156:159], v[206:209], v[80:83]
	v_mfma_f32_16x16x32_bf16 v[72:75], v[164:167], v[206:209], v[72:75]
	s_barrier
	ds_read_b128 v[210:213], v155
	ds_read_b128 v[214:217], v155 offset:1024
	ds_read_b128 v[218:221], v155 offset:2048
	ds_read_b128 v[222:225], v155 offset:3072
	s_add_i32 s48, s39, s29
	v_lshl_add_u64 v[148:149], s[20:21], 0, v[130:131]
	s_mov_b32 m0, s48
	s_nop 0
	global_load_lds_dwordx4 v[148:149], off
	v_lshl_add_u64 v[186:187], s[20:21], 0, v[134:135]
	s_add_i32 m0, s48, 0x2000
	s_nop 0
	global_load_lds_dwordx4 v[186:187], off
	s_waitcnt lgkmcnt(0)
	s_barrier
	v_mfma_f32_16x16x32_bf16 v[116:119], v[210:213], v[168:171], v[116:119]
	v_mfma_f32_16x16x32_bf16 v[108:111], v[218:221], v[168:171], v[108:111]
	v_mfma_f32_16x16x32_bf16 v[100:103], v[210:213], v[182:185], v[100:103]
	v_mfma_f32_16x16x32_bf16 v[92:95], v[218:221], v[182:185], v[92:95]
	v_mfma_f32_16x16x32_bf16 v[84:87], v[210:213], v[194:197], v[84:87]
	v_mfma_f32_16x16x32_bf16 v[76:79], v[218:221], v[194:197], v[76:79]
	v_mfma_f32_16x16x32_bf16 v[68:71], v[210:213], v[202:205], v[68:71]
	v_mfma_f32_16x16x32_bf16 v[64:67], v[218:221], v[202:205], v[64:67]
	v_mfma_f32_16x16x32_bf16 v[116:119], v[214:217], v[172:175], v[116:119]
	v_mfma_f32_16x16x32_bf16 v[108:111], v[222:225], v[172:175], v[108:111]
	v_mfma_f32_16x16x32_bf16 v[100:103], v[214:217], v[190:193], v[100:103]
	v_mfma_f32_16x16x32_bf16 v[92:95], v[222:225], v[190:193], v[92:95]
	v_mfma_f32_16x16x32_bf16 v[84:87], v[214:217], v[198:201], v[84:87]
	v_mfma_f32_16x16x32_bf16 v[76:79], v[222:225], v[198:201], v[76:79]
	v_mfma_f32_16x16x32_bf16 v[68:71], v[214:217], v[206:209], v[68:71]
	v_mfma_f32_16x16x32_bf16 v[64:67], v[222:225], v[206:209], v[64:67]
	s_barrier
	s_mov_b32 m0, s17
	v_lshl_add_u64 v[226:227], s[22:23], 0, v[128:129]
	ds_read_b128 v[168:171], v154 offset:16384
	ds_read_b128 v[172:175], v154 offset:17408
	ds_read_b128 v[182:185], v154 offset:18432
	ds_read_b128 v[190:193], v154 offset:19456
	ds_read_b128 v[194:197], v154 offset:20480
	ds_read_b128 v[198:201], v154 offset:21504
	ds_read_b128 v[202:205], v154 offset:22528
	ds_read_b128 v[206:209], v154 offset:23552
	global_load_lds_dwordx4 v[226:227], off
	v_lshl_add_u64 v[228:229], s[22:23], 0, v[132:133]
	s_mov_b32 m0, s30
	s_nop 0
	global_load_lds_dwordx4 v[228:229], off
	s_waitcnt lgkmcnt(0)
	s_barrier
	v_mfma_f32_16x16x32_bf16 v[60:63], v[144:147], v[168:171], v[60:63]
	v_mfma_f32_16x16x32_bf16 v[56:59], v[160:163], v[168:171], v[56:59]
	v_mfma_f32_16x16x32_bf16 v[48:51], v[144:147], v[182:185], v[48:51]
	v_mfma_f32_16x16x32_bf16 v[40:43], v[160:163], v[182:185], v[40:43]
	v_mfma_f32_16x16x32_bf16 v[32:35], v[144:147], v[194:197], v[32:35]
	v_mfma_f32_16x16x32_bf16 v[24:27], v[160:163], v[194:197], v[24:27]
	v_mfma_f32_16x16x32_bf16 v[16:19], v[144:147], v[202:205], v[16:19]
	v_mfma_f32_16x16x32_bf16 v[8:11], v[160:163], v[202:205], v[8:11]
	v_mfma_f32_16x16x32_bf16 v[60:63], v[156:159], v[172:175], v[60:63]
	v_mfma_f32_16x16x32_bf16 v[56:59], v[164:167], v[172:175], v[56:59]
	v_mfma_f32_16x16x32_bf16 v[48:51], v[156:159], v[190:193], v[48:51]
	v_mfma_f32_16x16x32_bf16 v[40:43], v[164:167], v[190:193], v[40:43]
	v_mfma_f32_16x16x32_bf16 v[32:35], v[156:159], v[198:201], v[32:35]
	v_mfma_f32_16x16x32_bf16 v[24:27], v[164:167], v[198:201], v[24:27]
	v_mfma_f32_16x16x32_bf16 v[16:19], v[156:159], v[206:209], v[16:19]
	v_mfma_f32_16x16x32_bf16 v[8:11], v[164:167], v[206:209], v[8:11]
	s_barrier
; #define PG8_STAGE(bufoff, gbase, voff) do { _Pragma("unroll") for (int _i = 0; _i < 2; ++_i) \
;         __builtin_amdgcn_global_load_lds((const unsigned*)((const char*)(gbase) + (voff)[_i]), (PG8_LAS unsigned*)(lds + (bufoff) + ldsw + _i * 8192), 16, 0, 0); } while (0)
; #define PG8_LDA(dst, b, h) do { _Pragma("unroll") for (int m = 0; m < 4; ++m) _Pragma("unroll") for (int k = 0; k < 2; ++k) dst[m][k] = *(const PG8_LAS bf16x8*)(lds + PG8_SA(b, h) + aoff + m * 2048 + k * 1024); } while (0)
; #define PG8_LDB(dst, b, h) do { _Pragma("unroll") for (int n = 0; n < 2; ++n) _Pragma("unroll") for (int k = 0; k < 2; ++k) dst[n][k] = *(const PG8_LAS bf16x8*)(lds + PG8_SB(b, h) + boff + n * 2048 + k * 1024); } while (0)
; #define PG8_MMA(ai, bj, At, Bt) do { __builtin_amdgcn_s_setprio(1); _Pragma("unroll") for (int m = 0; m < 4; ++m) _Pragma("unroll") for (int n = 0; n < 2; ++n) _Pragma("unroll") for (int k = 0; k < 2; ++k) \
;         acc[ai][bj][m][n] = __builtin_amdgcn_mfma_f32_16x16x32_bf16(Bt[n][k], At[m][k], acc[ai][bj][m][n], 0, 0, 0); __builtin_amdgcn_s_setprio(0); } while (0)
; #define PG8_WAIT_V(n) asm volatile("s_waitcnt vmcnt(" #n ")" ::: "memory")
; #define PG8_WAIT_L(n) asm volatile("s_waitcnt lgkmcnt(" #n ")" ::: "memory")
; #define PG8_BAR __builtin_amdgcn_s_barrier()
; #define PG8_SCHED __builtin_amdgcn_sched_barrier(0)
; template <class Epi, class Sched>
; __device__ __forceinline__ void gemm_phase(PG8_LAS unsigned char* lds, const Gemm g, const Sched& S, const Epi& E) {
;     ...
;             PG8_STAGE(PG8_SB(0, 1), b2 + hstep, voffB);
;             PG8_WAIT_V(6); PG8_BAR; PG8_MMA(1, 1, At, B1); PG8_BAR;
;             PG8_LDB(B0, 1, 0); PG8_SCHED; PG8_LDA(At, 1, 0); PG8_STAGE(PG8_SA(0, 1), a2 + hstep, voffA);
;             PG8_WAIT_L(8); PG8_BAR; PG8_WAIT_L(0); PG8_MMA(0, 0, At, B0); PG8_BAR; PG8_SCHED;
;             PG8_LDB(B1, 1, 1); PG8_STAGE(PG8_SB(1, 0), b3, voffB);
;             PG8_BAR; PG8_WAIT_L(0); PG8_MMA(0, 1, At, B1); PG8_BAR;
;             PG8_LDA(At, 1, 1); PG8_STAGE(PG8_SA(1, 0), a3, voffA);
;             PG8_BAR; PG8_WAIT_L(0); PG8_MMA(1, 0, At, B0); PG8_BAR; PG8_SCHED;
	s_add_u32 s48, s20, 0x40000
	s_addc_u32 s49, s21, 0
	s_add_i32 s50, s40, s29
	v_lshl_add_u64 v[144:145], s[48:49], 0, v[130:131]
	s_mov_b32 m0, s50
	s_nop 0
	global_load_lds_dwordx4 v[144:145], off
	v_lshl_add_u64 v[144:145], s[48:49], 0, v[134:135]
	s_add_i32 m0, s50, 0x2000
	s_nop 0
	global_load_lds_dwordx4 v[144:145], off
	s_waitcnt vmcnt(6)
	s_barrier
	v_mfma_f32_16x16x32_bf16 v[52:55], v[210:213], v[168:171], v[52:55]
	v_mfma_f32_16x16x32_bf16 v[44:47], v[218:221], v[168:171], v[44:47]
	v_mfma_f32_16x16x32_bf16 v[36:39], v[210:213], v[182:185], v[36:39]
	v_mfma_f32_16x16x32_bf16 v[28:31], v[218:221], v[182:185], v[28:31]
	v_mfma_f32_16x16x32_bf16 v[20:23], v[210:213], v[194:197], v[20:23]
	v_mfma_f32_16x16x32_bf16 v[12:15], v[218:221], v[194:197], v[12:15]
	v_mfma_f32_16x16x32_bf16 v[4:7], v[210:213], v[202:205], v[4:7]
	v_mfma_f32_16x16x32_bf16 v[0:3], v[218:221], v[202:205], v[0:3]
	v_mfma_f32_16x16x32_bf16 v[52:55], v[214:217], v[172:175], v[52:55]
	v_mfma_f32_16x16x32_bf16 v[44:47], v[222:225], v[172:175], v[44:47]
	v_mfma_f32_16x16x32_bf16 v[36:39], v[214:217], v[190:193], v[36:39]
	v_mfma_f32_16x16x32_bf16 v[28:31], v[222:225], v[190:193], v[28:31]
	v_mfma_f32_16x16x32_bf16 v[20:23], v[214:217], v[198:201], v[20:23]
	v_mfma_f32_16x16x32_bf16 v[12:15], v[222:225], v[198:201], v[12:15]
	v_mfma_f32_16x16x32_bf16 v[4:7], v[214:217], v[206:209], v[4:7]
	v_mfma_f32_16x16x32_bf16 v[0:3], v[222:225], v[206:209], v[0:3]
	s_barrier
	s_add_i32 s48, 0, 0x18000
	v_add_u32_e32 v164, s48, v151
	ds_read_b128 v[144:147], v164
	ds_read_b128 v[156:159], v164 offset:1024
	ds_read_b128 v[160:163], v164 offset:2048
	ds_read_b128 v[164:167], v164 offset:3072
	ds_read_b128 v[168:171], v154 offset:32768
	ds_read_b128 v[172:175], v154 offset:33792
	ds_read_b128 v[182:185], v154 offset:34816
	ds_read_b128 v[190:193], v154 offset:35840
	ds_read_b128 v[194:197], v154 offset:36864
	ds_read_b128 v[198:201], v154 offset:37888
	ds_read_b128 v[202:205], v154 offset:38912
	ds_read_b128 v[206:209], v154 offset:39936
	s_add_u32 s22, s22, 0x40000
	s_addc_u32 s23, s23, 0
	s_mov_b32 m0, s31
	v_lshl_add_u64 v[210:211], s[22:23], 0, v[128:129]
	global_load_lds_dwordx4 v[210:211], off
	v_lshl_add_u64 v[210:211], s[22:23], 0, v[132:133]
	s_mov_b32 m0, s34
	s_nop 0
	global_load_lds_dwordx4 v[210:211], off
	s_waitcnt lgkmcnt(0)
	s_barrier
	v_mfma_f32_16x16x32_bf16 v[124:127], v[144:147], v[168:171], v[124:127]
	v_mfma_f32_16x16x32_bf16 v[120:123], v[160:163], v[168:171], v[120:123]
	v_mfma_f32_16x16x32_bf16 v[112:115], v[144:147], v[182:185], v[112:115]
	v_mfma_f32_16x16x32_bf16 v[104:107], v[160:163], v[182:185], v[104:107]
	v_mfma_f32_16x16x32_bf16 v[96:99], v[144:147], v[194:197], v[96:99]
	v_mfma_f32_16x16x32_bf16 v[88:91], v[160:163], v[194:197], v[88:91]
	v_mfma_f32_16x16x32_bf16 v[80:83], v[144:147], v[202:205], v[80:83]
	v_mfma_f32_16x16x32_bf16 v[72:75], v[160:163], v[202:205], v[72:75]
	v_mfma_f32_16x16x32_bf16 v[124:127], v[156:159], v[172:175], v[124:127]
	v_mfma_f32_16x16x32_bf16 v[120:123], v[164:167], v[172:175], v[120:123]
	v_mfma_f32_16x16x32_bf16 v[112:115], v[156:159], v[190:193], v[112:115]
	v_mfma_f32_16x16x32_bf16 v[104:107], v[164:167], v[190:193], v[104:107]
	v_mfma_f32_16x16x32_bf16 v[96:99], v[156:159], v[198:201], v[96:99]
	v_mfma_f32_16x16x32_bf16 v[88:91], v[164:167], v[198:201], v[88:91]
	v_mfma_f32_16x16x32_bf16 v[80:83], v[156:159], v[206:209], v[80:83]
	v_mfma_f32_16x16x32_bf16 v[72:75], v[164:167], v[206:209], v[72:75]
	s_barrier
	s_add_i32 s22, 0, 0x1c000
	v_add_u32_e32 v179, s22, v151
	ds_read_b128 v[210:213], v179
	ds_read_b128 v[214:217], v179 offset:1024
	ds_read_b128 v[218:221], v179 offset:2048
	ds_read_b128 v[222:225], v179 offset:3072
	s_add_i32 s23, s48, s29
	v_lshl_add_u64 v[148:149], v[148:149], 0, s[6:7]
	s_mov_b32 m0, s23
	s_nop 0
	global_load_lds_dwordx4 v[148:149], off
	v_lshl_add_u64 v[148:149], v[186:187], 0, s[6:7]
	s_add_i32 m0, s23, 0x2000
	s_nop 0
	global_load_lds_dwordx4 v[148:149], off
	s_waitcnt lgkmcnt(0)
	s_barrier
	v_mfma_f32_16x16x32_bf16 v[116:119], v[210:213], v[168:171], v[116:119]
	v_mfma_f32_16x16x32_bf16 v[108:111], v[218:221], v[168:171], v[108:111]
	v_mfma_f32_16x16x32_bf16 v[100:103], v[210:213], v[182:185], v[100:103]
	v_mfma_f32_16x16x32_bf16 v[92:95], v[218:221], v[182:185], v[92:95]
	v_mfma_f32_16x16x32_bf16 v[84:87], v[210:213], v[194:197], v[84:87]
	v_mfma_f32_16x16x32_bf16 v[76:79], v[218:221], v[194:197], v[76:79]
	v_mfma_f32_16x16x32_bf16 v[68:71], v[210:213], v[202:205], v[68:71]
	v_mfma_f32_16x16x32_bf16 v[64:67], v[218:221], v[202:205], v[64:67]
	v_mfma_f32_16x16x32_bf16 v[116:119], v[214:217], v[172:175], v[116:119]
	v_mfma_f32_16x16x32_bf16 v[108:111], v[222:225], v[172:175], v[108:111]
	v_mfma_f32_16x16x32_bf16 v[100:103], v[214:217], v[190:193], v[100:103]
	v_mfma_f32_16x16x32_bf16 v[92:95], v[222:225], v[190:193], v[92:95]
	v_mfma_f32_16x16x32_bf16 v[84:87], v[214:217], v[198:201], v[84:87]
	v_mfma_f32_16x16x32_bf16 v[76:79], v[222:225], v[198:201], v[76:79]
	v_mfma_f32_16x16x32_bf16 v[68:71], v[214:217], v[206:209], v[68:71]
	v_mfma_f32_16x16x32_bf16 v[64:67], v[222:225], v[206:209], v[64:67]
	s_barrier
	s_mov_b32 m0, s36
	v_lshl_add_u64 v[148:149], v[226:227], 0, s[6:7]
	ds_read_b128 v[168:171], v154 offset:49152
	ds_read_b128 v[172:175], v154 offset:50176
	ds_read_b128 v[182:185], v154 offset:51200
	ds_read_b128 v[190:193], v154 offset:52224
	ds_read_b128 v[194:197], v154 offset:53248
	ds_read_b128 v[198:201], v154 offset:54272
	ds_read_b128 v[202:205], v154 offset:55296
	ds_read_b128 v[206:209], v154 offset:56320
	global_load_lds_dwordx4 v[148:149], off
	v_lshl_add_u64 v[148:149], v[228:229], 0, s[6:7]
	s_mov_b32 m0, s37
	s_nop 0
	global_load_lds_dwordx4 v[148:149], off
	s_waitcnt lgkmcnt(0)
	s_barrier
; __device__ __forceinline__ unsigned cvt_pk_bf16(float lo, float hi) { unsigned r; asm volatile("v_cvt_pk_bf16_f32 %0, %1, %2" : "=v"(r) : "v"(lo), "v"(hi)); return r; }
; __device__ __forceinline__ float bf_lo(unsigned u) { return __uint_as_float(u << 16); }
; __device__ __forceinline__ float bf_hi(unsigned u) { return __uint_as_float(u & 0xffff0000u); }
; #define PG8_STAGE(bufoff, gbase, voff) do { _Pragma("unroll") for (int _i = 0; _i < 2; ++_i) \
;         __builtin_amdgcn_global_load_lds((const unsigned*)((const char*)(gbase) + (voff)[_i]), (PG8_LAS unsigned*)(lds + (bufoff) + ldsw + _i * 8192), 16, 0, 0); } while (0)
; #define PG8_WAIT_V(n) asm volatile("s_waitcnt vmcnt(" #n ")" ::: "memory")
; #define PG8_BAR __builtin_amdgcn_s_barrier()
;     __device__ __forceinline__ void operator()(const f32x4 (&acc)[2][2][4][2], const Unit& u, int wr, int wc, int fr, int fq) const {
;     ...
;             for (int m = 0; m < 4; ++m) { const size_t r = (size_t)(row0 + ai * HALF + m * 16); bf16_t* rowp = O + r * ldc + col0; const bf16_t* gp = G + r * ldg + col0;
; #pragma unroll
;                 for (int bj = 0; bj < 2; ++bj) { const u32x4 gw = *(const u32x4*)(gp + bj * HALF);
;                     f32x4 v0 = acc[ai][bj][m][0], v1 = acc[ai][bj][m][1];
;                     v0[0] *= bf_lo(gw.x); v0[1] *= bf_hi(gw.x); v0[2] *= bf_lo(gw.y); v0[3] *= bf_hi(gw.y);
;                     v1[0] *= bf_lo(gw.z); v1[1] *= bf_hi(gw.z); v1[2] *= bf_lo(gw.w); v1[3] *= bf_hi(gw.w);
;                     if (ACCUM) { const u32x4 pw = *(const u32x4*)(rowp + bj * HALF);
;                         v0[0] += bf_lo(pw.x); v0[1] += bf_hi(pw.x); v0[2] += bf_lo(pw.y); v0[3] += bf_hi(pw.y);
;                         v1[0] += bf_lo(pw.z); v1[1] += bf_hi(pw.z); v1[2] += bf_lo(pw.w); v1[3] += bf_hi(pw.w); }
;                     u32x4 w; w.x = cvt_pk_bf16(v0[0], v0[1]); w.y = cvt_pk_bf16(v0[2], v0[3]); w.z = cvt_pk_bf16(v1[0], v1[1]); w.w = cvt_pk_bf16(v1[2], v1[3]);
;                     *(u32x4*)(rowp + bj * HALF) = w; } }
; template <class Epi, class Sched>
; __device__ __forceinline__ void gemm_phase(PG8_LAS unsigned char* lds, const Gemm g, const Sched& S, const Epi& E) {
;     ...
;             PG8_BAR; PG8_WAIT_L(0); PG8_MMA(1, 0, At, B0); PG8_BAR; PG8_SCHED;
;             PG8_STAGE(PG8_SB(1, 1), b3 + hstep, voffB);
;             PG8_WAIT_V(6); PG8_BAR; PG8_MMA(1, 1, At, B1); PG8_BAR;
;         }
	v_mfma_f32_16x16x32_bf16 v[60:63], v[144:147], v[168:171], v[60:63]
	v_mfma_f32_16x16x32_bf16 v[56:59], v[160:163], v[168:171], v[56:59]
	v_mfma_f32_16x16x32_bf16 v[48:51], v[144:147], v[182:185], v[48:51]
	v_mfma_f32_16x16x32_bf16 v[40:43], v[160:163], v[182:185], v[40:43]
	v_mfma_f32_16x16x32_bf16 v[32:35], v[144:147], v[194:197], v[32:35]
	v_mfma_f32_16x16x32_bf16 v[24:27], v[160:163], v[194:197], v[24:27]
	v_mfma_f32_16x16x32_bf16 v[16:19], v[144:147], v[202:205], v[16:19]
	v_mfma_f32_16x16x32_bf16 v[8:11], v[160:163], v[202:205], v[8:11]
	v_mfma_f32_16x16x32_bf16 v[60:63], v[156:159], v[172:175], v[60:63]
	v_mfma_f32_16x16x32_bf16 v[56:59], v[164:167], v[172:175], v[56:59]
	v_mfma_f32_16x16x32_bf16 v[48:51], v[156:159], v[190:193], v[48:51]
	v_mfma_f32_16x16x32_bf16 v[40:43], v[164:167], v[190:193], v[40:43]
	v_mfma_f32_16x16x32_bf16 v[32:35], v[156:159], v[198:201], v[32:35]
	v_mfma_f32_16x16x32_bf16 v[24:27], v[164:167], v[198:201], v[24:27]
	v_mfma_f32_16x16x32_bf16 v[16:19], v[156:159], v[206:209], v[16:19]
	v_mfma_f32_16x16x32_bf16 v[8:11], v[164:167], v[206:209], v[8:11]
	s_barrier
	s_add_u32 s20, s20, 0x40080
	s_addc_u32 s21, s21, 0
	s_add_i32 s22, s22, s29
	v_lshl_add_u64 v[144:145], s[20:21], 0, v[130:131]
	s_mov_b32 m0, s22
	s_nop 0
	global_load_lds_dwordx4 v[144:145], off
	v_lshl_add_u64 v[144:145], s[20:21], 0, v[134:135]
	s_add_i32 m0, s22, 0x2000
	s_nop 0
	global_load_lds_dwordx4 v[144:145], off
	s_waitcnt vmcnt(6)
	s_barrier
	v_mfma_f32_16x16x32_bf16 v[52:55], v[210:213], v[168:171], v[52:55]
	v_mfma_f32_16x16x32_bf16 v[44:47], v[218:221], v[168:171], v[44:47]
	v_mfma_f32_16x16x32_bf16 v[36:39], v[210:213], v[182:185], v[36:39]
	v_mfma_f32_16x16x32_bf16 v[28:31], v[218:221], v[182:185], v[28:31]
	v_mfma_f32_16x16x32_bf16 v[20:23], v[210:213], v[194:197], v[20:23]
	v_mfma_f32_16x16x32_bf16 v[12:15], v[218:221], v[194:197], v[12:15]
	v_mfma_f32_16x16x32_bf16 v[4:7], v[210:213], v[202:205], v[4:7]
	v_mfma_f32_16x16x32_bf16 v[0:3], v[218:221], v[202:205], v[0:3]
	v_mfma_f32_16x16x32_bf16 v[52:55], v[214:217], v[172:175], v[52:55]
	v_mfma_f32_16x16x32_bf16 v[44:47], v[222:225], v[172:175], v[44:47]
	v_mfma_f32_16x16x32_bf16 v[36:39], v[214:217], v[190:193], v[36:39]
	v_mfma_f32_16x16x32_bf16 v[28:31], v[222:225], v[190:193], v[28:31]
	v_mfma_f32_16x16x32_bf16 v[20:23], v[214:217], v[198:201], v[20:23]
	v_mfma_f32_16x16x32_bf16 v[12:15], v[222:225], v[198:201], v[12:15]
	v_mfma_f32_16x16x32_bf16 v[4:7], v[214:217], v[206:209], v[4:7]
	v_mfma_f32_16x16x32_bf16 v[0:3], v[222:225], v[206:209], v[0:3]
	s_barrier
	s_add_i32 s47, s47, 2
	s_add_u32 s18, s18, 0x100
	s_addc_u32 s19, s19, 0
	s_add_u32 s45, s45, 0x100
	s_addc_u32 s46, s46, 0
	s_cmp_gt_u32 s47, 13
	s_cbranch_scc0 .LBB0_991
	v_lshl_or_b32 v144, s42, 8, v152
	v_lshl_add_u32 v146, s16, 8, v150
	v_ashrrev_i32_e32 v145, 31, v144
	v_mov_b64_e32 v[148:149], s[4:5]
	v_lshlrev_b64 v[144:145], 1, v[144:145]
	v_mad_i64_i32 v[156:157], s[18:19], v146, s41, v[148:149]
	v_lshl_add_u64 v[160:161], v[156:157], 0, v[144:145]
	global_load_dwordx4 v[156:159], v[160:161], off offset:3072
	s_and_b64 vcc, exec, s[2:3]
	s_mov_b32 s42, s8
	s_mov_b32 s16, s10
	s_mov_b64 s[20:21], s[14:15]
	s_waitcnt vmcnt(0)
	v_lshlrev_b32_e32 v147, 16, v156
	v_and_b32_e32 v156, 0xffff0000, v156
	v_lshlrev_b32_e32 v162, 16, v157
	v_and_b32_e32 v157, 0xffff0000, v157
	v_lshlrev_b32_e32 v164, 16, v159
	v_and_b32_e32 v159, 0xffff0000, v159
	v_lshlrev_b32_e32 v163, 16, v158
	v_and_b32_e32 v158, 0xffff0000, v158
	v_mul_f32_e32 v124, v124, v147
	v_mul_f32_e32 v125, v125, v156
	v_mul_f32_e32 v126, v126, v162
	v_mul_f32_e32 v127, v127, v157
	v_mul_f32_e32 v123, v123, v159
	v_mul_f32_e32 v147, v120, v163
	v_mul_f32_e32 v156, v121, v158
	v_mul_f32_e32 v157, v122, v164
	v_cvt_pk_bf16_f32 v120, v124, v125
	v_cvt_pk_bf16_f32 v121, v126, v127
	v_cvt_pk_bf16_f32 v122, v147, v156
	v_cvt_pk_bf16_f32 v123, v157, v123
	global_load_dwordx4 v[124:127], v[160:161], off offset:3328
	v_ashrrev_i32_e32 v147, 31, v146
	v_lshlrev_b64 v[158:159], 11, v[146:147]
	v_lshl_add_u64 v[158:159], s[0:1], 0, v[158:159]
	v_or_b32_e32 v156, 16, v146
	v_lshl_add_u64 v[158:159], v[158:159], 0, v[144:145]
	v_mad_i64_i32 v[160:161], s[18:19], v156, s41, v[148:149]
	global_store_dwordx4 v[158:159], v[120:123], off
	v_lshl_add_u64 v[160:161], v[160:161], 0, v[144:145]
	v_ashrrev_i32_e32 v157, 31, v156
	s_waitcnt vmcnt(0)
	v_lshlrev_b32_e32 v120, 16, v124
	v_and_b32_e32 v121, 0xffff0000, v124
	v_lshlrev_b32_e32 v122, 16, v125
	v_and_b32_e32 v123, 0xffff0000, v125
	v_lshlrev_b32_e32 v124, 16, v126
	v_and_b32_e32 v125, 0xffff0000, v126
	v_lshlrev_b32_e32 v126, 16, v127
	v_and_b32_e32 v127, 0xffff0000, v127
	v_mul_f32_e32 v116, v116, v120
	v_mul_f32_e32 v117, v117, v121
	v_mul_f32_e32 v118, v118, v122
	v_mul_f32_e32 v119, v119, v123
	v_mul_f32_e32 v111, v111, v127
	v_mul_f32_e32 v120, v108, v124
	v_mul_f32_e32 v121, v109, v125
	v_mul_f32_e32 v122, v110, v126
	v_cvt_pk_bf16_f32 v108, v116, v117
	v_cvt_pk_bf16_f32 v109, v118, v119
	v_cvt_pk_bf16_f32 v110, v120, v121
	v_cvt_pk_bf16_f32 v111, v122, v111
	global_load_dwordx4 v[116:119], v[160:161], off offset:3072
	s_nop 0
	global_store_dwordx4 v[158:159], v[108:111], off offset:256
	s_waitcnt vmcnt(0)
; __device__ __forceinline__ unsigned cvt_pk_bf16(float lo, float hi) { unsigned r; asm volatile("v_cvt_pk_bf16_f32 %0, %1, %2" : "=v"(r) : "v"(lo), "v"(hi)); return r; }
; __device__ __forceinline__ float bf_lo(unsigned u) { return __uint_as_float(u << 16); }
; __device__ __forceinline__ float bf_hi(unsigned u) { return __uint_as_float(u & 0xffff0000u); }
;     __device__ __forceinline__ void operator()(const f32x4 (&acc)[2][2][4][2], const Unit& u, int wr, int wc, int fr, int fq) const {
;     ...
;             for (int m = 0; m < 4; ++m) { const size_t r = (size_t)(row0 + ai * HALF + m * 16); bf16_t* rowp = O + r * ldc + col0; const bf16_t* gp = G + r * ldg + col0;
; #pragma unroll
;                 for (int bj = 0; bj < 2; ++bj) { const u32x4 gw = *(const u32x4*)(gp + bj * HALF);
;                     f32x4 v0 = acc[ai][bj][m][0], v1 = acc[ai][bj][m][1];
;                     v0[0] *= bf_lo(gw.x); v0[1] *= bf_hi(gw.x); v0[2] *= bf_lo(gw.y); v0[3] *= bf_hi(gw.y);
;                     v1[0] *= bf_lo(gw.z); v1[1] *= bf_hi(gw.z); v1[2] *= bf_lo(gw.w); v1[3] *= bf_hi(gw.w);
;                     if (ACCUM) { const u32x4 pw = *(const u32x4*)(rowp + bj * HALF);
;                         v0[0] += bf_lo(pw.x); v0[1] += bf_hi(pw.x); v0[2] += bf_lo(pw.y); v0[3] += bf_hi(pw.y);
;                         v1[0] += bf_lo(pw.z); v1[1] += bf_hi(pw.z); v1[2] += bf_lo(pw.w); v1[3] += bf_hi(pw.w); }
;                     u32x4 w; w.x = cvt_pk_bf16(v0[0], v0[1]); w.y = cvt_pk_bf16(v0[2], v0[3]); w.z = cvt_pk_bf16(v1[0], v1[1]); w.w = cvt_pk_bf16(v1[2], v1[3]);
;                     *(u32x4*)(rowp + bj * HALF) = w; } }
	s_nop 0
	v_lshlrev_b32_e32 v108, 16, v116
	v_and_b32_e32 v109, 0xffff0000, v116
	v_lshlrev_b32_e32 v110, 16, v117
	v_and_b32_e32 v111, 0xffff0000, v117
	v_lshlrev_b32_e32 v116, 16, v118
	v_and_b32_e32 v117, 0xffff0000, v118
	v_lshlrev_b32_e32 v118, 16, v119
	v_and_b32_e32 v119, 0xffff0000, v119
	v_mul_f32_e32 v108, v112, v108
	v_mul_f32_e32 v109, v113, v109
	v_mul_f32_e32 v110, v114, v110
	v_mul_f32_e32 v111, v115, v111
	v_mul_f32_e32 v107, v107, v119
	v_mul_f32_e32 v112, v104, v116
	v_mul_f32_e32 v113, v105, v117
	v_mul_f32_e32 v114, v106, v118
	v_cvt_pk_bf16_f32 v104, v108, v109
	v_cvt_pk_bf16_f32 v105, v110, v111
	v_cvt_pk_bf16_f32 v106, v112, v113
	v_cvt_pk_bf16_f32 v107, v114, v107
	global_load_dwordx4 v[108:111], v[160:161], off offset:3328
	v_lshlrev_b64 v[116:117], 11, v[156:157]
	v_lshl_add_u64 v[116:117], s[0:1], 0, v[116:117]
	v_or_b32_e32 v112, 32, v146
	v_lshl_add_u64 v[116:117], v[116:117], 0, v[144:145]
	v_mad_i64_i32 v[114:115], s[18:19], v112, s41, v[148:149]
	global_store_dwordx4 v[116:117], v[104:107], off
	v_lshl_add_u64 v[114:115], v[114:115], 0, v[144:145]
	v_ashrrev_i32_e32 v113, 31, v112
	s_waitcnt vmcnt(0)
	v_lshlrev_b32_e32 v104, 16, v108
	v_and_b32_e32 v105, 0xffff0000, v108
	v_lshlrev_b32_e32 v106, 16, v109
	v_and_b32_e32 v107, 0xffff0000, v109
	v_lshlrev_b32_e32 v108, 16, v110
	v_and_b32_e32 v109, 0xffff0000, v110
	v_lshlrev_b32_e32 v110, 16, v111
	v_and_b32_e32 v111, 0xffff0000, v111
	v_mul_f32_e32 v100, v100, v104
	v_mul_f32_e32 v101, v101, v105
	v_mul_f32_e32 v102, v102, v106
	v_mul_f32_e32 v103, v103, v107
	v_mul_f32_e32 v95, v95, v111
	v_mul_f32_e32 v104, v92, v108
	v_mul_f32_e32 v105, v93, v109
	v_mul_f32_e32 v106, v94, v110
	v_cvt_pk_bf16_f32 v92, v100, v101
	v_cvt_pk_bf16_f32 v93, v102, v103
	v_cvt_pk_bf16_f32 v94, v104, v105
	v_cvt_pk_bf16_f32 v95, v106, v95
	global_load_dwordx4 v[100:103], v[114:115], off offset:3072
	s_nop 0
	global_store_dwordx4 v[116:117], v[92:95], off offset:256
	s_waitcnt vmcnt(0)
	s_nop 0
	v_lshlrev_b32_e32 v92, 16, v100
	v_and_b32_e32 v93, 0xffff0000, v100
	v_lshlrev_b32_e32 v94, 16, v101
	v_and_b32_e32 v95, 0xffff0000, v101
	v_lshlrev_b32_e32 v100, 16, v102
	v_and_b32_e32 v101, 0xffff0000, v102
	v_lshlrev_b32_e32 v102, 16, v103
	v_and_b32_e32 v103, 0xffff0000, v103
	v_mul_f32_e32 v92, v96, v92
	v_mul_f32_e32 v93, v97, v93
	v_mul_f32_e32 v94, v98, v94
	v_mul_f32_e32 v95, v99, v95
	v_mul_f32_e32 v91, v91, v103
	v_mul_f32_e32 v96, v88, v100
	v_mul_f32_e32 v97, v89, v101
	v_mul_f32_e32 v98, v90, v102
	v_cvt_pk_bf16_f32 v88, v92, v93
	v_cvt_pk_bf16_f32 v89, v94, v95
	v_cvt_pk_bf16_f32 v90, v96, v97
	v_cvt_pk_bf16_f32 v91, v98, v91
	global_load_dwordx4 v[92:95], v[114:115], off offset:3328
	v_lshlrev_b64 v[100:101], 11, v[112:113]
	v_lshl_add_u64 v[100:101], s[0:1], 0, v[100:101]
	v_or_b32_e32 v96, 48, v146
	v_lshl_add_u64 v[100:101], v[100:101], 0, v[144:145]
	v_mad_i64_i32 v[98:99], s[18:19], v96, s41, v[148:149]
	global_store_dwordx4 v[100:101], v[88:91], off
	v_lshl_add_u64 v[98:99], v[98:99], 0, v[144:145]
	v_ashrrev_i32_e32 v97, 31, v96
	s_waitcnt vmcnt(0)
	v_lshlrev_b32_e32 v88, 16, v92
	v_and_b32_e32 v89, 0xffff0000, v92
	v_lshlrev_b32_e32 v90, 16, v93
	v_and_b32_e32 v91, 0xffff0000, v93
	v_lshlrev_b32_e32 v92, 16, v94
	v_and_b32_e32 v93, 0xffff0000, v94
	v_lshlrev_b32_e32 v94, 16, v95
	v_and_b32_e32 v95, 0xffff0000, v95
	v_mul_f32_e32 v84, v84, v88
	v_mul_f32_e32 v85, v85, v89
	v_mul_f32_e32 v86, v86, v90
	v_mul_f32_e32 v87, v87, v91
	v_mul_f32_e32 v79, v79, v95
	v_mul_f32_e32 v88, v76, v92
	v_mul_f32_e32 v89, v77, v93
	v_mul_f32_e32 v90, v78, v94
	v_cvt_pk_bf16_f32 v76, v84, v85
	v_cvt_pk_bf16_f32 v77, v86, v87
	v_cvt_pk_bf16_f32 v78, v88, v89
	v_cvt_pk_bf16_f32 v79, v90, v79
	global_load_dwordx4 v[84:87], v[98:99], off offset:3072
	s_nop 0
	global_store_dwordx4 v[100:101], v[76:79], off offset:256
	s_waitcnt vmcnt(0)
	s_nop 0
	v_lshlrev_b32_e32 v76, 16, v84
	v_and_b32_e32 v77, 0xffff0000, v84
	v_lshlrev_b32_e32 v78, 16, v85
	v_and_b32_e32 v79, 0xffff0000, v85
	v_lshlrev_b32_e32 v84, 16, v86
	v_and_b32_e32 v85, 0xffff0000, v86
	v_lshlrev_b32_e32 v86, 16, v87
	v_and_b32_e32 v87, 0xffff0000, v87
	v_mul_f32_e32 v76, v80, v76
	v_mul_f32_e32 v77, v81, v77
	v_mul_f32_e32 v78, v82, v78
	v_mul_f32_e32 v79, v83, v79
	v_mul_f32_e32 v75, v75, v87
	v_mul_f32_e32 v80, v72, v84
	v_mul_f32_e32 v81, v73, v85
	v_mul_f32_e32 v82, v74, v86
	v_cvt_pk_bf16_f32 v72, v76, v77
	v_cvt_pk_bf16_f32 v73, v78, v79
	v_cvt_pk_bf16_f32 v74, v80, v81
	v_cvt_pk_bf16_f32 v75, v82, v75
	global_load_dwordx4 v[76:79], v[98:99], off offset:3328
	v_lshlrev_b64 v[84:85], 11, v[96:97]
	v_lshl_add_u64 v[84:85], s[0:1], 0, v[84:85]
	v_add_u32_e32 v80, 0x80, v146
	v_lshl_add_u64 v[84:85], v[84:85], 0, v[144:145]
	v_mad_i64_i32 v[82:83], s[18:19], v80, s41, v[148:149]
	global_store_dwordx4 v[84:85], v[72:75], off
	v_lshl_add_u64 v[82:83], v[82:83], 0, v[144:145]
	v_ashrrev_i32_e32 v81, 31, v80
	s_waitcnt vmcnt(0)
	v_lshlrev_b32_e32 v72, 16, v76
	v_and_b32_e32 v73, 0xffff0000, v76
	v_lshlrev_b32_e32 v74, 16, v77
	v_and_b32_e32 v75, 0xffff0000, v77
	v_lshlrev_b32_e32 v76, 16, v78
	v_and_b32_e32 v77, 0xffff0000, v78
	v_lshlrev_b32_e32 v78, 16, v79
	v_and_b32_e32 v79, 0xffff0000, v79
	v_mul_f32_e32 v68, v68, v72
	v_mul_f32_e32 v69, v69, v73
	v_mul_f32_e32 v70, v70, v74
	v_mul_f32_e32 v71, v71, v75
	v_mul_f32_e32 v67, v67, v79
	v_mul_f32_e32 v72, v64, v76
	v_mul_f32_e32 v73, v65, v77
	v_mul_f32_e32 v74, v66, v78
	v_cvt_pk_bf16_f32 v64, v68, v69
	v_cvt_pk_bf16_f32 v65, v70, v71
	v_cvt_pk_bf16_f32 v66, v72, v73
	v_cvt_pk_bf16_f32 v67, v74, v67
	global_load_dwordx4 v[68:71], v[82:83], off offset:3072
	s_nop 0
	global_store_dwordx4 v[84:85], v[64:67], off offset:256
	s_waitcnt vmcnt(0)
; __device__ __forceinline__ unsigned cvt_pk_bf16(float lo, float hi) { unsigned r; asm volatile("v_cvt_pk_bf16_f32 %0, %1, %2" : "=v"(r) : "v"(lo), "v"(hi)); return r; }
; __device__ __forceinline__ float bf_lo(unsigned u) { return __uint_as_float(u << 16); }
; __device__ __forceinline__ float bf_hi(unsigned u) { return __uint_as_float(u & 0xffff0000u); }
;     __device__ __forceinline__ void operator()(const f32x4 (&acc)[2][2][4][2], const Unit& u, int wr, int wc, int fr, int fq) const {
;     ...
;             for (int m = 0; m < 4; ++m) { const size_t r = (size_t)(row0 + ai * HALF + m * 16); bf16_t* rowp = O + r * ldc + col0; const bf16_t* gp = G + r * ldg + col0;
; #pragma unroll
;                 for (int bj = 0; bj < 2; ++bj) { const u32x4 gw = *(const u32x4*)(gp + bj * HALF);
;                     f32x4 v0 = acc[ai][bj][m][0], v1 = acc[ai][bj][m][1];
;                     v0[0] *= bf_lo(gw.x); v0[1] *= bf_hi(gw.x); v0[2] *= bf_lo(gw.y); v0[3] *= bf_hi(gw.y);
;                     v1[0] *= bf_lo(gw.z); v1[1] *= bf_hi(gw.z); v1[2] *= bf_lo(gw.w); v1[3] *= bf_hi(gw.w);
;                     if (ACCUM) { const u32x4 pw = *(const u32x4*)(rowp + bj * HALF);
;                         v0[0] += bf_lo(pw.x); v0[1] += bf_hi(pw.x); v0[2] += bf_lo(pw.y); v0[3] += bf_hi(pw.y);
;                         v1[0] += bf_lo(pw.z); v1[1] += bf_hi(pw.z); v1[2] += bf_lo(pw.w); v1[3] += bf_hi(pw.w); }
;                     u32x4 w; w.x = cvt_pk_bf16(v0[0], v0[1]); w.y = cvt_pk_bf16(v0[2], v0[3]); w.z = cvt_pk_bf16(v1[0], v1[1]); w.w = cvt_pk_bf16(v1[2], v1[3]);
;                     *(u32x4*)(rowp + bj * HALF) = w; } }
	s_nop 0
	v_lshlrev_b32_e32 v64, 16, v68
	v_and_b32_e32 v65, 0xffff0000, v68
	v_lshlrev_b32_e32 v66, 16, v69
	v_and_b32_e32 v67, 0xffff0000, v69
	v_lshlrev_b32_e32 v68, 16, v70
	v_and_b32_e32 v69, 0xffff0000, v70
	v_lshlrev_b32_e32 v70, 16, v71
	v_and_b32_e32 v71, 0xffff0000, v71
	v_mul_f32_e32 v60, v60, v64
	v_mul_f32_e32 v61, v61, v65
	v_mul_f32_e32 v62, v62, v66
	v_mul_f32_e32 v63, v63, v67
	v_mul_f32_e32 v59, v59, v71
	v_mul_f32_e32 v64, v56, v68
	v_mul_f32_e32 v65, v57, v69
	v_mul_f32_e32 v66, v58, v70
	v_cvt_pk_bf16_f32 v56, v60, v61
	v_cvt_pk_bf16_f32 v57, v62, v63
	v_cvt_pk_bf16_f32 v58, v64, v65
	v_cvt_pk_bf16_f32 v59, v66, v59
	global_load_dwordx4 v[60:63], v[82:83], off offset:3328
	v_lshlrev_b64 v[68:69], 11, v[80:81]
	v_lshl_add_u64 v[68:69], s[0:1], 0, v[68:69]
	v_add_u32_e32 v64, 0x90, v146
	v_lshl_add_u64 v[68:69], v[68:69], 0, v[144:145]
	v_mad_i64_i32 v[66:67], s[18:19], v64, s41, v[148:149]
	global_store_dwordx4 v[68:69], v[56:59], off
	v_lshl_add_u64 v[66:67], v[66:67], 0, v[144:145]
	v_ashrrev_i32_e32 v65, 31, v64
	s_waitcnt vmcnt(0)
	v_lshlrev_b32_e32 v56, 16, v60
	v_and_b32_e32 v57, 0xffff0000, v60
	v_lshlrev_b32_e32 v58, 16, v61
	v_and_b32_e32 v59, 0xffff0000, v61
	v_lshlrev_b32_e32 v60, 16, v62
	v_and_b32_e32 v61, 0xffff0000, v62
	v_lshlrev_b32_e32 v62, 16, v63
	v_and_b32_e32 v63, 0xffff0000, v63
	v_mul_f32_e32 v52, v52, v56
	v_mul_f32_e32 v53, v53, v57
	v_mul_f32_e32 v54, v54, v58
	v_mul_f32_e32 v55, v55, v59
	v_mul_f32_e32 v47, v47, v63
	v_mul_f32_e32 v56, v44, v60
	v_mul_f32_e32 v57, v45, v61
	v_mul_f32_e32 v58, v46, v62
	v_cvt_pk_bf16_f32 v44, v52, v53
	v_cvt_pk_bf16_f32 v45, v54, v55
	v_cvt_pk_bf16_f32 v46, v56, v57
	v_cvt_pk_bf16_f32 v47, v58, v47
	global_load_dwordx4 v[52:55], v[66:67], off offset:3072
	s_nop 0
	global_store_dwordx4 v[68:69], v[44:47], off offset:256
	s_waitcnt vmcnt(0)
	s_nop 0
	v_lshlrev_b32_e32 v44, 16, v52
	v_and_b32_e32 v45, 0xffff0000, v52
	v_lshlrev_b32_e32 v46, 16, v53
	v_and_b32_e32 v47, 0xffff0000, v53
	v_lshlrev_b32_e32 v52, 16, v54
	v_and_b32_e32 v53, 0xffff0000, v54
	v_lshlrev_b32_e32 v54, 16, v55
	v_and_b32_e32 v55, 0xffff0000, v55
	v_mul_f32_e32 v44, v48, v44
	v_mul_f32_e32 v45, v49, v45
	v_mul_f32_e32 v46, v50, v46
	v_mul_f32_e32 v47, v51, v47
	v_mul_f32_e32 v43, v43, v55
	v_mul_f32_e32 v48, v40, v52
	v_mul_f32_e32 v49, v41, v53
	v_mul_f32_e32 v50, v42, v54
	v_cvt_pk_bf16_f32 v40, v44, v45
	v_cvt_pk_bf16_f32 v41, v46, v47
	v_cvt_pk_bf16_f32 v42, v48, v49
	v_cvt_pk_bf16_f32 v43, v50, v43
	global_load_dwordx4 v[44:47], v[66:67], off offset:3328
	v_lshlrev_b64 v[52:53], 11, v[64:65]
	v_lshl_add_u64 v[52:53], s[0:1], 0, v[52:53]
	v_add_u32_e32 v48, 0xa0, v146
	v_lshl_add_u64 v[52:53], v[52:53], 0, v[144:145]
	v_mad_i64_i32 v[50:51], s[18:19], v48, s41, v[148:149]
	global_store_dwordx4 v[52:53], v[40:43], off
	v_lshl_add_u64 v[50:51], v[50:51], 0, v[144:145]
	v_ashrrev_i32_e32 v49, 31, v48
	s_waitcnt vmcnt(0)
	v_lshlrev_b32_e32 v40, 16, v44
	v_and_b32_e32 v41, 0xffff0000, v44
	v_lshlrev_b32_e32 v42, 16, v45
	v_and_b32_e32 v43, 0xffff0000, v45
	v_lshlrev_b32_e32 v44, 16, v46
	v_and_b32_e32 v45, 0xffff0000, v46
	v_lshlrev_b32_e32 v46, 16, v47
	v_and_b32_e32 v47, 0xffff0000, v47
	v_mul_f32_e32 v36, v36, v40
	v_mul_f32_e32 v37, v37, v41
	v_mul_f32_e32 v38, v38, v42
	v_mul_f32_e32 v39, v39, v43
	v_mul_f32_e32 v31, v31, v47
	v_mul_f32_e32 v40, v28, v44
	v_mul_f32_e32 v41, v29, v45
	v_mul_f32_e32 v42, v30, v46
	v_cvt_pk_bf16_f32 v28, v36, v37
	v_cvt_pk_bf16_f32 v29, v38, v39
	v_cvt_pk_bf16_f32 v30, v40, v41
	v_cvt_pk_bf16_f32 v31, v42, v31
	global_load_dwordx4 v[36:39], v[50:51], off offset:3072
	s_nop 0
	global_store_dwordx4 v[52:53], v[28:31], off offset:256
	s_waitcnt vmcnt(0)
; __device__ __forceinline__ unsigned cvt_pk_bf16(float lo, float hi) { unsigned r; asm volatile("v_cvt_pk_bf16_f32 %0, %1, %2" : "=v"(r) : "v"(lo), "v"(hi)); return r; }
; __device__ __forceinline__ float bf_lo(unsigned u) { return __uint_as_float(u << 16); }
; __device__ __forceinline__ float bf_hi(unsigned u) { return __uint_as_float(u & 0xffff0000u); }
; #define PG8_WAIT_V(n) asm volatile("s_waitcnt vmcnt(" #n ")" ::: "memory")
; #define PG8_BAR __builtin_amdgcn_s_barrier()
;     __device__ __forceinline__ void operator()(const f32x4 (&acc)[2][2][4][2], const Unit& u, int wr, int wc, int fr, int fq) const {
;     ...
;             for (int m = 0; m < 4; ++m) { const size_t r = (size_t)(row0 + ai * HALF + m * 16); bf16_t* rowp = O + r * ldc + col0; const bf16_t* gp = G + r * ldg + col0;
; #pragma unroll
;                 for (int bj = 0; bj < 2; ++bj) { const u32x4 gw = *(const u32x4*)(gp + bj * HALF);
;                     f32x4 v0 = acc[ai][bj][m][0], v1 = acc[ai][bj][m][1];
;                     v0[0] *= bf_lo(gw.x); v0[1] *= bf_hi(gw.x); v0[2] *= bf_lo(gw.y); v0[3] *= bf_hi(gw.y);
;                     v1[0] *= bf_lo(gw.z); v1[1] *= bf_hi(gw.z); v1[2] *= bf_lo(gw.w); v1[3] *= bf_hi(gw.w);
;                     if (ACCUM) { const u32x4 pw = *(const u32x4*)(rowp + bj * HALF);
;                         v0[0] += bf_lo(pw.x); v0[1] += bf_hi(pw.x); v0[2] += bf_lo(pw.y); v0[3] += bf_hi(pw.y);
;                         v1[0] += bf_lo(pw.z); v1[1] += bf_hi(pw.z); v1[2] += bf_lo(pw.w); v1[3] += bf_hi(pw.w); }
;                     u32x4 w; w.x = cvt_pk_bf16(v0[0], v0[1]); w.y = cvt_pk_bf16(v0[2], v0[3]); w.z = cvt_pk_bf16(v1[0], v1[1]); w.w = cvt_pk_bf16(v1[2], v1[3]);
;                     *(u32x4*)(rowp + bj * HALF) = w; } }
; template <class Epi, class Sched>
; __device__ __forceinline__ void gemm_phase(PG8_LAS unsigned char* lds, const Gemm g, const Sched& S, const Epi& E) {
;     ...
;         if (!has_next) break;
; #pragma unroll
;         for (int a = 0; a < 2; ++a)
; #pragma unroll
;             for (int b = 0; b < 2; ++b)
; #pragma unroll
;                 for (int m = 0; m < 4; ++m)
; #pragma unroll
;                     for (int n = 0; n < 2; ++n) acc[a][b][m][n] = (f32x4){0.f, 0.f, 0.f, 0.f};
;         cur = nxt; cA = nA; cB = nB; ++ui;
;     }
;     PG8_WAIT_V(0);
;     if (wr == 0) PG8_BAR;
;     PG8_BAR;
	s_nop 0
	v_lshlrev_b32_e32 v28, 16, v36
	v_and_b32_e32 v29, 0xffff0000, v36
	v_lshlrev_b32_e32 v30, 16, v37
	v_and_b32_e32 v31, 0xffff0000, v37
	v_lshlrev_b32_e32 v36, 16, v38
	v_and_b32_e32 v37, 0xffff0000, v38
	v_lshlrev_b32_e32 v38, 16, v39
	v_and_b32_e32 v39, 0xffff0000, v39
	v_mul_f32_e32 v28, v32, v28
	v_mul_f32_e32 v29, v33, v29
	v_mul_f32_e32 v30, v34, v30
	v_mul_f32_e32 v31, v35, v31
	v_mul_f32_e32 v27, v27, v39
	v_mul_f32_e32 v32, v24, v36
	v_mul_f32_e32 v33, v25, v37
	v_mul_f32_e32 v34, v26, v38
	v_cvt_pk_bf16_f32 v24, v28, v29
	v_cvt_pk_bf16_f32 v25, v30, v31
	v_cvt_pk_bf16_f32 v26, v32, v33
	v_cvt_pk_bf16_f32 v27, v34, v27
	global_load_dwordx4 v[28:31], v[50:51], off offset:3328
	v_lshlrev_b64 v[36:37], 11, v[48:49]
	v_lshl_add_u64 v[36:37], s[0:1], 0, v[36:37]
	v_add_u32_e32 v32, 0xb0, v146
	v_lshl_add_u64 v[36:37], v[36:37], 0, v[144:145]
	v_mad_i64_i32 v[34:35], s[18:19], v32, s41, v[148:149]
	global_store_dwordx4 v[36:37], v[24:27], off
	v_lshl_add_u64 v[34:35], v[34:35], 0, v[144:145]
	v_ashrrev_i32_e32 v33, 31, v32
	s_mov_b64 s[18:19], s[12:13]
	s_waitcnt vmcnt(0)
	v_lshlrev_b32_e32 v24, 16, v28
	v_and_b32_e32 v25, 0xffff0000, v28
	v_lshlrev_b32_e32 v26, 16, v29
	v_and_b32_e32 v27, 0xffff0000, v29
	v_lshlrev_b32_e32 v28, 16, v30
	v_and_b32_e32 v29, 0xffff0000, v30
	v_lshlrev_b32_e32 v30, 16, v31
	v_and_b32_e32 v31, 0xffff0000, v31
	v_mul_f32_e32 v20, v20, v24
	v_mul_f32_e32 v21, v21, v25
	v_mul_f32_e32 v22, v22, v26
	v_mul_f32_e32 v23, v23, v27
	v_mul_f32_e32 v15, v15, v31
	v_mul_f32_e32 v24, v12, v28
	v_mul_f32_e32 v25, v13, v29
	v_mul_f32_e32 v26, v14, v30
	v_cvt_pk_bf16_f32 v12, v20, v21
	v_cvt_pk_bf16_f32 v13, v22, v23
	v_cvt_pk_bf16_f32 v14, v24, v25
	v_cvt_pk_bf16_f32 v15, v26, v15
	global_load_dwordx4 v[20:23], v[34:35], off offset:3072
	s_nop 0
	global_store_dwordx4 v[36:37], v[12:15], off offset:256
	s_waitcnt vmcnt(0)
	s_nop 0
	v_lshlrev_b32_e32 v12, 16, v20
	v_and_b32_e32 v13, 0xffff0000, v20
	v_lshlrev_b32_e32 v14, 16, v21
	v_and_b32_e32 v15, 0xffff0000, v21
	v_lshlrev_b32_e32 v20, 16, v22
	v_and_b32_e32 v21, 0xffff0000, v22
	v_lshlrev_b32_e32 v22, 16, v23
	v_and_b32_e32 v23, 0xffff0000, v23
	v_mul_f32_e32 v12, v16, v12
	v_mul_f32_e32 v13, v17, v13
	v_mul_f32_e32 v14, v18, v14
	v_mul_f32_e32 v15, v19, v15
	v_mul_f32_e32 v11, v11, v23
	v_mul_f32_e32 v16, v8, v20
	v_mul_f32_e32 v17, v9, v21
	v_mul_f32_e32 v18, v10, v22
	v_cvt_pk_bf16_f32 v8, v12, v13
	v_cvt_pk_bf16_f32 v9, v14, v15
	v_cvt_pk_bf16_f32 v10, v16, v17
	v_cvt_pk_bf16_f32 v11, v18, v11
	global_load_dwordx4 v[12:15], v[34:35], off offset:3328
	v_lshlrev_b64 v[16:17], 11, v[32:33]
	v_lshl_add_u64 v[16:17], s[0:1], 0, v[16:17]
	v_lshl_add_u64 v[16:17], v[16:17], 0, v[144:145]
	global_store_dwordx4 v[16:17], v[8:11], off
	s_waitcnt vmcnt(0)
	s_nop 0
	v_lshlrev_b32_e32 v8, 16, v12
	v_and_b32_e32 v9, 0xffff0000, v12
	v_lshlrev_b32_e32 v10, 16, v13
	v_and_b32_e32 v11, 0xffff0000, v13
	v_lshlrev_b32_e32 v12, 16, v14
	v_and_b32_e32 v13, 0xffff0000, v14
	v_lshlrev_b32_e32 v14, 16, v15
	v_and_b32_e32 v15, 0xffff0000, v15
	v_mul_f32_e32 v3, v3, v15
	v_mul_f32_e32 v4, v4, v8
	v_mul_f32_e32 v5, v5, v9
	v_mul_f32_e32 v6, v6, v10
	v_mul_f32_e32 v7, v7, v11
	v_mul_f32_e32 v8, v0, v12
	v_mul_f32_e32 v9, v1, v13
	v_mul_f32_e32 v10, v2, v14
	v_cvt_pk_bf16_f32 v0, v4, v5
	v_cvt_pk_bf16_f32 v1, v6, v7
	v_cvt_pk_bf16_f32 v2, v8, v9
	v_cvt_pk_bf16_f32 v3, v10, v3
	global_store_dwordx4 v[16:17], v[0:3], off offset:256
	s_cbranch_vccz .LBB0_984
	s_waitcnt vmcnt(0)
	s_cmpk_gt_u32 s25, 0xff
	s_cbranch_scc1 .LBB0_995
	s_barrier

; #define PG8_STAGE(bufoff, gbase, voff) do { _Pragma("unroll") for (int _i = 0; _i < 2; ++_i) \
;         __builtin_amdgcn_global_load_lds((const unsigned*)((const char*)(gbase) + (voff)[_i]), (PG8_LAS unsigned*)(lds + (bufoff) + ldsw + _i * 8192), 16, 0, 0); } while (0)
; #define PG8_LDA(dst, b, h) do { _Pragma("unroll") for (int m = 0; m < 4; ++m) _Pragma("unroll") for (int k = 0; k < 2; ++k) dst[m][k] = *(const PG8_LAS bf16x8*)(lds + PG8_SA(b, h) + aoff + m * 2048 + k * 1024); } while (0)
; #define PG8_LDB(dst, b, h) do { _Pragma("unroll") for (int n = 0; n < 2; ++n) _Pragma("unroll") for (int k = 0; k < 2; ++k) dst[n][k] = *(const PG8_LAS bf16x8*)(lds + PG8_SB(b, h) + boff + n * 2048 + k * 1024); } while (0)
; #define PG8_MMA(ai, bj, At, Bt) do { __builtin_amdgcn_s_setprio(1); _Pragma("unroll") for (int m = 0; m < 4; ++m) _Pragma("unroll") for (int n = 0; n < 2; ++n) _Pragma("unroll") for (int k = 0; k < 2; ++k) \
;         acc[ai][bj][m][n] = __builtin_amdgcn_mfma_f32_16x16x32_bf16(Bt[n][k], At[m][k], acc[ai][bj][m][n], 0, 0, 0); __builtin_amdgcn_s_setprio(0); } while (0)
; #define PG8_WAIT_L(n) asm volatile("s_waitcnt lgkmcnt(" #n ")" ::: "memory")
; #define PG8_BAR __builtin_amdgcn_s_barrier()
; #define PG8_SCHED __builtin_amdgcn_sched_barrier(0)
; template <class Epi, class Sched>
; __device__ __forceinline__ void gemm_phase(PG8_LAS unsigned char* lds, const Gemm g, const Sched& S, const Epi& E) {
;     ...
;             const bool last = (t == nt - 2);
;             const char* a1 = cA + (size_t)(t + 1) * kstep;
;             const char* a2 = last ? nA : cA + (size_t)(t + 2) * kstep; const char* b2 = last ? nB : cB + (size_t)(t + 2) * kstep;
;             const char* a3 = a2 + kstep; const char* b3 = b2 + kstep;
;             if (last && has_next) S.a_ready(nxt);
;             PG8_LDB(B0, 0, 0); PG8_SCHED; PG8_LDA(At, 0, 0); PG8_STAGE(PG8_SA(1, 1), a1 + hstep, voffA);
;             PG8_WAIT_L(8); PG8_BAR; PG8_WAIT_L(0); PG8_MMA(0, 0, At, B0); PG8_BAR; PG8_SCHED;
;             PG8_LDB(B1, 0, 1); PG8_STAGE(PG8_SB(0, 0), b2, voffB);
;             PG8_BAR; PG8_WAIT_L(0); PG8_MMA(0, 1, At, B1); PG8_BAR;
;             PG8_LDA(At, 0, 1); PG8_STAGE(PG8_SA(0, 0), a2, voffA);
;             PG8_BAR; PG8_WAIT_L(0); PG8_MMA(1, 0, At, B0); PG8_BAR; PG8_SCHED;
.LBB0_1011:
	ds_read_b128 v[144:147], v153
	ds_read_b128 v[156:159], v153 offset:1024
	ds_read_b128 v[160:163], v153 offset:2048
	ds_read_b128 v[164:167], v153 offset:3072
	ds_read_b128 v[168:171], v154
	ds_read_b128 v[172:175], v154 offset:1024
	ds_read_b128 v[182:185], v154 offset:2048
	ds_read_b128 v[190:193], v154 offset:3072
	ds_read_b128 v[194:197], v154 offset:4096
	ds_read_b128 v[198:201], v154 offset:5120
	ds_read_b128 v[202:205], v154 offset:6144
	ds_read_b128 v[206:209], v154 offset:7168
	s_add_u32 s20, s18, 0xfffc0080
	s_addc_u32 s21, s19, -1
	s_cmp_eq_u32 s47, 12
	s_cselect_b32 s23, s11, s21
	s_cselect_b32 s22, s43, s20
	s_cselect_b32 s21, s9, s46
	s_cselect_b32 s20, s44, s45
	v_lshl_add_u64 v[148:149], s[18:19], 0, v[136:137]
	s_add_i32 m0, s17, 0xc000
	s_nop 0
	global_load_lds_dwordx4 v[148:149], off
	v_lshl_add_u64 v[148:149], s[18:19], 0, v[138:139]
	s_add_i32 m0, s17, 0xe000
	s_nop 0
	global_load_lds_dwordx4 v[148:149], off
	s_waitcnt lgkmcnt(0)
	s_barrier
	v_mfma_f32_16x16x32_bf16 v[124:127], v[144:147], v[168:171], v[124:127]
	v_mfma_f32_16x16x32_bf16 v[120:123], v[160:163], v[168:171], v[120:123]
	v_mfma_f32_16x16x32_bf16 v[108:111], v[144:147], v[182:185], v[108:111]
	v_mfma_f32_16x16x32_bf16 v[104:107], v[160:163], v[182:185], v[104:107]
	v_mfma_f32_16x16x32_bf16 v[92:95], v[144:147], v[194:197], v[92:95]
	v_mfma_f32_16x16x32_bf16 v[88:91], v[160:163], v[194:197], v[88:91]
	v_mfma_f32_16x16x32_bf16 v[76:79], v[144:147], v[202:205], v[76:79]
	v_mfma_f32_16x16x32_bf16 v[72:75], v[160:163], v[202:205], v[72:75]
	v_mfma_f32_16x16x32_bf16 v[124:127], v[156:159], v[172:175], v[124:127]
	v_mfma_f32_16x16x32_bf16 v[120:123], v[164:167], v[172:175], v[120:123]
	v_mfma_f32_16x16x32_bf16 v[108:111], v[156:159], v[190:193], v[108:111]
	v_mfma_f32_16x16x32_bf16 v[104:107], v[164:167], v[190:193], v[104:107]
	v_mfma_f32_16x16x32_bf16 v[92:95], v[156:159], v[198:201], v[92:95]
	v_mfma_f32_16x16x32_bf16 v[88:91], v[164:167], v[198:201], v[88:91]
	v_mfma_f32_16x16x32_bf16 v[76:79], v[156:159], v[206:209], v[76:79]
	v_mfma_f32_16x16x32_bf16 v[72:75], v[164:167], v[206:209], v[72:75]
	s_barrier
	ds_read_b128 v[210:213], v155
	ds_read_b128 v[214:217], v155 offset:1024
	ds_read_b128 v[218:221], v155 offset:2048
	ds_read_b128 v[222:225], v155 offset:3072
	s_add_i32 s48, s39, s29
	v_lshl_add_u64 v[148:149], s[20:21], 0, v[130:131]
	s_mov_b32 m0, s48
	s_nop 0
	global_load_lds_dwordx4 v[148:149], off
	v_lshl_add_u64 v[186:187], s[20:21], 0, v[134:135]
	s_add_i32 m0, s48, 0x2000
	s_nop 0
	global_load_lds_dwordx4 v[186:187], off
	s_waitcnt lgkmcnt(0)
	s_barrier
	v_mfma_f32_16x16x32_bf16 v[116:119], v[210:213], v[168:171], v[116:119]
	v_mfma_f32_16x16x32_bf16 v[112:115], v[218:221], v[168:171], v[112:115]
	v_mfma_f32_16x16x32_bf16 v[100:103], v[210:213], v[182:185], v[100:103]
	v_mfma_f32_16x16x32_bf16 v[96:99], v[218:221], v[182:185], v[96:99]
	v_mfma_f32_16x16x32_bf16 v[84:87], v[210:213], v[194:197], v[84:87]
	v_mfma_f32_16x16x32_bf16 v[80:83], v[218:221], v[194:197], v[80:83]
	v_mfma_f32_16x16x32_bf16 v[68:71], v[210:213], v[202:205], v[68:71]
	v_mfma_f32_16x16x32_bf16 v[64:67], v[218:221], v[202:205], v[64:67]
	v_mfma_f32_16x16x32_bf16 v[116:119], v[214:217], v[172:175], v[116:119]
	v_mfma_f32_16x16x32_bf16 v[112:115], v[222:225], v[172:175], v[112:115]
	v_mfma_f32_16x16x32_bf16 v[100:103], v[214:217], v[190:193], v[100:103]
	v_mfma_f32_16x16x32_bf16 v[96:99], v[222:225], v[190:193], v[96:99]
	v_mfma_f32_16x16x32_bf16 v[84:87], v[214:217], v[198:201], v[84:87]
	v_mfma_f32_16x16x32_bf16 v[80:83], v[222:225], v[198:201], v[80:83]
	v_mfma_f32_16x16x32_bf16 v[68:71], v[214:217], v[206:209], v[68:71]
	v_mfma_f32_16x16x32_bf16 v[64:67], v[222:225], v[206:209], v[64:67]
	s_barrier
	s_mov_b32 m0, s17
	v_lshl_add_u64 v[226:227], s[22:23], 0, v[128:129]
	ds_read_b128 v[168:171], v154 offset:16384
	ds_read_b128 v[172:175], v154 offset:17408
	ds_read_b128 v[182:185], v154 offset:18432
	ds_read_b128 v[190:193], v154 offset:19456
	ds_read_b128 v[194:197], v154 offset:20480
	ds_read_b128 v[198:201], v154 offset:21504
	ds_read_b128 v[202:205], v154 offset:22528
	ds_read_b128 v[206:209], v154 offset:23552
	global_load_lds_dwordx4 v[226:227], off
	v_lshl_add_u64 v[228:229], s[22:23], 0, v[132:133]
	s_mov_b32 m0, s30
	s_nop 0
	global_load_lds_dwordx4 v[228:229], off
	s_waitcnt lgkmcnt(0)
	s_barrier
	v_mfma_f32_16x16x32_bf16 v[60:63], v[144:147], v[168:171], v[60:63]
	v_mfma_f32_16x16x32_bf16 v[56:59], v[160:163], v[168:171], v[56:59]
	v_mfma_f32_16x16x32_bf16 v[44:47], v[144:147], v[182:185], v[44:47]
	v_mfma_f32_16x16x32_bf16 v[40:43], v[160:163], v[182:185], v[40:43]
	v_mfma_f32_16x16x32_bf16 v[28:31], v[144:147], v[194:197], v[28:31]
	v_mfma_f32_16x16x32_bf16 v[24:27], v[160:163], v[194:197], v[24:27]
	v_mfma_f32_16x16x32_bf16 v[12:15], v[144:147], v[202:205], v[12:15]
	v_mfma_f32_16x16x32_bf16 v[8:11], v[160:163], v[202:205], v[8:11]
	v_mfma_f32_16x16x32_bf16 v[60:63], v[156:159], v[172:175], v[60:63]
	v_mfma_f32_16x16x32_bf16 v[56:59], v[164:167], v[172:175], v[56:59]
	v_mfma_f32_16x16x32_bf16 v[44:47], v[156:159], v[190:193], v[44:47]
	v_mfma_f32_16x16x32_bf16 v[40:43], v[164:167], v[190:193], v[40:43]
	v_mfma_f32_16x16x32_bf16 v[28:31], v[156:159], v[198:201], v[28:31]
	v_mfma_f32_16x16x32_bf16 v[24:27], v[164:167], v[198:201], v[24:27]
	v_mfma_f32_16x16x32_bf16 v[12:15], v[156:159], v[206:209], v[12:15]
	v_mfma_f32_16x16x32_bf16 v[8:11], v[164:167], v[206:209], v[8:11]
	s_barrier
; #define PG8_STAGE(bufoff, gbase, voff) do { _Pragma("unroll") for (int _i = 0; _i < 2; ++_i) \
;         __builtin_amdgcn_global_load_lds((const unsigned*)((const char*)(gbase) + (voff)[_i]), (PG8_LAS unsigned*)(lds + (bufoff) + ldsw + _i * 8192), 16, 0, 0); } while (0)
; #define PG8_LDA(dst, b, h) do { _Pragma("unroll") for (int m = 0; m < 4; ++m) _Pragma("unroll") for (int k = 0; k < 2; ++k) dst[m][k] = *(const PG8_LAS bf16x8*)(lds + PG8_SA(b, h) + aoff + m * 2048 + k * 1024); } while (0)
; #define PG8_LDB(dst, b, h) do { _Pragma("unroll") for (int n = 0; n < 2; ++n) _Pragma("unroll") for (int k = 0; k < 2; ++k) dst[n][k] = *(const PG8_LAS bf16x8*)(lds + PG8_SB(b, h) + boff + n * 2048 + k * 1024); } while (0)
; #define PG8_MMA(ai, bj, At, Bt) do { __builtin_amdgcn_s_setprio(1); _Pragma("unroll") for (int m = 0; m < 4; ++m) _Pragma("unroll") for (int n = 0; n < 2; ++n) _Pragma("unroll") for (int k = 0; k < 2; ++k) \
;         acc[ai][bj][m][n] = __builtin_amdgcn_mfma_f32_16x16x32_bf16(Bt[n][k], At[m][k], acc[ai][bj][m][n], 0, 0, 0); __builtin_amdgcn_s_setprio(0); } while (0)
; #define PG8_WAIT_V(n) asm volatile("s_waitcnt vmcnt(" #n ")" ::: "memory")
; #define PG8_WAIT_L(n) asm volatile("s_waitcnt lgkmcnt(" #n ")" ::: "memory")
; #define PG8_BAR __builtin_amdgcn_s_barrier()
; #define PG8_SCHED __builtin_amdgcn_sched_barrier(0)
; template <class Epi, class Sched>
; __device__ __forceinline__ void gemm_phase(PG8_LAS unsigned char* lds, const Gemm g, const Sched& S, const Epi& E) {
;     ...
;             PG8_STAGE(PG8_SB(0, 1), b2 + hstep, voffB);
;             PG8_WAIT_V(6); PG8_BAR; PG8_MMA(1, 1, At, B1); PG8_BAR;
;             PG8_LDB(B0, 1, 0); PG8_SCHED; PG8_LDA(At, 1, 0); PG8_STAGE(PG8_SA(0, 1), a2 + hstep, voffA);
;             PG8_WAIT_L(8); PG8_BAR; PG8_WAIT_L(0); PG8_MMA(0, 0, At, B0); PG8_BAR; PG8_SCHED;
;             PG8_LDB(B1, 1, 1); PG8_STAGE(PG8_SB(1, 0), b3, voffB);
;             PG8_BAR; PG8_WAIT_L(0); PG8_MMA(0, 1, At, B1); PG8_BAR;
;             PG8_LDA(At, 1, 1); PG8_STAGE(PG8_SA(1, 0), a3, voffA);
;             PG8_BAR; PG8_WAIT_L(0); PG8_MMA(1, 0, At, B0); PG8_BAR; PG8_SCHED;
	s_add_u32 s48, s20, 0x40000
	s_addc_u32 s49, s21, 0
	s_add_i32 s50, s40, s29
	v_lshl_add_u64 v[144:145], s[48:49], 0, v[130:131]
	s_mov_b32 m0, s50
	s_nop 0
	global_load_lds_dwordx4 v[144:145], off
	v_lshl_add_u64 v[144:145], s[48:49], 0, v[134:135]
	s_add_i32 m0, s50, 0x2000
	s_nop 0
	global_load_lds_dwordx4 v[144:145], off
	s_waitcnt vmcnt(6)
	s_barrier
	v_mfma_f32_16x16x32_bf16 v[52:55], v[210:213], v[168:171], v[52:55]
	v_mfma_f32_16x16x32_bf16 v[48:51], v[218:221], v[168:171], v[48:51]
	v_mfma_f32_16x16x32_bf16 v[36:39], v[210:213], v[182:185], v[36:39]
	v_mfma_f32_16x16x32_bf16 v[32:35], v[218:221], v[182:185], v[32:35]
	v_mfma_f32_16x16x32_bf16 v[20:23], v[210:213], v[194:197], v[20:23]
	v_mfma_f32_16x16x32_bf16 v[16:19], v[218:221], v[194:197], v[16:19]
	v_mfma_f32_16x16x32_bf16 v[4:7], v[210:213], v[202:205], v[4:7]
	v_mfma_f32_16x16x32_bf16 v[0:3], v[218:221], v[202:205], v[0:3]
	v_mfma_f32_16x16x32_bf16 v[52:55], v[214:217], v[172:175], v[52:55]
	v_mfma_f32_16x16x32_bf16 v[48:51], v[222:225], v[172:175], v[48:51]
	v_mfma_f32_16x16x32_bf16 v[36:39], v[214:217], v[190:193], v[36:39]
	v_mfma_f32_16x16x32_bf16 v[32:35], v[222:225], v[190:193], v[32:35]
	v_mfma_f32_16x16x32_bf16 v[20:23], v[214:217], v[198:201], v[20:23]
	v_mfma_f32_16x16x32_bf16 v[16:19], v[222:225], v[198:201], v[16:19]
	v_mfma_f32_16x16x32_bf16 v[4:7], v[214:217], v[206:209], v[4:7]
	v_mfma_f32_16x16x32_bf16 v[0:3], v[222:225], v[206:209], v[0:3]
	s_barrier
	s_add_i32 s48, 0, 0x18000
	v_add_u32_e32 v164, s48, v151
	ds_read_b128 v[144:147], v164
	ds_read_b128 v[156:159], v164 offset:1024
	ds_read_b128 v[160:163], v164 offset:2048
	ds_read_b128 v[164:167], v164 offset:3072
	ds_read_b128 v[168:171], v154 offset:32768
	ds_read_b128 v[172:175], v154 offset:33792
	ds_read_b128 v[182:185], v154 offset:34816
	ds_read_b128 v[190:193], v154 offset:35840
	ds_read_b128 v[194:197], v154 offset:36864
	ds_read_b128 v[198:201], v154 offset:37888
	ds_read_b128 v[202:205], v154 offset:38912
	ds_read_b128 v[206:209], v154 offset:39936
	s_add_u32 s22, s22, 0x40000
	s_addc_u32 s23, s23, 0
	s_mov_b32 m0, s31
	v_lshl_add_u64 v[210:211], s[22:23], 0, v[128:129]
	global_load_lds_dwordx4 v[210:211], off
	v_lshl_add_u64 v[210:211], s[22:23], 0, v[132:133]
	s_mov_b32 m0, s34
	s_nop 0
	global_load_lds_dwordx4 v[210:211], off
	s_waitcnt lgkmcnt(0)
	s_barrier
	v_mfma_f32_16x16x32_bf16 v[124:127], v[144:147], v[168:171], v[124:127]
	v_mfma_f32_16x16x32_bf16 v[120:123], v[160:163], v[168:171], v[120:123]
	v_mfma_f32_16x16x32_bf16 v[108:111], v[144:147], v[182:185], v[108:111]
	v_mfma_f32_16x16x32_bf16 v[104:107], v[160:163], v[182:185], v[104:107]
	v_mfma_f32_16x16x32_bf16 v[92:95], v[144:147], v[194:197], v[92:95]
	v_mfma_f32_16x16x32_bf16 v[88:91], v[160:163], v[194:197], v[88:91]
	v_mfma_f32_16x16x32_bf16 v[76:79], v[144:147], v[202:205], v[76:79]
	v_mfma_f32_16x16x32_bf16 v[72:75], v[160:163], v[202:205], v[72:75]
	v_mfma_f32_16x16x32_bf16 v[124:127], v[156:159], v[172:175], v[124:127]
	v_mfma_f32_16x16x32_bf16 v[120:123], v[164:167], v[172:175], v[120:123]
	v_mfma_f32_16x16x32_bf16 v[108:111], v[156:159], v[190:193], v[108:111]
	v_mfma_f32_16x16x32_bf16 v[104:107], v[164:167], v[190:193], v[104:107]
	v_mfma_f32_16x16x32_bf16 v[92:95], v[156:159], v[198:201], v[92:95]
	v_mfma_f32_16x16x32_bf16 v[88:91], v[164:167], v[198:201], v[88:91]
	v_mfma_f32_16x16x32_bf16 v[76:79], v[156:159], v[206:209], v[76:79]
	v_mfma_f32_16x16x32_bf16 v[72:75], v[164:167], v[206:209], v[72:75]
	s_barrier
	s_add_i32 s22, 0, 0x1c000
	v_add_u32_e32 v179, s22, v151
	ds_read_b128 v[210:213], v179
	ds_read_b128 v[214:217], v179 offset:1024
	ds_read_b128 v[218:221], v179 offset:2048
	ds_read_b128 v[222:225], v179 offset:3072
	s_add_i32 s23, s48, s29
	v_lshl_add_u64 v[148:149], v[148:149], 0, s[6:7]
	s_mov_b32 m0, s23
	s_nop 0
	global_load_lds_dwordx4 v[148:149], off
	v_lshl_add_u64 v[148:149], v[186:187], 0, s[6:7]
	s_add_i32 m0, s23, 0x2000
	s_nop 0
	global_load_lds_dwordx4 v[148:149], off
	s_waitcnt lgkmcnt(0)
	s_barrier
	v_mfma_f32_16x16x32_bf16 v[116:119], v[210:213], v[168:171], v[116:119]
	v_mfma_f32_16x16x32_bf16 v[112:115], v[218:221], v[168:171], v[112:115]
	v_mfma_f32_16x16x32_bf16 v[100:103], v[210:213], v[182:185], v[100:103]
	v_mfma_f32_16x16x32_bf16 v[96:99], v[218:221], v[182:185], v[96:99]
	v_mfma_f32_16x16x32_bf16 v[84:87], v[210:213], v[194:197], v[84:87]
	v_mfma_f32_16x16x32_bf16 v[80:83], v[218:221], v[194:197], v[80:83]
	v_mfma_f32_16x16x32_bf16 v[68:71], v[210:213], v[202:205], v[68:71]
	v_mfma_f32_16x16x32_bf16 v[64:67], v[218:221], v[202:205], v[64:67]
	v_mfma_f32_16x16x32_bf16 v[116:119], v[214:217], v[172:175], v[116:119]
	v_mfma_f32_16x16x32_bf16 v[112:115], v[222:225], v[172:175], v[112:115]
	v_mfma_f32_16x16x32_bf16 v[100:103], v[214:217], v[190:193], v[100:103]
	v_mfma_f32_16x16x32_bf16 v[96:99], v[222:225], v[190:193], v[96:99]
	v_mfma_f32_16x16x32_bf16 v[84:87], v[214:217], v[198:201], v[84:87]
	v_mfma_f32_16x16x32_bf16 v[80:83], v[222:225], v[198:201], v[80:83]
	v_mfma_f32_16x16x32_bf16 v[68:71], v[214:217], v[206:209], v[68:71]
	v_mfma_f32_16x16x32_bf16 v[64:67], v[222:225], v[206:209], v[64:67]
	s_barrier
	s_mov_b32 m0, s36
	v_lshl_add_u64 v[148:149], v[226:227], 0, s[6:7]
	ds_read_b128 v[168:171], v154 offset:49152
	ds_read_b128 v[172:175], v154 offset:50176
	ds_read_b128 v[182:185], v154 offset:51200
	ds_read_b128 v[190:193], v154 offset:52224
	ds_read_b128 v[194:197], v154 offset:53248
	ds_read_b128 v[198:201], v154 offset:54272
	ds_read_b128 v[202:205], v154 offset:55296
	ds_read_b128 v[206:209], v154 offset:56320
	global_load_lds_dwordx4 v[148:149], off
	v_lshl_add_u64 v[148:149], v[228:229], 0, s[6:7]
	s_mov_b32 m0, s37
	s_nop 0
	global_load_lds_dwordx4 v[148:149], off
	s_waitcnt lgkmcnt(0)
	s_barrier
; __device__ __forceinline__ unsigned cvt_pk_bf16(float lo, float hi) { unsigned r; asm volatile("v_cvt_pk_bf16_f32 %0, %1, %2" : "=v"(r) : "v"(lo), "v"(hi)); return r; }
; __device__ __forceinline__ float bf_lo(unsigned u) { return __uint_as_float(u << 16); }
; __device__ __forceinline__ float bf_hi(unsigned u) { return __uint_as_float(u & 0xffff0000u); }
; #define PG8_STAGE(bufoff, gbase, voff) do { _Pragma("unroll") for (int _i = 0; _i < 2; ++_i) \
;         __builtin_amdgcn_global_load_lds((const unsigned*)((const char*)(gbase) + (voff)[_i]), (PG8_LAS unsigned*)(lds + (bufoff) + ldsw + _i * 8192), 16, 0, 0); } while (0)
; #define PG8_WAIT_V(n) asm volatile("s_waitcnt vmcnt(" #n ")" ::: "memory")
; #define PG8_BAR __builtin_amdgcn_s_barrier()
;     __device__ __forceinline__ void operator()(const f32x4 (&acc)[2][2][4][2], const Unit& u, int wr, int wc, int fr, int fq) const {
;     ...
;             for (int m = 0; m < 4; ++m) { const size_t r = (size_t)(row0 + ai * HALF + m * 16); bf16_t* rowp = O + r * ldc + col0; const bf16_t* gp = G + r * ldg + col0;
; #pragma unroll
;                 for (int bj = 0; bj < 2; ++bj) { const u32x4 gw = *(const u32x4*)(gp + bj * HALF);
;                     f32x4 v0 = acc[ai][bj][m][0], v1 = acc[ai][bj][m][1];
;                     v0[0] *= bf_lo(gw.x); v0[1] *= bf_hi(gw.x); v0[2] *= bf_lo(gw.y); v0[3] *= bf_hi(gw.y);
;                     v1[0] *= bf_lo(gw.z); v1[1] *= bf_hi(gw.z); v1[2] *= bf_lo(gw.w); v1[3] *= bf_hi(gw.w);
;                     if (ACCUM) { const u32x4 pw = *(const u32x4*)(rowp + bj * HALF);
;                         v0[0] += bf_lo(pw.x); v0[1] += bf_hi(pw.x); v0[2] += bf_lo(pw.y); v0[3] += bf_hi(pw.y);
;                         v1[0] += bf_lo(pw.z); v1[1] += bf_hi(pw.z); v1[2] += bf_lo(pw.w); v1[3] += bf_hi(pw.w); }
;                     u32x4 w; w.x = cvt_pk_bf16(v0[0], v0[1]); w.y = cvt_pk_bf16(v0[2], v0[3]); w.z = cvt_pk_bf16(v1[0], v1[1]); w.w = cvt_pk_bf16(v1[2], v1[3]);
;                     *(u32x4*)(rowp + bj * HALF) = w; } }
; template <class Epi, class Sched>
; __device__ __forceinline__ void gemm_phase(PG8_LAS unsigned char* lds, const Gemm g, const Sched& S, const Epi& E) {
;     ...
;             PG8_BAR; PG8_WAIT_L(0); PG8_MMA(1, 0, At, B0); PG8_BAR; PG8_SCHED;
;             PG8_STAGE(PG8_SB(1, 1), b3 + hstep, voffB);
;             PG8_WAIT_V(6); PG8_BAR; PG8_MMA(1, 1, At, B1); PG8_BAR;
;         }
	v_mfma_f32_16x16x32_bf16 v[60:63], v[144:147], v[168:171], v[60:63]
	v_mfma_f32_16x16x32_bf16 v[56:59], v[160:163], v[168:171], v[56:59]
	v_mfma_f32_16x16x32_bf16 v[44:47], v[144:147], v[182:185], v[44:47]
	v_mfma_f32_16x16x32_bf16 v[40:43], v[160:163], v[182:185], v[40:43]
	v_mfma_f32_16x16x32_bf16 v[28:31], v[144:147], v[194:197], v[28:31]
	v_mfma_f32_16x16x32_bf16 v[24:27], v[160:163], v[194:197], v[24:27]
	v_mfma_f32_16x16x32_bf16 v[12:15], v[144:147], v[202:205], v[12:15]
	v_mfma_f32_16x16x32_bf16 v[8:11], v[160:163], v[202:205], v[8:11]
	v_mfma_f32_16x16x32_bf16 v[60:63], v[156:159], v[172:175], v[60:63]
	v_mfma_f32_16x16x32_bf16 v[56:59], v[164:167], v[172:175], v[56:59]
	v_mfma_f32_16x16x32_bf16 v[44:47], v[156:159], v[190:193], v[44:47]
	v_mfma_f32_16x16x32_bf16 v[40:43], v[164:167], v[190:193], v[40:43]
	v_mfma_f32_16x16x32_bf16 v[28:31], v[156:159], v[198:201], v[28:31]
	v_mfma_f32_16x16x32_bf16 v[24:27], v[164:167], v[198:201], v[24:27]
	v_mfma_f32_16x16x32_bf16 v[12:15], v[156:159], v[206:209], v[12:15]
	v_mfma_f32_16x16x32_bf16 v[8:11], v[164:167], v[206:209], v[8:11]
	s_barrier
	s_add_u32 s20, s20, 0x40080
	s_addc_u32 s21, s21, 0
	s_add_i32 s22, s22, s29
	v_lshl_add_u64 v[144:145], s[20:21], 0, v[130:131]
	s_mov_b32 m0, s22
	s_nop 0
	global_load_lds_dwordx4 v[144:145], off
	v_lshl_add_u64 v[144:145], s[20:21], 0, v[134:135]
	s_add_i32 m0, s22, 0x2000
	s_nop 0
	global_load_lds_dwordx4 v[144:145], off
	s_waitcnt vmcnt(6)
	s_barrier
	v_mfma_f32_16x16x32_bf16 v[52:55], v[210:213], v[168:171], v[52:55]
	v_mfma_f32_16x16x32_bf16 v[48:51], v[218:221], v[168:171], v[48:51]
	v_mfma_f32_16x16x32_bf16 v[36:39], v[210:213], v[182:185], v[36:39]
	v_mfma_f32_16x16x32_bf16 v[32:35], v[218:221], v[182:185], v[32:35]
	v_mfma_f32_16x16x32_bf16 v[20:23], v[210:213], v[194:197], v[20:23]
	v_mfma_f32_16x16x32_bf16 v[16:19], v[218:221], v[194:197], v[16:19]
	v_mfma_f32_16x16x32_bf16 v[4:7], v[210:213], v[202:205], v[4:7]
	v_mfma_f32_16x16x32_bf16 v[0:3], v[218:221], v[202:205], v[0:3]
	v_mfma_f32_16x16x32_bf16 v[52:55], v[214:217], v[172:175], v[52:55]
	v_mfma_f32_16x16x32_bf16 v[48:51], v[222:225], v[172:175], v[48:51]
	v_mfma_f32_16x16x32_bf16 v[36:39], v[214:217], v[190:193], v[36:39]
	v_mfma_f32_16x16x32_bf16 v[32:35], v[222:225], v[190:193], v[32:35]
	v_mfma_f32_16x16x32_bf16 v[20:23], v[214:217], v[198:201], v[20:23]
	v_mfma_f32_16x16x32_bf16 v[16:19], v[222:225], v[198:201], v[16:19]
	v_mfma_f32_16x16x32_bf16 v[4:7], v[214:217], v[206:209], v[4:7]
	v_mfma_f32_16x16x32_bf16 v[0:3], v[222:225], v[206:209], v[0:3]
	s_barrier
	s_add_i32 s47, s47, 2
	s_add_u32 s18, s18, 0x100
	s_addc_u32 s19, s19, 0
	s_add_u32 s45, s45, 0x100
	s_addc_u32 s46, s46, 0
	s_cmp_gt_u32 s47, 13
	s_cbranch_scc0 .LBB0_1011
	v_lshl_add_u32 v146, s16, 8, v150
	v_lshl_or_b32 v144, s42, 8, v152
	v_ashrrev_i32_e32 v147, 31, v146
	v_ashrrev_i32_e32 v145, 31, v144
	v_mov_b64_e32 v[148:149], s[4:5]
	v_lshlrev_b64 v[160:161], 11, v[146:147]
	v_lshlrev_b64 v[144:145], 1, v[144:145]
	v_mad_i64_i32 v[156:157], s[18:19], v146, s41, v[148:149]
	v_lshl_add_u64 v[160:161], s[0:1], 0, v[160:161]
	v_lshl_add_u64 v[164:165], v[156:157], 0, v[144:145]
	v_lshl_add_u64 v[166:167], v[160:161], 0, v[144:145]
	global_load_dwordx4 v[156:159], v[164:165], off
	global_load_dwordx4 v[160:163], v[166:167], off
	s_and_b64 vcc, exec, s[2:3]
	s_mov_b32 s42, s8
	s_mov_b32 s16, s10
	s_mov_b64 s[20:21], s[14:15]
	s_waitcnt vmcnt(0)
	v_lshlrev_b32_e32 v147, 16, v156
	v_and_b32_e32 v156, 0xffff0000, v156
	v_lshlrev_b32_e32 v168, 16, v157
	v_and_b32_e32 v157, 0xffff0000, v157
	v_lshlrev_b32_e32 v169, 16, v158
	v_and_b32_e32 v158, 0xffff0000, v158
	v_lshlrev_b32_e32 v170, 16, v159
	v_and_b32_e32 v159, 0xffff0000, v159
	v_lshlrev_b32_e32 v171, 16, v160
	v_and_b32_e32 v160, 0xffff0000, v160
	v_lshlrev_b32_e32 v172, 16, v161
	v_and_b32_e32 v161, 0xffff0000, v161
	v_lshlrev_b32_e32 v173, 16, v162
	v_and_b32_e32 v162, 0xffff0000, v162
	v_lshlrev_b32_e32 v174, 16, v163
	v_and_b32_e32 v163, 0xffff0000, v163
	v_fmac_f32_e32 v171, v124, v147
	v_fmac_f32_e32 v160, v125, v156
	v_fmac_f32_e32 v172, v126, v168
	v_fmac_f32_e32 v161, v127, v157
	v_fmac_f32_e32 v173, v120, v169
	v_fmac_f32_e32 v162, v121, v158
	v_fmac_f32_e32 v174, v122, v170
	v_fmac_f32_e32 v163, v123, v159
	v_cvt_pk_bf16_f32 v120, v171, v160
	v_cvt_pk_bf16_f32 v121, v172, v161
	v_cvt_pk_bf16_f32 v122, v173, v162
	v_cvt_pk_bf16_f32 v123, v174, v163
	global_load_dwordx4 v[124:127], v[164:165], off offset:256
	global_load_dwordx4 v[156:159], v[166:167], off offset:256
	v_or_b32_e32 v160, 16, v146
	global_store_dwordx4 v[166:167], v[120:123], off
	v_mad_i64_i32 v[162:163], s[18:19], v160, s41, v[148:149]
	v_lshl_add_u64 v[162:163], v[162:163], 0, v[144:145]
	s_waitcnt vmcnt(0)
	v_lshlrev_b32_e32 v122, 16, v125
	v_lshlrev_b32_e32 v161, 16, v157
	v_lshlrev_b32_e32 v120, 16, v124
	v_and_b32_e32 v121, 0xffff0000, v124
	v_and_b32_e32 v123, 0xffff0000, v125
	v_lshlrev_b32_e32 v124, 16, v126
	v_and_b32_e32 v125, 0xffff0000, v126
	v_lshlrev_b32_e32 v147, 16, v156
	v_and_b32_e32 v156, 0xffff0000, v156
	v_and_b32_e32 v157, 0xffff0000, v157
	v_lshlrev_b32_e32 v164, 16, v158
	v_and_b32_e32 v158, 0xffff0000, v158
	v_fmac_f32_e32 v161, v118, v122
	v_fmac_f32_e32 v147, v116, v120
	v_fmac_f32_e32 v156, v117, v121
	v_fmac_f32_e32 v157, v119, v123
	v_fmac_f32_e32 v164, v112, v124
	v_fmac_f32_e32 v158, v113, v125
	v_cvt_pk_bf16_f32 v112, v147, v156
	v_cvt_pk_bf16_f32 v113, v161, v157
	v_ashrrev_i32_e32 v161, 31, v160
	v_lshlrev_b64 v[120:121], 11, v[160:161]
	v_lshl_add_u64 v[120:121], s[0:1], 0, v[120:121]
	v_lshlrev_b32_e32 v126, 16, v127
	v_and_b32_e32 v127, 0xffff0000, v127
	v_lshlrev_b32_e32 v165, 16, v159
	v_and_b32_e32 v159, 0xffff0000, v159
	v_lshl_add_u64 v[124:125], v[120:121], 0, v[144:145]
	v_fmac_f32_e32 v165, v114, v126
	v_fmac_f32_e32 v159, v115, v127
	v_cvt_pk_bf16_f32 v114, v164, v158
	v_cvt_pk_bf16_f32 v115, v165, v159
	global_load_dwordx4 v[116:119], v[162:163], off
	global_load_dwordx4 v[120:123], v[124:125], off
	s_waitcnt vmcnt(0)
; __device__ __forceinline__ unsigned cvt_pk_bf16(float lo, float hi) { unsigned r; asm volatile("v_cvt_pk_bf16_f32 %0, %1, %2" : "=v"(r) : "v"(lo), "v"(hi)); return r; }
; __device__ __forceinline__ float bf_lo(unsigned u) { return __uint_as_float(u << 16); }
; __device__ __forceinline__ float bf_hi(unsigned u) { return __uint_as_float(u & 0xffff0000u); }
;     __device__ __forceinline__ void operator()(const f32x4 (&acc)[2][2][4][2], const Unit& u, int wr, int wc, int fr, int fq) const {
;     ...
;             for (int m = 0; m < 4; ++m) { const size_t r = (size_t)(row0 + ai * HALF + m * 16); bf16_t* rowp = O + r * ldc + col0; const bf16_t* gp = G + r * ldg + col0;
; #pragma unroll
;                 for (int bj = 0; bj < 2; ++bj) { const u32x4 gw = *(const u32x4*)(gp + bj * HALF);
;                     f32x4 v0 = acc[ai][bj][m][0], v1 = acc[ai][bj][m][1];
;                     v0[0] *= bf_lo(gw.x); v0[1] *= bf_hi(gw.x); v0[2] *= bf_lo(gw.y); v0[3] *= bf_hi(gw.y);
;                     v1[0] *= bf_lo(gw.z); v1[1] *= bf_hi(gw.z); v1[2] *= bf_lo(gw.w); v1[3] *= bf_hi(gw.w);
;                     if (ACCUM) { const u32x4 pw = *(const u32x4*)(rowp + bj * HALF);
;                         v0[0] += bf_lo(pw.x); v0[1] += bf_hi(pw.x); v0[2] += bf_lo(pw.y); v0[3] += bf_hi(pw.y);
;                         v1[0] += bf_lo(pw.z); v1[1] += bf_hi(pw.z); v1[2] += bf_lo(pw.w); v1[3] += bf_hi(pw.w); }
;                     u32x4 w; w.x = cvt_pk_bf16(v0[0], v0[1]); w.y = cvt_pk_bf16(v0[2], v0[3]); w.z = cvt_pk_bf16(v1[0], v1[1]); w.w = cvt_pk_bf16(v1[2], v1[3]);
;                     *(u32x4*)(rowp + bj * HALF) = w; } }
	v_lshlrev_b32_e32 v126, 16, v120
	global_store_dwordx4 v[166:167], v[112:115], off offset:256
	v_and_b32_e32 v120, 0xffff0000, v120
	v_lshlrev_b32_e32 v127, 16, v121
	v_lshlrev_b32_e32 v112, 16, v116
	v_and_b32_e32 v113, 0xffff0000, v116
	v_lshlrev_b32_e32 v114, 16, v117
	v_and_b32_e32 v115, 0xffff0000, v117
	v_lshlrev_b32_e32 v116, 16, v118
	v_and_b32_e32 v117, 0xffff0000, v118
	v_lshlrev_b32_e32 v118, 16, v119
	v_and_b32_e32 v119, 0xffff0000, v119
	v_and_b32_e32 v121, 0xffff0000, v121
	v_lshlrev_b32_e32 v147, 16, v122
	v_and_b32_e32 v122, 0xffff0000, v122
	v_lshlrev_b32_e32 v156, 16, v123
	v_and_b32_e32 v123, 0xffff0000, v123
	v_fmac_f32_e32 v126, v108, v112
	v_fmac_f32_e32 v120, v109, v113
	v_fmac_f32_e32 v127, v110, v114
	v_fmac_f32_e32 v121, v111, v115
	v_fmac_f32_e32 v147, v104, v116
	v_fmac_f32_e32 v122, v105, v117
	v_fmac_f32_e32 v156, v106, v118
	v_fmac_f32_e32 v123, v107, v119
	v_cvt_pk_bf16_f32 v104, v126, v120
	v_cvt_pk_bf16_f32 v105, v127, v121
	v_cvt_pk_bf16_f32 v106, v147, v122
	v_cvt_pk_bf16_f32 v107, v156, v123
	global_load_dwordx4 v[108:111], v[162:163], off offset:256
	global_load_dwordx4 v[112:115], v[124:125], off offset:256
	v_or_b32_e32 v116, 32, v146
	global_store_dwordx4 v[124:125], v[104:107], off
	v_mad_i64_i32 v[118:119], s[18:19], v116, s41, v[148:149]
	v_lshl_add_u64 v[118:119], v[118:119], 0, v[144:145]
	s_waitcnt vmcnt(0)
	v_lshlrev_b32_e32 v104, 16, v108
	v_lshlrev_b32_e32 v117, 16, v112
	v_and_b32_e32 v105, 0xffff0000, v108
	v_lshlrev_b32_e32 v108, 16, v110
	v_and_b32_e32 v112, 0xffff0000, v112
	v_lshlrev_b32_e32 v121, 16, v114
	v_fmac_f32_e32 v117, v100, v104
	v_fmac_f32_e32 v112, v101, v105
	v_fmac_f32_e32 v121, v96, v108
	v_cvt_pk_bf16_f32 v96, v117, v112
	v_ashrrev_i32_e32 v117, 31, v116
	v_lshlrev_b64 v[104:105], 11, v[116:117]
	v_lshlrev_b32_e32 v106, 16, v109
	v_and_b32_e32 v107, 0xffff0000, v109
	v_and_b32_e32 v109, 0xffff0000, v110
	v_and_b32_e32 v114, 0xffff0000, v114
	v_lshl_add_u64 v[104:105], s[0:1], 0, v[104:105]
	v_lshlrev_b32_e32 v110, 16, v111
	v_and_b32_e32 v111, 0xffff0000, v111
	v_lshlrev_b32_e32 v120, 16, v113
	v_and_b32_e32 v113, 0xffff0000, v113
	v_lshlrev_b32_e32 v122, 16, v115
	v_and_b32_e32 v115, 0xffff0000, v115
	v_fmac_f32_e32 v114, v97, v109
	v_lshl_add_u64 v[108:109], v[104:105], 0, v[144:145]
	v_fmac_f32_e32 v120, v102, v106
	v_fmac_f32_e32 v113, v103, v107
	v_fmac_f32_e32 v122, v98, v110
	v_fmac_f32_e32 v115, v99, v111
	v_cvt_pk_bf16_f32 v97, v120, v113
	v_cvt_pk_bf16_f32 v98, v121, v114
	v_cvt_pk_bf16_f32 v99, v122, v115
	global_load_dwordx4 v[100:103], v[118:119], off
	global_load_dwordx4 v[104:107], v[108:109], off
	s_waitcnt vmcnt(0)
	v_lshlrev_b32_e32 v110, 16, v104
	global_store_dwordx4 v[124:125], v[96:99], off offset:256
	v_and_b32_e32 v104, 0xffff0000, v104
	v_lshlrev_b32_e32 v111, 16, v105
	v_lshlrev_b32_e32 v96, 16, v100
	v_and_b32_e32 v97, 0xffff0000, v100
	v_lshlrev_b32_e32 v98, 16, v101
	v_and_b32_e32 v99, 0xffff0000, v101
	v_lshlrev_b32_e32 v100, 16, v102
	v_and_b32_e32 v101, 0xffff0000, v102
	v_lshlrev_b32_e32 v102, 16, v103
	v_and_b32_e32 v103, 0xffff0000, v103
	v_and_b32_e32 v105, 0xffff0000, v105
	v_lshlrev_b32_e32 v112, 16, v106
	v_and_b32_e32 v106, 0xffff0000, v106
	v_lshlrev_b32_e32 v113, 16, v107
	v_and_b32_e32 v107, 0xffff0000, v107
	v_fmac_f32_e32 v110, v92, v96
	v_fmac_f32_e32 v104, v93, v97
	v_fmac_f32_e32 v111, v94, v98
	v_fmac_f32_e32 v105, v95, v99
	v_fmac_f32_e32 v112, v88, v100
	v_fmac_f32_e32 v106, v89, v101
	v_fmac_f32_e32 v113, v90, v102
	v_fmac_f32_e32 v107, v91, v103
	v_cvt_pk_bf16_f32 v88, v110, v104
	v_cvt_pk_bf16_f32 v89, v111, v105
	v_cvt_pk_bf16_f32 v90, v112, v106
	v_cvt_pk_bf16_f32 v91, v113, v107
	global_load_dwordx4 v[92:95], v[118:119], off offset:256
	global_load_dwordx4 v[96:99], v[108:109], off offset:256
	v_or_b32_e32 v100, 48, v146
	global_store_dwordx4 v[108:109], v[88:91], off
	v_mad_i64_i32 v[102:103], s[18:19], v100, s41, v[148:149]
	v_lshl_add_u64 v[102:103], v[102:103], 0, v[144:145]
	s_waitcnt vmcnt(0)
	v_lshlrev_b32_e32 v88, 16, v92
	v_lshlrev_b32_e32 v101, 16, v96
	v_and_b32_e32 v89, 0xffff0000, v92
	v_lshlrev_b32_e32 v92, 16, v94
	v_and_b32_e32 v96, 0xffff0000, v96
	v_lshlrev_b32_e32 v105, 16, v98
	v_fmac_f32_e32 v101, v84, v88
	v_fmac_f32_e32 v96, v85, v89
	v_fmac_f32_e32 v105, v80, v92
	v_cvt_pk_bf16_f32 v80, v101, v96
	v_ashrrev_i32_e32 v101, 31, v100
	v_lshlrev_b64 v[88:89], 11, v[100:101]
	v_lshlrev_b32_e32 v90, 16, v93
	v_and_b32_e32 v91, 0xffff0000, v93
	v_and_b32_e32 v93, 0xffff0000, v94
	v_and_b32_e32 v98, 0xffff0000, v98
	v_lshl_add_u64 v[88:89], s[0:1], 0, v[88:89]
	v_lshlrev_b32_e32 v94, 16, v95
	v_and_b32_e32 v95, 0xffff0000, v95
	v_lshlrev_b32_e32 v104, 16, v97
	v_and_b32_e32 v97, 0xffff0000, v97
	v_lshlrev_b32_e32 v106, 16, v99
	v_and_b32_e32 v99, 0xffff0000, v99
	v_fmac_f32_e32 v98, v81, v93
	v_lshl_add_u64 v[92:93], v[88:89], 0, v[144:145]
	v_fmac_f32_e32 v104, v86, v90
	v_fmac_f32_e32 v97, v87, v91
	v_fmac_f32_e32 v106, v82, v94
	v_fmac_f32_e32 v99, v83, v95
	v_cvt_pk_bf16_f32 v81, v104, v97
	v_cvt_pk_bf16_f32 v82, v105, v98
	v_cvt_pk_bf16_f32 v83, v106, v99
	global_load_dwordx4 v[84:87], v[102:103], off
	global_load_dwordx4 v[88:91], v[92:93], off
	s_waitcnt vmcnt(0)
; __device__ __forceinline__ unsigned cvt_pk_bf16(float lo, float hi) { unsigned r; asm volatile("v_cvt_pk_bf16_f32 %0, %1, %2" : "=v"(r) : "v"(lo), "v"(hi)); return r; }
; __device__ __forceinline__ float bf_lo(unsigned u) { return __uint_as_float(u << 16); }
; __device__ __forceinline__ float bf_hi(unsigned u) { return __uint_as_float(u & 0xffff0000u); }
;     __device__ __forceinline__ void operator()(const f32x4 (&acc)[2][2][4][2], const Unit& u, int wr, int wc, int fr, int fq) const {
;     ...
;             for (int m = 0; m < 4; ++m) { const size_t r = (size_t)(row0 + ai * HALF + m * 16); bf16_t* rowp = O + r * ldc + col0; const bf16_t* gp = G + r * ldg + col0;
; #pragma unroll
;                 for (int bj = 0; bj < 2; ++bj) { const u32x4 gw = *(const u32x4*)(gp + bj * HALF);
;                     f32x4 v0 = acc[ai][bj][m][0], v1 = acc[ai][bj][m][1];
;                     v0[0] *= bf_lo(gw.x); v0[1] *= bf_hi(gw.x); v0[2] *= bf_lo(gw.y); v0[3] *= bf_hi(gw.y);
;                     v1[0] *= bf_lo(gw.z); v1[1] *= bf_hi(gw.z); v1[2] *= bf_lo(gw.w); v1[3] *= bf_hi(gw.w);
;                     if (ACCUM) { const u32x4 pw = *(const u32x4*)(rowp + bj * HALF);
;                         v0[0] += bf_lo(pw.x); v0[1] += bf_hi(pw.x); v0[2] += bf_lo(pw.y); v0[3] += bf_hi(pw.y);
;                         v1[0] += bf_lo(pw.z); v1[1] += bf_hi(pw.z); v1[2] += bf_lo(pw.w); v1[3] += bf_hi(pw.w); }
;                     u32x4 w; w.x = cvt_pk_bf16(v0[0], v0[1]); w.y = cvt_pk_bf16(v0[2], v0[3]); w.z = cvt_pk_bf16(v1[0], v1[1]); w.w = cvt_pk_bf16(v1[2], v1[3]);
;                     *(u32x4*)(rowp + bj * HALF) = w; } }
	v_lshlrev_b32_e32 v94, 16, v88
	global_store_dwordx4 v[108:109], v[80:83], off offset:256
	v_and_b32_e32 v88, 0xffff0000, v88
	v_lshlrev_b32_e32 v95, 16, v89
	v_lshlrev_b32_e32 v80, 16, v84
	v_and_b32_e32 v81, 0xffff0000, v84
	v_lshlrev_b32_e32 v82, 16, v85
	v_and_b32_e32 v83, 0xffff0000, v85
	v_lshlrev_b32_e32 v84, 16, v86
	v_and_b32_e32 v85, 0xffff0000, v86
	v_lshlrev_b32_e32 v86, 16, v87
	v_and_b32_e32 v87, 0xffff0000, v87
	v_and_b32_e32 v89, 0xffff0000, v89
	v_lshlrev_b32_e32 v96, 16, v90
	v_and_b32_e32 v90, 0xffff0000, v90
	v_lshlrev_b32_e32 v97, 16, v91
	v_and_b32_e32 v91, 0xffff0000, v91
	v_fmac_f32_e32 v94, v76, v80
	v_fmac_f32_e32 v88, v77, v81
	v_fmac_f32_e32 v95, v78, v82
	v_fmac_f32_e32 v89, v79, v83
	v_fmac_f32_e32 v96, v72, v84
	v_fmac_f32_e32 v90, v73, v85
	v_fmac_f32_e32 v97, v74, v86
	v_fmac_f32_e32 v91, v75, v87
	v_cvt_pk_bf16_f32 v72, v94, v88
	v_cvt_pk_bf16_f32 v73, v95, v89
	v_cvt_pk_bf16_f32 v74, v96, v90
	v_cvt_pk_bf16_f32 v75, v97, v91
	global_load_dwordx4 v[76:79], v[102:103], off offset:256
	global_load_dwordx4 v[80:83], v[92:93], off offset:256
	v_add_u32_e32 v84, 0x80, v146
	global_store_dwordx4 v[92:93], v[72:75], off
	v_mad_i64_i32 v[86:87], s[18:19], v84, s41, v[148:149]
	v_lshl_add_u64 v[86:87], v[86:87], 0, v[144:145]
	s_waitcnt vmcnt(0)
	v_lshlrev_b32_e32 v72, 16, v76
	v_lshlrev_b32_e32 v85, 16, v80
	v_and_b32_e32 v73, 0xffff0000, v76
	v_lshlrev_b32_e32 v76, 16, v78
	v_and_b32_e32 v80, 0xffff0000, v80
	v_lshlrev_b32_e32 v89, 16, v82
	v_fmac_f32_e32 v85, v68, v72
	v_fmac_f32_e32 v80, v69, v73
	v_fmac_f32_e32 v89, v64, v76
	v_cvt_pk_bf16_f32 v64, v85, v80
	v_ashrrev_i32_e32 v85, 31, v84
	v_lshlrev_b64 v[72:73], 11, v[84:85]
	v_lshlrev_b32_e32 v74, 16, v77
	v_and_b32_e32 v75, 0xffff0000, v77
	v_and_b32_e32 v77, 0xffff0000, v78
	v_and_b32_e32 v82, 0xffff0000, v82
	v_lshl_add_u64 v[72:73], s[0:1], 0, v[72:73]
	v_lshlrev_b32_e32 v78, 16, v79
	v_and_b32_e32 v79, 0xffff0000, v79
	v_lshlrev_b32_e32 v88, 16, v81
	v_and_b32_e32 v81, 0xffff0000, v81
	v_lshlrev_b32_e32 v90, 16, v83
	v_and_b32_e32 v83, 0xffff0000, v83
	v_fmac_f32_e32 v82, v65, v77
	v_lshl_add_u64 v[76:77], v[72:73], 0, v[144:145]
	v_fmac_f32_e32 v88, v70, v74
	v_fmac_f32_e32 v81, v71, v75
	v_fmac_f32_e32 v90, v66, v78
	v_fmac_f32_e32 v83, v67, v79
	v_cvt_pk_bf16_f32 v65, v88, v81
	v_cvt_pk_bf16_f32 v66, v89, v82
	v_cvt_pk_bf16_f32 v67, v90, v83
	global_load_dwordx4 v[68:71], v[86:87], off
	global_load_dwordx4 v[72:75], v[76:77], off
	s_waitcnt vmcnt(0)
	v_lshlrev_b32_e32 v78, 16, v72
	global_store_dwordx4 v[92:93], v[64:67], off offset:256
	v_and_b32_e32 v72, 0xffff0000, v72
	v_lshlrev_b32_e32 v79, 16, v73
	v_lshlrev_b32_e32 v64, 16, v68
	v_and_b32_e32 v65, 0xffff0000, v68
	v_lshlrev_b32_e32 v66, 16, v69
	v_and_b32_e32 v67, 0xffff0000, v69
	v_lshlrev_b32_e32 v68, 16, v70
	v_and_b32_e32 v69, 0xffff0000, v70
	v_lshlrev_b32_e32 v70, 16, v71
	v_and_b32_e32 v71, 0xffff0000, v71
	v_and_b32_e32 v73, 0xffff0000, v73
	v_lshlrev_b32_e32 v80, 16, v74
	v_and_b32_e32 v74, 0xffff0000, v74
	v_lshlrev_b32_e32 v81, 16, v75
	v_and_b32_e32 v75, 0xffff0000, v75
	v_fmac_f32_e32 v78, v60, v64
	v_fmac_f32_e32 v72, v61, v65
	v_fmac_f32_e32 v79, v62, v66
	v_fmac_f32_e32 v73, v63, v67
	v_fmac_f32_e32 v80, v56, v68
	v_fmac_f32_e32 v74, v57, v69
	v_fmac_f32_e32 v81, v58, v70
	v_fmac_f32_e32 v75, v59, v71
	v_cvt_pk_bf16_f32 v56, v78, v72
	v_cvt_pk_bf16_f32 v57, v79, v73
	v_cvt_pk_bf16_f32 v58, v80, v74
	v_cvt_pk_bf16_f32 v59, v81, v75
	global_load_dwordx4 v[60:63], v[86:87], off offset:256
	global_load_dwordx4 v[64:67], v[76:77], off offset:256
	v_add_u32_e32 v68, 0x90, v146
	global_store_dwordx4 v[76:77], v[56:59], off
	v_mad_i64_i32 v[70:71], s[18:19], v68, s41, v[148:149]
	v_lshl_add_u64 v[70:71], v[70:71], 0, v[144:145]
	s_waitcnt vmcnt(0)
	v_lshlrev_b32_e32 v56, 16, v60
	v_lshlrev_b32_e32 v69, 16, v64
	v_and_b32_e32 v57, 0xffff0000, v60
	v_lshlrev_b32_e32 v60, 16, v62
	v_and_b32_e32 v64, 0xffff0000, v64
	v_lshlrev_b32_e32 v73, 16, v66
	v_fmac_f32_e32 v69, v52, v56
	v_fmac_f32_e32 v64, v53, v57
	v_fmac_f32_e32 v73, v48, v60
	v_cvt_pk_bf16_f32 v48, v69, v64
	v_ashrrev_i32_e32 v69, 31, v68
	v_lshlrev_b64 v[56:57], 11, v[68:69]
	v_lshlrev_b32_e32 v58, 16, v61
	v_and_b32_e32 v59, 0xffff0000, v61
	v_and_b32_e32 v61, 0xffff0000, v62
	v_and_b32_e32 v66, 0xffff0000, v66
	v_lshl_add_u64 v[56:57], s[0:1], 0, v[56:57]
	v_lshlrev_b32_e32 v62, 16, v63
	v_and_b32_e32 v63, 0xffff0000, v63
	v_lshlrev_b32_e32 v72, 16, v65
	v_and_b32_e32 v65, 0xffff0000, v65
	v_lshlrev_b32_e32 v74, 16, v67
	v_and_b32_e32 v67, 0xffff0000, v67
	v_fmac_f32_e32 v66, v49, v61
	v_lshl_add_u64 v[60:61], v[56:57], 0, v[144:145]
	v_fmac_f32_e32 v72, v54, v58
	v_fmac_f32_e32 v65, v55, v59
	v_fmac_f32_e32 v74, v50, v62
	v_fmac_f32_e32 v67, v51, v63
	v_cvt_pk_bf16_f32 v49, v72, v65
	v_cvt_pk_bf16_f32 v50, v73, v66
	v_cvt_pk_bf16_f32 v51, v74, v67
	global_load_dwordx4 v[52:55], v[70:71], off
	global_load_dwordx4 v[56:59], v[60:61], off
	s_waitcnt vmcnt(0)
	v_lshlrev_b32_e32 v62, 16, v56
	global_store_dwordx4 v[76:77], v[48:51], off offset:256
	v_and_b32_e32 v56, 0xffff0000, v56
	v_lshlrev_b32_e32 v63, 16, v57
	v_lshlrev_b32_e32 v48, 16, v52
	v_and_b32_e32 v49, 0xffff0000, v52
	v_lshlrev_b32_e32 v50, 16, v53
	v_and_b32_e32 v51, 0xffff0000, v53
	v_lshlrev_b32_e32 v52, 16, v54
	v_and_b32_e32 v53, 0xffff0000, v54
	v_lshlrev_b32_e32 v54, 16, v55
	v_and_b32_e32 v55, 0xffff0000, v55
	v_and_b32_e32 v57, 0xffff0000, v57
	v_lshlrev_b32_e32 v64, 16, v58
	v_and_b32_e32 v58, 0xffff0000, v58
	v_lshlrev_b32_e32 v65, 16, v59
	v_and_b32_e32 v59, 0xffff0000, v59
	v_fmac_f32_e32 v62, v44, v48
	v_fmac_f32_e32 v56, v45, v49
	v_fmac_f32_e32 v63, v46, v50
	v_fmac_f32_e32 v57, v47, v51
	v_fmac_f32_e32 v64, v40, v52
	v_fmac_f32_e32 v58, v41, v53
	v_fmac_f32_e32 v65, v42, v54
	v_fmac_f32_e32 v59, v43, v55
	v_cvt_pk_bf16_f32 v40, v62, v56
	v_cvt_pk_bf16_f32 v41, v63, v57
	v_cvt_pk_bf16_f32 v42, v64, v58
	v_cvt_pk_bf16_f32 v43, v65, v59
	global_load_dwordx4 v[44:47], v[70:71], off offset:256
	global_load_dwordx4 v[48:51], v[60:61], off offset:256
	v_add_u32_e32 v52, 0xa0, v146
	global_store_dwordx4 v[60:61], v[40:43], off
	v_mad_i64_i32 v[54:55], s[18:19], v52, s41, v[148:149]
	v_lshl_add_u64 v[54:55], v[54:55], 0, v[144:145]
	s_waitcnt vmcnt(0)
; __device__ __forceinline__ unsigned cvt_pk_bf16(float lo, float hi) { unsigned r; asm volatile("v_cvt_pk_bf16_f32 %0, %1, %2" : "=v"(r) : "v"(lo), "v"(hi)); return r; }
; __device__ __forceinline__ float bf_lo(unsigned u) { return __uint_as_float(u << 16); }
; __device__ __forceinline__ float bf_hi(unsigned u) { return __uint_as_float(u & 0xffff0000u); }
; #define PG8_WAIT_V(n) asm volatile("s_waitcnt vmcnt(" #n ")" ::: "memory")
; #define PG8_BAR __builtin_amdgcn_s_barrier()
;     __device__ __forceinline__ void operator()(const f32x4 (&acc)[2][2][4][2], const Unit& u, int wr, int wc, int fr, int fq) const {
;     ...
;             for (int m = 0; m < 4; ++m) { const size_t r = (size_t)(row0 + ai * HALF + m * 16); bf16_t* rowp = O + r * ldc + col0; const bf16_t* gp = G + r * ldg + col0;
; #pragma unroll
;                 for (int bj = 0; bj < 2; ++bj) { const u32x4 gw = *(const u32x4*)(gp + bj * HALF);
;                     f32x4 v0 = acc[ai][bj][m][0], v1 = acc[ai][bj][m][1];
;                     v0[0] *= bf_lo(gw.x); v0[1] *= bf_hi(gw.x); v0[2] *= bf_lo(gw.y); v0[3] *= bf_hi(gw.y);
;                     v1[0] *= bf_lo(gw.z); v1[1] *= bf_hi(gw.z); v1[2] *= bf_lo(gw.w); v1[3] *= bf_hi(gw.w);
;                     if (ACCUM) { const u32x4 pw = *(const u32x4*)(rowp + bj * HALF);
;                         v0[0] += bf_lo(pw.x); v0[1] += bf_hi(pw.x); v0[2] += bf_lo(pw.y); v0[3] += bf_hi(pw.y);
;                         v1[0] += bf_lo(pw.z); v1[1] += bf_hi(pw.z); v1[2] += bf_lo(pw.w); v1[3] += bf_hi(pw.w); }
;                     u32x4 w; w.x = cvt_pk_bf16(v0[0], v0[1]); w.y = cvt_pk_bf16(v0[2], v0[3]); w.z = cvt_pk_bf16(v1[0], v1[1]); w.w = cvt_pk_bf16(v1[2], v1[3]);
;                     *(u32x4*)(rowp + bj * HALF) = w; } }
; template <class Epi, class Sched>
; __device__ __forceinline__ void gemm_phase(PG8_LAS unsigned char* lds, const Gemm g, const Sched& S, const Epi& E) {
;     ...
;         if (!has_next) break;
; #pragma unroll
;         for (int a = 0; a < 2; ++a)
; #pragma unroll
;             for (int b = 0; b < 2; ++b)
; #pragma unroll
;                 for (int m = 0; m < 4; ++m)
; #pragma unroll
;                     for (int n = 0; n < 2; ++n) acc[a][b][m][n] = (f32x4){0.f, 0.f, 0.f, 0.f};
;         cur = nxt; cA = nA; cB = nB; ++ui;
;     }
;     PG8_WAIT_V(0);
;     if (wr == 0) PG8_BAR;
;     PG8_BAR;
	v_lshlrev_b32_e32 v40, 16, v44
	v_lshlrev_b32_e32 v53, 16, v48
	v_and_b32_e32 v41, 0xffff0000, v44
	v_lshlrev_b32_e32 v44, 16, v46
	v_and_b32_e32 v48, 0xffff0000, v48
	v_lshlrev_b32_e32 v57, 16, v50
	v_fmac_f32_e32 v53, v36, v40
	v_fmac_f32_e32 v48, v37, v41
	v_fmac_f32_e32 v57, v32, v44
	v_cvt_pk_bf16_f32 v32, v53, v48
	v_ashrrev_i32_e32 v53, 31, v52
	v_lshlrev_b64 v[40:41], 11, v[52:53]
	v_lshlrev_b32_e32 v42, 16, v45
	v_and_b32_e32 v43, 0xffff0000, v45
	v_and_b32_e32 v45, 0xffff0000, v46
	v_and_b32_e32 v50, 0xffff0000, v50
	v_lshl_add_u64 v[40:41], s[0:1], 0, v[40:41]
	v_lshlrev_b32_e32 v46, 16, v47
	v_and_b32_e32 v47, 0xffff0000, v47
	v_lshlrev_b32_e32 v56, 16, v49
	v_and_b32_e32 v49, 0xffff0000, v49
	v_lshlrev_b32_e32 v58, 16, v51
	v_and_b32_e32 v51, 0xffff0000, v51
	v_fmac_f32_e32 v50, v33, v45
	v_lshl_add_u64 v[44:45], v[40:41], 0, v[144:145]
	v_fmac_f32_e32 v56, v38, v42
	v_fmac_f32_e32 v49, v39, v43
	v_fmac_f32_e32 v58, v34, v46
	v_fmac_f32_e32 v51, v35, v47
	v_cvt_pk_bf16_f32 v33, v56, v49
	v_cvt_pk_bf16_f32 v34, v57, v50
	v_cvt_pk_bf16_f32 v35, v58, v51
	global_load_dwordx4 v[36:39], v[54:55], off
	global_load_dwordx4 v[40:43], v[44:45], off
	s_waitcnt vmcnt(0)
	v_lshlrev_b32_e32 v46, 16, v40
	global_store_dwordx4 v[60:61], v[32:35], off offset:256
	v_and_b32_e32 v40, 0xffff0000, v40
	v_lshlrev_b32_e32 v47, 16, v41
	v_lshlrev_b32_e32 v32, 16, v36
	v_and_b32_e32 v33, 0xffff0000, v36
	v_lshlrev_b32_e32 v34, 16, v37
	v_and_b32_e32 v35, 0xffff0000, v37
	v_lshlrev_b32_e32 v36, 16, v38
	v_and_b32_e32 v37, 0xffff0000, v38
	v_lshlrev_b32_e32 v38, 16, v39
	v_and_b32_e32 v39, 0xffff0000, v39
	v_and_b32_e32 v41, 0xffff0000, v41
	v_lshlrev_b32_e32 v48, 16, v42
	v_and_b32_e32 v42, 0xffff0000, v42
	v_lshlrev_b32_e32 v49, 16, v43
	v_and_b32_e32 v43, 0xffff0000, v43
	v_fmac_f32_e32 v46, v28, v32
	v_fmac_f32_e32 v40, v29, v33
	v_fmac_f32_e32 v47, v30, v34
	v_fmac_f32_e32 v41, v31, v35
	v_fmac_f32_e32 v48, v24, v36
	v_fmac_f32_e32 v42, v25, v37
	v_fmac_f32_e32 v49, v26, v38
	v_fmac_f32_e32 v43, v27, v39
	v_cvt_pk_bf16_f32 v24, v46, v40
	v_cvt_pk_bf16_f32 v25, v47, v41
	v_cvt_pk_bf16_f32 v26, v48, v42
	v_cvt_pk_bf16_f32 v27, v49, v43
	global_load_dwordx4 v[28:31], v[54:55], off offset:256
	global_load_dwordx4 v[32:35], v[44:45], off offset:256
	v_add_u32_e32 v36, 0xb0, v146
	global_store_dwordx4 v[44:45], v[24:27], off
	v_mad_i64_i32 v[38:39], s[18:19], v36, s41, v[148:149]
	v_lshl_add_u64 v[38:39], v[38:39], 0, v[144:145]
	s_mov_b64 s[18:19], s[12:13]
	s_waitcnt vmcnt(0)
	v_lshlrev_b32_e32 v24, 16, v28
	v_lshlrev_b32_e32 v37, 16, v32
	v_and_b32_e32 v25, 0xffff0000, v28
	v_lshlrev_b32_e32 v28, 16, v30
	v_and_b32_e32 v32, 0xffff0000, v32
	v_lshlrev_b32_e32 v41, 16, v34
	v_fmac_f32_e32 v37, v20, v24
	v_fmac_f32_e32 v32, v21, v25
	v_fmac_f32_e32 v41, v16, v28
	v_cvt_pk_bf16_f32 v16, v37, v32
	v_ashrrev_i32_e32 v37, 31, v36
	v_lshlrev_b64 v[24:25], 11, v[36:37]
	v_lshlrev_b32_e32 v26, 16, v29
	v_and_b32_e32 v27, 0xffff0000, v29
	v_and_b32_e32 v29, 0xffff0000, v30
	v_and_b32_e32 v34, 0xffff0000, v34
	v_lshl_add_u64 v[24:25], s[0:1], 0, v[24:25]
	v_lshlrev_b32_e32 v30, 16, v31
	v_and_b32_e32 v31, 0xffff0000, v31
	v_lshlrev_b32_e32 v40, 16, v33
	v_and_b32_e32 v33, 0xffff0000, v33
	v_lshlrev_b32_e32 v42, 16, v35
	v_and_b32_e32 v35, 0xffff0000, v35
	v_fmac_f32_e32 v34, v17, v29
	v_lshl_add_u64 v[28:29], v[24:25], 0, v[144:145]
	v_fmac_f32_e32 v40, v22, v26
	v_fmac_f32_e32 v33, v23, v27
	v_fmac_f32_e32 v42, v18, v30
	v_fmac_f32_e32 v35, v19, v31
	v_cvt_pk_bf16_f32 v17, v40, v33
	v_cvt_pk_bf16_f32 v18, v41, v34
	v_cvt_pk_bf16_f32 v19, v42, v35
	global_load_dwordx4 v[20:23], v[38:39], off
	global_load_dwordx4 v[24:27], v[28:29], off
	s_waitcnt vmcnt(0)
	v_lshlrev_b32_e32 v30, 16, v24
	global_store_dwordx4 v[44:45], v[16:19], off offset:256
	v_and_b32_e32 v24, 0xffff0000, v24
	v_lshlrev_b32_e32 v31, 16, v25
	v_lshlrev_b32_e32 v16, 16, v20
	v_and_b32_e32 v17, 0xffff0000, v20
	v_lshlrev_b32_e32 v18, 16, v21
	v_and_b32_e32 v19, 0xffff0000, v21
	v_lshlrev_b32_e32 v20, 16, v22
	v_and_b32_e32 v21, 0xffff0000, v22
	v_lshlrev_b32_e32 v22, 16, v23
	v_and_b32_e32 v23, 0xffff0000, v23
	v_and_b32_e32 v25, 0xffff0000, v25
	v_lshlrev_b32_e32 v32, 16, v26
	v_and_b32_e32 v26, 0xffff0000, v26
	v_lshlrev_b32_e32 v33, 16, v27
	v_and_b32_e32 v27, 0xffff0000, v27
	v_fmac_f32_e32 v30, v12, v16
	v_fmac_f32_e32 v24, v13, v17
	v_fmac_f32_e32 v31, v14, v18
	v_fmac_f32_e32 v25, v15, v19
	v_fmac_f32_e32 v32, v8, v20
	v_fmac_f32_e32 v26, v9, v21
	v_fmac_f32_e32 v33, v10, v22
	v_fmac_f32_e32 v27, v11, v23
	v_cvt_pk_bf16_f32 v8, v30, v24
	v_cvt_pk_bf16_f32 v9, v31, v25
	v_cvt_pk_bf16_f32 v10, v32, v26
	v_cvt_pk_bf16_f32 v11, v33, v27
	global_load_dwordx4 v[12:15], v[38:39], off offset:256
	global_load_dwordx4 v[16:19], v[28:29], off offset:256
	s_waitcnt vmcnt(0)
	v_lshlrev_b32_e32 v20, 16, v16
	global_store_dwordx4 v[28:29], v[8:11], off
	v_and_b32_e32 v16, 0xffff0000, v16
	v_lshlrev_b32_e32 v21, 16, v17
	v_lshlrev_b32_e32 v8, 16, v12
	v_and_b32_e32 v9, 0xffff0000, v12
	v_lshlrev_b32_e32 v10, 16, v13
	v_and_b32_e32 v11, 0xffff0000, v13
	v_lshlrev_b32_e32 v12, 16, v14
	v_and_b32_e32 v13, 0xffff0000, v14
	v_lshlrev_b32_e32 v14, 16, v15
	v_and_b32_e32 v15, 0xffff0000, v15
	v_and_b32_e32 v17, 0xffff0000, v17
	v_lshlrev_b32_e32 v22, 16, v18
	v_and_b32_e32 v18, 0xffff0000, v18
	v_lshlrev_b32_e32 v23, 16, v19
	v_and_b32_e32 v19, 0xffff0000, v19
	v_fmac_f32_e32 v20, v4, v8
	v_fmac_f32_e32 v16, v5, v9
	v_fmac_f32_e32 v21, v6, v10
	v_fmac_f32_e32 v17, v7, v11
	v_fmac_f32_e32 v22, v0, v12
	v_fmac_f32_e32 v18, v1, v13
	v_fmac_f32_e32 v23, v2, v14
	v_fmac_f32_e32 v19, v3, v15
	v_cvt_pk_bf16_f32 v0, v20, v16
	v_cvt_pk_bf16_f32 v1, v21, v17
	v_cvt_pk_bf16_f32 v2, v22, v18
	v_cvt_pk_bf16_f32 v3, v23, v19
	global_store_dwordx4 v[28:29], v[0:3], off offset:256
	s_cbranch_vccz .LBB0_1004
	s_waitcnt vmcnt(0)
	s_cmpk_gt_u32 s25, 0xff
	s_cbranch_scc1 .LBB0_1015
	s_barrier

; #define PG8_STAGE(bufoff, gbase, voff) do { _Pragma("unroll") for (int _i = 0; _i < 2; ++_i) \
;         __builtin_amdgcn_global_load_lds((const unsigned*)((const char*)(gbase) + (voff)[_i]), (PG8_LAS unsigned*)(lds + (bufoff) + ldsw + _i * 8192), 16, 0, 0); } while (0)
; #define PG8_LDA(dst, b, h) do { _Pragma("unroll") for (int m = 0; m < 4; ++m) _Pragma("unroll") for (int k = 0; k < 2; ++k) dst[m][k] = *(const PG8_LAS bf16x8*)(lds + PG8_SA(b, h) + aoff + m * 2048 + k * 1024); } while (0)
; #define PG8_LDB(dst, b, h) do { _Pragma("unroll") for (int n = 0; n < 2; ++n) _Pragma("unroll") for (int k = 0; k < 2; ++k) dst[n][k] = *(const PG8_LAS bf16x8*)(lds + PG8_SB(b, h) + boff + n * 2048 + k * 1024); } while (0)
; #define PG8_MMA(ai, bj, At, Bt) do { __builtin_amdgcn_s_setprio(1); _Pragma("unroll") for (int m = 0; m < 4; ++m) _Pragma("unroll") for (int n = 0; n < 2; ++n) _Pragma("unroll") for (int k = 0; k < 2; ++k) \
;         acc[ai][bj][m][n] = __builtin_amdgcn_mfma_f32_16x16x32_bf16(Bt[n][k], At[m][k], acc[ai][bj][m][n], 0, 0, 0); __builtin_amdgcn_s_setprio(0); } while (0)
; #define PG8_WAIT_L(n) asm volatile("s_waitcnt lgkmcnt(" #n ")" ::: "memory")
; #define PG8_BAR __builtin_amdgcn_s_barrier()
; #define PG8_SCHED __builtin_amdgcn_sched_barrier(0)
; template <class Epi, class Sched>
; __device__ __forceinline__ void gemm_phase(PG8_LAS unsigned char* lds, const Gemm g, const Sched& S, const Epi& E) {
;     ...
;             PG8_LDB(B0, 0, 0); PG8_SCHED; PG8_LDA(At, 0, 0); PG8_STAGE(PG8_SA(1, 1), a1 + hstep, voffA);
;             PG8_WAIT_L(8); PG8_BAR; PG8_WAIT_L(0); PG8_MMA(0, 0, At, B0); PG8_BAR; PG8_SCHED;
;             PG8_LDB(B1, 0, 1); PG8_STAGE(PG8_SB(0, 0), b2, voffB);
;             PG8_BAR; PG8_WAIT_L(0); PG8_MMA(0, 1, At, B1); PG8_BAR;
;             PG8_LDA(At, 0, 1); PG8_STAGE(PG8_SA(0, 0), a2, voffA);
;             PG8_BAR; PG8_WAIT_L(0); PG8_MMA(1, 0, At, B0); PG8_BAR; PG8_SCHED;
.LBB0_1083:
	ds_read_b128 v[152:155], v149
	ds_read_b128 v[156:159], v149 offset:1024
	ds_read_b128 v[160:163], v149 offset:2048
	ds_read_b128 v[164:167], v149 offset:3072
	ds_read_b128 v[168:171], v150
	ds_read_b128 v[172:175], v150 offset:1024
	ds_read_b128 v[182:185], v150 offset:2048
	ds_read_b128 v[190:193], v150 offset:3072
	ds_read_b128 v[194:197], v150 offset:4096
	ds_read_b128 v[198:201], v150 offset:5120
	ds_read_b128 v[202:205], v150 offset:6144
	ds_read_b128 v[206:209], v150 offset:7168
	s_add_u32 s26, s24, 0xfffc0080
	s_addc_u32 s27, s25, -1
	s_cmp_eq_u32 s56, 12
	s_cselect_b32 s29, s17, s27
	s_cselect_b32 s28, s52, s26
	s_cselect_b32 s27, s15, s55
	s_cselect_b32 s26, s53, s54
	v_lshl_add_u64 v[144:145], s[24:25], 0, v[136:137]
	s_add_i32 m0, s23, 0xc000
	s_nop 0
	global_load_lds_dwordx4 v[144:145], off
	v_lshl_add_u64 v[144:145], s[24:25], 0, v[138:139]
	s_add_i32 m0, s23, 0xe000
	s_nop 0
	global_load_lds_dwordx4 v[144:145], off
	s_waitcnt lgkmcnt(0)
	s_barrier
	v_mfma_f32_16x16x32_bf16 v[124:127], v[152:155], v[168:171], v[124:127]
	v_mfma_f32_16x16x32_bf16 v[120:123], v[160:163], v[168:171], v[120:123]
	v_mfma_f32_16x16x32_bf16 v[108:111], v[152:155], v[182:185], v[108:111]
	v_mfma_f32_16x16x32_bf16 v[104:107], v[160:163], v[182:185], v[104:107]
	v_mfma_f32_16x16x32_bf16 v[92:95], v[152:155], v[194:197], v[92:95]
	v_mfma_f32_16x16x32_bf16 v[88:91], v[160:163], v[194:197], v[88:91]
	v_mfma_f32_16x16x32_bf16 v[76:79], v[152:155], v[202:205], v[76:79]
	v_mfma_f32_16x16x32_bf16 v[72:75], v[160:163], v[202:205], v[72:75]
	v_mfma_f32_16x16x32_bf16 v[124:127], v[156:159], v[172:175], v[124:127]
	v_mfma_f32_16x16x32_bf16 v[120:123], v[164:167], v[172:175], v[120:123]
	v_mfma_f32_16x16x32_bf16 v[108:111], v[156:159], v[190:193], v[108:111]
	v_mfma_f32_16x16x32_bf16 v[104:107], v[164:167], v[190:193], v[104:107]
	v_mfma_f32_16x16x32_bf16 v[92:95], v[156:159], v[198:201], v[92:95]
	v_mfma_f32_16x16x32_bf16 v[88:91], v[164:167], v[198:201], v[88:91]
	v_mfma_f32_16x16x32_bf16 v[76:79], v[156:159], v[206:209], v[76:79]
	v_mfma_f32_16x16x32_bf16 v[72:75], v[164:167], v[206:209], v[72:75]
	s_barrier
	ds_read_b128 v[210:213], v151
	ds_read_b128 v[214:217], v151 offset:1024
	ds_read_b128 v[218:221], v151 offset:2048
	ds_read_b128 v[222:225], v151 offset:3072
	s_add_i32 s57, s45, s37
	v_lshl_add_u64 v[144:145], s[26:27], 0, v[130:131]
	s_mov_b32 m0, s57
	s_nop 0
	global_load_lds_dwordx4 v[144:145], off
	v_lshl_add_u64 v[186:187], s[26:27], 0, v[134:135]
	s_add_i32 m0, s57, 0x2000
	s_nop 0
	global_load_lds_dwordx4 v[186:187], off
	s_waitcnt lgkmcnt(0)
	s_barrier
	v_mfma_f32_16x16x32_bf16 v[116:119], v[210:213], v[168:171], v[116:119]
	v_mfma_f32_16x16x32_bf16 v[112:115], v[218:221], v[168:171], v[112:115]
	v_mfma_f32_16x16x32_bf16 v[100:103], v[210:213], v[182:185], v[100:103]
	v_mfma_f32_16x16x32_bf16 v[96:99], v[218:221], v[182:185], v[96:99]
	v_mfma_f32_16x16x32_bf16 v[84:87], v[210:213], v[194:197], v[84:87]
	v_mfma_f32_16x16x32_bf16 v[80:83], v[218:221], v[194:197], v[80:83]
	v_mfma_f32_16x16x32_bf16 v[68:71], v[210:213], v[202:205], v[68:71]
	v_mfma_f32_16x16x32_bf16 v[64:67], v[218:221], v[202:205], v[64:67]
	v_mfma_f32_16x16x32_bf16 v[116:119], v[214:217], v[172:175], v[116:119]
	v_mfma_f32_16x16x32_bf16 v[112:115], v[222:225], v[172:175], v[112:115]
	v_mfma_f32_16x16x32_bf16 v[100:103], v[214:217], v[190:193], v[100:103]
	v_mfma_f32_16x16x32_bf16 v[96:99], v[222:225], v[190:193], v[96:99]
	v_mfma_f32_16x16x32_bf16 v[84:87], v[214:217], v[198:201], v[84:87]
	v_mfma_f32_16x16x32_bf16 v[80:83], v[222:225], v[198:201], v[80:83]
	v_mfma_f32_16x16x32_bf16 v[68:71], v[214:217], v[206:209], v[68:71]
	v_mfma_f32_16x16x32_bf16 v[64:67], v[222:225], v[206:209], v[64:67]
	s_barrier
	s_mov_b32 m0, s23
	v_lshl_add_u64 v[226:227], s[28:29], 0, v[128:129]
	ds_read_b128 v[168:171], v150 offset:16384
	ds_read_b128 v[172:175], v150 offset:17408
	ds_read_b128 v[182:185], v150 offset:18432
	ds_read_b128 v[190:193], v150 offset:19456
	ds_read_b128 v[194:197], v150 offset:20480
	ds_read_b128 v[198:201], v150 offset:21504
	ds_read_b128 v[202:205], v150 offset:22528
	ds_read_b128 v[206:209], v150 offset:23552
	global_load_lds_dwordx4 v[226:227], off
	v_lshl_add_u64 v[228:229], s[28:29], 0, v[132:133]
	s_mov_b32 m0, s38
	s_nop 0
	global_load_lds_dwordx4 v[228:229], off
	s_waitcnt lgkmcnt(0)
	s_barrier
	v_mfma_f32_16x16x32_bf16 v[60:63], v[152:155], v[168:171], v[60:63]
	v_mfma_f32_16x16x32_bf16 v[56:59], v[160:163], v[168:171], v[56:59]
	v_mfma_f32_16x16x32_bf16 v[48:51], v[152:155], v[182:185], v[48:51]
	v_mfma_f32_16x16x32_bf16 v[40:43], v[160:163], v[182:185], v[40:43]
	v_mfma_f32_16x16x32_bf16 v[32:35], v[152:155], v[194:197], v[32:35]
	v_mfma_f32_16x16x32_bf16 v[24:27], v[160:163], v[194:197], v[24:27]
	v_mfma_f32_16x16x32_bf16 v[16:19], v[152:155], v[202:205], v[16:19]
	v_mfma_f32_16x16x32_bf16 v[8:11], v[160:163], v[202:205], v[8:11]
	v_mfma_f32_16x16x32_bf16 v[60:63], v[156:159], v[172:175], v[60:63]
	v_mfma_f32_16x16x32_bf16 v[56:59], v[164:167], v[172:175], v[56:59]
	v_mfma_f32_16x16x32_bf16 v[48:51], v[156:159], v[190:193], v[48:51]
	v_mfma_f32_16x16x32_bf16 v[40:43], v[164:167], v[190:193], v[40:43]
	v_mfma_f32_16x16x32_bf16 v[32:35], v[156:159], v[198:201], v[32:35]
	v_mfma_f32_16x16x32_bf16 v[24:27], v[164:167], v[198:201], v[24:27]
	v_mfma_f32_16x16x32_bf16 v[16:19], v[156:159], v[206:209], v[16:19]
	v_mfma_f32_16x16x32_bf16 v[8:11], v[164:167], v[206:209], v[8:11]
	s_barrier
; #define PG8_STAGE(bufoff, gbase, voff) do { _Pragma("unroll") for (int _i = 0; _i < 2; ++_i) \
;         __builtin_amdgcn_global_load_lds((const unsigned*)((const char*)(gbase) + (voff)[_i]), (PG8_LAS unsigned*)(lds + (bufoff) + ldsw + _i * 8192), 16, 0, 0); } while (0)
; #define PG8_LDA(dst, b, h) do { _Pragma("unroll") for (int m = 0; m < 4; ++m) _Pragma("unroll") for (int k = 0; k < 2; ++k) dst[m][k] = *(const PG8_LAS bf16x8*)(lds + PG8_SA(b, h) + aoff + m * 2048 + k * 1024); } while (0)
; #define PG8_LDB(dst, b, h) do { _Pragma("unroll") for (int n = 0; n < 2; ++n) _Pragma("unroll") for (int k = 0; k < 2; ++k) dst[n][k] = *(const PG8_LAS bf16x8*)(lds + PG8_SB(b, h) + boff + n * 2048 + k * 1024); } while (0)
; #define PG8_MMA(ai, bj, At, Bt) do { __builtin_amdgcn_s_setprio(1); _Pragma("unroll") for (int m = 0; m < 4; ++m) _Pragma("unroll") for (int n = 0; n < 2; ++n) _Pragma("unroll") for (int k = 0; k < 2; ++k) \
;         acc[ai][bj][m][n] = __builtin_amdgcn_mfma_f32_16x16x32_bf16(Bt[n][k], At[m][k], acc[ai][bj][m][n], 0, 0, 0); __builtin_amdgcn_s_setprio(0); } while (0)
; #define PG8_WAIT_V(n) asm volatile("s_waitcnt vmcnt(" #n ")" ::: "memory")
; #define PG8_WAIT_L(n) asm volatile("s_waitcnt lgkmcnt(" #n ")" ::: "memory")
; #define PG8_BAR __builtin_amdgcn_s_barrier()
; #define PG8_SCHED __builtin_amdgcn_sched_barrier(0)
; template <class Epi, class Sched>
; __device__ __forceinline__ void gemm_phase(PG8_LAS unsigned char* lds, const Gemm g, const Sched& S, const Epi& E) {
;     ...
;             PG8_STAGE(PG8_SB(0, 1), b2 + hstep, voffB);
;             PG8_WAIT_V(6); PG8_BAR; PG8_MMA(1, 1, At, B1); PG8_BAR;
;             PG8_LDB(B0, 1, 0); PG8_SCHED; PG8_LDA(At, 1, 0); PG8_STAGE(PG8_SA(0, 1), a2 + hstep, voffA);
;             PG8_WAIT_L(8); PG8_BAR; PG8_WAIT_L(0); PG8_MMA(0, 0, At, B0); PG8_BAR; PG8_SCHED;
;             PG8_LDB(B1, 1, 1); PG8_STAGE(PG8_SB(1, 0), b3, voffB);
;             PG8_BAR; PG8_WAIT_L(0); PG8_MMA(0, 1, At, B1); PG8_BAR;
;             PG8_LDA(At, 1, 1); PG8_STAGE(PG8_SA(1, 0), a3, voffA);
	s_add_u32 s58, s26, 0x40000
	s_addc_u32 s59, s27, 0
	s_add_i32 s57, s46, s37
	v_lshl_add_u64 v[152:153], s[58:59], 0, v[130:131]
	s_mov_b32 m0, s57
	s_nop 0
	global_load_lds_dwordx4 v[152:153], off
	v_lshl_add_u64 v[152:153], s[58:59], 0, v[134:135]
	s_add_i32 m0, s57, 0x2000
	s_nop 0
	global_load_lds_dwordx4 v[152:153], off
	s_waitcnt vmcnt(6)
	s_barrier
	v_mfma_f32_16x16x32_bf16 v[52:55], v[210:213], v[168:171], v[52:55]
	v_mfma_f32_16x16x32_bf16 v[44:47], v[218:221], v[168:171], v[44:47]
	v_mfma_f32_16x16x32_bf16 v[36:39], v[210:213], v[182:185], v[36:39]
	v_mfma_f32_16x16x32_bf16 v[28:31], v[218:221], v[182:185], v[28:31]
	v_mfma_f32_16x16x32_bf16 v[20:23], v[210:213], v[194:197], v[20:23]
	v_mfma_f32_16x16x32_bf16 v[12:15], v[218:221], v[194:197], v[12:15]
	v_mfma_f32_16x16x32_bf16 v[4:7], v[210:213], v[202:205], v[4:7]
	v_mfma_f32_16x16x32_bf16 v[0:3], v[218:221], v[202:205], v[0:3]
	v_mfma_f32_16x16x32_bf16 v[52:55], v[214:217], v[172:175], v[52:55]
	v_mfma_f32_16x16x32_bf16 v[44:47], v[222:225], v[172:175], v[44:47]
	v_mfma_f32_16x16x32_bf16 v[36:39], v[214:217], v[190:193], v[36:39]
	v_mfma_f32_16x16x32_bf16 v[28:31], v[222:225], v[190:193], v[28:31]
	v_mfma_f32_16x16x32_bf16 v[20:23], v[214:217], v[198:201], v[20:23]
	v_mfma_f32_16x16x32_bf16 v[12:15], v[222:225], v[198:201], v[12:15]
	v_mfma_f32_16x16x32_bf16 v[4:7], v[214:217], v[206:209], v[4:7]
	v_mfma_f32_16x16x32_bf16 v[0:3], v[222:225], v[206:209], v[0:3]
	s_barrier
	s_add_i32 s57, 0, 0x18000
	v_add_u32_e32 v164, s57, v147
	ds_read_b128 v[152:155], v164
	ds_read_b128 v[156:159], v164 offset:1024
	ds_read_b128 v[160:163], v164 offset:2048
	ds_read_b128 v[164:167], v164 offset:3072
	ds_read_b128 v[168:171], v150 offset:32768
	ds_read_b128 v[172:175], v150 offset:33792
	ds_read_b128 v[182:185], v150 offset:34816
	ds_read_b128 v[190:193], v150 offset:35840
	ds_read_b128 v[194:197], v150 offset:36864
	ds_read_b128 v[198:201], v150 offset:37888
	ds_read_b128 v[202:205], v150 offset:38912
	ds_read_b128 v[206:209], v150 offset:39936
	s_add_u32 s28, s28, 0x40000
	s_addc_u32 s29, s29, 0
	s_mov_b32 m0, s39
	v_lshl_add_u64 v[210:211], s[28:29], 0, v[128:129]
	global_load_lds_dwordx4 v[210:211], off
	v_lshl_add_u64 v[210:211], s[28:29], 0, v[132:133]
	s_mov_b32 m0, s40
	s_nop 0
	global_load_lds_dwordx4 v[210:211], off
	s_waitcnt lgkmcnt(0)
	s_barrier
	v_mfma_f32_16x16x32_bf16 v[124:127], v[152:155], v[168:171], v[124:127]
	v_mfma_f32_16x16x32_bf16 v[120:123], v[160:163], v[168:171], v[120:123]
	v_mfma_f32_16x16x32_bf16 v[108:111], v[152:155], v[182:185], v[108:111]
	v_mfma_f32_16x16x32_bf16 v[104:107], v[160:163], v[182:185], v[104:107]
	v_mfma_f32_16x16x32_bf16 v[92:95], v[152:155], v[194:197], v[92:95]
	v_mfma_f32_16x16x32_bf16 v[88:91], v[160:163], v[194:197], v[88:91]
	v_mfma_f32_16x16x32_bf16 v[76:79], v[152:155], v[202:205], v[76:79]
	v_mfma_f32_16x16x32_bf16 v[72:75], v[160:163], v[202:205], v[72:75]
	v_mfma_f32_16x16x32_bf16 v[124:127], v[156:159], v[172:175], v[124:127]
	v_mfma_f32_16x16x32_bf16 v[120:123], v[164:167], v[172:175], v[120:123]
	v_mfma_f32_16x16x32_bf16 v[108:111], v[156:159], v[190:193], v[108:111]
	v_mfma_f32_16x16x32_bf16 v[104:107], v[164:167], v[190:193], v[104:107]
	v_mfma_f32_16x16x32_bf16 v[92:95], v[156:159], v[198:201], v[92:95]
	v_mfma_f32_16x16x32_bf16 v[88:91], v[164:167], v[198:201], v[88:91]
	v_mfma_f32_16x16x32_bf16 v[76:79], v[156:159], v[206:209], v[76:79]
	v_mfma_f32_16x16x32_bf16 v[72:75], v[164:167], v[206:209], v[72:75]
	s_barrier
	s_add_i32 s28, 0, 0x1c000
	v_add_u32_e32 v179, s28, v147
	ds_read_b128 v[210:213], v179
	ds_read_b128 v[214:217], v179 offset:1024
	ds_read_b128 v[218:221], v179 offset:2048
	ds_read_b128 v[222:225], v179 offset:3072
	s_add_i32 s29, s57, s37
	v_lshl_add_u64 v[144:145], v[144:145], 0, s[6:7]
	s_mov_b32 m0, s29
	s_nop 0
	global_load_lds_dwordx4 v[144:145], off
	v_lshl_add_u64 v[144:145], v[186:187], 0, s[6:7]
	s_add_i32 m0, s29, 0x2000
	s_nop 0
	global_load_lds_dwordx4 v[144:145], off
	s_waitcnt lgkmcnt(0)
	s_barrier
	v_mfma_f32_16x16x32_bf16 v[116:119], v[210:213], v[168:171], v[116:119]
	v_mfma_f32_16x16x32_bf16 v[112:115], v[218:221], v[168:171], v[112:115]
	v_mfma_f32_16x16x32_bf16 v[100:103], v[210:213], v[182:185], v[100:103]
	v_mfma_f32_16x16x32_bf16 v[96:99], v[218:221], v[182:185], v[96:99]
	v_mfma_f32_16x16x32_bf16 v[84:87], v[210:213], v[194:197], v[84:87]
	v_mfma_f32_16x16x32_bf16 v[80:83], v[218:221], v[194:197], v[80:83]
	v_mfma_f32_16x16x32_bf16 v[68:71], v[210:213], v[202:205], v[68:71]
	v_mfma_f32_16x16x32_bf16 v[64:67], v[218:221], v[202:205], v[64:67]
	v_mfma_f32_16x16x32_bf16 v[116:119], v[214:217], v[172:175], v[116:119]
	v_mfma_f32_16x16x32_bf16 v[112:115], v[222:225], v[172:175], v[112:115]
	v_mfma_f32_16x16x32_bf16 v[100:103], v[214:217], v[190:193], v[100:103]
	v_mfma_f32_16x16x32_bf16 v[96:99], v[222:225], v[190:193], v[96:99]
	v_mfma_f32_16x16x32_bf16 v[84:87], v[214:217], v[198:201], v[84:87]
	v_mfma_f32_16x16x32_bf16 v[80:83], v[222:225], v[198:201], v[80:83]
	v_mfma_f32_16x16x32_bf16 v[68:71], v[214:217], v[206:209], v[68:71]
	v_mfma_f32_16x16x32_bf16 v[64:67], v[222:225], v[206:209], v[64:67]
	s_barrier
	s_mov_b32 m0, s42
	v_lshl_add_u64 v[144:145], v[226:227], 0, s[6:7]
	ds_read_b128 v[168:171], v150 offset:49152
	ds_read_b128 v[172:175], v150 offset:50176
	ds_read_b128 v[182:185], v150 offset:51200
	ds_read_b128 v[190:193], v150 offset:52224
	ds_read_b128 v[194:197], v150 offset:53248
	ds_read_b128 v[198:201], v150 offset:54272
	ds_read_b128 v[202:205], v150 offset:55296
	ds_read_b128 v[206:209], v150 offset:56320
	global_load_lds_dwordx4 v[144:145], off
	v_lshl_add_u64 v[144:145], v[228:229], 0, s[6:7]
	s_mov_b32 m0, s43
	s_nop 0
	global_load_lds_dwordx4 v[144:145], off
	s_waitcnt lgkmcnt(0)
	s_barrier
; __device__ __forceinline__ unsigned cvt_pk_bf16(float lo, float hi) { unsigned r; asm volatile("v_cvt_pk_bf16_f32 %0, %1, %2" : "=v"(r) : "v"(lo), "v"(hi)); return r; }
; __device__ __forceinline__ float flogsig16(float x) { return (fminf(x, 0.f) - __logf(1.0f + __expf(-fabsf(x)))) * 0.0625f; }
; #define PG8_WAIT_V(n) asm volatile("s_waitcnt vmcnt(" #n ")" ::: "memory")
; #define PG8_WAIT_L(n) asm volatile("s_waitcnt lgkmcnt(" #n ")" ::: "memory")
;     __device__ __forceinline__ void operator()(const f32x4 (&acc)[2][2][4][2], const Unit& u, int wr, int wc, int fr, int fq) const {
;     ...
;         const int row0 = u.pm * BM + wr * 64 + fr, col0 = u.pn * BM + wc * 32 + 8 * fq, bcol0 = wc * 32 + 8 * fq;
;         f32x4 bv[2][2];
; #pragma unroll
;         for (int bj = 0; bj < 2; ++bj)
; #pragma unroll
;             for (int n = 0; n < 2; ++n) bv[bj][n] = bias ? *(const f32x4*)(bias + bcol0 + bj * HALF + 4 * n) : (f32x4){0.f, 0.f, 0.f, 0.f};
; #pragma unroll
;         for (int ai = 0; ai < 2; ++ai)
; #pragma unroll
;             for (int m = 0; m < 4; ++m) { bf16_t* rowp = O + (size_t)(row0 + ai * HALF + m * 16) * ldc + col0;
; #pragma unroll
;                 for (int bj = 0; bj < 2; ++bj) { f32x4 v0 = acc[ai][bj][m][0] + bv[bj][0], v1 = acc[ai][bj][m][1] + bv[bj][1];
;                     if (act == 1) {
; #pragma unroll
;                         for (int j = 0; j < 1; ++j) { v0 = v0 * sigmoid4(v0); v1 = v1 * sigmoid4(v1); } }
;                     else if (act == 2) {
; #pragma unroll
;                         for (int j = 0; j < 1; ++j) { v0 = sigmoid4(v0); v1 = sigmoid4(v1); } }
;                     else if (act == 3) {
; #pragma unroll
;                         for (int j = 0; j < 4; ++j) { v0[j] = flogsig16(v0[j]); v1[j] = flogsig16(v1[j]); } }
;                     u32x4 w; w.x = cvt_pk_bf16(v0[0], v0[1]); w.y = cvt_pk_bf16(v0[2], v0[3]); w.z = cvt_pk_bf16(v1[0], v1[1]); w.w = cvt_pk_bf16(v1[2], v1[3]);
;                     *(u32x4*)(rowp + bj * HALF) = w; } }
; template <class Epi, class Sched>
; __device__ __forceinline__ void gemm_phase(PG8_LAS unsigned char* lds, const Gemm g, const Sched& S, const Epi& E) {
;     ...
;             PG8_BAR; PG8_WAIT_L(0); PG8_MMA(1, 0, At, B0); PG8_BAR; PG8_SCHED;
;             PG8_STAGE(PG8_SB(1, 1), b3 + hstep, voffB);
;             PG8_WAIT_V(6); PG8_BAR; PG8_MMA(1, 1, At, B1); PG8_BAR;
	v_mfma_f32_16x16x32_bf16 v[60:63], v[152:155], v[168:171], v[60:63]
	v_mfma_f32_16x16x32_bf16 v[56:59], v[160:163], v[168:171], v[56:59]
	v_mfma_f32_16x16x32_bf16 v[48:51], v[152:155], v[182:185], v[48:51]
	v_mfma_f32_16x16x32_bf16 v[40:43], v[160:163], v[182:185], v[40:43]
	v_mfma_f32_16x16x32_bf16 v[32:35], v[152:155], v[194:197], v[32:35]
	v_mfma_f32_16x16x32_bf16 v[24:27], v[160:163], v[194:197], v[24:27]
	v_mfma_f32_16x16x32_bf16 v[16:19], v[152:155], v[202:205], v[16:19]
	v_mfma_f32_16x16x32_bf16 v[8:11], v[160:163], v[202:205], v[8:11]
	v_mfma_f32_16x16x32_bf16 v[60:63], v[156:159], v[172:175], v[60:63]
	v_mfma_f32_16x16x32_bf16 v[56:59], v[164:167], v[172:175], v[56:59]
	v_mfma_f32_16x16x32_bf16 v[48:51], v[156:159], v[190:193], v[48:51]
	v_mfma_f32_16x16x32_bf16 v[40:43], v[164:167], v[190:193], v[40:43]
	v_mfma_f32_16x16x32_bf16 v[32:35], v[156:159], v[198:201], v[32:35]
	v_mfma_f32_16x16x32_bf16 v[24:27], v[164:167], v[198:201], v[24:27]
	v_mfma_f32_16x16x32_bf16 v[16:19], v[156:159], v[206:209], v[16:19]
	v_mfma_f32_16x16x32_bf16 v[8:11], v[164:167], v[206:209], v[8:11]
	s_barrier
	s_add_u32 s26, s26, 0x40080
	s_addc_u32 s27, s27, 0
	s_add_i32 s28, s28, s37
	v_lshl_add_u64 v[144:145], s[26:27], 0, v[130:131]
	s_mov_b32 m0, s28
	s_nop 0
	global_load_lds_dwordx4 v[144:145], off
	v_lshl_add_u64 v[144:145], s[26:27], 0, v[134:135]
	s_add_i32 m0, s28, 0x2000
	s_nop 0
	global_load_lds_dwordx4 v[144:145], off
	s_waitcnt vmcnt(6)
	s_barrier
	v_mfma_f32_16x16x32_bf16 v[52:55], v[210:213], v[168:171], v[52:55]
	v_mfma_f32_16x16x32_bf16 v[44:47], v[218:221], v[168:171], v[44:47]
	v_mfma_f32_16x16x32_bf16 v[36:39], v[210:213], v[182:185], v[36:39]
	v_mfma_f32_16x16x32_bf16 v[28:31], v[218:221], v[182:185], v[28:31]
	v_mfma_f32_16x16x32_bf16 v[20:23], v[210:213], v[194:197], v[20:23]
	v_mfma_f32_16x16x32_bf16 v[12:15], v[218:221], v[194:197], v[12:15]
	v_mfma_f32_16x16x32_bf16 v[4:7], v[210:213], v[202:205], v[4:7]
	v_mfma_f32_16x16x32_bf16 v[0:3], v[218:221], v[202:205], v[0:3]
	v_mfma_f32_16x16x32_bf16 v[52:55], v[214:217], v[172:175], v[52:55]
	v_mfma_f32_16x16x32_bf16 v[44:47], v[222:225], v[172:175], v[44:47]
	v_mfma_f32_16x16x32_bf16 v[36:39], v[214:217], v[190:193], v[36:39]
	v_mfma_f32_16x16x32_bf16 v[28:31], v[222:225], v[190:193], v[28:31]
	v_mfma_f32_16x16x32_bf16 v[20:23], v[214:217], v[198:201], v[20:23]
	v_mfma_f32_16x16x32_bf16 v[12:15], v[222:225], v[198:201], v[12:15]
	v_mfma_f32_16x16x32_bf16 v[4:7], v[214:217], v[206:209], v[4:7]
	v_mfma_f32_16x16x32_bf16 v[0:3], v[222:225], v[206:209], v[0:3]
	s_barrier
	s_add_i32 s56, s56, 2
	s_add_u32 s24, s24, 0x100
	s_addc_u32 s25, s25, 0
	s_add_u32 s54, s54, 0x100
	s_addc_u32 s55, s55, 0
	s_cmp_gt_u32 s56, 13
	s_cbranch_scc0 .LBB0_1083
	v_lshl_add_u32 v152, s22, 8, v146
	v_lshl_or_b32 v144, s51, 8, v148
	v_ashrrev_i32_e32 v153, 31, v152
	v_ashrrev_i32_e32 v145, 31, v144
	v_lshlrev_b64 v[154:155], 11, v[152:153]
	v_lshl_add_u64 v[154:155], s[4:5], 0, v[154:155]
	v_lshlrev_b64 v[156:157], 1, v[144:145]
	v_lshl_add_u64 v[144:145], v[154:155], 0, v[156:157]
	v_pk_add_f32 v[126:127], v[126:127], 0 op_sel_hi:[1,0]
	v_pk_add_f32 v[124:125], v[124:125], 0 op_sel_hi:[1,0]
	v_pk_add_f32 v[154:155], v[122:123], 0 op_sel_hi:[1,0]
	v_pk_add_f32 v[122:123], v[120:121], 0 op_sel_hi:[1,0]
	v_cvt_pk_bf16_f32 v120, v124, v125
	v_cvt_pk_bf16_f32 v121, v126, v127
	v_pk_add_f32 v[116:117], v[116:117], 0 op_sel_hi:[1,0]
	v_cvt_pk_bf16_f32 v122, v122, v123
	v_cvt_pk_bf16_f32 v123, v154, v155
	global_store_dwordx4 v[144:145], v[120:123], off
	v_pk_add_f32 v[118:119], v[118:119], 0 op_sel_hi:[1,0]
	v_pk_add_f32 v[110:111], v[110:111], 0 op_sel_hi:[1,0]
	v_pk_add_f32 v[120:121], v[114:115], 0 op_sel_hi:[1,0]
	v_pk_add_f32 v[114:115], v[112:113], 0 op_sel_hi:[1,0]
	v_cvt_pk_bf16_f32 v112, v116, v117
	v_cvt_pk_bf16_f32 v113, v118, v119
	v_pk_add_f32 v[108:109], v[108:109], 0 op_sel_hi:[1,0]
	v_cvt_pk_bf16_f32 v114, v114, v115
	v_cvt_pk_bf16_f32 v115, v120, v121
	global_store_dwordx4 v[144:145], v[112:115], off offset:256
	v_pk_add_f32 v[100:101], v[100:101], 0 op_sel_hi:[1,0]
	v_pk_add_f32 v[102:103], v[102:103], 0 op_sel_hi:[1,0]
	v_or_b32_e32 v112, 16, v152
	v_ashrrev_i32_e32 v113, 31, v112
	v_lshlrev_b64 v[112:113], 11, v[112:113]
	v_lshl_add_u64 v[112:113], s[4:5], 0, v[112:113]
	v_lshl_add_u64 v[112:113], v[112:113], 0, v[156:157]
	v_pk_add_f32 v[114:115], v[106:107], 0 op_sel_hi:[1,0]
	v_pk_add_f32 v[106:107], v[104:105], 0 op_sel_hi:[1,0]
	v_cvt_pk_bf16_f32 v104, v108, v109
	v_cvt_pk_bf16_f32 v105, v110, v111
	v_pk_add_f32 v[94:95], v[94:95], 0 op_sel_hi:[1,0]
	v_cvt_pk_bf16_f32 v106, v106, v107
	v_cvt_pk_bf16_f32 v107, v114, v115
	global_store_dwordx4 v[112:113], v[104:107], off
	v_pk_add_f32 v[92:93], v[92:93], 0 op_sel_hi:[1,0]
	v_pk_add_f32 v[84:85], v[84:85], 0 op_sel_hi:[1,0]
	v_pk_add_f32 v[104:105], v[98:99], 0 op_sel_hi:[1,0]
	v_pk_add_f32 v[98:99], v[96:97], 0 op_sel_hi:[1,0]
	v_cvt_pk_bf16_f32 v96, v100, v101
	v_cvt_pk_bf16_f32 v97, v102, v103
	v_pk_add_f32 v[86:87], v[86:87], 0 op_sel_hi:[1,0]
	v_cvt_pk_bf16_f32 v98, v98, v99
	v_cvt_pk_bf16_f32 v99, v104, v105
	global_store_dwordx4 v[112:113], v[96:99], off offset:256
	v_pk_add_f32 v[78:79], v[78:79], 0 op_sel_hi:[1,0]
	v_pk_add_f32 v[76:77], v[76:77], 0 op_sel_hi:[1,0]
	v_or_b32_e32 v96, 32, v152
	v_ashrrev_i32_e32 v97, 31, v96
	v_lshlrev_b64 v[96:97], 11, v[96:97]
	v_lshl_add_u64 v[96:97], s[4:5], 0, v[96:97]
; __device__ __forceinline__ unsigned cvt_pk_bf16(float lo, float hi) { unsigned r; asm volatile("v_cvt_pk_bf16_f32 %0, %1, %2" : "=v"(r) : "v"(lo), "v"(hi)); return r; }
; __device__ __forceinline__ float flogsig16(float x) { return (fminf(x, 0.f) - __logf(1.0f + __expf(-fabsf(x)))) * 0.0625f; }
;     __device__ __forceinline__ void operator()(const f32x4 (&acc)[2][2][4][2], const Unit& u, int wr, int wc, int fr, int fq) const {
;     ...
;         for (int ai = 0; ai < 2; ++ai)
; #pragma unroll
;             for (int m = 0; m < 4; ++m) { bf16_t* rowp = O + (size_t)(row0 + ai * HALF + m * 16) * ldc + col0;
; #pragma unroll
;                 for (int bj = 0; bj < 2; ++bj) { f32x4 v0 = acc[ai][bj][m][0] + bv[bj][0], v1 = acc[ai][bj][m][1] + bv[bj][1];
;                     if (act == 1) {
; #pragma unroll
;                         for (int j = 0; j < 1; ++j) { v0 = v0 * sigmoid4(v0); v1 = v1 * sigmoid4(v1); } }
;                     else if (act == 2) {
; #pragma unroll
;                         for (int j = 0; j < 1; ++j) { v0 = sigmoid4(v0); v1 = sigmoid4(v1); } }
;                     else if (act == 3) {
; #pragma unroll
;                         for (int j = 0; j < 4; ++j) { v0[j] = flogsig16(v0[j]); v1[j] = flogsig16(v1[j]); } }
;                     u32x4 w; w.x = cvt_pk_bf16(v0[0], v0[1]); w.y = cvt_pk_bf16(v0[2], v0[3]); w.z = cvt_pk_bf16(v1[0], v1[1]); w.w = cvt_pk_bf16(v1[2], v1[3]);
;                     *(u32x4*)(rowp + bj * HALF) = w; } }
	v_lshl_add_u64 v[96:97], v[96:97], 0, v[156:157]
	v_pk_add_f32 v[98:99], v[90:91], 0 op_sel_hi:[1,0]
	v_pk_add_f32 v[90:91], v[88:89], 0 op_sel_hi:[1,0]
	v_cvt_pk_bf16_f32 v88, v92, v93
	v_cvt_pk_bf16_f32 v89, v94, v95
	v_pk_add_f32 v[70:71], v[70:71], 0 op_sel_hi:[1,0]
	v_cvt_pk_bf16_f32 v90, v90, v91
	v_cvt_pk_bf16_f32 v91, v98, v99
	global_store_dwordx4 v[96:97], v[88:91], off
	v_pk_add_f32 v[68:69], v[68:69], 0 op_sel_hi:[1,0]
	v_pk_add_f32 v[60:61], v[60:61], 0 op_sel_hi:[1,0]
	v_pk_add_f32 v[88:89], v[82:83], 0 op_sel_hi:[1,0]
	v_pk_add_f32 v[82:83], v[80:81], 0 op_sel_hi:[1,0]
	v_cvt_pk_bf16_f32 v80, v84, v85
	v_cvt_pk_bf16_f32 v81, v86, v87
	v_pk_add_f32 v[62:63], v[62:63], 0 op_sel_hi:[1,0]
	v_cvt_pk_bf16_f32 v82, v82, v83
	v_cvt_pk_bf16_f32 v83, v88, v89
	global_store_dwordx4 v[96:97], v[80:83], off offset:256
	v_pk_add_f32 v[54:55], v[54:55], 0 op_sel_hi:[1,0]
	v_pk_add_f32 v[52:53], v[52:53], 0 op_sel_hi:[1,0]
	v_or_b32_e32 v80, 48, v152
	v_ashrrev_i32_e32 v81, 31, v80
	v_lshlrev_b64 v[80:81], 11, v[80:81]
	v_lshl_add_u64 v[80:81], s[4:5], 0, v[80:81]
	v_lshl_add_u64 v[80:81], v[80:81], 0, v[156:157]
	v_pk_add_f32 v[82:83], v[74:75], 0 op_sel_hi:[1,0]
	v_pk_add_f32 v[74:75], v[72:73], 0 op_sel_hi:[1,0]
	v_cvt_pk_bf16_f32 v72, v76, v77
	v_cvt_pk_bf16_f32 v73, v78, v79
	v_pk_add_f32 v[48:49], v[48:49], 0 op_sel_hi:[1,0]
	v_cvt_pk_bf16_f32 v74, v74, v75
	v_cvt_pk_bf16_f32 v75, v82, v83
	global_store_dwordx4 v[80:81], v[72:75], off
	v_pk_add_f32 v[38:39], v[38:39], 0 op_sel_hi:[1,0]
	v_pk_add_f32 v[36:37], v[36:37], 0 op_sel_hi:[1,0]
	v_pk_add_f32 v[72:73], v[66:67], 0 op_sel_hi:[1,0]
	v_pk_add_f32 v[66:67], v[64:65], 0 op_sel_hi:[1,0]
	v_cvt_pk_bf16_f32 v64, v68, v69
	v_cvt_pk_bf16_f32 v65, v70, v71
	v_pk_add_f32 v[32:33], v[32:33], 0 op_sel_hi:[1,0]
	v_cvt_pk_bf16_f32 v66, v66, v67
	v_cvt_pk_bf16_f32 v67, v72, v73
	global_store_dwordx4 v[80:81], v[64:67], off offset:256
	v_pk_add_f32 v[22:23], v[22:23], 0 op_sel_hi:[1,0]
	v_pk_add_f32 v[20:21], v[20:21], 0 op_sel_hi:[1,0]
	v_pk_add_f32 v[66:67], v[58:59], 0 op_sel_hi:[1,0]
	v_pk_add_f32 v[58:59], v[56:57], 0 op_sel_hi:[1,0]
	v_cvt_pk_bf16_f32 v56, v60, v61
	v_add_co_u32_e32 v60, vcc, s47, v144
	v_cvt_pk_bf16_f32 v57, v62, v63
	v_cvt_pk_bf16_f32 v58, v58, v59
	v_cvt_pk_bf16_f32 v59, v66, v67
	v_lshl_add_u64 v[64:65], v[144:145], 0, s[0:1]
	s_nop 0
	v_addc_co_u32_e32 v61, vcc, 0, v145, vcc
	global_store_dwordx4 v[60:61], v[56:59], off
	v_pk_add_f32 v[16:17], v[16:17], 0 op_sel_hi:[1,0]
	s_mov_b32 s51, s14
	v_pk_add_f32 v[56:57], v[46:47], 0 op_sel_hi:[1,0]
	v_pk_add_f32 v[46:47], v[44:45], 0 op_sel_hi:[1,0]
	v_cvt_pk_bf16_f32 v44, v52, v53
	v_cvt_pk_bf16_f32 v45, v54, v55
	s_mov_b32 s22, s16
	v_cvt_pk_bf16_f32 v46, v46, v47
	v_cvt_pk_bf16_f32 v47, v56, v57
	global_store_dwordx4 v[64:65], v[44:47], off offset:256
	s_mov_b64 s[26:27], s[20:21]
	s_mov_b64 s[24:25], s[18:19]
	v_pk_add_f32 v[46:47], v[50:51], 0 op_sel_hi:[1,0]
	v_pk_add_f32 v[50:51], v[42:43], 0 op_sel_hi:[1,0]
	v_pk_add_f32 v[42:43], v[40:41], 0 op_sel_hi:[1,0]
	v_cvt_pk_bf16_f32 v40, v48, v49
	v_cvt_pk_bf16_f32 v41, v46, v47
	v_add_co_u32_e32 v46, vcc, s48, v144
	v_cvt_pk_bf16_f32 v42, v42, v43
	v_cvt_pk_bf16_f32 v43, v50, v51
	v_lshl_add_u64 v[44:45], v[144:145], 0, s[8:9]
	s_nop 0
	v_addc_co_u32_e32 v47, vcc, 0, v145, vcc
	global_store_dwordx4 v[46:47], v[40:43], off
	v_pk_add_f32 v[6:7], v[6:7], 0 op_sel_hi:[1,0]
	v_pk_add_f32 v[4:5], v[4:5], 0 op_sel_hi:[1,0]
	v_pk_add_f32 v[40:41], v[30:31], 0 op_sel_hi:[1,0]
	v_pk_add_f32 v[30:31], v[28:29], 0 op_sel_hi:[1,0]
	v_cvt_pk_bf16_f32 v28, v36, v37
	v_cvt_pk_bf16_f32 v29, v38, v39
	s_nop 0
	v_cvt_pk_bf16_f32 v30, v30, v31
	v_cvt_pk_bf16_f32 v31, v40, v41
	global_store_dwordx4 v[44:45], v[28:31], off offset:256
	s_nop 1
	v_pk_add_f32 v[30:31], v[34:35], 0 op_sel_hi:[1,0]
	v_pk_add_f32 v[34:35], v[26:27], 0 op_sel_hi:[1,0]
	v_pk_add_f32 v[26:27], v[24:25], 0 op_sel_hi:[1,0]
	v_cvt_pk_bf16_f32 v24, v32, v33
	v_cvt_pk_bf16_f32 v25, v30, v31
	v_add_co_u32_e32 v30, vcc, s49, v144
	v_cvt_pk_bf16_f32 v26, v26, v27
	v_cvt_pk_bf16_f32 v27, v34, v35
	v_lshl_add_u64 v[28:29], v[144:145], 0, s[10:11]
	s_nop 0
	v_addc_co_u32_e32 v31, vcc, 0, v145, vcc
	global_store_dwordx4 v[30:31], v[24:27], off
	s_nop 1
	v_pk_add_f32 v[24:25], v[14:15], 0 op_sel_hi:[1,0]
	v_pk_add_f32 v[14:15], v[12:13], 0 op_sel_hi:[1,0]
	v_cvt_pk_bf16_f32 v12, v20, v21
	v_cvt_pk_bf16_f32 v13, v22, v23
	s_nop 0
	v_cvt_pk_bf16_f32 v14, v14, v15
	v_cvt_pk_bf16_f32 v15, v24, v25
	global_store_dwordx4 v[28:29], v[12:15], off offset:256
	s_nop 1
	v_pk_add_f32 v[14:15], v[18:19], 0 op_sel_hi:[1,0]
	v_pk_add_f32 v[18:19], v[10:11], 0 op_sel_hi:[1,0]
	v_pk_add_f32 v[10:11], v[8:9], 0 op_sel_hi:[1,0]
	v_cvt_pk_bf16_f32 v8, v16, v17
	v_cvt_pk_bf16_f32 v9, v14, v15
	v_add_co_u32_e32 v14, vcc, s50, v144
	v_lshl_add_u64 v[12:13], v[144:145], 0, s[12:13]
	s_nop 0
	v_addc_co_u32_e32 v15, vcc, 0, v145, vcc
	v_cvt_pk_bf16_f32 v10, v10, v11
	v_cvt_pk_bf16_f32 v11, v18, v19
	global_store_dwordx4 v[14:15], v[8:11], off
	s_and_b64 vcc, exec, s[2:3]
	s_nop 0
	v_pk_add_f32 v[8:9], v[2:3], 0 op_sel_hi:[1,0]
	v_pk_add_f32 v[2:3], v[0:1], 0 op_sel_hi:[1,0]
	v_cvt_pk_bf16_f32 v0, v4, v5
	v_cvt_pk_bf16_f32 v1, v6, v7
	s_nop 0
	v_cvt_pk_bf16_f32 v2, v2, v3
	v_cvt_pk_bf16_f32 v3, v8, v9
	global_store_dwordx4 v[12:13], v[0:3], off offset:256
	s_cbranch_vccz .LBB0_1076
	s_waitcnt vmcnt(0)
	s_cmpk_gt_u32 s31, 0xff
	s_cbranch_scc1 .LBB0_1087
	s_barrier

; #define PG8_STAGE(bufoff, gbase, voff) do { _Pragma("unroll") for (int _i = 0; _i < 2; ++_i) \
;         __builtin_amdgcn_global_load_lds((const unsigned*)((const char*)(gbase) + (voff)[_i]), (PG8_LAS unsigned*)(lds + (bufoff) + ldsw + _i * 8192), 16, 0, 0); } while (0)
; #define PG8_LDA(dst, b, h) do { _Pragma("unroll") for (int m = 0; m < 4; ++m) _Pragma("unroll") for (int k = 0; k < 2; ++k) dst[m][k] = *(const PG8_LAS bf16x8*)(lds + PG8_SA(b, h) + aoff + m * 2048 + k * 1024); } while (0)
; #define PG8_LDB(dst, b, h) do { _Pragma("unroll") for (int n = 0; n < 2; ++n) _Pragma("unroll") for (int k = 0; k < 2; ++k) dst[n][k] = *(const PG8_LAS bf16x8*)(lds + PG8_SB(b, h) + boff + n * 2048 + k * 1024); } while (0)
; #define PG8_MMA(ai, bj, At, Bt) do { __builtin_amdgcn_s_setprio(1); _Pragma("unroll") for (int m = 0; m < 4; ++m) _Pragma("unroll") for (int n = 0; n < 2; ++n) _Pragma("unroll") for (int k = 0; k < 2; ++k) \
;         acc[ai][bj][m][n] = __builtin_amdgcn_mfma_f32_16x16x32_bf16(Bt[n][k], At[m][k], acc[ai][bj][m][n], 0, 0, 0); __builtin_amdgcn_s_setprio(0); } while (0)
; #define PG8_WAIT_L(n) asm volatile("s_waitcnt lgkmcnt(" #n ")" ::: "memory")
; #define PG8_BAR __builtin_amdgcn_s_barrier()
; #define PG8_SCHED __builtin_amdgcn_sched_barrier(0)
; template <class Epi, class Sched>
; __device__ __forceinline__ void gemm_phase(PG8_LAS unsigned char* lds, const Gemm g, const Sched& S, const Epi& E) {
;     ...
;             PG8_LDB(B0, 0, 0); PG8_SCHED; PG8_LDA(At, 0, 0); PG8_STAGE(PG8_SA(1, 1), a1 + hstep, voffA);
;             PG8_WAIT_L(8); PG8_BAR; PG8_WAIT_L(0); PG8_MMA(0, 0, At, B0); PG8_BAR; PG8_SCHED;
;             PG8_LDB(B1, 0, 1); PG8_STAGE(PG8_SB(0, 0), b2, voffB);
;             PG8_BAR; PG8_WAIT_L(0); PG8_MMA(0, 1, At, B1); PG8_BAR;
;             PG8_LDA(At, 0, 1); PG8_STAGE(PG8_SA(0, 0), a2, voffA);
;             PG8_BAR; PG8_WAIT_L(0); PG8_MMA(1, 0, At, B0); PG8_BAR; PG8_SCHED;
.LBB0_1202:
	ds_read_b128 v[144:147], v151
	ds_read_b128 v[154:157], v151 offset:1024
	ds_read_b128 v[158:161], v151 offset:2048
	ds_read_b128 v[162:165], v151 offset:3072
	ds_read_b128 v[166:169], v152
	ds_read_b128 v[170:173], v152 offset:1024
	ds_read_b128 v[182:185], v152 offset:2048
	ds_read_b128 v[190:193], v152 offset:3072
	ds_read_b128 v[194:197], v152 offset:4096
	ds_read_b128 v[198:201], v152 offset:5120
	ds_read_b128 v[202:205], v152 offset:6144
	ds_read_b128 v[206:209], v152 offset:7168
	s_add_u32 s18, s16, 0xfffc0080
	s_addc_u32 s19, s17, -1
	s_cmp_eq_u32 s46, 12
	s_cselect_b32 s21, s9, s19
	s_cselect_b32 s20, s42, s18
	s_cselect_b32 s19, s7, s45
	s_cselect_b32 s18, s43, s44
	v_lshl_add_u64 v[174:175], s[16:17], 0, v[136:137]
	s_add_i32 m0, s15, 0xc000
	s_nop 0
	global_load_lds_dwordx4 v[174:175], off
	v_lshl_add_u64 v[174:175], s[16:17], 0, v[138:139]
	s_add_i32 m0, s15, 0xe000
	s_nop 0
	global_load_lds_dwordx4 v[174:175], off
	s_waitcnt lgkmcnt(0)
	s_barrier
	v_mfma_f32_16x16x32_bf16 v[124:127], v[144:147], v[166:169], v[124:127]
	v_mfma_f32_16x16x32_bf16 v[120:123], v[158:161], v[166:169], v[120:123]
	v_mfma_f32_16x16x32_bf16 v[108:111], v[144:147], v[182:185], v[108:111]
	v_mfma_f32_16x16x32_bf16 v[104:107], v[158:161], v[182:185], v[104:107]
	v_mfma_f32_16x16x32_bf16 v[92:95], v[144:147], v[194:197], v[92:95]
	v_mfma_f32_16x16x32_bf16 v[88:91], v[158:161], v[194:197], v[88:91]
	v_mfma_f32_16x16x32_bf16 v[76:79], v[144:147], v[202:205], v[76:79]
	v_mfma_f32_16x16x32_bf16 v[72:75], v[158:161], v[202:205], v[72:75]
	v_mfma_f32_16x16x32_bf16 v[124:127], v[154:157], v[170:173], v[124:127]
	v_mfma_f32_16x16x32_bf16 v[120:123], v[162:165], v[170:173], v[120:123]
	v_mfma_f32_16x16x32_bf16 v[108:111], v[154:157], v[190:193], v[108:111]
	v_mfma_f32_16x16x32_bf16 v[104:107], v[162:165], v[190:193], v[104:107]
	v_mfma_f32_16x16x32_bf16 v[92:95], v[154:157], v[198:201], v[92:95]
	v_mfma_f32_16x16x32_bf16 v[88:91], v[162:165], v[198:201], v[88:91]
	v_mfma_f32_16x16x32_bf16 v[76:79], v[154:157], v[206:209], v[76:79]
	v_mfma_f32_16x16x32_bf16 v[72:75], v[162:165], v[206:209], v[72:75]
	s_barrier
	ds_read_b128 v[210:213], v153
	ds_read_b128 v[214:217], v153 offset:1024
	ds_read_b128 v[218:221], v153 offset:2048
	ds_read_b128 v[222:225], v153 offset:3072
	s_add_i32 s47, s38, s26
	v_lshl_add_u64 v[174:175], s[18:19], 0, v[132:133]
	s_mov_b32 m0, s47
	s_nop 0
	global_load_lds_dwordx4 v[174:175], off
	v_lshl_add_u64 v[186:187], s[18:19], 0, v[128:129]
	s_add_i32 m0, s47, 0x2000
	s_nop 0
	global_load_lds_dwordx4 v[186:187], off
	s_waitcnt lgkmcnt(0)
	s_barrier
	v_mfma_f32_16x16x32_bf16 v[116:119], v[210:213], v[166:169], v[116:119]
	v_mfma_f32_16x16x32_bf16 v[112:115], v[218:221], v[166:169], v[112:115]
	v_mfma_f32_16x16x32_bf16 v[100:103], v[210:213], v[182:185], v[100:103]
	v_mfma_f32_16x16x32_bf16 v[96:99], v[218:221], v[182:185], v[96:99]
	v_mfma_f32_16x16x32_bf16 v[84:87], v[210:213], v[194:197], v[84:87]
	v_mfma_f32_16x16x32_bf16 v[80:83], v[218:221], v[194:197], v[80:83]
	v_mfma_f32_16x16x32_bf16 v[68:71], v[210:213], v[202:205], v[68:71]
	v_mfma_f32_16x16x32_bf16 v[64:67], v[218:221], v[202:205], v[64:67]
	v_mfma_f32_16x16x32_bf16 v[116:119], v[214:217], v[170:173], v[116:119]
	v_mfma_f32_16x16x32_bf16 v[112:115], v[222:225], v[170:173], v[112:115]
	v_mfma_f32_16x16x32_bf16 v[100:103], v[214:217], v[190:193], v[100:103]
	v_mfma_f32_16x16x32_bf16 v[96:99], v[222:225], v[190:193], v[96:99]
	v_mfma_f32_16x16x32_bf16 v[84:87], v[214:217], v[198:201], v[84:87]
	v_mfma_f32_16x16x32_bf16 v[80:83], v[222:225], v[198:201], v[80:83]
	v_mfma_f32_16x16x32_bf16 v[68:71], v[214:217], v[206:209], v[68:71]
	v_mfma_f32_16x16x32_bf16 v[64:67], v[222:225], v[206:209], v[64:67]
	s_barrier
	s_mov_b32 m0, s15
	v_lshl_add_u64 v[226:227], s[20:21], 0, v[134:135]
	ds_read_b128 v[166:169], v152 offset:16384
	ds_read_b128 v[170:173], v152 offset:17408
	ds_read_b128 v[182:185], v152 offset:18432
	ds_read_b128 v[190:193], v152 offset:19456
	ds_read_b128 v[194:197], v152 offset:20480
	ds_read_b128 v[198:201], v152 offset:21504
	ds_read_b128 v[202:205], v152 offset:22528
	ds_read_b128 v[206:209], v152 offset:23552
	global_load_lds_dwordx4 v[226:227], off
	v_lshl_add_u64 v[228:229], s[20:21], 0, v[130:131]
	s_mov_b32 m0, s29
	s_nop 0
	global_load_lds_dwordx4 v[228:229], off
	s_waitcnt lgkmcnt(0)
	s_barrier
	v_mfma_f32_16x16x32_bf16 v[60:63], v[144:147], v[166:169], v[60:63]
	v_mfma_f32_16x16x32_bf16 v[56:59], v[158:161], v[166:169], v[56:59]
	v_mfma_f32_16x16x32_bf16 v[44:47], v[144:147], v[182:185], v[44:47]
	v_mfma_f32_16x16x32_bf16 v[40:43], v[158:161], v[182:185], v[40:43]
	v_mfma_f32_16x16x32_bf16 v[28:31], v[144:147], v[194:197], v[28:31]
	v_mfma_f32_16x16x32_bf16 v[24:27], v[158:161], v[194:197], v[24:27]
	v_mfma_f32_16x16x32_bf16 v[12:15], v[144:147], v[202:205], v[12:15]
	v_mfma_f32_16x16x32_bf16 v[8:11], v[158:161], v[202:205], v[8:11]
	v_mfma_f32_16x16x32_bf16 v[60:63], v[154:157], v[170:173], v[60:63]
	v_mfma_f32_16x16x32_bf16 v[56:59], v[162:165], v[170:173], v[56:59]
	v_mfma_f32_16x16x32_bf16 v[44:47], v[154:157], v[190:193], v[44:47]
	v_mfma_f32_16x16x32_bf16 v[40:43], v[162:165], v[190:193], v[40:43]
	v_mfma_f32_16x16x32_bf16 v[28:31], v[154:157], v[198:201], v[28:31]
	v_mfma_f32_16x16x32_bf16 v[24:27], v[162:165], v[198:201], v[24:27]
	v_mfma_f32_16x16x32_bf16 v[12:15], v[154:157], v[206:209], v[12:15]
	v_mfma_f32_16x16x32_bf16 v[8:11], v[162:165], v[206:209], v[8:11]
	s_barrier
; #define PG8_STAGE(bufoff, gbase, voff) do { _Pragma("unroll") for (int _i = 0; _i < 2; ++_i) \
;         __builtin_amdgcn_global_load_lds((const unsigned*)((const char*)(gbase) + (voff)[_i]), (PG8_LAS unsigned*)(lds + (bufoff) + ldsw + _i * 8192), 16, 0, 0); } while (0)
; #define PG8_LDA(dst, b, h) do { _Pragma("unroll") for (int m = 0; m < 4; ++m) _Pragma("unroll") for (int k = 0; k < 2; ++k) dst[m][k] = *(const PG8_LAS bf16x8*)(lds + PG8_SA(b, h) + aoff + m * 2048 + k * 1024); } while (0)
; #define PG8_LDB(dst, b, h) do { _Pragma("unroll") for (int n = 0; n < 2; ++n) _Pragma("unroll") for (int k = 0; k < 2; ++k) dst[n][k] = *(const PG8_LAS bf16x8*)(lds + PG8_SB(b, h) + boff + n * 2048 + k * 1024); } while (0)
; #define PG8_MMA(ai, bj, At, Bt) do { __builtin_amdgcn_s_setprio(1); _Pragma("unroll") for (int m = 0; m < 4; ++m) _Pragma("unroll") for (int n = 0; n < 2; ++n) _Pragma("unroll") for (int k = 0; k < 2; ++k) \
;         acc[ai][bj][m][n] = __builtin_amdgcn_mfma_f32_16x16x32_bf16(Bt[n][k], At[m][k], acc[ai][bj][m][n], 0, 0, 0); __builtin_amdgcn_s_setprio(0); } while (0)
; #define PG8_WAIT_V(n) asm volatile("s_waitcnt vmcnt(" #n ")" ::: "memory")
; #define PG8_WAIT_L(n) asm volatile("s_waitcnt lgkmcnt(" #n ")" ::: "memory")
; #define PG8_BAR __builtin_amdgcn_s_barrier()
; #define PG8_SCHED __builtin_amdgcn_sched_barrier(0)
; template <class Epi, class Sched>
; __device__ __forceinline__ void gemm_phase(PG8_LAS unsigned char* lds, const Gemm g, const Sched& S, const Epi& E) {
;     ...
;             PG8_STAGE(PG8_SB(0, 1), b2 + hstep, voffB);
;             PG8_WAIT_V(6); PG8_BAR; PG8_MMA(1, 1, At, B1); PG8_BAR;
;             PG8_LDB(B0, 1, 0); PG8_SCHED; PG8_LDA(At, 1, 0); PG8_STAGE(PG8_SA(0, 1), a2 + hstep, voffA);
;             PG8_WAIT_L(8); PG8_BAR; PG8_WAIT_L(0); PG8_MMA(0, 0, At, B0); PG8_BAR; PG8_SCHED;
;             PG8_LDB(B1, 1, 1); PG8_STAGE(PG8_SB(1, 0), b3, voffB);
;             PG8_BAR; PG8_WAIT_L(0); PG8_MMA(0, 1, At, B1); PG8_BAR;
;             PG8_LDA(At, 1, 1); PG8_STAGE(PG8_SA(1, 0), a3, voffA);
	s_add_u32 s48, s18, 0x40000
	s_addc_u32 s49, s19, 0
	s_add_i32 s47, s39, s26
	v_lshl_add_u64 v[144:145], s[48:49], 0, v[132:133]
	s_mov_b32 m0, s47
	s_nop 0
	global_load_lds_dwordx4 v[144:145], off
	v_lshl_add_u64 v[144:145], s[48:49], 0, v[128:129]
	s_add_i32 m0, s47, 0x2000
	s_nop 0
	global_load_lds_dwordx4 v[144:145], off
	s_waitcnt vmcnt(6)
	s_barrier
	v_mfma_f32_16x16x32_bf16 v[52:55], v[210:213], v[166:169], v[52:55]
	v_mfma_f32_16x16x32_bf16 v[48:51], v[218:221], v[166:169], v[48:51]
	v_mfma_f32_16x16x32_bf16 v[36:39], v[210:213], v[182:185], v[36:39]
	v_mfma_f32_16x16x32_bf16 v[32:35], v[218:221], v[182:185], v[32:35]
	v_mfma_f32_16x16x32_bf16 v[20:23], v[210:213], v[194:197], v[20:23]
	v_mfma_f32_16x16x32_bf16 v[16:19], v[218:221], v[194:197], v[16:19]
	v_mfma_f32_16x16x32_bf16 v[4:7], v[210:213], v[202:205], v[4:7]
	v_mfma_f32_16x16x32_bf16 v[0:3], v[218:221], v[202:205], v[0:3]
	v_mfma_f32_16x16x32_bf16 v[52:55], v[214:217], v[170:173], v[52:55]
	v_mfma_f32_16x16x32_bf16 v[48:51], v[222:225], v[170:173], v[48:51]
	v_mfma_f32_16x16x32_bf16 v[36:39], v[214:217], v[190:193], v[36:39]
	v_mfma_f32_16x16x32_bf16 v[32:35], v[222:225], v[190:193], v[32:35]
	v_mfma_f32_16x16x32_bf16 v[20:23], v[214:217], v[198:201], v[20:23]
	v_mfma_f32_16x16x32_bf16 v[16:19], v[222:225], v[198:201], v[16:19]
	v_mfma_f32_16x16x32_bf16 v[4:7], v[214:217], v[206:209], v[4:7]
	v_mfma_f32_16x16x32_bf16 v[0:3], v[222:225], v[206:209], v[0:3]
	s_barrier
	s_add_i32 s47, 0, 0x18000
	v_add_u32_e32 v162, s47, v149
	ds_read_b128 v[144:147], v162
	ds_read_b128 v[154:157], v162 offset:1024
	ds_read_b128 v[158:161], v162 offset:2048
	ds_read_b128 v[162:165], v162 offset:3072
	ds_read_b128 v[166:169], v152 offset:32768
	ds_read_b128 v[170:173], v152 offset:33792
	ds_read_b128 v[182:185], v152 offset:34816
	ds_read_b128 v[190:193], v152 offset:35840
	ds_read_b128 v[194:197], v152 offset:36864
	ds_read_b128 v[198:201], v152 offset:37888
	ds_read_b128 v[202:205], v152 offset:38912
	ds_read_b128 v[206:209], v152 offset:39936
	s_add_u32 s20, s20, 0x40000
	s_addc_u32 s21, s21, 0
	s_mov_b32 m0, s30
	v_lshl_add_u64 v[210:211], s[20:21], 0, v[134:135]
	global_load_lds_dwordx4 v[210:211], off
	v_lshl_add_u64 v[210:211], s[20:21], 0, v[130:131]
	s_mov_b32 m0, s31
	s_nop 0
	global_load_lds_dwordx4 v[210:211], off
	s_waitcnt lgkmcnt(0)
	s_barrier
	v_mfma_f32_16x16x32_bf16 v[124:127], v[144:147], v[166:169], v[124:127]
	v_mfma_f32_16x16x32_bf16 v[120:123], v[158:161], v[166:169], v[120:123]
	v_mfma_f32_16x16x32_bf16 v[108:111], v[144:147], v[182:185], v[108:111]
	v_mfma_f32_16x16x32_bf16 v[104:107], v[158:161], v[182:185], v[104:107]
	v_mfma_f32_16x16x32_bf16 v[92:95], v[144:147], v[194:197], v[92:95]
	v_mfma_f32_16x16x32_bf16 v[88:91], v[158:161], v[194:197], v[88:91]
	v_mfma_f32_16x16x32_bf16 v[76:79], v[144:147], v[202:205], v[76:79]
	v_mfma_f32_16x16x32_bf16 v[72:75], v[158:161], v[202:205], v[72:75]
	v_mfma_f32_16x16x32_bf16 v[124:127], v[154:157], v[170:173], v[124:127]
	v_mfma_f32_16x16x32_bf16 v[120:123], v[162:165], v[170:173], v[120:123]
	v_mfma_f32_16x16x32_bf16 v[108:111], v[154:157], v[190:193], v[108:111]
	v_mfma_f32_16x16x32_bf16 v[104:107], v[162:165], v[190:193], v[104:107]
	v_mfma_f32_16x16x32_bf16 v[92:95], v[154:157], v[198:201], v[92:95]
	v_mfma_f32_16x16x32_bf16 v[88:91], v[162:165], v[198:201], v[88:91]
	v_mfma_f32_16x16x32_bf16 v[76:79], v[154:157], v[206:209], v[76:79]
	v_mfma_f32_16x16x32_bf16 v[72:75], v[162:165], v[206:209], v[72:75]
	s_barrier
	s_add_i32 s20, 0, 0x1c000
	v_add_u32_e32 v179, s20, v149
	ds_read_b128 v[210:213], v179
	ds_read_b128 v[214:217], v179 offset:1024
	ds_read_b128 v[218:221], v179 offset:2048
	ds_read_b128 v[222:225], v179 offset:3072
	s_add_i32 s21, s47, s26
	v_lshl_add_u64 v[174:175], v[174:175], 0, s[4:5]
	s_mov_b32 m0, s21
	s_nop 0
	global_load_lds_dwordx4 v[174:175], off
	v_lshl_add_u64 v[174:175], v[186:187], 0, s[4:5]
	s_add_i32 m0, s21, 0x2000
	s_nop 0
	global_load_lds_dwordx4 v[174:175], off
	s_waitcnt lgkmcnt(0)
	s_barrier
	v_mfma_f32_16x16x32_bf16 v[116:119], v[210:213], v[166:169], v[116:119]
	v_mfma_f32_16x16x32_bf16 v[112:115], v[218:221], v[166:169], v[112:115]
	v_mfma_f32_16x16x32_bf16 v[100:103], v[210:213], v[182:185], v[100:103]
	v_mfma_f32_16x16x32_bf16 v[96:99], v[218:221], v[182:185], v[96:99]
	v_mfma_f32_16x16x32_bf16 v[84:87], v[210:213], v[194:197], v[84:87]
	v_mfma_f32_16x16x32_bf16 v[80:83], v[218:221], v[194:197], v[80:83]
	v_mfma_f32_16x16x32_bf16 v[68:71], v[210:213], v[202:205], v[68:71]
	v_mfma_f32_16x16x32_bf16 v[64:67], v[218:221], v[202:205], v[64:67]
	v_mfma_f32_16x16x32_bf16 v[116:119], v[214:217], v[170:173], v[116:119]
	v_mfma_f32_16x16x32_bf16 v[112:115], v[222:225], v[170:173], v[112:115]
	v_mfma_f32_16x16x32_bf16 v[100:103], v[214:217], v[190:193], v[100:103]
	v_mfma_f32_16x16x32_bf16 v[96:99], v[222:225], v[190:193], v[96:99]
	v_mfma_f32_16x16x32_bf16 v[84:87], v[214:217], v[198:201], v[84:87]
	v_mfma_f32_16x16x32_bf16 v[80:83], v[222:225], v[198:201], v[80:83]
	v_mfma_f32_16x16x32_bf16 v[68:71], v[214:217], v[206:209], v[68:71]
	v_mfma_f32_16x16x32_bf16 v[64:67], v[222:225], v[206:209], v[64:67]
	s_barrier
	s_mov_b32 m0, s35
	v_lshl_add_u64 v[174:175], v[226:227], 0, s[4:5]
	ds_read_b128 v[166:169], v152 offset:49152
	ds_read_b128 v[170:173], v152 offset:50176
	ds_read_b128 v[182:185], v152 offset:51200
	ds_read_b128 v[190:193], v152 offset:52224
	ds_read_b128 v[194:197], v152 offset:53248
	ds_read_b128 v[198:201], v152 offset:54272
	ds_read_b128 v[202:205], v152 offset:55296
	ds_read_b128 v[206:209], v152 offset:56320
	global_load_lds_dwordx4 v[174:175], off
	v_lshl_add_u64 v[174:175], v[228:229], 0, s[4:5]
	s_mov_b32 m0, s36
	s_nop 0
	global_load_lds_dwordx4 v[174:175], off
	s_waitcnt lgkmcnt(0)
	s_barrier
; __device__ __forceinline__ unsigned cvt_pk_bf16(float lo, float hi) { unsigned r; asm volatile("v_cvt_pk_bf16_f32 %0, %1, %2" : "=v"(r) : "v"(lo), "v"(hi)); return r; }
; #define PG8_STAGE(bufoff, gbase, voff) do { _Pragma("unroll") for (int _i = 0; _i < 2; ++_i) \
;         __builtin_amdgcn_global_load_lds((const unsigned*)((const char*)(gbase) + (voff)[_i]), (PG8_LAS unsigned*)(lds + (bufoff) + ldsw + _i * 8192), 16, 0, 0); } while (0)
; #define PG8_MMA(ai, bj, At, Bt) do { __builtin_amdgcn_s_setprio(1); _Pragma("unroll") for (int m = 0; m < 4; ++m) _Pragma("unroll") for (int n = 0; n < 2; ++n) _Pragma("unroll") for (int k = 0; k < 2; ++k) \
;         acc[ai][bj][m][n] = __builtin_amdgcn_mfma_f32_16x16x32_bf16(Bt[n][k], At[m][k], acc[ai][bj][m][n], 0, 0, 0); __builtin_amdgcn_s_setprio(0); } while (0)
; #define PG8_WAIT_V(n) asm volatile("s_waitcnt vmcnt(" #n ")" ::: "memory")
; #define PG8_WAIT_L(n) asm volatile("s_waitcnt lgkmcnt(" #n ")" ::: "memory")
; #define PG8_BAR __builtin_amdgcn_s_barrier()
; #define PG8_SCHED __builtin_amdgcn_sched_barrier(0)
;     __device__ __forceinline__ void operator()(const f32x4 (&acc)[2][2][4][2], const Unit& u, int wr, int wc, int fr, int fq) const {
;         const int row0 = u.pm * BM + wr * 64 + fr, col0 = u.pn * HALF + wc * 32 + 8 * fq;
; #pragma unroll
;         for (int ai = 0; ai < 2; ++ai)
; #pragma unroll
;             for (int m = 0; m < 4; ++m) { bf16_t* rowp = O + (size_t)(row0 + ai * HALF + m * 16) * ldc + col0;
;                 f32x4 v0, v1;
; #pragma unroll
;                 for (int j = 0; j < 1; ++j) { v0 = acc[ai][0][m][0] * sigmoid4(acc[ai][0][m][0]) * acc[ai][1][m][0]; v1 = acc[ai][0][m][1] * sigmoid4(acc[ai][0][m][1]) * acc[ai][1][m][1]; }
;                 u32x4 w; w.x = cvt_pk_bf16(v0[0], v0[1]); w.y = cvt_pk_bf16(v0[2], v0[3]); w.z = cvt_pk_bf16(v1[0], v1[1]); w.w = cvt_pk_bf16(v1[2], v1[3]);
;                 *(u32x4*)rowp = w; }
; template <class Epi, class Sched>
; __device__ __forceinline__ void gemm_phase(PG8_LAS unsigned char* lds, const Gemm g, const Sched& S, const Epi& E) {
;     ...
;             PG8_BAR; PG8_WAIT_L(0); PG8_MMA(1, 0, At, B0); PG8_BAR; PG8_SCHED;
;             PG8_STAGE(PG8_SB(1, 1), b3 + hstep, voffB);
;             PG8_WAIT_V(6); PG8_BAR; PG8_MMA(1, 1, At, B1); PG8_BAR;
	v_mfma_f32_16x16x32_bf16 v[60:63], v[144:147], v[166:169], v[60:63]
	v_mfma_f32_16x16x32_bf16 v[56:59], v[158:161], v[166:169], v[56:59]
	v_mfma_f32_16x16x32_bf16 v[44:47], v[144:147], v[182:185], v[44:47]
	v_mfma_f32_16x16x32_bf16 v[40:43], v[158:161], v[182:185], v[40:43]
	v_mfma_f32_16x16x32_bf16 v[28:31], v[144:147], v[194:197], v[28:31]
	v_mfma_f32_16x16x32_bf16 v[24:27], v[158:161], v[194:197], v[24:27]
	v_mfma_f32_16x16x32_bf16 v[12:15], v[144:147], v[202:205], v[12:15]
	v_mfma_f32_16x16x32_bf16 v[8:11], v[158:161], v[202:205], v[8:11]
	v_mfma_f32_16x16x32_bf16 v[60:63], v[154:157], v[170:173], v[60:63]
	v_mfma_f32_16x16x32_bf16 v[56:59], v[162:165], v[170:173], v[56:59]
	v_mfma_f32_16x16x32_bf16 v[44:47], v[154:157], v[190:193], v[44:47]
	v_mfma_f32_16x16x32_bf16 v[40:43], v[162:165], v[190:193], v[40:43]
	v_mfma_f32_16x16x32_bf16 v[28:31], v[154:157], v[198:201], v[28:31]
	v_mfma_f32_16x16x32_bf16 v[24:27], v[162:165], v[198:201], v[24:27]
	v_mfma_f32_16x16x32_bf16 v[12:15], v[154:157], v[206:209], v[12:15]
	v_mfma_f32_16x16x32_bf16 v[8:11], v[162:165], v[206:209], v[8:11]
	s_barrier
	s_add_u32 s18, s18, 0x40080
	s_addc_u32 s19, s19, 0
	s_add_i32 s20, s20, s26
	v_lshl_add_u64 v[144:145], s[18:19], 0, v[132:133]
	s_mov_b32 m0, s20
	s_nop 0
	global_load_lds_dwordx4 v[144:145], off
	v_lshl_add_u64 v[144:145], s[18:19], 0, v[128:129]
	s_add_i32 m0, s20, 0x2000
	s_nop 0
	global_load_lds_dwordx4 v[144:145], off
	s_waitcnt vmcnt(6)
	s_barrier
	v_mfma_f32_16x16x32_bf16 v[52:55], v[210:213], v[166:169], v[52:55]
	v_mfma_f32_16x16x32_bf16 v[48:51], v[218:221], v[166:169], v[48:51]
	v_mfma_f32_16x16x32_bf16 v[36:39], v[210:213], v[182:185], v[36:39]
	v_mfma_f32_16x16x32_bf16 v[32:35], v[218:221], v[182:185], v[32:35]
	v_mfma_f32_16x16x32_bf16 v[20:23], v[210:213], v[194:197], v[20:23]
	v_mfma_f32_16x16x32_bf16 v[16:19], v[218:221], v[194:197], v[16:19]
	v_mfma_f32_16x16x32_bf16 v[4:7], v[210:213], v[202:205], v[4:7]
	v_mfma_f32_16x16x32_bf16 v[0:3], v[218:221], v[202:205], v[0:3]
	v_mfma_f32_16x16x32_bf16 v[52:55], v[214:217], v[170:173], v[52:55]
	v_mfma_f32_16x16x32_bf16 v[48:51], v[222:225], v[170:173], v[48:51]
	v_mfma_f32_16x16x32_bf16 v[36:39], v[214:217], v[190:193], v[36:39]
	v_mfma_f32_16x16x32_bf16 v[32:35], v[222:225], v[190:193], v[32:35]
	v_mfma_f32_16x16x32_bf16 v[20:23], v[214:217], v[198:201], v[20:23]
	v_mfma_f32_16x16x32_bf16 v[16:19], v[222:225], v[198:201], v[16:19]
	v_mfma_f32_16x16x32_bf16 v[4:7], v[214:217], v[206:209], v[4:7]
	v_mfma_f32_16x16x32_bf16 v[0:3], v[222:225], v[206:209], v[0:3]
	s_barrier
	s_add_i32 s46, s46, 2
	s_add_u32 s16, s16, 0x100
	s_addc_u32 s17, s17, 0
	s_add_u32 s44, s44, 0x100
	s_addc_u32 s45, s45, 0
	s_cmp_gt_u32 s46, 13
	s_cbranch_scc0 .LBB0_1202
	v_max_f32_e32 v144, v124, v124
	v_max_f32_e32 v144, 0xc1a00000, v144
	v_mul_f32_e32 v144, 0xbfb8aa3b, v144
	v_exp_f32_e32 v157, v144
	v_max_f32_e32 v144, v125, v125
	v_max_f32_e32 v144, 0xc1a00000, v144
	v_mul_f32_e32 v144, 0xbfb8aa3b, v144
	v_exp_f32_e32 v156, v144
	v_max_f32_e32 v144, v126, v126
	v_max_f32_e32 v144, 0xc1a00000, v144
	v_mul_f32_e32 v144, 0xbfb8aa3b, v144
	v_exp_f32_e32 v159, v144
	v_max_f32_e32 v144, v127, v127
	v_max_f32_e32 v144, 0xc1a00000, v144
	v_mul_f32_e32 v144, 0xbfb8aa3b, v144
	v_exp_f32_e32 v158, v144
	v_pk_add_f32 v[156:157], v[156:157], 1.0 op_sel_hi:[1,0]
	v_lshl_or_b32 v146, s41, 7, v150
	v_mov_b32_e32 v160, v157
	v_pk_add_f32 v[158:159], v[158:159], 1.0 op_sel_hi:[1,0]
	v_mov_b32_e32 v162, v156
	v_mov_b32_e32 v161, v159
	v_mov_b32_e32 v163, v158
	v_pk_mul_f32 v[160:161], v[160:161], v[162:163]
	v_lshl_add_u32 v154, s14, 8, v148
	v_mul_f32_e32 v155, v160, v161
	v_rcp_f32_e32 v155, v155
	v_ashrrev_i32_e32 v147, 31, v146
	v_mov_b64_e32 v[144:145], s[0:1]
	v_mad_i64_i32 v[162:163], s[16:17], v154, s40, v[144:145]
	v_mul_f32_e32 v164, v161, v155
	v_mul_f32_e32 v160, v160, v155
	v_max_f32_e32 v155, v120, v120
	v_max_f32_e32 v155, 0xc1a00000, v155
	v_mul_f32_e32 v155, 0xbfb8aa3b, v155
	v_pk_mul_f32 v[158:159], v[158:159], v[160:161] op_sel_hi:[1,0]
	v_exp_f32_e32 v161, v155
	v_max_f32_e32 v155, v121, v121
	v_max_f32_e32 v155, 0xc1a00000, v155
	v_mul_f32_e32 v155, 0xbfb8aa3b, v155
	v_exp_f32_e32 v160, v155
	v_max_f32_e32 v155, v122, v122
	v_max_f32_e32 v155, 0xc1a00000, v155
	v_mul_f32_e32 v155, 0xbfb8aa3b, v155
	v_exp_f32_e32 v167, v155
	v_max_f32_e32 v155, v123, v123
	v_max_f32_e32 v155, 0xc1a00000, v155
	v_mul_f32_e32 v155, 0xbfb8aa3b, v155
	v_exp_f32_e32 v166, v155
	v_pk_mul_f32 v[156:157], v[156:157], v[164:165] op_sel_hi:[1,0]
	v_pk_mul_f32 v[126:127], v[126:127], v[158:159]
	v_pk_mul_f32 v[124:125], v[124:125], v[156:157]
	v_pk_add_f32 v[156:157], v[160:161], 1.0 op_sel_hi:[1,0]
	v_pk_add_f32 v[160:161], v[166:167], 1.0 op_sel_hi:[1,0]
	v_mov_b32_e32 v164, v157
	v_mov_b32_e32 v165, v161
	v_mov_b32_e32 v166, v156
	v_mov_b32_e32 v167, v160
	v_pk_mul_f32 v[164:165], v[164:165], v[166:167]
	v_pk_mul_f32 v[118:119], v[126:127], v[118:119]
	v_mul_f32_e32 v155, v164, v165
	v_rcp_f32_e32 v155, v155
	v_pk_mul_f32 v[116:117], v[124:125], v[116:117]
	v_lshlrev_b64 v[146:147], 1, v[146:147]
	v_lshl_add_u64 v[162:163], v[162:163], 0, v[146:147]
	v_mul_f32_e32 v124, v165, v155
	v_mul_f32_e32 v126, v164, v155
	v_pk_mul_f32 v[126:127], v[160:161], v[126:127] op_sel_hi:[1,0]
	v_pk_mul_f32 v[124:125], v[156:157], v[124:125] op_sel_hi:[1,0]
	v_pk_mul_f32 v[122:123], v[122:123], v[126:127]
	v_pk_mul_f32 v[120:121], v[120:121], v[124:125]
	v_pk_mul_f32 v[122:123], v[122:123], v[114:115]
	v_pk_mul_f32 v[114:115], v[120:121], v[112:113]
	v_cvt_pk_bf16_f32 v112, v116, v117
	v_cvt_pk_bf16_f32 v113, v118, v119
	v_max_f32_e32 v116, v108, v108
; __device__ __forceinline__ unsigned cvt_pk_bf16(float lo, float hi) { unsigned r; asm volatile("v_cvt_pk_bf16_f32 %0, %1, %2" : "=v"(r) : "v"(lo), "v"(hi)); return r; }
; __device__ __forceinline__ f32x4 sigmoid4(f32x4 x) {
;     f32x4 d;
; #pragma unroll
;     for (int j = 0; j < 4; ++j) d[j] = 1.0f + __expf(-fmaxf(x[j], -20.0f));
;     const float p01 = d[0] * d[1], p23 = d[2] * d[3], r = __builtin_amdgcn_rcpf(p01 * p23), r01 = r * p23, r23 = r * p01;
;     return (f32x4){r01 * d[1], r01 * d[0], r23 * d[3], r23 * d[2]};
; }
;     __device__ __forceinline__ void operator()(const f32x4 (&acc)[2][2][4][2], const Unit& u, int wr, int wc, int fr, int fq) const {
;         const int row0 = u.pm * BM + wr * 64 + fr, col0 = u.pn * HALF + wc * 32 + 8 * fq;
; #pragma unroll
;         for (int ai = 0; ai < 2; ++ai)
; #pragma unroll
;             for (int m = 0; m < 4; ++m) { bf16_t* rowp = O + (size_t)(row0 + ai * HALF + m * 16) * ldc + col0;
;                 f32x4 v0, v1;
; #pragma unroll
;                 for (int j = 0; j < 1; ++j) { v0 = acc[ai][0][m][0] * sigmoid4(acc[ai][0][m][0]) * acc[ai][1][m][0]; v1 = acc[ai][0][m][1] * sigmoid4(acc[ai][0][m][1]) * acc[ai][1][m][1]; }
;                 u32x4 w; w.x = cvt_pk_bf16(v0[0], v0[1]); w.y = cvt_pk_bf16(v0[2], v0[3]); w.z = cvt_pk_bf16(v1[0], v1[1]); w.w = cvt_pk_bf16(v1[2], v1[3]);
;                 *(u32x4*)rowp = w; }
	v_max_f32_e32 v118, v110, v110
	v_max_f32_e32 v116, 0xc1a00000, v116
	v_max_f32_e32 v118, 0xc1a00000, v118
	v_mul_f32_e32 v116, 0xbfb8aa3b, v116
	v_mul_f32_e32 v118, 0xbfb8aa3b, v118
	v_exp_f32_e32 v117, v116
	v_max_f32_e32 v116, v109, v109
	v_exp_f32_e32 v119, v118
	v_max_f32_e32 v118, v111, v111
	v_max_f32_e32 v116, 0xc1a00000, v116
	v_max_f32_e32 v118, 0xc1a00000, v118
	v_mul_f32_e32 v116, 0xbfb8aa3b, v116
	v_mul_f32_e32 v118, 0xbfb8aa3b, v118
	v_exp_f32_e32 v116, v116
	v_exp_f32_e32 v118, v118
	v_cvt_pk_bf16_f32 v114, v114, v115
	v_cvt_pk_bf16_f32 v115, v122, v123
	global_store_dwordx4 v[162:163], v[112:115], off
	v_or_b32_e32 v120, 16, v154
	s_and_b64 vcc, exec, s[2:3]
	v_pk_add_f32 v[112:113], v[116:117], 1.0 op_sel_hi:[1,0]
	v_pk_add_f32 v[114:115], v[118:119], 1.0 op_sel_hi:[1,0]
	v_mov_b32_e32 v116, v113
	v_mov_b32_e32 v117, v115
	v_mov_b32_e32 v118, v112
	v_mov_b32_e32 v119, v114
	v_pk_mul_f32 v[116:117], v[116:117], v[118:119]
	s_mov_b32 s41, s6
	v_mul_f32_e32 v118, v116, v117
	v_rcp_f32_e32 v121, v118
	v_mad_i64_i32 v[118:119], s[16:17], v120, s40, v[144:145]
	v_lshl_add_u64 v[118:119], v[118:119], 0, v[146:147]
	v_mul_f32_e32 v116, v116, v121
	v_mul_f32_e32 v120, v117, v121
	v_pk_mul_f32 v[114:115], v[114:115], v[116:117] op_sel_hi:[1,0]
	v_max_f32_e32 v116, v104, v104
	v_max_f32_e32 v121, v106, v106
	v_max_f32_e32 v116, 0xc1a00000, v116
	v_max_f32_e32 v121, 0xc1a00000, v121
	v_mul_f32_e32 v116, 0xbfb8aa3b, v116
	v_mul_f32_e32 v121, 0xbfb8aa3b, v121
	v_exp_f32_e32 v117, v116
	v_max_f32_e32 v116, v105, v105
	v_exp_f32_e32 v123, v121
	v_max_f32_e32 v121, v107, v107
	v_max_f32_e32 v116, 0xc1a00000, v116
	v_max_f32_e32 v121, 0xc1a00000, v121
	v_mul_f32_e32 v116, 0xbfb8aa3b, v116
	v_mul_f32_e32 v121, 0xbfb8aa3b, v121
	v_exp_f32_e32 v116, v116
	v_exp_f32_e32 v122, v121
	v_pk_mul_f32 v[112:113], v[112:113], v[120:121] op_sel_hi:[1,0]
	v_pk_mul_f32 v[110:111], v[110:111], v[114:115]
	v_pk_mul_f32 v[108:109], v[108:109], v[112:113]
	v_pk_add_f32 v[112:113], v[116:117], 1.0 op_sel_hi:[1,0]
	v_pk_add_f32 v[116:117], v[122:123], 1.0 op_sel_hi:[1,0]
	v_mov_b32_e32 v120, v113
	v_mov_b32_e32 v121, v117
	v_mov_b32_e32 v122, v112
	v_mov_b32_e32 v123, v116
	v_pk_mul_f32 v[120:121], v[120:121], v[122:123]
	v_pk_mul_f32 v[102:103], v[110:111], v[102:103]
	v_mul_f32_e32 v122, v120, v121
	v_rcp_f32_e32 v122, v122
	v_pk_mul_f32 v[100:101], v[108:109], v[100:101]
	s_mov_b32 s14, s8
	s_mov_b64 s[18:19], s[12:13]
	v_mul_f32_e32 v108, v121, v122
	v_mul_f32_e32 v110, v120, v122
	v_pk_mul_f32 v[110:111], v[116:117], v[110:111] op_sel_hi:[1,0]
	v_pk_mul_f32 v[108:109], v[112:113], v[108:109] op_sel_hi:[1,0]
	v_pk_mul_f32 v[106:107], v[106:107], v[110:111]
	v_pk_mul_f32 v[104:105], v[104:105], v[108:109]
	v_pk_mul_f32 v[106:107], v[106:107], v[98:99]
	v_pk_mul_f32 v[98:99], v[104:105], v[96:97]
	v_cvt_pk_bf16_f32 v96, v100, v101
	v_cvt_pk_bf16_f32 v97, v102, v103
	v_max_f32_e32 v100, v92, v92
	v_max_f32_e32 v102, v94, v94
	v_max_f32_e32 v100, 0xc1a00000, v100
	v_max_f32_e32 v102, 0xc1a00000, v102
	v_mul_f32_e32 v100, 0xbfb8aa3b, v100
	v_mul_f32_e32 v102, 0xbfb8aa3b, v102
	v_exp_f32_e32 v101, v100
	v_max_f32_e32 v100, v93, v93
	v_exp_f32_e32 v103, v102
	v_max_f32_e32 v102, v95, v95
	v_max_f32_e32 v100, 0xc1a00000, v100
	v_max_f32_e32 v102, 0xc1a00000, v102
	v_mul_f32_e32 v100, 0xbfb8aa3b, v100
	v_mul_f32_e32 v102, 0xbfb8aa3b, v102
	v_exp_f32_e32 v100, v100
	v_exp_f32_e32 v102, v102
	v_cvt_pk_bf16_f32 v98, v98, v99
	v_cvt_pk_bf16_f32 v99, v106, v107
	global_store_dwordx4 v[118:119], v[96:99], off
	v_or_b32_e32 v104, 32, v154
	s_nop 0
	v_pk_add_f32 v[96:97], v[100:101], 1.0 op_sel_hi:[1,0]
	v_pk_add_f32 v[98:99], v[102:103], 1.0 op_sel_hi:[1,0]
	v_mov_b32_e32 v100, v97
	v_mov_b32_e32 v101, v99
	v_mov_b32_e32 v102, v96
	v_mov_b32_e32 v103, v98
	v_pk_mul_f32 v[100:101], v[100:101], v[102:103]
	s_nop 0
	v_mul_f32_e32 v102, v100, v101
	v_rcp_f32_e32 v105, v102
	v_mad_i64_i32 v[102:103], s[16:17], v104, s40, v[144:145]
	v_lshl_add_u64 v[102:103], v[102:103], 0, v[146:147]
	v_mul_f32_e32 v100, v100, v105
	v_mul_f32_e32 v104, v101, v105
	v_pk_mul_f32 v[98:99], v[98:99], v[100:101] op_sel_hi:[1,0]
	v_max_f32_e32 v100, v88, v88
	v_max_f32_e32 v105, v90, v90
	v_max_f32_e32 v100, 0xc1a00000, v100
	v_max_f32_e32 v105, 0xc1a00000, v105
	v_mul_f32_e32 v100, 0xbfb8aa3b, v100
	v_mul_f32_e32 v105, 0xbfb8aa3b, v105
	v_exp_f32_e32 v101, v100
	v_max_f32_e32 v100, v89, v89
	v_exp_f32_e32 v107, v105
	v_max_f32_e32 v105, v91, v91
	v_max_f32_e32 v100, 0xc1a00000, v100
	v_max_f32_e32 v105, 0xc1a00000, v105
	v_mul_f32_e32 v100, 0xbfb8aa3b, v100
	v_mul_f32_e32 v105, 0xbfb8aa3b, v105
	v_exp_f32_e32 v100, v100
	v_exp_f32_e32 v106, v105
	v_pk_mul_f32 v[96:97], v[96:97], v[104:105] op_sel_hi:[1,0]
	v_pk_mul_f32 v[94:95], v[94:95], v[98:99]
	v_pk_mul_f32 v[92:93], v[92:93], v[96:97]
	v_pk_add_f32 v[96:97], v[100:101], 1.0 op_sel_hi:[1,0]
	v_pk_add_f32 v[100:101], v[106:107], 1.0 op_sel_hi:[1,0]
	v_mov_b32_e32 v104, v97
	v_mov_b32_e32 v105, v101
	v_mov_b32_e32 v106, v96
	v_mov_b32_e32 v107, v100
	v_pk_mul_f32 v[104:105], v[104:105], v[106:107]
	v_pk_mul_f32 v[86:87], v[94:95], v[86:87]
	v_mul_f32_e32 v106, v104, v105
	v_rcp_f32_e32 v106, v106
	v_pk_mul_f32 v[84:85], v[92:93], v[84:85]
	v_mul_f32_e32 v92, v105, v106
	v_mul_f32_e32 v94, v104, v106
	v_pk_mul_f32 v[94:95], v[100:101], v[94:95] op_sel_hi:[1,0]
	v_pk_mul_f32 v[92:93], v[96:97], v[92:93] op_sel_hi:[1,0]
	v_pk_mul_f32 v[90:91], v[90:91], v[94:95]
	v_pk_mul_f32 v[88:89], v[88:89], v[92:93]
	v_pk_mul_f32 v[90:91], v[90:91], v[82:83]
	v_pk_mul_f32 v[82:83], v[88:89], v[80:81]
	v_cvt_pk_bf16_f32 v80, v84, v85
	v_cvt_pk_bf16_f32 v81, v86, v87
; __device__ __forceinline__ unsigned cvt_pk_bf16(float lo, float hi) { unsigned r; asm volatile("v_cvt_pk_bf16_f32 %0, %1, %2" : "=v"(r) : "v"(lo), "v"(hi)); return r; }
; __device__ __forceinline__ f32x4 sigmoid4(f32x4 x) {
;     f32x4 d;
; #pragma unroll
;     for (int j = 0; j < 4; ++j) d[j] = 1.0f + __expf(-fmaxf(x[j], -20.0f));
;     const float p01 = d[0] * d[1], p23 = d[2] * d[3], r = __builtin_amdgcn_rcpf(p01 * p23), r01 = r * p23, r23 = r * p01;
;     return (f32x4){r01 * d[1], r01 * d[0], r23 * d[3], r23 * d[2]};
; }
;     __device__ __forceinline__ void operator()(const f32x4 (&acc)[2][2][4][2], const Unit& u, int wr, int wc, int fr, int fq) const {
;         const int row0 = u.pm * BM + wr * 64 + fr, col0 = u.pn * HALF + wc * 32 + 8 * fq;
; #pragma unroll
;         for (int ai = 0; ai < 2; ++ai)
; #pragma unroll
;             for (int m = 0; m < 4; ++m) { bf16_t* rowp = O + (size_t)(row0 + ai * HALF + m * 16) * ldc + col0;
;                 f32x4 v0, v1;
; #pragma unroll
;                 for (int j = 0; j < 1; ++j) { v0 = acc[ai][0][m][0] * sigmoid4(acc[ai][0][m][0]) * acc[ai][1][m][0]; v1 = acc[ai][0][m][1] * sigmoid4(acc[ai][0][m][1]) * acc[ai][1][m][1]; }
;                 u32x4 w; w.x = cvt_pk_bf16(v0[0], v0[1]); w.y = cvt_pk_bf16(v0[2], v0[3]); w.z = cvt_pk_bf16(v1[0], v1[1]); w.w = cvt_pk_bf16(v1[2], v1[3]);
;                 *(u32x4*)rowp = w; }
	v_max_f32_e32 v84, v76, v76
	v_max_f32_e32 v86, v78, v78
	v_max_f32_e32 v84, 0xc1a00000, v84
	v_max_f32_e32 v86, 0xc1a00000, v86
	v_mul_f32_e32 v84, 0xbfb8aa3b, v84
	v_mul_f32_e32 v86, 0xbfb8aa3b, v86
	v_exp_f32_e32 v85, v84
	v_max_f32_e32 v84, v77, v77
	v_exp_f32_e32 v87, v86
	v_max_f32_e32 v86, v79, v79
	v_max_f32_e32 v84, 0xc1a00000, v84
	v_max_f32_e32 v86, 0xc1a00000, v86
	v_mul_f32_e32 v84, 0xbfb8aa3b, v84
	v_mul_f32_e32 v86, 0xbfb8aa3b, v86
	v_exp_f32_e32 v84, v84
	v_exp_f32_e32 v86, v86
	v_cvt_pk_bf16_f32 v82, v82, v83
	v_cvt_pk_bf16_f32 v83, v90, v91
	global_store_dwordx4 v[102:103], v[80:83], off
	v_or_b32_e32 v88, 48, v154
	s_nop 0
	v_pk_add_f32 v[80:81], v[84:85], 1.0 op_sel_hi:[1,0]
	v_pk_add_f32 v[82:83], v[86:87], 1.0 op_sel_hi:[1,0]
	v_mov_b32_e32 v84, v81
	v_mov_b32_e32 v85, v83
	v_mov_b32_e32 v86, v80
	v_mov_b32_e32 v87, v82
	v_pk_mul_f32 v[84:85], v[84:85], v[86:87]
	s_nop 0
	v_mul_f32_e32 v86, v84, v85
	v_rcp_f32_e32 v89, v86
	v_mad_i64_i32 v[86:87], s[16:17], v88, s40, v[144:145]
	v_lshl_add_u64 v[86:87], v[86:87], 0, v[146:147]
	v_mul_f32_e32 v84, v84, v89
	v_mul_f32_e32 v88, v85, v89
	v_pk_mul_f32 v[82:83], v[82:83], v[84:85] op_sel_hi:[1,0]
	v_max_f32_e32 v84, v72, v72
	v_max_f32_e32 v89, v74, v74
	v_max_f32_e32 v84, 0xc1a00000, v84
	v_max_f32_e32 v89, 0xc1a00000, v89
	v_mul_f32_e32 v84, 0xbfb8aa3b, v84
	v_mul_f32_e32 v89, 0xbfb8aa3b, v89
	v_exp_f32_e32 v85, v84
	v_max_f32_e32 v84, v73, v73
	v_exp_f32_e32 v91, v89
	v_max_f32_e32 v89, v75, v75
	v_max_f32_e32 v84, 0xc1a00000, v84
	v_max_f32_e32 v89, 0xc1a00000, v89
	v_mul_f32_e32 v84, 0xbfb8aa3b, v84
	v_mul_f32_e32 v89, 0xbfb8aa3b, v89
	v_exp_f32_e32 v84, v84
	v_exp_f32_e32 v90, v89
	v_pk_mul_f32 v[80:81], v[80:81], v[88:89] op_sel_hi:[1,0]
	v_pk_mul_f32 v[78:79], v[78:79], v[82:83]
	v_pk_mul_f32 v[76:77], v[76:77], v[80:81]
	v_pk_add_f32 v[80:81], v[84:85], 1.0 op_sel_hi:[1,0]
	v_pk_add_f32 v[84:85], v[90:91], 1.0 op_sel_hi:[1,0]
	v_mov_b32_e32 v88, v81
	v_mov_b32_e32 v89, v85
	v_mov_b32_e32 v90, v80
	v_mov_b32_e32 v91, v84
	v_pk_mul_f32 v[88:89], v[88:89], v[90:91]
	v_pk_mul_f32 v[70:71], v[78:79], v[70:71]
	v_mul_f32_e32 v90, v88, v89
	v_rcp_f32_e32 v90, v90
	v_pk_mul_f32 v[68:69], v[76:77], v[68:69]
	v_mul_f32_e32 v76, v89, v90
	v_mul_f32_e32 v78, v88, v90
	v_pk_mul_f32 v[78:79], v[84:85], v[78:79] op_sel_hi:[1,0]
	v_pk_mul_f32 v[76:77], v[80:81], v[76:77] op_sel_hi:[1,0]
	v_pk_mul_f32 v[74:75], v[74:75], v[78:79]
	v_pk_mul_f32 v[72:73], v[72:73], v[76:77]
	v_pk_mul_f32 v[74:75], v[74:75], v[66:67]
	v_pk_mul_f32 v[66:67], v[72:73], v[64:65]
	v_cvt_pk_bf16_f32 v64, v68, v69
	v_cvt_pk_bf16_f32 v65, v70, v71
	v_max_f32_e32 v68, v60, v60
	v_max_f32_e32 v70, v62, v62
	v_max_f32_e32 v68, 0xc1a00000, v68
	v_max_f32_e32 v70, 0xc1a00000, v70
	v_mul_f32_e32 v68, 0xbfb8aa3b, v68
	v_mul_f32_e32 v70, 0xbfb8aa3b, v70
	v_exp_f32_e32 v69, v68
	v_max_f32_e32 v68, v61, v61
	v_exp_f32_e32 v71, v70
	v_max_f32_e32 v70, v63, v63
	v_max_f32_e32 v68, 0xc1a00000, v68
	v_max_f32_e32 v70, 0xc1a00000, v70
	v_mul_f32_e32 v68, 0xbfb8aa3b, v68
	v_mul_f32_e32 v70, 0xbfb8aa3b, v70
	v_exp_f32_e32 v68, v68
	v_exp_f32_e32 v70, v70
	v_cvt_pk_bf16_f32 v66, v66, v67
	v_cvt_pk_bf16_f32 v67, v74, v75
	global_store_dwordx4 v[86:87], v[64:67], off
	v_add_u32_e32 v72, 0x80, v154
	s_nop 0
	v_pk_add_f32 v[64:65], v[68:69], 1.0 op_sel_hi:[1,0]
	v_pk_add_f32 v[66:67], v[70:71], 1.0 op_sel_hi:[1,0]
	v_mov_b32_e32 v68, v65
	v_mov_b32_e32 v69, v67
	v_mov_b32_e32 v70, v64
	v_mov_b32_e32 v71, v66
	v_pk_mul_f32 v[68:69], v[68:69], v[70:71]
	s_nop 0
	v_mul_f32_e32 v70, v68, v69
	v_rcp_f32_e32 v73, v70
	v_mad_i64_i32 v[70:71], s[16:17], v72, s40, v[144:145]
	v_lshl_add_u64 v[70:71], v[70:71], 0, v[146:147]
	v_mul_f32_e32 v68, v68, v73
	v_mul_f32_e32 v72, v69, v73
	v_pk_mul_f32 v[66:67], v[66:67], v[68:69] op_sel_hi:[1,0]
	v_max_f32_e32 v68, v56, v56
	v_max_f32_e32 v73, v58, v58
	v_max_f32_e32 v68, 0xc1a00000, v68
	v_max_f32_e32 v73, 0xc1a00000, v73
	v_mul_f32_e32 v68, 0xbfb8aa3b, v68
	v_mul_f32_e32 v73, 0xbfb8aa3b, v73
	v_exp_f32_e32 v69, v68
	v_max_f32_e32 v68, v57, v57
	v_exp_f32_e32 v75, v73
	v_max_f32_e32 v73, v59, v59
	v_max_f32_e32 v68, 0xc1a00000, v68
	v_max_f32_e32 v73, 0xc1a00000, v73
	v_mul_f32_e32 v68, 0xbfb8aa3b, v68
	v_mul_f32_e32 v73, 0xbfb8aa3b, v73
	v_exp_f32_e32 v68, v68
	v_exp_f32_e32 v74, v73
	v_pk_mul_f32 v[64:65], v[64:65], v[72:73] op_sel_hi:[1,0]
	v_pk_mul_f32 v[62:63], v[62:63], v[66:67]
	v_pk_mul_f32 v[60:61], v[60:61], v[64:65]
	v_pk_add_f32 v[64:65], v[68:69], 1.0 op_sel_hi:[1,0]
	v_pk_add_f32 v[68:69], v[74:75], 1.0 op_sel_hi:[1,0]
	v_mov_b32_e32 v72, v65
	v_mov_b32_e32 v73, v69
	v_mov_b32_e32 v74, v64
	v_mov_b32_e32 v75, v68
	v_pk_mul_f32 v[72:73], v[72:73], v[74:75]
	v_pk_mul_f32 v[54:55], v[62:63], v[54:55]
	v_mul_f32_e32 v74, v72, v73
	v_rcp_f32_e32 v74, v74
	v_pk_mul_f32 v[52:53], v[60:61], v[52:53]
	v_mul_f32_e32 v60, v73, v74
	v_mul_f32_e32 v62, v72, v74
	v_pk_mul_f32 v[62:63], v[68:69], v[62:63] op_sel_hi:[1,0]
	v_pk_mul_f32 v[60:61], v[64:65], v[60:61] op_sel_hi:[1,0]
	v_pk_mul_f32 v[58:59], v[58:59], v[62:63]
	v_pk_mul_f32 v[56:57], v[56:57], v[60:61]
	v_pk_mul_f32 v[58:59], v[58:59], v[50:51]
	v_pk_mul_f32 v[50:51], v[56:57], v[48:49]
	v_cvt_pk_bf16_f32 v48, v52, v53
	v_cvt_pk_bf16_f32 v49, v54, v55
	v_max_f32_e32 v52, v44, v44
	v_max_f32_e32 v54, v46, v46
	v_max_f32_e32 v52, 0xc1a00000, v52
	v_max_f32_e32 v54, 0xc1a00000, v54
	v_mul_f32_e32 v52, 0xbfb8aa3b, v52
	v_mul_f32_e32 v54, 0xbfb8aa3b, v54
	v_exp_f32_e32 v53, v52
	v_max_f32_e32 v52, v45, v45
	v_exp_f32_e32 v55, v54
	v_max_f32_e32 v54, v47, v47
	v_max_f32_e32 v52, 0xc1a00000, v52
	v_max_f32_e32 v54, 0xc1a00000, v54
; __device__ __forceinline__ unsigned cvt_pk_bf16(float lo, float hi) { unsigned r; asm volatile("v_cvt_pk_bf16_f32 %0, %1, %2" : "=v"(r) : "v"(lo), "v"(hi)); return r; }
; __device__ __forceinline__ f32x4 sigmoid4(f32x4 x) {
;     f32x4 d;
; #pragma unroll
;     for (int j = 0; j < 4; ++j) d[j] = 1.0f + __expf(-fmaxf(x[j], -20.0f));
;     const float p01 = d[0] * d[1], p23 = d[2] * d[3], r = __builtin_amdgcn_rcpf(p01 * p23), r01 = r * p23, r23 = r * p01;
;     return (f32x4){r01 * d[1], r01 * d[0], r23 * d[3], r23 * d[2]};
; }
;     __device__ __forceinline__ void operator()(const f32x4 (&acc)[2][2][4][2], const Unit& u, int wr, int wc, int fr, int fq) const {
;         const int row0 = u.pm * BM + wr * 64 + fr, col0 = u.pn * HALF + wc * 32 + 8 * fq;
; #pragma unroll
;         for (int ai = 0; ai < 2; ++ai)
; #pragma unroll
;             for (int m = 0; m < 4; ++m) { bf16_t* rowp = O + (size_t)(row0 + ai * HALF + m * 16) * ldc + col0;
;                 f32x4 v0, v1;
; #pragma unroll
;                 for (int j = 0; j < 1; ++j) { v0 = acc[ai][0][m][0] * sigmoid4(acc[ai][0][m][0]) * acc[ai][1][m][0]; v1 = acc[ai][0][m][1] * sigmoid4(acc[ai][0][m][1]) * acc[ai][1][m][1]; }
;                 u32x4 w; w.x = cvt_pk_bf16(v0[0], v0[1]); w.y = cvt_pk_bf16(v0[2], v0[3]); w.z = cvt_pk_bf16(v1[0], v1[1]); w.w = cvt_pk_bf16(v1[2], v1[3]);
;                 *(u32x4*)rowp = w; }
	v_mul_f32_e32 v52, 0xbfb8aa3b, v52
	v_mul_f32_e32 v54, 0xbfb8aa3b, v54
	v_exp_f32_e32 v52, v52
	v_exp_f32_e32 v54, v54
	v_cvt_pk_bf16_f32 v50, v50, v51
	v_cvt_pk_bf16_f32 v51, v58, v59
	global_store_dwordx4 v[70:71], v[48:51], off
	v_add_u32_e32 v56, 0x90, v154
	s_nop 0
	v_pk_add_f32 v[48:49], v[52:53], 1.0 op_sel_hi:[1,0]
	v_pk_add_f32 v[50:51], v[54:55], 1.0 op_sel_hi:[1,0]
	v_mov_b32_e32 v52, v49
	v_mov_b32_e32 v53, v51
	v_mov_b32_e32 v54, v48
	v_mov_b32_e32 v55, v50
	v_pk_mul_f32 v[52:53], v[52:53], v[54:55]
	s_nop 0
	v_mul_f32_e32 v54, v52, v53
	v_rcp_f32_e32 v57, v54
	v_mad_i64_i32 v[54:55], s[16:17], v56, s40, v[144:145]
	v_lshl_add_u64 v[54:55], v[54:55], 0, v[146:147]
	v_mul_f32_e32 v52, v52, v57
	v_mul_f32_e32 v56, v53, v57
	v_pk_mul_f32 v[50:51], v[50:51], v[52:53] op_sel_hi:[1,0]
	v_max_f32_e32 v52, v40, v40
	v_max_f32_e32 v57, v42, v42
	v_max_f32_e32 v52, 0xc1a00000, v52
	v_max_f32_e32 v57, 0xc1a00000, v57
	v_mul_f32_e32 v52, 0xbfb8aa3b, v52
	v_mul_f32_e32 v57, 0xbfb8aa3b, v57
	v_exp_f32_e32 v53, v52
	v_max_f32_e32 v52, v41, v41
	v_exp_f32_e32 v59, v57
	v_max_f32_e32 v57, v43, v43
	v_max_f32_e32 v52, 0xc1a00000, v52
	v_max_f32_e32 v57, 0xc1a00000, v57
	v_mul_f32_e32 v52, 0xbfb8aa3b, v52
	v_mul_f32_e32 v57, 0xbfb8aa3b, v57
	v_exp_f32_e32 v52, v52
	v_exp_f32_e32 v58, v57
	v_pk_mul_f32 v[48:49], v[48:49], v[56:57] op_sel_hi:[1,0]
	v_pk_mul_f32 v[46:47], v[46:47], v[50:51]
	v_pk_mul_f32 v[44:45], v[44:45], v[48:49]
	v_pk_add_f32 v[48:49], v[52:53], 1.0 op_sel_hi:[1,0]
	v_pk_add_f32 v[52:53], v[58:59], 1.0 op_sel_hi:[1,0]
	v_mov_b32_e32 v56, v49
	v_mov_b32_e32 v57, v53
	v_mov_b32_e32 v58, v48
	v_mov_b32_e32 v59, v52
	v_pk_mul_f32 v[56:57], v[56:57], v[58:59]
	v_pk_mul_f32 v[38:39], v[46:47], v[38:39]
	v_mul_f32_e32 v58, v56, v57
	v_rcp_f32_e32 v58, v58
	v_pk_mul_f32 v[36:37], v[44:45], v[36:37]
	v_mul_f32_e32 v44, v57, v58
	v_mul_f32_e32 v46, v56, v58
	v_pk_mul_f32 v[46:47], v[52:53], v[46:47] op_sel_hi:[1,0]
	v_pk_mul_f32 v[44:45], v[48:49], v[44:45] op_sel_hi:[1,0]
	v_pk_mul_f32 v[42:43], v[42:43], v[46:47]
	v_pk_mul_f32 v[40:41], v[40:41], v[44:45]
	v_pk_mul_f32 v[42:43], v[42:43], v[34:35]
	v_pk_mul_f32 v[34:35], v[40:41], v[32:33]
	v_cvt_pk_bf16_f32 v32, v36, v37
	v_cvt_pk_bf16_f32 v33, v38, v39
	v_max_f32_e32 v36, v28, v28
	v_max_f32_e32 v38, v30, v30
	v_max_f32_e32 v36, 0xc1a00000, v36
	v_max_f32_e32 v38, 0xc1a00000, v38
	v_mul_f32_e32 v36, 0xbfb8aa3b, v36
	v_mul_f32_e32 v38, 0xbfb8aa3b, v38
	v_exp_f32_e32 v37, v36
	v_max_f32_e32 v36, v29, v29
	v_exp_f32_e32 v39, v38
	v_max_f32_e32 v38, v31, v31
	v_max_f32_e32 v36, 0xc1a00000, v36
	v_max_f32_e32 v38, 0xc1a00000, v38
	v_mul_f32_e32 v36, 0xbfb8aa3b, v36
	v_mul_f32_e32 v38, 0xbfb8aa3b, v38
	v_exp_f32_e32 v36, v36
	v_exp_f32_e32 v38, v38
	v_cvt_pk_bf16_f32 v34, v34, v35
	v_cvt_pk_bf16_f32 v35, v42, v43
	global_store_dwordx4 v[54:55], v[32:35], off
	v_add_u32_e32 v40, 0xa0, v154
	s_nop 0
	v_pk_add_f32 v[32:33], v[36:37], 1.0 op_sel_hi:[1,0]
	v_pk_add_f32 v[34:35], v[38:39], 1.0 op_sel_hi:[1,0]
	v_mov_b32_e32 v36, v33
	v_mov_b32_e32 v37, v35
	v_mov_b32_e32 v38, v32
	v_mov_b32_e32 v39, v34
	v_pk_mul_f32 v[36:37], v[36:37], v[38:39]
	s_nop 0
	v_mul_f32_e32 v38, v36, v37
	v_rcp_f32_e32 v41, v38
	v_mad_i64_i32 v[38:39], s[16:17], v40, s40, v[144:145]
	v_lshl_add_u64 v[38:39], v[38:39], 0, v[146:147]
	v_mul_f32_e32 v36, v36, v41
	v_mul_f32_e32 v40, v37, v41
	v_pk_mul_f32 v[34:35], v[34:35], v[36:37] op_sel_hi:[1,0]
	v_max_f32_e32 v36, v24, v24
	v_max_f32_e32 v41, v26, v26
	v_max_f32_e32 v36, 0xc1a00000, v36
	v_max_f32_e32 v41, 0xc1a00000, v41
	v_mul_f32_e32 v36, 0xbfb8aa3b, v36
	v_mul_f32_e32 v41, 0xbfb8aa3b, v41
	v_exp_f32_e32 v37, v36
	v_max_f32_e32 v36, v25, v25
	v_exp_f32_e32 v43, v41
	v_max_f32_e32 v41, v27, v27
	v_max_f32_e32 v36, 0xc1a00000, v36
	v_max_f32_e32 v41, 0xc1a00000, v41
	v_mul_f32_e32 v36, 0xbfb8aa3b, v36
; __device__ __forceinline__ unsigned cvt_pk_bf16(float lo, float hi) { unsigned r; asm volatile("v_cvt_pk_bf16_f32 %0, %1, %2" : "=v"(r) : "v"(lo), "v"(hi)); return r; }
; __device__ __forceinline__ f32x4 sigmoid4(f32x4 x) {
;     f32x4 d;
; #pragma unroll
;     for (int j = 0; j < 4; ++j) d[j] = 1.0f + __expf(-fmaxf(x[j], -20.0f));
;     const float p01 = d[0] * d[1], p23 = d[2] * d[3], r = __builtin_amdgcn_rcpf(p01 * p23), r01 = r * p23, r23 = r * p01;
;     return (f32x4){r01 * d[1], r01 * d[0], r23 * d[3], r23 * d[2]};
; }
;     __device__ __forceinline__ void operator()(const f32x4 (&acc)[2][2][4][2], const Unit& u, int wr, int wc, int fr, int fq) const {
;         const int row0 = u.pm * BM + wr * 64 + fr, col0 = u.pn * HALF + wc * 32 + 8 * fq;
; #pragma unroll
;         for (int ai = 0; ai < 2; ++ai)
; #pragma unroll
;             for (int m = 0; m < 4; ++m) { bf16_t* rowp = O + (size_t)(row0 + ai * HALF + m * 16) * ldc + col0;
;                 f32x4 v0, v1;
; #pragma unroll
;                 for (int j = 0; j < 1; ++j) { v0 = acc[ai][0][m][0] * sigmoid4(acc[ai][0][m][0]) * acc[ai][1][m][0]; v1 = acc[ai][0][m][1] * sigmoid4(acc[ai][0][m][1]) * acc[ai][1][m][1]; }
;                 u32x4 w; w.x = cvt_pk_bf16(v0[0], v0[1]); w.y = cvt_pk_bf16(v0[2], v0[3]); w.z = cvt_pk_bf16(v1[0], v1[1]); w.w = cvt_pk_bf16(v1[2], v1[3]);
;                 *(u32x4*)rowp = w; }
	v_mul_f32_e32 v41, 0xbfb8aa3b, v41
	v_exp_f32_e32 v36, v36
	v_exp_f32_e32 v42, v41
	v_pk_mul_f32 v[32:33], v[32:33], v[40:41] op_sel_hi:[1,0]
	v_pk_mul_f32 v[30:31], v[30:31], v[34:35]
	v_pk_mul_f32 v[28:29], v[28:29], v[32:33]
	v_pk_add_f32 v[32:33], v[36:37], 1.0 op_sel_hi:[1,0]
	v_pk_add_f32 v[36:37], v[42:43], 1.0 op_sel_hi:[1,0]
	v_mov_b32_e32 v40, v33
	v_mov_b32_e32 v41, v37
	v_mov_b32_e32 v42, v32
	v_mov_b32_e32 v43, v36
	v_pk_mul_f32 v[40:41], v[40:41], v[42:43]
	v_pk_mul_f32 v[22:23], v[30:31], v[22:23]
	v_mul_f32_e32 v42, v40, v41
	v_rcp_f32_e32 v42, v42
	v_pk_mul_f32 v[20:21], v[28:29], v[20:21]
	v_mul_f32_e32 v28, v41, v42
	v_mul_f32_e32 v30, v40, v42
	v_pk_mul_f32 v[30:31], v[36:37], v[30:31] op_sel_hi:[1,0]
	v_pk_mul_f32 v[28:29], v[32:33], v[28:29] op_sel_hi:[1,0]
	v_pk_mul_f32 v[26:27], v[26:27], v[30:31]
	v_pk_mul_f32 v[24:25], v[24:25], v[28:29]
	v_pk_mul_f32 v[26:27], v[26:27], v[18:19]
	v_pk_mul_f32 v[18:19], v[24:25], v[16:17]
	v_cvt_pk_bf16_f32 v16, v20, v21
	v_cvt_pk_bf16_f32 v17, v22, v23
	v_max_f32_e32 v20, v12, v12
	v_max_f32_e32 v22, v14, v14
	v_max_f32_e32 v20, 0xc1a00000, v20
	v_max_f32_e32 v22, 0xc1a00000, v22
	v_mul_f32_e32 v20, 0xbfb8aa3b, v20
	v_mul_f32_e32 v22, 0xbfb8aa3b, v22
	v_exp_f32_e32 v21, v20
	v_max_f32_e32 v20, v13, v13
	v_exp_f32_e32 v23, v22
	v_max_f32_e32 v22, v15, v15
	v_max_f32_e32 v20, 0xc1a00000, v20
	v_max_f32_e32 v22, 0xc1a00000, v22
	v_mul_f32_e32 v20, 0xbfb8aa3b, v20
	v_mul_f32_e32 v22, 0xbfb8aa3b, v22
	v_exp_f32_e32 v20, v20
	v_exp_f32_e32 v22, v22
	v_cvt_pk_bf16_f32 v18, v18, v19
	v_cvt_pk_bf16_f32 v19, v26, v27
	global_store_dwordx4 v[38:39], v[16:19], off
	v_add_u32_e32 v24, 0xb0, v154
	s_nop 0
	v_pk_add_f32 v[16:17], v[20:21], 1.0 op_sel_hi:[1,0]
	v_pk_add_f32 v[18:19], v[22:23], 1.0 op_sel_hi:[1,0]
	v_mov_b32_e32 v20, v17
	v_mov_b32_e32 v21, v19
	v_mov_b32_e32 v22, v16
	v_mov_b32_e32 v23, v18
	v_pk_mul_f32 v[20:21], v[20:21], v[22:23]
	s_nop 0
	v_mul_f32_e32 v22, v20, v21
	v_rcp_f32_e32 v25, v22
	v_mad_i64_i32 v[22:23], s[16:17], v24, s40, v[144:145]
	v_lshl_add_u64 v[22:23], v[22:23], 0, v[146:147]
	v_mul_f32_e32 v20, v20, v25
	v_mul_f32_e32 v24, v21, v25
	v_pk_mul_f32 v[18:19], v[18:19], v[20:21] op_sel_hi:[1,0]
	v_max_f32_e32 v20, v8, v8
	v_max_f32_e32 v25, v10, v10
	v_max_f32_e32 v20, 0xc1a00000, v20
	v_max_f32_e32 v25, 0xc1a00000, v25
	v_mul_f32_e32 v20, 0xbfb8aa3b, v20
	v_mul_f32_e32 v25, 0xbfb8aa3b, v25
	v_exp_f32_e32 v21, v20
	v_max_f32_e32 v20, v9, v9
	v_exp_f32_e32 v27, v25
	v_max_f32_e32 v25, v11, v11
	v_max_f32_e32 v20, 0xc1a00000, v20
	v_max_f32_e32 v25, 0xc1a00000, v25
	v_mul_f32_e32 v20, 0xbfb8aa3b, v20
	v_mul_f32_e32 v25, 0xbfb8aa3b, v25
	v_exp_f32_e32 v20, v20
	v_exp_f32_e32 v26, v25
	v_pk_mul_f32 v[16:17], v[16:17], v[24:25] op_sel_hi:[1,0]
	v_pk_mul_f32 v[14:15], v[14:15], v[18:19]
	v_pk_mul_f32 v[12:13], v[12:13], v[16:17]
	v_pk_add_f32 v[16:17], v[20:21], 1.0 op_sel_hi:[1,0]
	v_pk_add_f32 v[20:21], v[26:27], 1.0 op_sel_hi:[1,0]
	v_mov_b32_e32 v24, v17
	v_mov_b32_e32 v25, v21
	v_mov_b32_e32 v26, v16
	v_mov_b32_e32 v27, v20
	v_pk_mul_f32 v[24:25], v[24:25], v[26:27]
	v_pk_mul_f32 v[6:7], v[14:15], v[6:7]
	v_mul_f32_e32 v26, v24, v25
	v_rcp_f32_e32 v26, v26
	v_pk_mul_f32 v[4:5], v[12:13], v[4:5]
	s_mov_b64 s[16:17], s[10:11]
	v_mul_f32_e32 v12, v25, v26
	v_mul_f32_e32 v14, v24, v26
	v_pk_mul_f32 v[14:15], v[20:21], v[14:15] op_sel_hi:[1,0]
	v_pk_mul_f32 v[12:13], v[16:17], v[12:13] op_sel_hi:[1,0]
	v_pk_mul_f32 v[10:11], v[10:11], v[14:15]
	v_pk_mul_f32 v[8:9], v[8:9], v[12:13]
	v_pk_mul_f32 v[10:11], v[10:11], v[2:3]
	v_pk_mul_f32 v[2:3], v[8:9], v[0:1]
	v_cvt_pk_bf16_f32 v0, v4, v5
	v_cvt_pk_bf16_f32 v1, v6, v7
	s_nop 0
	v_cvt_pk_bf16_f32 v2, v2, v3
	v_cvt_pk_bf16_f32 v3, v10, v11
	global_store_dwordx4 v[22:23], v[0:3], off
	s_cbranch_vccz .LBB0_1199
	s_waitcnt vmcnt(0)
	s_cmpk_gt_u32 s23, 0xff
	s_cbranch_scc1 .LBB0_1206
	s_barrier

; #define PG8_STAGE(bufoff, gbase, voff) do { _Pragma("unroll") for (int _i = 0; _i < 2; ++_i) \
;         __builtin_amdgcn_global_load_lds((const unsigned*)((const char*)(gbase) + (voff)[_i]), (PG8_LAS unsigned*)(lds + (bufoff) + ldsw + _i * 8192), 16, 0, 0); } while (0)
; #define PG8_LDA(dst, b, h) do { _Pragma("unroll") for (int m = 0; m < 4; ++m) _Pragma("unroll") for (int k = 0; k < 2; ++k) dst[m][k] = *(const PG8_LAS bf16x8*)(lds + PG8_SA(b, h) + aoff + m * 2048 + k * 1024); } while (0)
; #define PG8_LDB(dst, b, h) do { _Pragma("unroll") for (int n = 0; n < 2; ++n) _Pragma("unroll") for (int k = 0; k < 2; ++k) dst[n][k] = *(const PG8_LAS bf16x8*)(lds + PG8_SB(b, h) + boff + n * 2048 + k * 1024); } while (0)
; #define PG8_MMA(ai, bj, At, Bt) do { __builtin_amdgcn_s_setprio(1); _Pragma("unroll") for (int m = 0; m < 4; ++m) _Pragma("unroll") for (int n = 0; n < 2; ++n) _Pragma("unroll") for (int k = 0; k < 2; ++k) \
;         acc[ai][bj][m][n] = __builtin_amdgcn_mfma_f32_16x16x32_bf16(Bt[n][k], At[m][k], acc[ai][bj][m][n], 0, 0, 0); __builtin_amdgcn_s_setprio(0); } while (0)
; #define PG8_WAIT_L(n) asm volatile("s_waitcnt lgkmcnt(" #n ")" ::: "memory")
; #define PG8_BAR __builtin_amdgcn_s_barrier()
; #define PG8_SCHED __builtin_amdgcn_sched_barrier(0)
; template <class Epi, class Sched>
; __device__ __forceinline__ void gemm_phase(PG8_LAS unsigned char* lds, const Gemm g, const Sched& S, const Epi& E) {
;     ...
;             PG8_LDB(B0, 0, 0); PG8_SCHED; PG8_LDA(At, 0, 0); PG8_STAGE(PG8_SA(1, 1), a1 + hstep, voffA);
;             PG8_WAIT_L(8); PG8_BAR; PG8_WAIT_L(0); PG8_MMA(0, 0, At, B0); PG8_BAR; PG8_SCHED;
;             PG8_LDB(B1, 0, 1); PG8_STAGE(PG8_SB(0, 0), b2, voffB);
;             PG8_BAR; PG8_WAIT_L(0); PG8_MMA(0, 1, At, B1); PG8_BAR;
;             PG8_LDA(At, 0, 1); PG8_STAGE(PG8_SA(0, 0), a2, voffA);
;             PG8_BAR; PG8_WAIT_L(0); PG8_MMA(1, 0, At, B0); PG8_BAR; PG8_SCHED;
.LBB0_1278:
	ds_read_b128 v[152:155], v149
	ds_read_b128 v[156:159], v149 offset:1024
	ds_read_b128 v[160:163], v149 offset:2048
	ds_read_b128 v[164:167], v149 offset:3072
	ds_read_b128 v[168:171], v150
	ds_read_b128 v[172:175], v150 offset:1024
	ds_read_b128 v[182:185], v150 offset:2048
	ds_read_b128 v[190:193], v150 offset:3072
	ds_read_b128 v[194:197], v150 offset:4096
	ds_read_b128 v[198:201], v150 offset:5120
	ds_read_b128 v[202:205], v150 offset:6144
	ds_read_b128 v[206:209], v150 offset:7168
	s_add_u32 s20, s18, 0x100
	s_addc_u32 s21, s19, 0
	s_cmp_eq_u32 s54, 40
	s_cselect_b32 s25, s1, s21
	s_cselect_b32 s24, s0, s20
	s_cselect_b32 s23, s5, s53
	s_cselect_b32 s22, s4, s52
	v_lshl_add_u64 v[144:145], s[18:19], 0, v[136:137]
	s_add_i32 m0, s34, 0xc000
	s_nop 0
	global_load_lds_dwordx4 v[144:145], off
	v_lshl_add_u64 v[144:145], s[18:19], 0, v[138:139]
	s_add_i32 m0, s34, 0xe000
	s_nop 0
	global_load_lds_dwordx4 v[144:145], off
	s_waitcnt lgkmcnt(0)
	s_barrier
	v_mfma_f32_16x16x32_bf16 v[124:127], v[152:155], v[168:171], v[124:127]
	v_mfma_f32_16x16x32_bf16 v[120:123], v[160:163], v[168:171], v[120:123]
	v_mfma_f32_16x16x32_bf16 v[108:111], v[152:155], v[182:185], v[108:111]
	v_mfma_f32_16x16x32_bf16 v[104:107], v[160:163], v[182:185], v[104:107]
	v_mfma_f32_16x16x32_bf16 v[92:95], v[152:155], v[194:197], v[92:95]
	v_mfma_f32_16x16x32_bf16 v[88:91], v[160:163], v[194:197], v[88:91]
	v_mfma_f32_16x16x32_bf16 v[76:79], v[152:155], v[202:205], v[76:79]
	v_mfma_f32_16x16x32_bf16 v[72:75], v[160:163], v[202:205], v[72:75]
	v_mfma_f32_16x16x32_bf16 v[124:127], v[156:159], v[172:175], v[124:127]
	v_mfma_f32_16x16x32_bf16 v[120:123], v[164:167], v[172:175], v[120:123]
	v_mfma_f32_16x16x32_bf16 v[108:111], v[156:159], v[190:193], v[108:111]
	v_mfma_f32_16x16x32_bf16 v[104:107], v[164:167], v[190:193], v[104:107]
	v_mfma_f32_16x16x32_bf16 v[92:95], v[156:159], v[198:201], v[92:95]
	v_mfma_f32_16x16x32_bf16 v[88:91], v[164:167], v[198:201], v[88:91]
	v_mfma_f32_16x16x32_bf16 v[76:79], v[156:159], v[206:209], v[76:79]
	v_mfma_f32_16x16x32_bf16 v[72:75], v[164:167], v[206:209], v[72:75]
	s_barrier
	ds_read_b128 v[210:213], v151
	ds_read_b128 v[214:217], v151 offset:1024
	ds_read_b128 v[218:221], v151 offset:2048
	ds_read_b128 v[222:225], v151 offset:3072
	s_add_i32 s18, s42, s31
	v_lshl_add_u64 v[144:145], s[22:23], 0, v[130:131]
	s_mov_b32 m0, s18
	s_nop 0
	global_load_lds_dwordx4 v[144:145], off
	v_lshl_add_u64 v[186:187], s[22:23], 0, v[134:135]
	s_add_i32 m0, s18, 0x2000
	s_nop 0
	global_load_lds_dwordx4 v[186:187], off
	s_waitcnt lgkmcnt(0)
	s_barrier
	v_mfma_f32_16x16x32_bf16 v[116:119], v[210:213], v[168:171], v[116:119]
	v_mfma_f32_16x16x32_bf16 v[112:115], v[218:221], v[168:171], v[112:115]
	v_mfma_f32_16x16x32_bf16 v[100:103], v[210:213], v[182:185], v[100:103]
	v_mfma_f32_16x16x32_bf16 v[96:99], v[218:221], v[182:185], v[96:99]
	v_mfma_f32_16x16x32_bf16 v[84:87], v[210:213], v[194:197], v[84:87]
	v_mfma_f32_16x16x32_bf16 v[80:83], v[218:221], v[194:197], v[80:83]
	v_mfma_f32_16x16x32_bf16 v[68:71], v[210:213], v[202:205], v[68:71]
	v_mfma_f32_16x16x32_bf16 v[64:67], v[218:221], v[202:205], v[64:67]
	v_mfma_f32_16x16x32_bf16 v[116:119], v[214:217], v[172:175], v[116:119]
	v_mfma_f32_16x16x32_bf16 v[112:115], v[222:225], v[172:175], v[112:115]
	v_mfma_f32_16x16x32_bf16 v[100:103], v[214:217], v[190:193], v[100:103]
	v_mfma_f32_16x16x32_bf16 v[96:99], v[222:225], v[190:193], v[96:99]
	v_mfma_f32_16x16x32_bf16 v[84:87], v[214:217], v[198:201], v[84:87]
	v_mfma_f32_16x16x32_bf16 v[80:83], v[222:225], v[198:201], v[80:83]
	v_mfma_f32_16x16x32_bf16 v[68:71], v[214:217], v[206:209], v[68:71]
	v_mfma_f32_16x16x32_bf16 v[64:67], v[222:225], v[206:209], v[64:67]
	s_barrier
	s_mov_b32 m0, s34
	v_lshl_add_u64 v[226:227], s[24:25], 0, v[128:129]
	ds_read_b128 v[168:171], v150 offset:16384
	ds_read_b128 v[172:175], v150 offset:17408
	ds_read_b128 v[182:185], v150 offset:18432
	ds_read_b128 v[190:193], v150 offset:19456
	ds_read_b128 v[194:197], v150 offset:20480
	ds_read_b128 v[198:201], v150 offset:21504
	ds_read_b128 v[202:205], v150 offset:22528
	ds_read_b128 v[206:209], v150 offset:23552
	global_load_lds_dwordx4 v[226:227], off
	v_lshl_add_u64 v[228:229], s[24:25], 0, v[132:133]
	s_mov_b32 m0, s35
	s_nop 0
	global_load_lds_dwordx4 v[228:229], off
	s_waitcnt lgkmcnt(0)
	s_barrier
	v_mfma_f32_16x16x32_bf16 v[60:63], v[152:155], v[168:171], v[60:63]
	v_mfma_f32_16x16x32_bf16 v[56:59], v[160:163], v[168:171], v[56:59]
	v_mfma_f32_16x16x32_bf16 v[48:51], v[152:155], v[182:185], v[48:51]
	v_mfma_f32_16x16x32_bf16 v[40:43], v[160:163], v[182:185], v[40:43]
	v_mfma_f32_16x16x32_bf16 v[32:35], v[152:155], v[194:197], v[32:35]
	v_mfma_f32_16x16x32_bf16 v[24:27], v[160:163], v[194:197], v[24:27]
	v_mfma_f32_16x16x32_bf16 v[16:19], v[152:155], v[202:205], v[16:19]
	v_mfma_f32_16x16x32_bf16 v[8:11], v[160:163], v[202:205], v[8:11]
	v_mfma_f32_16x16x32_bf16 v[60:63], v[156:159], v[172:175], v[60:63]
	v_mfma_f32_16x16x32_bf16 v[56:59], v[164:167], v[172:175], v[56:59]
	v_mfma_f32_16x16x32_bf16 v[48:51], v[156:159], v[190:193], v[48:51]
	v_mfma_f32_16x16x32_bf16 v[40:43], v[164:167], v[190:193], v[40:43]
	v_mfma_f32_16x16x32_bf16 v[32:35], v[156:159], v[198:201], v[32:35]
	v_mfma_f32_16x16x32_bf16 v[24:27], v[164:167], v[198:201], v[24:27]
	v_mfma_f32_16x16x32_bf16 v[16:19], v[156:159], v[206:209], v[16:19]
	v_mfma_f32_16x16x32_bf16 v[8:11], v[164:167], v[206:209], v[8:11]
	s_barrier
; #define PG8_STAGE(bufoff, gbase, voff) do { _Pragma("unroll") for (int _i = 0; _i < 2; ++_i) \
;         __builtin_amdgcn_global_load_lds((const unsigned*)((const char*)(gbase) + (voff)[_i]), (PG8_LAS unsigned*)(lds + (bufoff) + ldsw + _i * 8192), 16, 0, 0); } while (0)
; #define PG8_LDA(dst, b, h) do { _Pragma("unroll") for (int m = 0; m < 4; ++m) _Pragma("unroll") for (int k = 0; k < 2; ++k) dst[m][k] = *(const PG8_LAS bf16x8*)(lds + PG8_SA(b, h) + aoff + m * 2048 + k * 1024); } while (0)
; #define PG8_LDB(dst, b, h) do { _Pragma("unroll") for (int n = 0; n < 2; ++n) _Pragma("unroll") for (int k = 0; k < 2; ++k) dst[n][k] = *(const PG8_LAS bf16x8*)(lds + PG8_SB(b, h) + boff + n * 2048 + k * 1024); } while (0)
; #define PG8_MMA(ai, bj, At, Bt) do { __builtin_amdgcn_s_setprio(1); _Pragma("unroll") for (int m = 0; m < 4; ++m) _Pragma("unroll") for (int n = 0; n < 2; ++n) _Pragma("unroll") for (int k = 0; k < 2; ++k) \
;         acc[ai][bj][m][n] = __builtin_amdgcn_mfma_f32_16x16x32_bf16(Bt[n][k], At[m][k], acc[ai][bj][m][n], 0, 0, 0); __builtin_amdgcn_s_setprio(0); } while (0)
; #define PG8_WAIT_V(n) asm volatile("s_waitcnt vmcnt(" #n ")" ::: "memory")
; #define PG8_WAIT_L(n) asm volatile("s_waitcnt lgkmcnt(" #n ")" ::: "memory")
; #define PG8_BAR __builtin_amdgcn_s_barrier()
; #define PG8_SCHED __builtin_amdgcn_sched_barrier(0)
; template <class Epi, class Sched>
; __device__ __forceinline__ void gemm_phase(PG8_LAS unsigned char* lds, const Gemm g, const Sched& S, const Epi& E) {
;     ...
;             PG8_STAGE(PG8_SB(0, 1), b2 + hstep, voffB);
;             PG8_WAIT_V(6); PG8_BAR; PG8_MMA(1, 1, At, B1); PG8_BAR;
;             PG8_LDB(B0, 1, 0); PG8_SCHED; PG8_LDA(At, 1, 0); PG8_STAGE(PG8_SA(0, 1), a2 + hstep, voffA);
;             PG8_WAIT_L(8); PG8_BAR; PG8_WAIT_L(0); PG8_MMA(0, 0, At, B0); PG8_BAR; PG8_SCHED;
;             PG8_LDB(B1, 1, 1); PG8_STAGE(PG8_SB(1, 0), b3, voffB);
;             PG8_BAR; PG8_WAIT_L(0); PG8_MMA(0, 1, At, B1); PG8_BAR;
;             PG8_LDA(At, 1, 1); PG8_STAGE(PG8_SA(1, 0), a3, voffA);
	s_add_u32 s18, s22, 0xb0000
	s_addc_u32 s19, s23, 0
	s_add_i32 s55, s43, s31
	v_lshl_add_u64 v[152:153], s[18:19], 0, v[130:131]
	s_mov_b32 m0, s55
	s_nop 0
	global_load_lds_dwordx4 v[152:153], off
	v_lshl_add_u64 v[152:153], s[18:19], 0, v[134:135]
	s_add_i32 m0, s55, 0x2000
	s_nop 0
	global_load_lds_dwordx4 v[152:153], off
	s_waitcnt vmcnt(6)
	s_barrier
	v_mfma_f32_16x16x32_bf16 v[52:55], v[210:213], v[168:171], v[52:55]
	v_mfma_f32_16x16x32_bf16 v[44:47], v[218:221], v[168:171], v[44:47]
	v_mfma_f32_16x16x32_bf16 v[36:39], v[210:213], v[182:185], v[36:39]
	v_mfma_f32_16x16x32_bf16 v[28:31], v[218:221], v[182:185], v[28:31]
	v_mfma_f32_16x16x32_bf16 v[20:23], v[210:213], v[194:197], v[20:23]
	v_mfma_f32_16x16x32_bf16 v[12:15], v[218:221], v[194:197], v[12:15]
	v_mfma_f32_16x16x32_bf16 v[4:7], v[210:213], v[202:205], v[4:7]
	v_mfma_f32_16x16x32_bf16 v[0:3], v[218:221], v[202:205], v[0:3]
	v_mfma_f32_16x16x32_bf16 v[52:55], v[214:217], v[172:175], v[52:55]
	v_mfma_f32_16x16x32_bf16 v[44:47], v[222:225], v[172:175], v[44:47]
	v_mfma_f32_16x16x32_bf16 v[36:39], v[214:217], v[190:193], v[36:39]
	v_mfma_f32_16x16x32_bf16 v[28:31], v[222:225], v[190:193], v[28:31]
	v_mfma_f32_16x16x32_bf16 v[20:23], v[214:217], v[198:201], v[20:23]
	v_mfma_f32_16x16x32_bf16 v[12:15], v[222:225], v[198:201], v[12:15]
	v_mfma_f32_16x16x32_bf16 v[4:7], v[214:217], v[206:209], v[4:7]
	v_mfma_f32_16x16x32_bf16 v[0:3], v[222:225], v[206:209], v[0:3]
	s_barrier
	s_add_i32 s55, 0, 0x18000
	v_add_u32_e32 v164, s55, v147
	ds_read_b128 v[152:155], v164
	ds_read_b128 v[156:159], v164 offset:1024
	ds_read_b128 v[160:163], v164 offset:2048
	ds_read_b128 v[164:167], v164 offset:3072
	ds_read_b128 v[168:171], v150 offset:32768
	ds_read_b128 v[172:175], v150 offset:33792
	ds_read_b128 v[182:185], v150 offset:34816
	ds_read_b128 v[190:193], v150 offset:35840
	ds_read_b128 v[194:197], v150 offset:36864
	ds_read_b128 v[198:201], v150 offset:37888
	ds_read_b128 v[202:205], v150 offset:38912
	ds_read_b128 v[206:209], v150 offset:39936
	s_add_u32 s18, s24, 0xb0000
	s_addc_u32 s19, s25, 0
	s_mov_b32 m0, s36
	v_lshl_add_u64 v[210:211], s[18:19], 0, v[128:129]
	global_load_lds_dwordx4 v[210:211], off
	v_lshl_add_u64 v[210:211], s[18:19], 0, v[132:133]
	s_mov_b32 m0, s37
	s_nop 0
	global_load_lds_dwordx4 v[210:211], off
	s_waitcnt lgkmcnt(0)
	s_barrier
	v_mfma_f32_16x16x32_bf16 v[124:127], v[152:155], v[168:171], v[124:127]
	v_mfma_f32_16x16x32_bf16 v[120:123], v[160:163], v[168:171], v[120:123]
	v_mfma_f32_16x16x32_bf16 v[108:111], v[152:155], v[182:185], v[108:111]
	v_mfma_f32_16x16x32_bf16 v[104:107], v[160:163], v[182:185], v[104:107]
	v_mfma_f32_16x16x32_bf16 v[92:95], v[152:155], v[194:197], v[92:95]
	v_mfma_f32_16x16x32_bf16 v[88:91], v[160:163], v[194:197], v[88:91]
	v_mfma_f32_16x16x32_bf16 v[76:79], v[152:155], v[202:205], v[76:79]
	v_mfma_f32_16x16x32_bf16 v[72:75], v[160:163], v[202:205], v[72:75]
	v_mfma_f32_16x16x32_bf16 v[124:127], v[156:159], v[172:175], v[124:127]
	v_mfma_f32_16x16x32_bf16 v[120:123], v[164:167], v[172:175], v[120:123]
	v_mfma_f32_16x16x32_bf16 v[108:111], v[156:159], v[190:193], v[108:111]
	v_mfma_f32_16x16x32_bf16 v[104:107], v[164:167], v[190:193], v[104:107]
	v_mfma_f32_16x16x32_bf16 v[92:95], v[156:159], v[198:201], v[92:95]
	v_mfma_f32_16x16x32_bf16 v[88:91], v[164:167], v[198:201], v[88:91]
	v_mfma_f32_16x16x32_bf16 v[76:79], v[156:159], v[206:209], v[76:79]
	v_mfma_f32_16x16x32_bf16 v[72:75], v[164:167], v[206:209], v[72:75]
	s_barrier
	s_add_i32 s24, 0, 0x1c000
	v_add_u32_e32 v179, s24, v147
	ds_read_b128 v[210:213], v179
	ds_read_b128 v[214:217], v179 offset:1024
	ds_read_b128 v[218:221], v179 offset:2048
	ds_read_b128 v[222:225], v179 offset:3072
	s_add_i32 s18, s55, s31
	v_lshl_add_u64 v[144:145], v[144:145], 0, s[8:9]
	s_mov_b32 m0, s18
	s_nop 0
	global_load_lds_dwordx4 v[144:145], off
	v_lshl_add_u64 v[144:145], v[186:187], 0, s[8:9]
	s_add_i32 m0, s18, 0x2000
	s_nop 0
	global_load_lds_dwordx4 v[144:145], off
	s_waitcnt lgkmcnt(0)
	s_barrier
	v_mfma_f32_16x16x32_bf16 v[116:119], v[210:213], v[168:171], v[116:119]
	v_mfma_f32_16x16x32_bf16 v[112:115], v[218:221], v[168:171], v[112:115]
	v_mfma_f32_16x16x32_bf16 v[100:103], v[210:213], v[182:185], v[100:103]
	v_mfma_f32_16x16x32_bf16 v[96:99], v[218:221], v[182:185], v[96:99]
	v_mfma_f32_16x16x32_bf16 v[84:87], v[210:213], v[194:197], v[84:87]
	v_mfma_f32_16x16x32_bf16 v[80:83], v[218:221], v[194:197], v[80:83]
	v_mfma_f32_16x16x32_bf16 v[68:71], v[210:213], v[202:205], v[68:71]
	v_mfma_f32_16x16x32_bf16 v[64:67], v[218:221], v[202:205], v[64:67]
	v_mfma_f32_16x16x32_bf16 v[116:119], v[214:217], v[172:175], v[116:119]
	v_mfma_f32_16x16x32_bf16 v[112:115], v[222:225], v[172:175], v[112:115]
	v_mfma_f32_16x16x32_bf16 v[100:103], v[214:217], v[190:193], v[100:103]
	v_mfma_f32_16x16x32_bf16 v[96:99], v[222:225], v[190:193], v[96:99]
	v_mfma_f32_16x16x32_bf16 v[84:87], v[214:217], v[198:201], v[84:87]
	v_mfma_f32_16x16x32_bf16 v[80:83], v[222:225], v[198:201], v[80:83]
	v_mfma_f32_16x16x32_bf16 v[68:71], v[214:217], v[206:209], v[68:71]
	v_mfma_f32_16x16x32_bf16 v[64:67], v[222:225], v[206:209], v[64:67]
	s_barrier
	s_mov_b32 m0, s39
	v_lshl_add_u64 v[144:145], v[226:227], 0, s[8:9]
	ds_read_b128 v[168:171], v150 offset:49152
	ds_read_b128 v[172:175], v150 offset:50176
	ds_read_b128 v[182:185], v150 offset:51200
	ds_read_b128 v[190:193], v150 offset:52224
	ds_read_b128 v[194:197], v150 offset:53248
	ds_read_b128 v[198:201], v150 offset:54272
	ds_read_b128 v[202:205], v150 offset:55296
	ds_read_b128 v[206:209], v150 offset:56320
	global_load_lds_dwordx4 v[144:145], off
	v_lshl_add_u64 v[144:145], v[228:229], 0, s[8:9]
	s_mov_b32 m0, s40
	s_nop 0
	global_load_lds_dwordx4 v[144:145], off
	s_waitcnt lgkmcnt(0)
	s_barrier
; __device__ __forceinline__ unsigned cvt_pk_bf16(float lo, float hi) { unsigned r; asm volatile("v_cvt_pk_bf16_f32 %0, %1, %2" : "=v"(r) : "v"(lo), "v"(hi)); return r; }
; __device__ __forceinline__ float flogsig16(float x) { return (fminf(x, 0.f) - __logf(1.0f + __expf(-fabsf(x)))) * 0.0625f; }
; #define PG8_WAIT_V(n) asm volatile("s_waitcnt vmcnt(" #n ")" ::: "memory")
; #define PG8_WAIT_L(n) asm volatile("s_waitcnt lgkmcnt(" #n ")" ::: "memory")
;     __device__ __forceinline__ void operator()(const f32x4 (&acc)[2][2][4][2], const Unit& u, int wr, int wc, int fr, int fq) const {
;     ...
;         const int row0 = u.pm * BM + wr * 64 + fr, col0 = u.pn * BM + wc * 32 + 8 * fq, bcol0 = wc * 32 + 8 * fq;
;         f32x4 bv[2][2];
; #pragma unroll
;         for (int bj = 0; bj < 2; ++bj)
; #pragma unroll
;             for (int n = 0; n < 2; ++n) bv[bj][n] = bias ? *(const f32x4*)(bias + bcol0 + bj * HALF + 4 * n) : (f32x4){0.f, 0.f, 0.f, 0.f};
; #pragma unroll
;         for (int ai = 0; ai < 2; ++ai)
; #pragma unroll
;             for (int m = 0; m < 4; ++m) { bf16_t* rowp = O + (size_t)(row0 + ai * HALF + m * 16) * ldc + col0;
; #pragma unroll
;                 for (int bj = 0; bj < 2; ++bj) { f32x4 v0 = acc[ai][bj][m][0] + bv[bj][0], v1 = acc[ai][bj][m][1] + bv[bj][1];
;                     if (act == 1) {
; #pragma unroll
;                         for (int j = 0; j < 1; ++j) { v0 = v0 * sigmoid4(v0); v1 = v1 * sigmoid4(v1); } }
;                     else if (act == 2) {
; #pragma unroll
;                         for (int j = 0; j < 1; ++j) { v0 = sigmoid4(v0); v1 = sigmoid4(v1); } }
;                     else if (act == 3) {
; #pragma unroll
;                         for (int j = 0; j < 4; ++j) { v0[j] = flogsig16(v0[j]); v1[j] = flogsig16(v1[j]); } }
;                     u32x4 w; w.x = cvt_pk_bf16(v0[0], v0[1]); w.y = cvt_pk_bf16(v0[2], v0[3]); w.z = cvt_pk_bf16(v1[0], v1[1]); w.w = cvt_pk_bf16(v1[2], v1[3]);
;                     *(u32x4*)(rowp + bj * HALF) = w; } }
; template <class Epi, class Sched>
; __device__ __forceinline__ void gemm_phase(PG8_LAS unsigned char* lds, const Gemm g, const Sched& S, const Epi& E) {
;     ...
;             PG8_BAR; PG8_WAIT_L(0); PG8_MMA(1, 0, At, B0); PG8_BAR; PG8_SCHED;
;             PG8_STAGE(PG8_SB(1, 1), b3 + hstep, voffB);
;             PG8_WAIT_V(6); PG8_BAR; PG8_MMA(1, 1, At, B1); PG8_BAR;
	v_mfma_f32_16x16x32_bf16 v[60:63], v[152:155], v[168:171], v[60:63]
	v_mfma_f32_16x16x32_bf16 v[56:59], v[160:163], v[168:171], v[56:59]
	v_mfma_f32_16x16x32_bf16 v[48:51], v[152:155], v[182:185], v[48:51]
	v_mfma_f32_16x16x32_bf16 v[40:43], v[160:163], v[182:185], v[40:43]
	v_mfma_f32_16x16x32_bf16 v[32:35], v[152:155], v[194:197], v[32:35]
	v_mfma_f32_16x16x32_bf16 v[24:27], v[160:163], v[194:197], v[24:27]
	v_mfma_f32_16x16x32_bf16 v[16:19], v[152:155], v[202:205], v[16:19]
	v_mfma_f32_16x16x32_bf16 v[8:11], v[160:163], v[202:205], v[8:11]
	v_mfma_f32_16x16x32_bf16 v[60:63], v[156:159], v[172:175], v[60:63]
	v_mfma_f32_16x16x32_bf16 v[56:59], v[164:167], v[172:175], v[56:59]
	v_mfma_f32_16x16x32_bf16 v[48:51], v[156:159], v[190:193], v[48:51]
	v_mfma_f32_16x16x32_bf16 v[40:43], v[164:167], v[190:193], v[40:43]
	v_mfma_f32_16x16x32_bf16 v[32:35], v[156:159], v[198:201], v[32:35]
	v_mfma_f32_16x16x32_bf16 v[24:27], v[164:167], v[198:201], v[24:27]
	v_mfma_f32_16x16x32_bf16 v[16:19], v[156:159], v[206:209], v[16:19]
	v_mfma_f32_16x16x32_bf16 v[8:11], v[164:167], v[206:209], v[8:11]
	s_barrier
	s_add_u32 s18, s22, 0xb0080
	s_addc_u32 s19, s23, 0
	s_add_i32 s22, s24, s31
	v_lshl_add_u64 v[144:145], s[18:19], 0, v[130:131]
	s_mov_b32 m0, s22
	s_nop 0
	global_load_lds_dwordx4 v[144:145], off
	v_lshl_add_u64 v[144:145], s[18:19], 0, v[134:135]
	s_add_i32 m0, s22, 0x2000
	s_nop 0
	global_load_lds_dwordx4 v[144:145], off
	s_waitcnt vmcnt(6)
	s_barrier
	v_mfma_f32_16x16x32_bf16 v[52:55], v[210:213], v[168:171], v[52:55]
	v_mfma_f32_16x16x32_bf16 v[44:47], v[218:221], v[168:171], v[44:47]
	v_mfma_f32_16x16x32_bf16 v[36:39], v[210:213], v[182:185], v[36:39]
	v_mfma_f32_16x16x32_bf16 v[28:31], v[218:221], v[182:185], v[28:31]
	v_mfma_f32_16x16x32_bf16 v[20:23], v[210:213], v[194:197], v[20:23]
	v_mfma_f32_16x16x32_bf16 v[12:15], v[218:221], v[194:197], v[12:15]
	v_mfma_f32_16x16x32_bf16 v[4:7], v[210:213], v[202:205], v[4:7]
	v_mfma_f32_16x16x32_bf16 v[0:3], v[218:221], v[202:205], v[0:3]
	v_mfma_f32_16x16x32_bf16 v[52:55], v[214:217], v[172:175], v[52:55]
	v_mfma_f32_16x16x32_bf16 v[44:47], v[222:225], v[172:175], v[44:47]
	v_mfma_f32_16x16x32_bf16 v[36:39], v[214:217], v[190:193], v[36:39]
	v_mfma_f32_16x16x32_bf16 v[28:31], v[222:225], v[190:193], v[28:31]
	v_mfma_f32_16x16x32_bf16 v[20:23], v[214:217], v[198:201], v[20:23]
	v_mfma_f32_16x16x32_bf16 v[12:15], v[222:225], v[198:201], v[12:15]
	v_mfma_f32_16x16x32_bf16 v[4:7], v[214:217], v[206:209], v[4:7]
	v_mfma_f32_16x16x32_bf16 v[0:3], v[222:225], v[206:209], v[0:3]
	s_add_i32 s54, s54, 2
	s_add_u32 s52, s52, 0x100
	s_addc_u32 s53, s53, 0
	s_cmp_gt_u32 s54, 41
	s_mov_b64 s[18:19], s[20:21]
	s_barrier
	s_cbranch_scc0 .LBB0_1278
	v_lshl_add_u32 v152, s50, 8, v146
	v_lshl_or_b32 v144, s51, 8, v148
	v_ashrrev_i32_e32 v153, 31, v152
	v_ashrrev_i32_e32 v145, 31, v144
	v_lshlrev_b64 v[154:155], 11, v[152:153]
	v_lshl_add_u64 v[154:155], s[6:7], 0, v[154:155]
	v_lshlrev_b64 v[156:157], 1, v[144:145]
	v_lshl_add_u64 v[144:145], v[154:155], 0, v[156:157]
	v_pk_add_f32 v[126:127], v[126:127], 0 op_sel_hi:[1,0]
	v_pk_add_f32 v[124:125], v[124:125], 0 op_sel_hi:[1,0]
	v_pk_add_f32 v[154:155], v[122:123], 0 op_sel_hi:[1,0]
	v_pk_add_f32 v[122:123], v[120:121], 0 op_sel_hi:[1,0]
	v_cvt_pk_bf16_f32 v120, v124, v125
	v_cvt_pk_bf16_f32 v121, v126, v127
	v_pk_add_f32 v[116:117], v[116:117], 0 op_sel_hi:[1,0]
	v_cvt_pk_bf16_f32 v122, v122, v123
	v_cvt_pk_bf16_f32 v123, v154, v155
	global_store_dwordx4 v[144:145], v[120:123], off
	v_pk_add_f32 v[118:119], v[118:119], 0 op_sel_hi:[1,0]
	v_pk_add_f32 v[110:111], v[110:111], 0 op_sel_hi:[1,0]
	v_pk_add_f32 v[120:121], v[114:115], 0 op_sel_hi:[1,0]
	v_pk_add_f32 v[114:115], v[112:113], 0 op_sel_hi:[1,0]
	v_cvt_pk_bf16_f32 v112, v116, v117
	v_cvt_pk_bf16_f32 v113, v118, v119
	v_pk_add_f32 v[108:109], v[108:109], 0 op_sel_hi:[1,0]
	v_cvt_pk_bf16_f32 v114, v114, v115
	v_cvt_pk_bf16_f32 v115, v120, v121
	global_store_dwordx4 v[144:145], v[112:115], off offset:256
	v_pk_add_f32 v[100:101], v[100:101], 0 op_sel_hi:[1,0]
	v_pk_add_f32 v[102:103], v[102:103], 0 op_sel_hi:[1,0]
	v_or_b32_e32 v112, 16, v152
	v_ashrrev_i32_e32 v113, 31, v112
	v_lshlrev_b64 v[112:113], 11, v[112:113]
	v_lshl_add_u64 v[112:113], s[6:7], 0, v[112:113]
	v_lshl_add_u64 v[112:113], v[112:113], 0, v[156:157]
	v_pk_add_f32 v[114:115], v[106:107], 0 op_sel_hi:[1,0]
	v_pk_add_f32 v[106:107], v[104:105], 0 op_sel_hi:[1,0]
	v_cvt_pk_bf16_f32 v104, v108, v109
	v_cvt_pk_bf16_f32 v105, v110, v111
	v_pk_add_f32 v[94:95], v[94:95], 0 op_sel_hi:[1,0]
	v_cvt_pk_bf16_f32 v106, v106, v107
	v_cvt_pk_bf16_f32 v107, v114, v115
	global_store_dwordx4 v[112:113], v[104:107], off
	v_pk_add_f32 v[92:93], v[92:93], 0 op_sel_hi:[1,0]
	v_pk_add_f32 v[84:85], v[84:85], 0 op_sel_hi:[1,0]
	v_pk_add_f32 v[104:105], v[98:99], 0 op_sel_hi:[1,0]
	v_pk_add_f32 v[98:99], v[96:97], 0 op_sel_hi:[1,0]
	v_cvt_pk_bf16_f32 v96, v100, v101
	v_cvt_pk_bf16_f32 v97, v102, v103
	v_pk_add_f32 v[86:87], v[86:87], 0 op_sel_hi:[1,0]
	v_cvt_pk_bf16_f32 v98, v98, v99
	v_cvt_pk_bf16_f32 v99, v104, v105
	global_store_dwordx4 v[112:113], v[96:99], off offset:256
	v_pk_add_f32 v[78:79], v[78:79], 0 op_sel_hi:[1,0]
	v_pk_add_f32 v[76:77], v[76:77], 0 op_sel_hi:[1,0]
	v_or_b32_e32 v96, 32, v152
	v_ashrrev_i32_e32 v97, 31, v96
	v_lshlrev_b64 v[96:97], 11, v[96:97]
	v_lshl_add_u64 v[96:97], s[6:7], 0, v[96:97]
	v_lshl_add_u64 v[96:97], v[96:97], 0, v[156:157]
; __device__ __forceinline__ unsigned cvt_pk_bf16(float lo, float hi) { unsigned r; asm volatile("v_cvt_pk_bf16_f32 %0, %1, %2" : "=v"(r) : "v"(lo), "v"(hi)); return r; }
; __device__ __forceinline__ float flogsig16(float x) { return (fminf(x, 0.f) - __logf(1.0f + __expf(-fabsf(x)))) * 0.0625f; }
;     __device__ __forceinline__ void operator()(const f32x4 (&acc)[2][2][4][2], const Unit& u, int wr, int wc, int fr, int fq) const {
;     ...
;         for (int ai = 0; ai < 2; ++ai)
; #pragma unroll
;             for (int m = 0; m < 4; ++m) { bf16_t* rowp = O + (size_t)(row0 + ai * HALF + m * 16) * ldc + col0;
; #pragma unroll
;                 for (int bj = 0; bj < 2; ++bj) { f32x4 v0 = acc[ai][bj][m][0] + bv[bj][0], v1 = acc[ai][bj][m][1] + bv[bj][1];
;                     if (act == 1) {
; #pragma unroll
;                         for (int j = 0; j < 1; ++j) { v0 = v0 * sigmoid4(v0); v1 = v1 * sigmoid4(v1); } }
;                     else if (act == 2) {
; #pragma unroll
;                         for (int j = 0; j < 1; ++j) { v0 = sigmoid4(v0); v1 = sigmoid4(v1); } }
;                     else if (act == 3) {
; #pragma unroll
;                         for (int j = 0; j < 4; ++j) { v0[j] = flogsig16(v0[j]); v1[j] = flogsig16(v1[j]); } }
;                     u32x4 w; w.x = cvt_pk_bf16(v0[0], v0[1]); w.y = cvt_pk_bf16(v0[2], v0[3]); w.z = cvt_pk_bf16(v1[0], v1[1]); w.w = cvt_pk_bf16(v1[2], v1[3]);
;                     *(u32x4*)(rowp + bj * HALF) = w; } }
	v_pk_add_f32 v[98:99], v[90:91], 0 op_sel_hi:[1,0]
	v_pk_add_f32 v[90:91], v[88:89], 0 op_sel_hi:[1,0]
	v_cvt_pk_bf16_f32 v88, v92, v93
	v_cvt_pk_bf16_f32 v89, v94, v95
	v_pk_add_f32 v[70:71], v[70:71], 0 op_sel_hi:[1,0]
	v_cvt_pk_bf16_f32 v90, v90, v91
	v_cvt_pk_bf16_f32 v91, v98, v99
	global_store_dwordx4 v[96:97], v[88:91], off
	v_pk_add_f32 v[68:69], v[68:69], 0 op_sel_hi:[1,0]
	v_pk_add_f32 v[60:61], v[60:61], 0 op_sel_hi:[1,0]
	v_pk_add_f32 v[88:89], v[82:83], 0 op_sel_hi:[1,0]
	v_pk_add_f32 v[82:83], v[80:81], 0 op_sel_hi:[1,0]
	v_cvt_pk_bf16_f32 v80, v84, v85
	v_cvt_pk_bf16_f32 v81, v86, v87
	v_pk_add_f32 v[62:63], v[62:63], 0 op_sel_hi:[1,0]
	v_cvt_pk_bf16_f32 v82, v82, v83
	v_cvt_pk_bf16_f32 v83, v88, v89
	global_store_dwordx4 v[96:97], v[80:83], off offset:256
	v_pk_add_f32 v[54:55], v[54:55], 0 op_sel_hi:[1,0]
	v_pk_add_f32 v[52:53], v[52:53], 0 op_sel_hi:[1,0]
	v_or_b32_e32 v80, 48, v152
	v_ashrrev_i32_e32 v81, 31, v80
	v_lshlrev_b64 v[80:81], 11, v[80:81]
	v_lshl_add_u64 v[80:81], s[6:7], 0, v[80:81]
	v_lshl_add_u64 v[80:81], v[80:81], 0, v[156:157]
	v_pk_add_f32 v[82:83], v[74:75], 0 op_sel_hi:[1,0]
	v_pk_add_f32 v[74:75], v[72:73], 0 op_sel_hi:[1,0]
	v_cvt_pk_bf16_f32 v72, v76, v77
	v_cvt_pk_bf16_f32 v73, v78, v79
	v_pk_add_f32 v[48:49], v[48:49], 0 op_sel_hi:[1,0]
	v_cvt_pk_bf16_f32 v74, v74, v75
	v_cvt_pk_bf16_f32 v75, v82, v83
	global_store_dwordx4 v[80:81], v[72:75], off
	v_pk_add_f32 v[38:39], v[38:39], 0 op_sel_hi:[1,0]
	v_pk_add_f32 v[36:37], v[36:37], 0 op_sel_hi:[1,0]
	v_pk_add_f32 v[72:73], v[66:67], 0 op_sel_hi:[1,0]
	v_pk_add_f32 v[66:67], v[64:65], 0 op_sel_hi:[1,0]
	v_cvt_pk_bf16_f32 v64, v68, v69
	v_cvt_pk_bf16_f32 v65, v70, v71
	v_pk_add_f32 v[32:33], v[32:33], 0 op_sel_hi:[1,0]
	v_cvt_pk_bf16_f32 v66, v66, v67
	v_cvt_pk_bf16_f32 v67, v72, v73
	global_store_dwordx4 v[80:81], v[64:67], off offset:256
	v_pk_add_f32 v[22:23], v[22:23], 0 op_sel_hi:[1,0]
	v_pk_add_f32 v[20:21], v[20:21], 0 op_sel_hi:[1,0]
	v_pk_add_f32 v[66:67], v[58:59], 0 op_sel_hi:[1,0]
	v_pk_add_f32 v[58:59], v[56:57], 0 op_sel_hi:[1,0]
	v_cvt_pk_bf16_f32 v56, v60, v61
	v_add_co_u32_e32 v60, vcc, s44, v144
	v_cvt_pk_bf16_f32 v57, v62, v63
	v_cvt_pk_bf16_f32 v58, v58, v59
	v_cvt_pk_bf16_f32 v59, v66, v67
	v_lshl_add_u64 v[64:65], v[144:145], 0, s[10:11]
	s_nop 0
	v_addc_co_u32_e32 v61, vcc, 0, v145, vcc
	global_store_dwordx4 v[60:61], v[56:59], off
	v_pk_add_f32 v[16:17], v[16:17], 0 op_sel_hi:[1,0]
	s_mov_b32 s51, s48
	v_pk_add_f32 v[56:57], v[46:47], 0 op_sel_hi:[1,0]
	v_pk_add_f32 v[46:47], v[44:45], 0 op_sel_hi:[1,0]
	v_cvt_pk_bf16_f32 v44, v52, v53
	v_cvt_pk_bf16_f32 v45, v54, v55
	s_mov_b32 s50, s49
	v_cvt_pk_bf16_f32 v46, v46, v47
	v_cvt_pk_bf16_f32 v47, v56, v57
	global_store_dwordx4 v[64:65], v[44:47], off offset:256
	s_mov_b64 s[20:21], s[4:5]
	s_mov_b64 s[18:19], s[0:1]
	v_pk_add_f32 v[46:47], v[50:51], 0 op_sel_hi:[1,0]
	v_pk_add_f32 v[50:51], v[42:43], 0 op_sel_hi:[1,0]
	v_pk_add_f32 v[42:43], v[40:41], 0 op_sel_hi:[1,0]
	v_cvt_pk_bf16_f32 v40, v48, v49
	v_cvt_pk_bf16_f32 v41, v46, v47
	v_add_co_u32_e32 v46, vcc, s45, v144
	v_cvt_pk_bf16_f32 v42, v42, v43
	v_cvt_pk_bf16_f32 v43, v50, v51
	v_lshl_add_u64 v[44:45], v[144:145], 0, s[12:13]
	s_nop 0
	v_addc_co_u32_e32 v47, vcc, 0, v145, vcc
	global_store_dwordx4 v[46:47], v[40:43], off
	v_pk_add_f32 v[6:7], v[6:7], 0 op_sel_hi:[1,0]
	v_pk_add_f32 v[4:5], v[4:5], 0 op_sel_hi:[1,0]
	v_pk_add_f32 v[40:41], v[30:31], 0 op_sel_hi:[1,0]
	v_pk_add_f32 v[30:31], v[28:29], 0 op_sel_hi:[1,0]
	v_cvt_pk_bf16_f32 v28, v36, v37
	v_cvt_pk_bf16_f32 v29, v38, v39
	s_nop 0
	v_cvt_pk_bf16_f32 v30, v30, v31
	v_cvt_pk_bf16_f32 v31, v40, v41
	global_store_dwordx4 v[44:45], v[28:31], off offset:256
	s_nop 1
	v_pk_add_f32 v[30:31], v[34:35], 0 op_sel_hi:[1,0]
	v_pk_add_f32 v[34:35], v[26:27], 0 op_sel_hi:[1,0]
	v_pk_add_f32 v[26:27], v[24:25], 0 op_sel_hi:[1,0]
	v_cvt_pk_bf16_f32 v24, v32, v33
	v_cvt_pk_bf16_f32 v25, v30, v31
	v_add_co_u32_e32 v30, vcc, s46, v144
	v_cvt_pk_bf16_f32 v26, v26, v27
	v_cvt_pk_bf16_f32 v27, v34, v35
	v_lshl_add_u64 v[28:29], v[144:145], 0, s[14:15]
	s_nop 0
	v_addc_co_u32_e32 v31, vcc, 0, v145, vcc
	global_store_dwordx4 v[30:31], v[24:27], off
	s_nop 1
	v_pk_add_f32 v[24:25], v[14:15], 0 op_sel_hi:[1,0]
	v_pk_add_f32 v[14:15], v[12:13], 0 op_sel_hi:[1,0]
	v_cvt_pk_bf16_f32 v12, v20, v21
	v_cvt_pk_bf16_f32 v13, v22, v23
	s_nop 0
	v_cvt_pk_bf16_f32 v14, v14, v15
	v_cvt_pk_bf16_f32 v15, v24, v25
	global_store_dwordx4 v[28:29], v[12:15], off offset:256
	s_nop 1
	v_pk_add_f32 v[14:15], v[18:19], 0 op_sel_hi:[1,0]
	v_pk_add_f32 v[18:19], v[10:11], 0 op_sel_hi:[1,0]
	v_pk_add_f32 v[10:11], v[8:9], 0 op_sel_hi:[1,0]
	v_cvt_pk_bf16_f32 v8, v16, v17
	v_cvt_pk_bf16_f32 v9, v14, v15
	v_add_co_u32_e32 v14, vcc, s47, v144
	v_lshl_add_u64 v[12:13], v[144:145], 0, s[16:17]
	s_nop 0
	v_addc_co_u32_e32 v15, vcc, 0, v145, vcc
	v_cvt_pk_bf16_f32 v10, v10, v11
	v_cvt_pk_bf16_f32 v11, v18, v19
	global_store_dwordx4 v[14:15], v[8:11], off
	s_and_b64 vcc, exec, s[2:3]
	s_nop 0
	v_pk_add_f32 v[8:9], v[2:3], 0 op_sel_hi:[1,0]
	v_pk_add_f32 v[2:3], v[0:1], 0 op_sel_hi:[1,0]
	v_cvt_pk_bf16_f32 v0, v4, v5
	v_cvt_pk_bf16_f32 v1, v6, v7
	s_nop 0
	v_cvt_pk_bf16_f32 v2, v2, v3
	v_cvt_pk_bf16_f32 v3, v8, v9
	global_store_dwordx4 v[12:13], v[0:3], off offset:256
	s_cbranch_vccz .LBB0_1267
	s_waitcnt vmcnt(0)
	s_cmpk_gt_u32 s27, 0xff
	s_cbranch_scc1 .LBB0_1282
	s_barrier
